# K=2 late barrier + residual stream X loads/stores made cacheable (nt removed) in residual epilogues and final phase
# baseline (speedup 1.0000x reference)
.LBB0_899:
	s_lshr_b32 s16, s94, 4
	s_add_i32 s16, s16, -1
	s_cmp_gt_i32 s94, 31
	s_cselect_b32 s16, s16, 0
	v_lshl_or_b32 v70, s12, 8, v228
	s_mul_i32 s47, s16, 0xc000
	s_mul_hi_i32 s46, s16, 0xc000
	s_add_u32 s16, s91, s47
	v_ashrrev_i32_e32 v71, 31, v70
	s_addc_u32 s17, s92, s46
	v_lshlrev_b64 v[108:109], 2, v[70:71]
	v_lshl_add_u64 v[26:27], s[16:17], 0, v[108:109]
	v_lshl_add_u64 v[28:29], s[24:25], 0, v[108:109]
	s_waitcnt lgkmcnt(0)
	global_load_dwordx4 v[2:5], v[26:27], off offset:16
	global_load_dwordx4 v[6:9], v[26:27], off
	global_load_dwordx4 v[10:13], v[28:29], off offset:16
	global_load_dwordx4 v[14:17], v[28:29], off
	s_add_u32 s16, s88, s47
	v_lshl_add_u64 v[30:31], s[28:29], 0, v[108:109]
	s_addc_u32 s17, s89, s46
	v_lshl_add_u64 v[32:33], s[16:17], 0, v[108:109]
	v_lshl_add_u32 v118, s94, 8, v226
	v_cmp_gt_i32_e32 vcc, s87, v118
	v_ashrrev_i32_e32 v119, 31, v118
	v_or_b32_e32 v34, 16, v118
	v_ashrrev_i32_e32 v35, 31, v34
	s_lshl_b32 s46, s12, 2
	s_ashr_i32 s47, s46, 31
	s_waitcnt vmcnt(0)
	v_pk_mul_f32 v[88:89], v[4:5], v[12:13]
	v_pk_mul_f32 v[76:77], v[8:9], v[16:17]
	v_pk_mul_f32 v[78:79], v[6:7], v[14:15]
	global_load_dwordx4 v[6:9], v[30:31], off offset:16
	global_load_dwordx4 v[14:17], v[30:31], off
	global_load_dwordx4 v[18:21], v[32:33], off offset:16
	global_load_dwordx4 v[22:25], v[32:33], off
	v_pk_mul_f32 v[90:91], v[2:3], v[10:11]
	s_waitcnt vmcnt(0)
	v_pk_add_f32 v[2:3], v[20:21], 1.0 op_sel_hi:[1,0]
	v_pk_add_f32 v[24:25], v[24:25], 1.0 op_sel_hi:[1,0]
	v_pk_add_f32 v[22:23], v[22:23], 1.0 op_sel_hi:[1,0]
	v_pk_add_f32 v[4:5], v[18:19], 1.0 op_sel_hi:[1,0]
	v_pk_mul_f32 v[80:81], v[16:17], v[24:25]
	v_pk_mul_f32 v[82:83], v[14:15], v[22:23]
	v_pk_mul_f32 v[84:85], v[8:9], v[2:3]
	v_pk_mul_f32 v[86:87], v[6:7], v[4:5]
	global_load_dwordx4 v[2:5], v[26:27], off offset:528
	global_load_dwordx4 v[6:9], v[26:27], off offset:512
	global_load_dwordx4 v[10:13], v[28:29], off offset:528
	global_load_dwordx4 v[14:17], v[28:29], off offset:512
	s_waitcnt vmcnt(0)
	v_pk_mul_f32 v[72:73], v[2:3], v[10:11]
	v_pk_mul_f32 v[66:67], v[8:9], v[16:17]
	v_pk_mul_f32 v[68:69], v[6:7], v[14:15]
	global_load_dwordx4 v[6:9], v[30:31], off offset:528
	global_load_dwordx4 v[14:17], v[30:31], off offset:512
	global_load_dwordx4 v[18:21], v[32:33], off offset:528
	global_load_dwordx4 v[22:25], v[32:33], off offset:512
	v_pk_mul_f32 v[74:75], v[4:5], v[12:13]
	s_waitcnt vmcnt(0)
	v_pk_add_f32 v[2:3], v[20:21], 1.0 op_sel_hi:[1,0]
	v_pk_add_f32 v[4:5], v[18:19], 1.0 op_sel_hi:[1,0]
	v_pk_mul_f32 v[62:63], v[8:9], v[2:3]
	v_add_u32_e32 v2, 0xffffe000, v118
	v_pk_mul_f32 v[64:65], v[6:7], v[4:5]
	v_cndmask_b32_e32 v3, 0, v119, vcc
	v_cndmask_b32_e32 v2, v2, v118, vcc
	v_mov_b32_e32 v6, s59
	v_mov_b32_e32 v7, s57
	v_mov_b32_e32 v8, s58
	v_mov_b32_e32 v9, s56
	v_cndmask_b32_e32 v5, v6, v7, vcc
	v_cndmask_b32_e32 v4, v8, v9, vcc
	v_lshlrev_b64 v[2:3], 13, v[2:3]
	v_lshl_add_u64 v[2:3], v[4:5], 0, v[2:3]
	v_pk_add_f32 v[24:25], v[24:25], 1.0 op_sel_hi:[1,0]
	v_pk_add_f32 v[22:23], v[22:23], 1.0 op_sel_hi:[1,0]
	v_lshl_add_u64 v[2:3], v[2:3], 0, v[108:109]
	v_pk_mul_f32 v[58:59], v[16:17], v[24:25]
	v_pk_mul_f32 v[60:61], v[14:15], v[22:23]
	global_load_dwordx4 v[26:29], v[2:3], off offset:16
	global_load_dwordx4 v[30:33], v[2:3], off
	global_load_dwordx4 v[18:21], v[2:3], off offset:528
	global_load_dwordx4 v[22:25], v[2:3], off offset:512
	v_cmp_gt_i32_e32 vcc, s87, v34
	v_add_u32_e32 v2, 0xffffe010, v118
	s_nop 0
	v_cndmask_b32_e32 v3, 0, v35, vcc
	v_cndmask_b32_e32 v2, v2, v34, vcc
	v_cndmask_b32_e32 v5, v6, v7, vcc
	v_cndmask_b32_e32 v4, v8, v9, vcc
	v_lshlrev_b64 v[2:3], 13, v[2:3]
	v_lshl_add_u64 v[2:3], v[4:5], 0, v[2:3]
	v_lshl_add_u64 v[6:7], v[2:3], 0, v[108:109]
	global_load_dwordx4 v[10:13], v[6:7], off offset:16
	global_load_dwordx4 v[14:17], v[6:7], off
	global_load_dwordx4 v[2:5], v[6:7], off offset:528
	s_nop 0
	global_load_dwordx4 v[6:9], v[6:7], off offset:512
	v_lshl_add_u64 v[176:177], v[118:119], 2, s[22:23]
	global_load_dword v38, v[176:177], off
	v_lshlrev_b64 v[36:37], 13, v[118:119]
	v_lshl_add_u64 v[36:37], s[20:21], 0, v[36:37]
	v_lshl_add_u64 v[36:37], v[36:37], 0, v[108:109]
	s_waitcnt vmcnt(0)
	v_pk_mul_f32 v[40:41], v[38:39], v[220:221] op_sel_hi:[0,1]
	v_pk_mul_f32 v[218:219], v[38:39], v[218:219] op_sel_hi:[0,1]
	v_pk_fma_f32 v[32:33], v[76:77], v[218:219], v[32:33]
	v_pk_fma_f32 v[30:31], v[78:79], v[40:41], v[30:31]
	v_pk_mul_f32 v[220:221], v[38:39], v[224:225] op_sel_hi:[0,1]
	v_pk_mul_f32 v[222:223], v[38:39], v[222:223] op_sel_hi:[0,1]
	v_mul_f32_e32 v39, v31, v31
	v_mul_f32_e32 v40, v33, v33
	v_pk_fma_f32 v[26:27], v[90:91], v[220:221], v[26:27]
	v_fmac_f32_e32 v39, v30, v30
	v_fmac_f32_e32 v40, v32, v32
	v_add_f32_e32 v39, v39, v40
	v_mul_f32_e32 v40, v27, v27
	v_pk_fma_f32 v[28:29], v[88:89], v[222:223], v[28:29]
	v_fmac_f32_e32 v40, v26, v26
	v_add_f32_e32 v39, v40, v39
	v_mul_f32_e32 v40, v29, v29
	global_store_dwordx4 v[36:37], v[30:33], off
	global_store_dwordx4 v[36:37], v[26:29], off offset:16
	v_fmac_f32_e32 v40, v28, v28
	v_pk_mul_f32 v[30:31], v[82:83], v[30:31]
	v_add_f32_e32 v218, v40, v39
	v_pk_mul_f32 v[40:41], v[84:85], v[28:29]
	v_pk_mul_f32 v[28:29], v[86:87], v[26:27]
	v_cvt_pk_bf16_f32 v26, v30, v31
	v_lshlrev_b64 v[30:31], 12, v[118:119]
	v_lshl_add_u64 v[30:31], s[26:27], 0, v[30:31]
	v_pk_mul_f32 v[32:33], v[80:81], v[32:33]
	v_lshl_add_u64 v[30:31], v[70:71], 1, v[30:31]
	v_cvt_pk_bf16_f32 v27, v32, v33
	v_cvt_pk_bf16_f32 v28, v28, v29
	v_cvt_pk_bf16_f32 v29, v40, v41
	global_store_dwordx4 v[30:31], v[26:29], off
	v_lshlrev_b32_e32 v32, 16, v26
	s_nop 0
	v_and_b32_e32 v26, 0xffff0000, v26
	v_max3_f32 v26, |v32|, 0, |v26|
	v_lshlrev_b32_e32 v32, 16, v27
	v_and_b32_e32 v27, 0xffff0000, v27
	v_max3_f32 v26, v26, |v32|, |v27|
	v_lshlrev_b32_e32 v27, 16, v28
	v_and_b32_e32 v28, 0xffff0000, v28
	v_max3_f32 v26, v26, |v27|, |v28|
	v_lshlrev_b32_e32 v27, 16, v29
	v_and_b32_e32 v28, 0xffff0000, v29
	v_max3_f32 v40, v26, |v27|, |v28|
	v_pk_mul_f32 v[26:27], v[38:39], v[212:213] op_sel_hi:[0,1]
	v_pk_mul_f32 v[28:29], v[38:39], v[210:211] op_sel_hi:[0,1]
	v_pk_mul_f32 v[32:33], v[38:39], v[216:217] op_sel_hi:[0,1]
	v_pk_fma_f32 v[24:25], v[66:67], v[28:29], v[24:25]
	v_pk_fma_f32 v[22:23], v[68:69], v[26:27], v[22:23]
	v_pk_fma_f32 v[26:27], v[72:73], v[32:33], v[18:19]
	v_mul_f32_e32 v18, v23, v23
	v_mul_f32_e32 v19, v25, v25
	v_fmac_f32_e32 v18, v22, v22
	v_fmac_f32_e32 v19, v24, v24
	v_pk_mul_f32 v[38:39], v[38:39], v[214:215] op_sel_hi:[0,1]
	v_add_f32_e32 v18, v18, v19
	v_mul_f32_e32 v19, v27, v27
	v_pk_fma_f32 v[28:29], v[74:75], v[38:39], v[20:21]
	v_fmac_f32_e32 v19, v26, v26
	v_add_f32_e32 v18, v19, v18
	v_mul_f32_e32 v19, v29, v29
	v_fmac_f32_e32 v19, v28, v28
	v_pk_mul_f32 v[20:21], v[60:61], v[22:23]
	global_store_dwordx4 v[36:37], v[22:25], off offset:512
	global_store_dwordx4 v[36:37], v[26:29], off offset:528
	v_add_f32_e32 v18, v19, v18
	v_pk_mul_f32 v[22:23], v[64:65], v[26:27]
	v_cvt_pk_bf16_f32 v20, v20, v21
	v_add_f32_e32 v19, v218, v18
	v_pk_mul_f32 v[24:25], v[58:59], v[24:25]
	v_pk_mul_f32 v[28:29], v[62:63], v[28:29]
	v_cvt_pk_bf16_f32 v21, v24, v25
	v_cvt_pk_bf16_f32 v22, v22, v23
	v_lshlrev_b32_e32 v18, 16, v20
	v_cvt_pk_bf16_f32 v23, v28, v29
	global_store_dwordx4 v[30:31], v[20:23], off offset:256
	s_nop 1
	v_and_b32_e32 v20, 0xffff0000, v20
	v_max3_f32 v18, v40, |v18|, |v20|
	v_lshlrev_b32_e32 v20, 16, v21
	v_and_b32_e32 v21, 0xffff0000, v21
	v_max3_f32 v18, v18, |v20|, |v21|
	v_lshlrev_b32_e32 v20, 16, v22
	v_and_b32_e32 v21, 0xffff0000, v22
	v_max3_f32 v18, v18, |v20|, |v21|
	v_lshlrev_b32_e32 v20, 16, v23
	v_and_b32_e32 v21, 0xffff0000, v23
	v_max3_f32 v18, v18, |v20|, |v21|
	v_and_b32_e32 v21, 64, v230
	v_xor_b32_e32 v20, 16, v230
	v_add_u32_e32 v21, 64, v21
	v_cmp_lt_i32_e32 vcc, v20, v21
	s_nop 1
	v_cndmask_b32_e32 v20, v230, v20, vcc
	v_lshlrev_b32_e32 v212, 2, v20
	ds_bpermute_b32 v20, v212, v19
	s_waitcnt lgkmcnt(0)
	v_add_f32_e32 v19, v19, v20
	v_xor_b32_e32 v20, 32, v230
	v_cmp_lt_i32_e32 vcc, v20, v21
	ds_bpermute_b32 v21, v212, v18
	s_waitcnt lgkmcnt(0)
	v_max_f32_e32 v21, v21, v21
	v_cndmask_b32_e32 v20, v230, v20, vcc
	v_lshlrev_b32_e32 v213, 2, v20
	v_max_f32_e32 v18, v18, v21
	ds_bpermute_b32 v20, v213, v19
	ds_bpermute_b32 v21, v213, v18
	s_and_saveexec_b64 s[50:51], s[0:1]
	s_cbranch_execz .LBB0_901
	s_waitcnt lgkmcnt(0)
	v_max_f32_e32 v21, v21, v21
	v_max_f32_e32 v18, v18, v18
	v_max_f32_e32 v22, v18, v21
	v_add_f32_e32 v23, v19, v20
	v_lshlrev_b64 v[18:19], 7, v[118:119]
	v_lshl_add_u64 v[20:21], s[30:31], 0, v[18:19]
	s_lshl_b64 s[16:17], s[46:47], 2
	v_lshl_add_u64 v[18:19], s[34:35], 0, v[18:19]
	v_lshl_add_u64 v[20:21], v[20:21], 0, s[16:17]
	s_lshl_b32 s12, s93, 2
	v_lshl_add_u64 v[18:19], v[18:19], 0, s[16:17]
	v_lshl_add_u64 v[20:21], v[20:21], 0, s[12:13]
	v_lshl_add_u64 v[18:19], v[18:19], 0, s[12:13]
	global_store_dword v[20:21], v23, off
	global_store_dword v[18:19], v22, off
.LBB0_901:
	s_or_b64 exec, exec, s[50:51]
	v_or_b32_e32 v210, 32, v118
	v_ashrrev_i32_e32 v211, 31, v210
	v_add_u32_e32 v18, 0xffffe020, v118
	v_cmp_gt_i32_e32 vcc, s87, v210
	s_waitcnt lgkmcnt(1)
	v_mov_b32_e32 v20, s59
	s_waitcnt lgkmcnt(0)
	v_mov_b32_e32 v21, s57
	v_cndmask_b32_e32 v19, 0, v211, vcc
	v_cndmask_b32_e32 v18, v18, v210, vcc
	v_cndmask_b32_e32 v21, v20, v21, vcc
	v_mov_b32_e32 v20, s58
	v_mov_b32_e32 v22, s56
	v_cndmask_b32_e32 v20, v20, v22, vcc
	v_lshlrev_b64 v[18:19], 13, v[18:19]
	v_lshl_add_u64 v[18:19], v[20:21], 0, v[18:19]
	v_lshl_add_u64 v[22:23], v[18:19], 0, v[108:109]
	global_load_dwordx4 v[26:29], v[22:23], off offset:16
	global_load_dwordx4 v[30:33], v[22:23], off
	global_load_dwordx4 v[18:21], v[22:23], off offset:528
	s_nop 0
	global_load_dwordx4 v[22:25], v[22:23], off offset:512
	v_lshlrev_b64 v[36:37], 13, v[34:35]
	v_lshl_add_u64 v[214:215], s[20:21], 0, v[36:37]
	v_lshl_add_u64 v[36:37], v[34:35], 2, s[22:23]
	global_load_dword v36, v[36:37], off
	s_waitcnt vmcnt(0)
	v_pk_mul_f32 v[38:39], v[36:37], v[204:205] op_sel_hi:[0,1]
	v_pk_mul_f32 v[40:41], v[36:37], v[202:203] op_sel_hi:[0,1]
	v_pk_mul_f32 v[202:203], v[36:37], v[208:209] op_sel_hi:[0,1]
	v_pk_fma_f32 v[16:17], v[76:77], v[40:41], v[16:17]
	v_pk_fma_f32 v[14:15], v[78:79], v[38:39], v[14:15]
	v_pk_fma_f32 v[38:39], v[90:91], v[202:203], v[10:11]
	v_mul_f32_e32 v10, v15, v15
	v_mul_f32_e32 v11, v17, v17
	v_fmac_f32_e32 v10, v14, v14
	v_fmac_f32_e32 v11, v16, v16
	v_pk_mul_f32 v[204:205], v[36:37], v[206:207] op_sel_hi:[0,1]
	v_add_f32_e32 v10, v10, v11
	v_mul_f32_e32 v11, v39, v39
	v_pk_fma_f32 v[40:41], v[88:89], v[204:205], v[12:13]
	v_fmac_f32_e32 v11, v38, v38
	v_add_f32_e32 v10, v11, v10
	v_mul_f32_e32 v11, v41, v41
	v_lshl_add_u64 v[12:13], v[214:215], 0, v[108:109]
	v_fmac_f32_e32 v11, v40, v40
	global_store_dwordx4 v[12:13], v[14:17], off
	global_store_dwordx4 v[12:13], v[38:41], off offset:16
	v_add_f32_e32 v119, v11, v10
	v_pk_mul_f32 v[10:11], v[80:81], v[16:17]
	v_pk_mul_f32 v[14:15], v[82:83], v[14:15]
	v_pk_mul_f32 v[16:17], v[86:87], v[38:39]
	v_cvt_pk_bf16_f32 v14, v14, v15
	v_cvt_pk_bf16_f32 v15, v10, v11
	v_lshlrev_b64 v[10:11], 12, v[34:35]
	v_lshl_add_u64 v[10:11], s[26:27], 0, v[10:11]
	v_lshl_add_u64 v[10:11], v[70:71], 1, v[10:11]
	v_pk_mul_f32 v[40:41], v[84:85], v[40:41]
	v_cvt_pk_bf16_f32 v16, v16, v17
	v_lshlrev_b32_e32 v37, 16, v14
	v_cvt_pk_bf16_f32 v17, v40, v41
	global_store_dwordx4 v[10:11], v[14:17], off
	s_nop 1
	v_and_b32_e32 v14, 0xffff0000, v14
	v_max3_f32 v14, |v37|, 0, |v14|
	v_lshlrev_b32_e32 v37, 16, v15
	v_and_b32_e32 v15, 0xffff0000, v15
	v_max3_f32 v14, v14, |v37|, |v15|
	v_lshlrev_b32_e32 v15, 16, v16
	v_and_b32_e32 v16, 0xffff0000, v16
	v_max3_f32 v14, v14, |v15|, |v16|
	v_lshlrev_b32_e32 v15, 16, v17
	v_and_b32_e32 v16, 0xffff0000, v17
	v_max3_f32 v40, v14, |v15|, |v16|
	v_pk_mul_f32 v[14:15], v[36:37], v[198:199] op_sel_hi:[0,1]
	v_pk_mul_f32 v[16:17], v[36:37], v[194:195] op_sel_hi:[0,1]
	v_pk_mul_f32 v[38:39], v[36:37], v[200:201] op_sel_hi:[0,1]
	v_pk_mul_f32 v[36:37], v[36:37], v[196:197] op_sel_hi:[0,1]
	v_pk_fma_f32 v[8:9], v[66:67], v[16:17], v[8:9]
	v_pk_fma_f32 v[6:7], v[68:69], v[14:15], v[6:7]
	v_pk_fma_f32 v[4:5], v[74:75], v[36:37], v[4:5]
	v_pk_fma_f32 v[2:3], v[72:73], v[38:39], v[2:3]
	global_store_dwordx4 v[12:13], v[6:9], off offset:512
	global_store_dwordx4 v[12:13], v[2:5], off offset:528
	v_mul_f32_e32 v12, v7, v7
	v_mul_f32_e32 v13, v9, v9
	v_fmac_f32_e32 v12, v6, v6
	v_fmac_f32_e32 v13, v8, v8
	v_add_f32_e32 v12, v12, v13
	v_mul_f32_e32 v13, v3, v3
	v_fmac_f32_e32 v13, v2, v2
	v_add_f32_e32 v12, v13, v12
	v_mul_f32_e32 v13, v5, v5
	v_fmac_f32_e32 v13, v4, v4
	v_add_f32_e32 v12, v13, v12
	v_add_f32_e32 v14, v119, v12
	v_pk_mul_f32 v[6:7], v[60:61], v[6:7]
	v_pk_mul_f32 v[12:13], v[62:63], v[4:5]
	v_pk_mul_f32 v[4:5], v[64:65], v[2:3]
	v_cvt_pk_bf16_f32 v2, v6, v7
	v_pk_mul_f32 v[8:9], v[58:59], v[8:9]
	v_lshlrev_b32_e32 v6, 16, v2
	v_cvt_pk_bf16_f32 v3, v8, v9
	v_cvt_pk_bf16_f32 v4, v4, v5
	v_cvt_pk_bf16_f32 v5, v12, v13
	global_store_dwordx4 v[10:11], v[2:5], off offset:256
	s_nop 1
	v_and_b32_e32 v2, 0xffff0000, v2
	v_max3_f32 v2, v40, |v6|, |v2|
	v_lshlrev_b32_e32 v6, 16, v3
	v_and_b32_e32 v3, 0xffff0000, v3
	v_max3_f32 v2, v2, |v6|, |v3|
	v_lshlrev_b32_e32 v3, 16, v4
	v_and_b32_e32 v4, 0xffff0000, v4
	v_max3_f32 v2, v2, |v3|, |v4|
	v_lshlrev_b32_e32 v3, 16, v5
	v_and_b32_e32 v4, 0xffff0000, v5
	v_max3_f32 v4, v2, |v3|, |v4|
	ds_bpermute_b32 v5, v212, v4
	ds_bpermute_b32 v2, v212, v14
	s_waitcnt lgkmcnt(1)
	v_max_f32_e32 v5, v5, v5
	s_waitcnt lgkmcnt(0)
	v_add_f32_e32 v2, v14, v2
	v_max_f32_e32 v4, v4, v5
	ds_bpermute_b32 v3, v213, v2
	ds_bpermute_b32 v5, v213, v4
	s_and_saveexec_b64 s[50:51], s[0:1]
	s_cbranch_execz .LBB0_903
	s_waitcnt lgkmcnt(0)
	v_max_f32_e32 v5, v5, v5
	v_max_f32_e32 v4, v4, v4
	v_add_f32_e32 v7, v2, v3
	v_lshlrev_b64 v[2:3], 7, v[34:35]
	v_max_f32_e32 v6, v4, v5
	v_lshl_add_u64 v[4:5], s[30:31], 0, v[2:3]
	s_lshl_b64 s[16:17], s[46:47], 2
	v_lshl_add_u64 v[2:3], s[34:35], 0, v[2:3]
	v_lshl_add_u64 v[4:5], v[4:5], 0, s[16:17]
	s_lshl_b32 s12, s93, 2
	v_lshl_add_u64 v[2:3], v[2:3], 0, s[16:17]
	v_lshl_add_u64 v[4:5], v[4:5], 0, s[12:13]
	v_lshl_add_u64 v[2:3], v[2:3], 0, s[12:13]
	global_store_dword v[4:5], v7, off
	global_store_dword v[2:3], v6, off
.LBB0_903:
	s_or_b64 exec, exec, s[50:51]
	v_or_b32_e32 v194, 48, v118
	v_ashrrev_i32_e32 v195, 31, v194
	v_add_u32_e32 v2, 0xffffe030, v118
	v_cmp_gt_i32_e32 vcc, s87, v194
	v_mov_b32_e32 v4, s59
	s_waitcnt lgkmcnt(0)
	v_mov_b32_e32 v5, s57
	v_cndmask_b32_e32 v3, 0, v195, vcc
	v_cndmask_b32_e32 v2, v2, v194, vcc
	v_cndmask_b32_e32 v5, v4, v5, vcc
	v_mov_b32_e32 v4, s58
	v_mov_b32_e32 v6, s56
	v_cndmask_b32_e32 v4, v4, v6, vcc
	v_lshlrev_b64 v[2:3], 13, v[2:3]
	v_lshl_add_u64 v[2:3], v[4:5], 0, v[2:3]
	v_lshl_add_u64 v[2:3], v[2:3], 0, v[108:109]
	global_load_dwordx4 v[34:37], v[2:3], off offset:16
	global_load_dwordx4 v[38:41], v[2:3], off
	global_load_dwordx4 v[6:9], v[2:3], off offset:528
	global_load_dwordx4 v[14:17], v[2:3], off offset:512
	v_lshl_add_u64 v[4:5], v[210:211], 2, s[22:23]
	global_load_dword v10, v[4:5], off
	v_lshlrev_b64 v[2:3], 13, v[210:211]
	v_lshl_add_u64 v[2:3], s[20:21], 0, v[2:3]
	s_waitcnt vmcnt(0)
	v_pk_mul_f32 v[4:5], v[10:11], v[188:189] op_sel_hi:[0,1]
	v_pk_mul_f32 v[12:13], v[10:11], v[186:187] op_sel_hi:[0,1]
	v_pk_fma_f32 v[32:33], v[76:77], v[12:13], v[32:33]
	v_pk_fma_f32 v[30:31], v[78:79], v[4:5], v[30:31]
	v_pk_mul_f32 v[186:187], v[10:11], v[192:193] op_sel_hi:[0,1]
	v_lshl_add_u64 v[4:5], v[2:3], 0, v[108:109]
	v_mul_f32_e32 v2, v31, v31
	v_mul_f32_e32 v3, v33, v33
	v_pk_fma_f32 v[26:27], v[90:91], v[186:187], v[26:27]
	v_fmac_f32_e32 v2, v30, v30
	v_fmac_f32_e32 v3, v32, v32
	v_pk_mul_f32 v[188:189], v[10:11], v[190:191] op_sel_hi:[0,1]
	v_add_f32_e32 v2, v2, v3
	v_mul_f32_e32 v3, v27, v27
	v_pk_fma_f32 v[28:29], v[88:89], v[188:189], v[28:29]
	v_fmac_f32_e32 v3, v26, v26
	v_add_f32_e32 v2, v3, v2
	v_mul_f32_e32 v3, v29, v29
	v_fmac_f32_e32 v3, v28, v28
	v_pk_mul_f32 v[12:13], v[82:83], v[30:31]
	global_store_dwordx4 v[4:5], v[30:33], off
	global_store_dwordx4 v[4:5], v[26:29], off offset:16
	v_add_f32_e32 v119, v3, v2
	v_pk_mul_f32 v[2:3], v[80:81], v[32:33]
	v_pk_mul_f32 v[30:31], v[84:85], v[28:29]
	v_pk_mul_f32 v[28:29], v[86:87], v[26:27]
	v_cvt_pk_bf16_f32 v26, v12, v13
	v_cvt_pk_bf16_f32 v27, v2, v3
	v_lshlrev_b64 v[2:3], 12, v[210:211]
	v_lshlrev_b32_e32 v11, 16, v26
	v_and_b32_e32 v12, 0xffff0000, v26
	v_max3_f32 v11, |v11|, 0, |v12|
	v_lshlrev_b32_e32 v12, 16, v27
	v_and_b32_e32 v13, 0xffff0000, v27
	v_cvt_pk_bf16_f32 v28, v28, v29
	v_lshl_add_u64 v[2:3], s[26:27], 0, v[2:3]
	v_max3_f32 v11, v11, |v12|, |v13|
	v_lshlrev_b32_e32 v12, 16, v28
	v_and_b32_e32 v13, 0xffff0000, v28
	v_cvt_pk_bf16_f32 v29, v30, v31
	v_lshl_add_u64 v[2:3], v[70:71], 1, v[2:3]
	v_max3_f32 v11, v11, |v12|, |v13|
	v_lshlrev_b32_e32 v12, 16, v29
	v_and_b32_e32 v13, 0xffff0000, v29
	global_store_dwordx4 v[2:3], v[26:29], off
	v_max3_f32 v32, v11, |v12|, |v13|
	v_pk_mul_f32 v[12:13], v[10:11], v[178:179] op_sel_hi:[0,1]
	v_pk_mul_f32 v[26:27], v[10:11], v[182:183] op_sel_hi:[0,1]
	v_pk_mul_f32 v[28:29], v[10:11], v[184:185] op_sel_hi:[0,1]
	v_pk_mul_f32 v[30:31], v[10:11], v[180:181] op_sel_hi:[0,1]
	v_pk_fma_f32 v[12:13], v[66:67], v[12:13], v[24:25]
	v_pk_fma_f32 v[10:11], v[68:69], v[26:27], v[22:23]
	v_pk_fma_f32 v[20:21], v[74:75], v[30:31], v[20:21]
	v_pk_fma_f32 v[18:19], v[72:73], v[28:29], v[18:19]
	global_store_dwordx4 v[4:5], v[10:13], off offset:512
	global_store_dwordx4 v[4:5], v[18:21], off offset:528
	v_mul_f32_e32 v4, v11, v11
	v_mul_f32_e32 v5, v13, v13
	v_fmac_f32_e32 v4, v10, v10
	v_fmac_f32_e32 v5, v12, v12
	v_add_f32_e32 v4, v4, v5
	v_mul_f32_e32 v5, v19, v19
	v_fmac_f32_e32 v5, v18, v18
	v_add_f32_e32 v4, v5, v4
	v_mul_f32_e32 v5, v21, v21
	v_fmac_f32_e32 v5, v20, v20
	v_add_f32_e32 v4, v5, v4
	v_add_f32_e32 v22, v119, v4
	v_pk_mul_f32 v[4:5], v[58:59], v[12:13]
	v_pk_mul_f32 v[10:11], v[60:61], v[10:11]
	v_pk_mul_f32 v[12:13], v[64:65], v[18:19]
	v_pk_mul_f32 v[20:21], v[62:63], v[20:21]
	v_cvt_pk_bf16_f32 v10, v10, v11
	v_cvt_pk_bf16_f32 v11, v4, v5
	v_cvt_pk_bf16_f32 v12, v12, v13
	s_nop 0
	v_cvt_pk_bf16_f32 v13, v20, v21
	global_store_dwordx4 v[2:3], v[10:13], off offset:256
	v_lshlrev_b32_e32 v2, 16, v10
	v_and_b32_e32 v3, 0xffff0000, v10
	v_max3_f32 v2, v32, |v2|, |v3|
	v_lshlrev_b32_e32 v3, 16, v11
	v_and_b32_e32 v4, 0xffff0000, v11
	v_max3_f32 v2, v2, |v3|, |v4|
	v_lshlrev_b32_e32 v3, 16, v12
	v_and_b32_e32 v4, 0xffff0000, v12
	v_max3_f32 v2, v2, |v3|, |v4|
	v_lshlrev_b32_e32 v3, 16, v13
	v_and_b32_e32 v4, 0xffff0000, v13
	v_max3_f32 v4, v2, |v3|, |v4|
	ds_bpermute_b32 v5, v212, v4
	ds_bpermute_b32 v2, v212, v22
	s_waitcnt lgkmcnt(1)
	v_max_f32_e32 v5, v5, v5
	s_waitcnt lgkmcnt(0)
	v_add_f32_e32 v2, v22, v2
	v_max_f32_e32 v4, v4, v5
	ds_bpermute_b32 v3, v213, v2
	ds_bpermute_b32 v5, v213, v4
	s_and_saveexec_b64 s[50:51], s[0:1]
	s_cbranch_execz .LBB0_905
	s_waitcnt lgkmcnt(0)
	v_max_f32_e32 v5, v5, v5
	v_max_f32_e32 v4, v4, v4
	v_add_f32_e32 v11, v2, v3
	v_lshlrev_b64 v[2:3], 7, v[210:211]
	v_max_f32_e32 v10, v4, v5
	v_lshl_add_u64 v[4:5], s[30:31], 0, v[2:3]
	s_lshl_b64 s[16:17], s[46:47], 2
	v_lshl_add_u64 v[2:3], s[34:35], 0, v[2:3]
	v_lshl_add_u64 v[4:5], v[4:5], 0, s[16:17]
	s_lshl_b32 s12, s93, 2
	v_lshl_add_u64 v[2:3], v[2:3], 0, s[16:17]
	v_lshl_add_u64 v[4:5], v[4:5], 0, s[12:13]
	v_lshl_add_u64 v[2:3], v[2:3], 0, s[12:13]
	global_store_dword v[4:5], v11, off
	global_store_dword v[2:3], v10, off
.LBB0_905:
	s_or_b64 exec, exec, s[50:51]
	v_add_u32_e32 v178, 0x80, v118
	s_movk_i32 s12, 0x1f80
	v_ashrrev_i32_e32 v179, 31, v178
	v_add_u32_e32 v2, 0xffffe080, v118
	v_cmp_gt_i32_e32 vcc, s12, v118
	v_mov_b32_e32 v4, s59
	s_waitcnt lgkmcnt(0)
	v_mov_b32_e32 v5, s57
	v_cndmask_b32_e32 v3, 0, v179, vcc
	v_cndmask_b32_e32 v2, v2, v178, vcc
	v_cndmask_b32_e32 v5, v4, v5, vcc
	v_mov_b32_e32 v4, s58
	v_mov_b32_e32 v10, s56
	v_cndmask_b32_e32 v4, v4, v10, vcc
	v_lshlrev_b64 v[2:3], 13, v[2:3]
	v_lshl_add_u64 v[2:3], v[4:5], 0, v[2:3]
	v_lshl_add_u64 v[10:11], v[2:3], 0, v[108:109]
	global_load_dwordx4 v[18:21], v[10:11], off offset:16
	global_load_dwordx4 v[22:25], v[10:11], off
	global_load_dwordx4 v[2:5], v[10:11], off offset:528
	s_nop 0
	global_load_dwordx4 v[10:13], v[10:11], off offset:512
	v_lshl_add_u64 v[28:29], v[194:195], 2, s[22:23]
	global_load_dword v30, v[28:29], off
	v_lshlrev_b64 v[26:27], 13, v[194:195]
	v_lshl_add_u64 v[26:27], s[20:21], 0, v[26:27]
	s_waitcnt vmcnt(0)
	v_pk_mul_f32 v[28:29], v[30:31], v[170:171] op_sel_hi:[0,1]
	v_pk_mul_f32 v[32:33], v[30:31], v[168:169] op_sel_hi:[0,1]
	v_pk_fma_f32 v[40:41], v[76:77], v[32:33], v[40:41]
	v_pk_fma_f32 v[38:39], v[78:79], v[28:29], v[38:39]
	v_pk_mul_f32 v[168:169], v[30:31], v[174:175] op_sel_hi:[0,1]
	v_lshl_add_u64 v[28:29], v[26:27], 0, v[108:109]
	v_mul_f32_e32 v26, v39, v39
	v_mul_f32_e32 v27, v41, v41
	v_pk_fma_f32 v[34:35], v[90:91], v[168:169], v[34:35]
	v_fmac_f32_e32 v26, v38, v38
	v_fmac_f32_e32 v27, v40, v40
	v_pk_mul_f32 v[170:171], v[30:31], v[172:173] op_sel_hi:[0,1]
	v_add_f32_e32 v26, v26, v27
	v_mul_f32_e32 v27, v35, v35
	v_pk_fma_f32 v[36:37], v[88:89], v[170:171], v[36:37]
	v_fmac_f32_e32 v27, v34, v34
	v_add_f32_e32 v26, v27, v26
	v_mul_f32_e32 v27, v37, v37
	v_fmac_f32_e32 v27, v36, v36
	v_add_f32_e32 v119, v27, v26
	v_pk_mul_f32 v[26:27], v[80:81], v[40:41]
	v_pk_mul_f32 v[32:33], v[82:83], v[38:39]
	global_store_dwordx4 v[28:29], v[38:41], off
	global_store_dwordx4 v[28:29], v[34:37], off offset:16
	v_cvt_pk_bf16_f32 v32, v32, v33
	v_cvt_pk_bf16_f32 v33, v26, v27
	v_lshlrev_b64 v[26:27], 12, v[194:195]
	v_lshl_add_u64 v[26:27], s[26:27], 0, v[26:27]
	v_pk_mul_f32 v[34:35], v[86:87], v[34:35]
	v_lshl_add_u64 v[26:27], v[70:71], 1, v[26:27]
	v_pk_mul_f32 v[36:37], v[84:85], v[36:37]
	v_cvt_pk_bf16_f32 v34, v34, v35
	v_lshlrev_b32_e32 v31, 16, v32
	v_cvt_pk_bf16_f32 v35, v36, v37
	global_store_dwordx4 v[26:27], v[32:35], off
	s_nop 1
	v_and_b32_e32 v32, 0xffff0000, v32
	v_max3_f32 v31, |v31|, 0, |v32|
	v_lshlrev_b32_e32 v32, 16, v33
	v_and_b32_e32 v33, 0xffff0000, v33
	v_max3_f32 v31, v31, |v32|, |v33|
	v_lshlrev_b32_e32 v32, 16, v34
	v_and_b32_e32 v33, 0xffff0000, v34
	v_max3_f32 v31, v31, |v32|, |v33|
	v_lshlrev_b32_e32 v32, 16, v35
	v_and_b32_e32 v33, 0xffff0000, v35
	v_max3_f32 v38, v31, |v32|, |v33|
	v_pk_mul_f32 v[32:33], v[30:31], v[164:165] op_sel_hi:[0,1]
	v_pk_mul_f32 v[34:35], v[30:31], v[160:161] op_sel_hi:[0,1]
	v_pk_mul_f32 v[36:37], v[30:31], v[166:167] op_sel_hi:[0,1]
	v_pk_mul_f32 v[30:31], v[30:31], v[162:163] op_sel_hi:[0,1]
	v_pk_fma_f32 v[16:17], v[66:67], v[34:35], v[16:17]
	v_pk_fma_f32 v[14:15], v[68:69], v[32:33], v[14:15]
	v_pk_fma_f32 v[8:9], v[74:75], v[30:31], v[8:9]
	v_pk_fma_f32 v[6:7], v[72:73], v[36:37], v[6:7]
	global_store_dwordx4 v[28:29], v[14:17], off offset:512
	global_store_dwordx4 v[28:29], v[6:9], off offset:528
	v_mul_f32_e32 v28, v15, v15
	v_mul_f32_e32 v29, v17, v17
	v_fmac_f32_e32 v28, v14, v14
	v_fmac_f32_e32 v29, v16, v16
	v_add_f32_e32 v28, v28, v29
	v_mul_f32_e32 v29, v7, v7
	v_fmac_f32_e32 v29, v6, v6
	v_add_f32_e32 v28, v29, v28
	v_mul_f32_e32 v29, v9, v9
	v_fmac_f32_e32 v29, v8, v8
	v_add_f32_e32 v28, v29, v28
	v_add_f32_e32 v30, v119, v28
	v_pk_mul_f32 v[14:15], v[60:61], v[14:15]
	v_pk_mul_f32 v[28:29], v[62:63], v[8:9]
	v_pk_mul_f32 v[8:9], v[64:65], v[6:7]
	v_cvt_pk_bf16_f32 v6, v14, v15
	v_pk_mul_f32 v[16:17], v[58:59], v[16:17]
	v_lshlrev_b32_e32 v14, 16, v6
	v_cvt_pk_bf16_f32 v7, v16, v17
	v_cvt_pk_bf16_f32 v8, v8, v9
	v_cvt_pk_bf16_f32 v9, v28, v29
	global_store_dwordx4 v[26:27], v[6:9], off offset:256
	s_nop 1
	v_and_b32_e32 v6, 0xffff0000, v6
	v_max3_f32 v6, v38, |v14|, |v6|
	v_lshlrev_b32_e32 v14, 16, v7
	v_and_b32_e32 v7, 0xffff0000, v7
	v_max3_f32 v6, v6, |v14|, |v7|
	v_lshlrev_b32_e32 v7, 16, v8
	v_and_b32_e32 v8, 0xffff0000, v8
	v_max3_f32 v6, v6, |v7|, |v8|
	v_lshlrev_b32_e32 v7, 16, v9
	v_and_b32_e32 v8, 0xffff0000, v9
	v_max3_f32 v8, v6, |v7|, |v8|
	ds_bpermute_b32 v9, v212, v8
	ds_bpermute_b32 v6, v212, v30
	s_waitcnt lgkmcnt(1)
	v_max_f32_e32 v9, v9, v9
	s_waitcnt lgkmcnt(0)
	v_add_f32_e32 v6, v30, v6
	v_max_f32_e32 v8, v8, v9
	ds_bpermute_b32 v7, v213, v6
	ds_bpermute_b32 v9, v213, v8
	s_and_saveexec_b64 s[50:51], s[0:1]
	s_cbranch_execz .LBB0_907
	s_waitcnt lgkmcnt(0)
	v_max_f32_e32 v9, v9, v9
	v_max_f32_e32 v8, v8, v8
	v_add_f32_e32 v15, v6, v7
	v_lshlrev_b64 v[6:7], 7, v[194:195]
	v_max_f32_e32 v14, v8, v9
	v_lshl_add_u64 v[8:9], s[30:31], 0, v[6:7]
	s_lshl_b64 s[16:17], s[46:47], 2
	v_lshl_add_u64 v[6:7], s[34:35], 0, v[6:7]
	v_lshl_add_u64 v[8:9], v[8:9], 0, s[16:17]
	s_lshl_b32 s12, s93, 2
	v_lshl_add_u64 v[6:7], v[6:7], 0, s[16:17]
	v_lshl_add_u64 v[8:9], v[8:9], 0, s[12:13]
	v_lshl_add_u64 v[6:7], v[6:7], 0, s[12:13]
	global_store_dword v[8:9], v15, off
	global_store_dword v[6:7], v14, off
.LBB0_907:
	s_or_b64 exec, exec, s[50:51]
	v_or_b32_e32 v36, 16, v178
	v_ashrrev_i32_e32 v37, 31, v36
	v_add_u32_e32 v6, 0xffffe090, v118
	v_cmp_gt_i32_e32 vcc, s87, v36
	v_mov_b32_e32 v8, s59
	s_waitcnt lgkmcnt(0)
	v_mov_b32_e32 v9, s57
	v_cndmask_b32_e32 v7, 0, v37, vcc
	v_cndmask_b32_e32 v6, v6, v36, vcc
	v_cndmask_b32_e32 v9, v8, v9, vcc
	v_mov_b32_e32 v8, s58
	v_mov_b32_e32 v14, s56
	v_cndmask_b32_e32 v8, v8, v14, vcc
	v_lshlrev_b64 v[6:7], 13, v[6:7]
	v_lshl_add_u64 v[6:7], v[8:9], 0, v[6:7]
	v_lshl_add_u64 v[14:15], v[6:7], 0, v[108:109]
	global_load_dwordx4 v[26:29], v[14:15], off offset:16
	global_load_dwordx4 v[30:33], v[14:15], off
	global_load_dwordx4 v[6:9], v[14:15], off offset:528
	s_nop 0
	global_load_dwordx4 v[14:17], v[14:15], off offset:512
	v_lshlrev_b64 v[34:35], 13, v[178:179]
	v_lshl_add_u64 v[160:161], s[20:21], 0, v[34:35]
	global_load_dword v34, v[176:177], off offset:512
	s_waitcnt vmcnt(0)
	v_pk_mul_f32 v[38:39], v[34:35], v[154:155] op_sel_hi:[0,1]
	v_pk_mul_f32 v[40:41], v[34:35], v[152:153] op_sel_hi:[0,1]
	v_pk_mul_f32 v[152:153], v[34:35], v[158:159] op_sel_hi:[0,1]
	v_pk_fma_f32 v[24:25], v[76:77], v[40:41], v[24:25]
	v_pk_fma_f32 v[22:23], v[78:79], v[38:39], v[22:23]
	v_pk_fma_f32 v[38:39], v[90:91], v[152:153], v[18:19]
	v_mul_f32_e32 v18, v23, v23
	v_mul_f32_e32 v19, v25, v25
	v_fmac_f32_e32 v18, v22, v22
	v_fmac_f32_e32 v19, v24, v24
	v_pk_mul_f32 v[154:155], v[34:35], v[156:157] op_sel_hi:[0,1]
	v_add_f32_e32 v18, v18, v19
	v_mul_f32_e32 v19, v39, v39
	v_pk_fma_f32 v[40:41], v[88:89], v[154:155], v[20:21]
	v_fmac_f32_e32 v19, v38, v38
	v_add_f32_e32 v18, v19, v18
	v_mul_f32_e32 v19, v41, v41
	v_lshl_add_u64 v[20:21], v[160:161], 0, v[108:109]
	v_fmac_f32_e32 v19, v40, v40
	global_store_dwordx4 v[20:21], v[22:25], off
	global_store_dwordx4 v[20:21], v[38:41], off offset:16
	v_add_f32_e32 v119, v19, v18
	v_pk_mul_f32 v[18:19], v[80:81], v[24:25]
	v_pk_mul_f32 v[22:23], v[82:83], v[22:23]
	v_pk_mul_f32 v[24:25], v[86:87], v[38:39]
	v_cvt_pk_bf16_f32 v22, v22, v23
	v_cvt_pk_bf16_f32 v23, v18, v19
	v_lshlrev_b64 v[18:19], 12, v[178:179]
	v_lshl_add_u64 v[18:19], s[26:27], 0, v[18:19]
	v_lshl_add_u64 v[18:19], v[70:71], 1, v[18:19]
	v_pk_mul_f32 v[40:41], v[84:85], v[40:41]
	v_cvt_pk_bf16_f32 v24, v24, v25
	v_lshlrev_b32_e32 v35, 16, v22
	v_cvt_pk_bf16_f32 v25, v40, v41
	global_store_dwordx4 v[18:19], v[22:25], off
	s_nop 1
	v_and_b32_e32 v22, 0xffff0000, v22
	v_max3_f32 v22, |v35|, 0, |v22|
	v_lshlrev_b32_e32 v35, 16, v23
	v_and_b32_e32 v23, 0xffff0000, v23
	v_max3_f32 v22, v22, |v35|, |v23|
	v_lshlrev_b32_e32 v23, 16, v24
	v_and_b32_e32 v24, 0xffff0000, v24
	v_max3_f32 v22, v22, |v23|, |v24|
	v_lshlrev_b32_e32 v23, 16, v25
	v_and_b32_e32 v24, 0xffff0000, v25
	v_max3_f32 v40, v22, |v23|, |v24|
	v_pk_mul_f32 v[22:23], v[34:35], v[148:149] op_sel_hi:[0,1]
	v_pk_mul_f32 v[24:25], v[34:35], v[128:129] op_sel_hi:[0,1]
	v_pk_mul_f32 v[38:39], v[34:35], v[150:151] op_sel_hi:[0,1]
	v_pk_mul_f32 v[34:35], v[34:35], v[146:147] op_sel_hi:[0,1]
	v_pk_fma_f32 v[12:13], v[66:67], v[24:25], v[12:13]
	v_pk_fma_f32 v[10:11], v[68:69], v[22:23], v[10:11]
	v_pk_fma_f32 v[4:5], v[74:75], v[34:35], v[4:5]
	v_pk_fma_f32 v[2:3], v[72:73], v[38:39], v[2:3]
	global_store_dwordx4 v[20:21], v[10:13], off offset:512
	global_store_dwordx4 v[20:21], v[2:5], off offset:528
	v_mul_f32_e32 v20, v11, v11
	v_mul_f32_e32 v21, v13, v13
	v_fmac_f32_e32 v20, v10, v10
	v_fmac_f32_e32 v21, v12, v12
	v_add_f32_e32 v20, v20, v21
	v_mul_f32_e32 v21, v3, v3
	v_fmac_f32_e32 v21, v2, v2
	v_add_f32_e32 v20, v21, v20
	v_mul_f32_e32 v21, v5, v5
	v_fmac_f32_e32 v21, v4, v4
	v_add_f32_e32 v20, v21, v20
	v_add_f32_e32 v22, v119, v20
	v_pk_mul_f32 v[10:11], v[60:61], v[10:11]
	v_pk_mul_f32 v[20:21], v[62:63], v[4:5]
	v_pk_mul_f32 v[4:5], v[64:65], v[2:3]
	v_cvt_pk_bf16_f32 v2, v10, v11
	v_pk_mul_f32 v[12:13], v[58:59], v[12:13]
	v_lshlrev_b32_e32 v10, 16, v2
	v_cvt_pk_bf16_f32 v3, v12, v13
	v_cvt_pk_bf16_f32 v4, v4, v5
	v_cvt_pk_bf16_f32 v5, v20, v21
	global_store_dwordx4 v[18:19], v[2:5], off offset:256
	s_nop 1
	v_and_b32_e32 v2, 0xffff0000, v2
	v_max3_f32 v2, v40, |v10|, |v2|
	v_lshlrev_b32_e32 v10, 16, v3
	v_and_b32_e32 v3, 0xffff0000, v3
	v_max3_f32 v2, v2, |v10|, |v3|
	v_lshlrev_b32_e32 v3, 16, v4
	v_and_b32_e32 v4, 0xffff0000, v4
	v_max3_f32 v2, v2, |v3|, |v4|
	v_lshlrev_b32_e32 v3, 16, v5
	v_and_b32_e32 v4, 0xffff0000, v5
	v_max3_f32 v4, v2, |v3|, |v4|
	ds_bpermute_b32 v5, v212, v4
	ds_bpermute_b32 v2, v212, v22
	s_waitcnt lgkmcnt(1)
	v_max_f32_e32 v5, v5, v5
	s_waitcnt lgkmcnt(0)
	v_add_f32_e32 v2, v22, v2
	v_max_f32_e32 v4, v4, v5
	ds_bpermute_b32 v3, v213, v2
	ds_bpermute_b32 v5, v213, v4
	s_and_saveexec_b64 s[50:51], s[0:1]
	s_cbranch_execz .LBB0_909
	s_waitcnt lgkmcnt(0)
	v_max_f32_e32 v5, v5, v5
	v_max_f32_e32 v4, v4, v4
	v_add_f32_e32 v11, v2, v3
	v_lshlrev_b64 v[2:3], 7, v[178:179]
	v_max_f32_e32 v10, v4, v5
	v_lshl_add_u64 v[4:5], s[30:31], 0, v[2:3]
	s_lshl_b64 s[16:17], s[46:47], 2
	v_lshl_add_u64 v[2:3], s[34:35], 0, v[2:3]
	v_lshl_add_u64 v[4:5], v[4:5], 0, s[16:17]
	s_lshl_b32 s12, s93, 2
	v_lshl_add_u64 v[2:3], v[2:3], 0, s[16:17]
	v_lshl_add_u64 v[4:5], v[4:5], 0, s[12:13]
	v_lshl_add_u64 v[2:3], v[2:3], 0, s[12:13]
	global_store_dword v[4:5], v11, off
	global_store_dword v[2:3], v10, off
.LBB0_909:
	s_or_b64 exec, exec, s[50:51]
	v_or_b32_e32 v34, 32, v178
	v_ashrrev_i32_e32 v35, 31, v34
	v_add_u32_e32 v2, 0xffffe0a0, v118
	v_cmp_gt_i32_e32 vcc, s87, v34
	v_mov_b32_e32 v4, s59
	s_waitcnt lgkmcnt(0)
	v_mov_b32_e32 v5, s57
	v_cndmask_b32_e32 v3, 0, v35, vcc
	v_cndmask_b32_e32 v2, v2, v34, vcc
	v_cndmask_b32_e32 v5, v4, v5, vcc
	v_mov_b32_e32 v4, s58
	v_mov_b32_e32 v10, s56
	v_cndmask_b32_e32 v4, v4, v10, vcc
	v_lshlrev_b64 v[2:3], 13, v[2:3]
	v_lshl_add_u64 v[2:3], v[4:5], 0, v[2:3]
	v_lshl_add_u64 v[10:11], v[2:3], 0, v[108:109]
	global_load_dwordx4 v[18:21], v[10:11], off offset:16
	global_load_dwordx4 v[22:25], v[10:11], off
	global_load_dwordx4 v[2:5], v[10:11], off offset:528
	s_nop 0
	global_load_dwordx4 v[10:13], v[10:11], off offset:512
	v_lshlrev_b64 v[38:39], 13, v[36:37]
	v_lshl_add_u64 v[40:41], s[20:21], 0, v[38:39]
	v_lshl_add_u64 v[38:39], v[36:37], 2, s[22:23]
	global_load_dword v38, v[38:39], off
	s_waitcnt vmcnt(0)
	v_pk_mul_f32 v[122:123], v[38:39], v[122:123] op_sel_hi:[0,1]
	v_pk_mul_f32 v[120:121], v[38:39], v[120:121] op_sel_hi:[0,1]
	v_pk_mul_f32 v[126:127], v[38:39], v[126:127] op_sel_hi:[0,1]
	v_pk_fma_f32 v[32:33], v[76:77], v[120:121], v[32:33]
	v_pk_fma_f32 v[30:31], v[78:79], v[122:123], v[30:31]
	v_pk_fma_f32 v[120:121], v[90:91], v[126:127], v[26:27]
	v_mul_f32_e32 v26, v31, v31
	v_mul_f32_e32 v27, v33, v33
	v_fmac_f32_e32 v26, v30, v30
	v_fmac_f32_e32 v27, v32, v32
	v_pk_mul_f32 v[124:125], v[38:39], v[124:125] op_sel_hi:[0,1]
	v_add_f32_e32 v26, v26, v27
	v_mul_f32_e32 v27, v121, v121
	v_pk_fma_f32 v[122:123], v[88:89], v[124:125], v[28:29]
	v_fmac_f32_e32 v27, v120, v120
	v_add_f32_e32 v26, v27, v26
	v_mul_f32_e32 v27, v123, v123
	v_lshl_add_u64 v[28:29], v[40:41], 0, v[108:109]
	v_fmac_f32_e32 v27, v122, v122
	global_store_dwordx4 v[28:29], v[30:33], off
	global_store_dwordx4 v[28:29], v[120:123], off offset:16
	v_add_f32_e32 v119, v27, v26
	v_pk_mul_f32 v[26:27], v[80:81], v[32:33]
	v_pk_mul_f32 v[30:31], v[82:83], v[30:31]
	v_pk_mul_f32 v[32:33], v[86:87], v[120:121]
	v_cvt_pk_bf16_f32 v30, v30, v31
	v_cvt_pk_bf16_f32 v31, v26, v27
	v_lshlrev_b64 v[26:27], 12, v[36:37]
	v_lshl_add_u64 v[26:27], s[26:27], 0, v[26:27]
	v_lshl_add_u64 v[26:27], v[70:71], 1, v[26:27]
	v_pk_mul_f32 v[40:41], v[84:85], v[122:123]
	v_cvt_pk_bf16_f32 v32, v32, v33
	v_lshlrev_b32_e32 v39, 16, v30
	v_cvt_pk_bf16_f32 v33, v40, v41
	global_store_dwordx4 v[26:27], v[30:33], off
	s_nop 1
	v_and_b32_e32 v30, 0xffff0000, v30
	v_max3_f32 v30, |v39|, 0, |v30|
	v_lshlrev_b32_e32 v39, 16, v31
	v_and_b32_e32 v31, 0xffff0000, v31
	v_max3_f32 v30, v30, |v39|, |v31|
	v_lshlrev_b32_e32 v31, 16, v32
	v_and_b32_e32 v32, 0xffff0000, v32
	v_max3_f32 v30, v30, |v31|, |v32|
	v_lshlrev_b32_e32 v31, 16, v33
	v_and_b32_e32 v32, 0xffff0000, v33
	v_max3_f32 v120, v30, |v31|, |v32|
	v_pk_mul_f32 v[30:31], v[38:39], v[114:115] op_sel_hi:[0,1]
	v_pk_mul_f32 v[32:33], v[38:39], v[110:111] op_sel_hi:[0,1]
	v_pk_mul_f32 v[40:41], v[38:39], v[116:117] op_sel_hi:[0,1]
	v_pk_mul_f32 v[38:39], v[38:39], v[112:113] op_sel_hi:[0,1]
	v_pk_fma_f32 v[16:17], v[66:67], v[32:33], v[16:17]
	v_pk_fma_f32 v[14:15], v[68:69], v[30:31], v[14:15]
	v_pk_fma_f32 v[8:9], v[74:75], v[38:39], v[8:9]
	v_pk_fma_f32 v[6:7], v[72:73], v[40:41], v[6:7]
	global_store_dwordx4 v[28:29], v[14:17], off offset:512
	global_store_dwordx4 v[28:29], v[6:9], off offset:528
	v_mul_f32_e32 v28, v15, v15
	v_mul_f32_e32 v29, v17, v17
	v_fmac_f32_e32 v28, v14, v14
	v_fmac_f32_e32 v29, v16, v16
	v_add_f32_e32 v28, v28, v29
	v_mul_f32_e32 v29, v7, v7
	v_fmac_f32_e32 v29, v6, v6
	v_add_f32_e32 v28, v29, v28
	v_mul_f32_e32 v29, v9, v9
	v_fmac_f32_e32 v29, v8, v8
	v_add_f32_e32 v28, v29, v28
	v_add_f32_e32 v30, v119, v28
	v_pk_mul_f32 v[14:15], v[60:61], v[14:15]
	v_pk_mul_f32 v[28:29], v[62:63], v[8:9]
	v_pk_mul_f32 v[8:9], v[64:65], v[6:7]
	v_cvt_pk_bf16_f32 v6, v14, v15
	v_pk_mul_f32 v[16:17], v[58:59], v[16:17]
	v_lshlrev_b32_e32 v14, 16, v6
	v_cvt_pk_bf16_f32 v7, v16, v17
	v_cvt_pk_bf16_f32 v8, v8, v9
	v_cvt_pk_bf16_f32 v9, v28, v29
	global_store_dwordx4 v[26:27], v[6:9], off offset:256
	s_nop 1
	v_and_b32_e32 v6, 0xffff0000, v6
	v_max3_f32 v6, v120, |v14|, |v6|
	v_lshlrev_b32_e32 v14, 16, v7
	v_and_b32_e32 v7, 0xffff0000, v7
	v_max3_f32 v6, v6, |v14|, |v7|
	v_lshlrev_b32_e32 v7, 16, v8
	v_and_b32_e32 v8, 0xffff0000, v8
	v_max3_f32 v6, v6, |v7|, |v8|
	v_lshlrev_b32_e32 v7, 16, v9
	v_and_b32_e32 v8, 0xffff0000, v9
	v_max3_f32 v8, v6, |v7|, |v8|
	ds_bpermute_b32 v9, v212, v8
	ds_bpermute_b32 v6, v212, v30
	s_waitcnt lgkmcnt(1)
	v_max_f32_e32 v9, v9, v9
	s_waitcnt lgkmcnt(0)
	v_add_f32_e32 v6, v30, v6
	v_max_f32_e32 v8, v8, v9
	ds_bpermute_b32 v7, v213, v6
	ds_bpermute_b32 v9, v213, v8
	s_and_saveexec_b64 s[50:51], s[0:1]
	s_cbranch_execz .LBB0_911
	s_waitcnt lgkmcnt(0)
	v_max_f32_e32 v9, v9, v9
	v_max_f32_e32 v8, v8, v8
	v_add_f32_e32 v15, v6, v7
	v_lshlrev_b64 v[6:7], 7, v[36:37]
	v_max_f32_e32 v14, v8, v9
	v_lshl_add_u64 v[8:9], s[30:31], 0, v[6:7]
	s_lshl_b64 s[16:17], s[46:47], 2
	v_lshl_add_u64 v[6:7], s[34:35], 0, v[6:7]
	v_lshl_add_u64 v[8:9], v[8:9], 0, s[16:17]
	s_lshl_b32 s12, s93, 2
	v_lshl_add_u64 v[6:7], v[6:7], 0, s[16:17]
	v_lshl_add_u64 v[8:9], v[8:9], 0, s[12:13]
	v_lshl_add_u64 v[6:7], v[6:7], 0, s[12:13]
	global_store_dword v[8:9], v15, off
	global_store_dword v[6:7], v14, off
.LBB0_911:
	s_or_b64 exec, exec, s[50:51]
	v_or_b32_e32 v36, 48, v178
	v_ashrrev_i32_e32 v37, 31, v36
	v_add_u32_e32 v6, 0xffffe0b0, v118
	v_cmp_gt_i32_e32 vcc, s87, v36
	v_mov_b32_e32 v8, s59
	s_waitcnt lgkmcnt(0)
	v_mov_b32_e32 v9, s57
	v_cndmask_b32_e32 v7, 0, v37, vcc
	v_cndmask_b32_e32 v6, v6, v36, vcc
	v_cndmask_b32_e32 v9, v8, v9, vcc
	v_mov_b32_e32 v8, s58
	v_mov_b32_e32 v14, s56
	v_cndmask_b32_e32 v8, v8, v14, vcc
	v_lshlrev_b64 v[6:7], 13, v[6:7]
	v_lshl_add_u64 v[6:7], v[8:9], 0, v[6:7]
	v_lshl_add_u64 v[14:15], v[6:7], 0, v[108:109]
	global_load_dwordx4 v[26:29], v[14:15], off offset:16
	global_load_dwordx4 v[30:33], v[14:15], off
	global_load_dwordx4 v[6:9], v[14:15], off offset:528
	s_nop 0
	global_load_dwordx4 v[14:17], v[14:15], off offset:512
	v_lshlrev_b64 v[38:39], 13, v[34:35]
	v_lshl_add_u64 v[40:41], s[20:21], 0, v[38:39]
	v_lshl_add_u64 v[38:39], v[34:35], 2, s[22:23]
	global_load_dword v38, v[38:39], off
	s_waitcnt vmcnt(0)
	v_pk_mul_f32 v[102:103], v[38:39], v[102:103] op_sel_hi:[0,1]
	v_pk_mul_f32 v[100:101], v[38:39], v[100:101] op_sel_hi:[0,1]
	v_pk_mul_f32 v[106:107], v[38:39], v[106:107] op_sel_hi:[0,1]
	v_pk_fma_f32 v[24:25], v[76:77], v[100:101], v[24:25]
	v_pk_fma_f32 v[22:23], v[78:79], v[102:103], v[22:23]
	v_pk_fma_f32 v[100:101], v[90:91], v[106:107], v[18:19]
	v_mul_f32_e32 v18, v23, v23
	v_mul_f32_e32 v19, v25, v25
	v_fmac_f32_e32 v18, v22, v22
	v_fmac_f32_e32 v19, v24, v24
	v_pk_mul_f32 v[104:105], v[38:39], v[104:105] op_sel_hi:[0,1]
	v_add_f32_e32 v18, v18, v19
	v_mul_f32_e32 v19, v101, v101
	v_pk_fma_f32 v[102:103], v[88:89], v[104:105], v[20:21]
	v_fmac_f32_e32 v19, v100, v100
	v_add_f32_e32 v18, v19, v18
	v_mul_f32_e32 v19, v103, v103
	v_lshl_add_u64 v[20:21], v[40:41], 0, v[108:109]
	v_fmac_f32_e32 v19, v102, v102
	global_store_dwordx4 v[20:21], v[22:25], off
	global_store_dwordx4 v[20:21], v[100:103], off offset:16
	v_add_f32_e32 v104, v19, v18
	v_pk_mul_f32 v[18:19], v[80:81], v[24:25]
	v_pk_mul_f32 v[22:23], v[82:83], v[22:23]
	v_pk_mul_f32 v[24:25], v[86:87], v[100:101]
	v_cvt_pk_bf16_f32 v22, v22, v23
	v_cvt_pk_bf16_f32 v23, v18, v19
	v_lshlrev_b64 v[18:19], 12, v[34:35]
	v_lshl_add_u64 v[18:19], s[26:27], 0, v[18:19]
	v_lshl_add_u64 v[18:19], v[70:71], 1, v[18:19]
	v_pk_mul_f32 v[40:41], v[84:85], v[102:103]
	v_cvt_pk_bf16_f32 v24, v24, v25
	v_lshlrev_b32_e32 v39, 16, v22
	v_cvt_pk_bf16_f32 v25, v40, v41
	global_store_dwordx4 v[18:19], v[22:25], off
	s_nop 1
	v_and_b32_e32 v22, 0xffff0000, v22
	v_max3_f32 v22, |v39|, 0, |v22|
	v_lshlrev_b32_e32 v39, 16, v23
	v_and_b32_e32 v23, 0xffff0000, v23
	v_max3_f32 v22, v22, |v39|, |v23|
	v_lshlrev_b32_e32 v23, 16, v24
	v_and_b32_e32 v24, 0xffff0000, v24
	v_max3_f32 v22, v22, |v23|, |v24|
	v_lshlrev_b32_e32 v23, 16, v25
	v_and_b32_e32 v24, 0xffff0000, v25
	v_max3_f32 v100, v22, |v23|, |v24|
	v_pk_mul_f32 v[22:23], v[38:39], v[96:97] op_sel_hi:[0,1]
	v_pk_mul_f32 v[24:25], v[38:39], v[92:93] op_sel_hi:[0,1]
	v_pk_mul_f32 v[40:41], v[38:39], v[98:99] op_sel_hi:[0,1]
	v_pk_mul_f32 v[38:39], v[38:39], v[94:95] op_sel_hi:[0,1]
	v_pk_fma_f32 v[12:13], v[66:67], v[24:25], v[12:13]
	v_pk_fma_f32 v[10:11], v[68:69], v[22:23], v[10:11]
	v_pk_fma_f32 v[4:5], v[74:75], v[38:39], v[4:5]
	v_pk_fma_f32 v[2:3], v[72:73], v[40:41], v[2:3]
	global_store_dwordx4 v[20:21], v[10:13], off offset:512
	global_store_dwordx4 v[20:21], v[2:5], off offset:528
	v_mul_f32_e32 v20, v11, v11
	v_mul_f32_e32 v21, v13, v13
	v_fmac_f32_e32 v20, v10, v10
	v_fmac_f32_e32 v21, v12, v12
	v_add_f32_e32 v20, v20, v21
	v_mul_f32_e32 v21, v3, v3
	v_fmac_f32_e32 v21, v2, v2
	v_add_f32_e32 v20, v21, v20
	v_mul_f32_e32 v21, v5, v5
	v_fmac_f32_e32 v21, v4, v4
	v_add_f32_e32 v20, v21, v20
	v_add_f32_e32 v22, v104, v20
	v_pk_mul_f32 v[10:11], v[60:61], v[10:11]
	v_pk_mul_f32 v[20:21], v[62:63], v[4:5]
	v_pk_mul_f32 v[4:5], v[64:65], v[2:3]
	v_cvt_pk_bf16_f32 v2, v10, v11
	v_pk_mul_f32 v[12:13], v[58:59], v[12:13]
	v_lshlrev_b32_e32 v10, 16, v2
	v_cvt_pk_bf16_f32 v3, v12, v13
	v_cvt_pk_bf16_f32 v4, v4, v5
	v_cvt_pk_bf16_f32 v5, v20, v21
	global_store_dwordx4 v[18:19], v[2:5], off offset:256
	s_nop 1
	v_and_b32_e32 v2, 0xffff0000, v2
	v_max3_f32 v2, v100, |v10|, |v2|
	v_lshlrev_b32_e32 v10, 16, v3
	v_and_b32_e32 v3, 0xffff0000, v3
	v_max3_f32 v2, v2, |v10|, |v3|
	v_lshlrev_b32_e32 v3, 16, v4
	v_and_b32_e32 v4, 0xffff0000, v4
	v_max3_f32 v2, v2, |v3|, |v4|
	v_lshlrev_b32_e32 v3, 16, v5
	v_and_b32_e32 v4, 0xffff0000, v5
	v_max3_f32 v4, v2, |v3|, |v4|
	ds_bpermute_b32 v5, v212, v4
	ds_bpermute_b32 v2, v212, v22
	s_waitcnt lgkmcnt(1)
	v_max_f32_e32 v5, v5, v5
	s_waitcnt lgkmcnt(0)
	v_add_f32_e32 v2, v22, v2
	v_max_f32_e32 v4, v4, v5
	ds_bpermute_b32 v3, v213, v2
	ds_bpermute_b32 v5, v213, v4
	s_and_saveexec_b64 s[50:51], s[0:1]
	s_cbranch_execz .LBB0_913
	s_waitcnt lgkmcnt(0)
	v_max_f32_e32 v5, v5, v5
	v_max_f32_e32 v4, v4, v4
	v_add_f32_e32 v11, v2, v3
	v_lshlrev_b64 v[2:3], 7, v[34:35]
	v_max_f32_e32 v10, v4, v5
	v_lshl_add_u64 v[4:5], s[30:31], 0, v[2:3]
	s_lshl_b64 s[16:17], s[46:47], 2
	v_lshl_add_u64 v[2:3], s[34:35], 0, v[2:3]
	v_lshl_add_u64 v[4:5], v[4:5], 0, s[16:17]
	s_lshl_b32 s12, s93, 2
	v_lshl_add_u64 v[2:3], v[2:3], 0, s[16:17]
	v_lshl_add_u64 v[4:5], v[4:5], 0, s[12:13]
	v_lshl_add_u64 v[2:3], v[2:3], 0, s[12:13]
	global_store_dword v[4:5], v11, off
	global_store_dword v[2:3], v10, off
.LBB0_913:
	s_or_b64 exec, exec, s[50:51]
	s_waitcnt lgkmcnt(0)
	v_lshl_add_u64 v[4:5], v[36:37], 2, s[22:23]
	global_load_dword v10, v[4:5], off
	v_lshlrev_b64 v[2:3], 13, v[36:37]
	v_lshl_add_u64 v[2:3], s[20:21], 0, v[2:3]
	s_waitcnt vmcnt(0)
	v_pk_mul_f32 v[4:5], v[10:11], v[52:53] op_sel_hi:[0,1]
	v_pk_mul_f32 v[12:13], v[10:11], v[50:51] op_sel_hi:[0,1]
	v_pk_fma_f32 v[20:21], v[76:77], v[12:13], v[32:33]
	v_pk_fma_f32 v[18:19], v[78:79], v[4:5], v[30:31]
	v_pk_mul_f32 v[22:23], v[10:11], v[56:57] op_sel_hi:[0,1]
	v_lshl_add_u64 v[4:5], v[70:71], 2, v[2:3]
	v_mul_f32_e32 v2, v19, v19
	v_mul_f32_e32 v3, v21, v21
	v_pk_fma_f32 v[22:23], v[90:91], v[22:23], v[26:27]
	v_fmac_f32_e32 v2, v18, v18
	v_fmac_f32_e32 v3, v20, v20
	v_pk_mul_f32 v[24:25], v[10:11], v[54:55] op_sel_hi:[0,1]
	v_add_f32_e32 v2, v2, v3
	v_mul_f32_e32 v3, v23, v23
	v_pk_fma_f32 v[24:25], v[88:89], v[24:25], v[28:29]
	v_fmac_f32_e32 v3, v22, v22
	v_add_f32_e32 v2, v3, v2
	v_mul_f32_e32 v3, v25, v25
	v_fmac_f32_e32 v3, v24, v24
	v_pk_mul_f32 v[12:13], v[82:83], v[18:19]
	global_store_dwordx4 v[4:5], v[18:21], off
	global_store_dwordx4 v[4:5], v[22:25], off offset:16
	v_add_f32_e32 v26, v3, v2
	v_pk_mul_f32 v[2:3], v[80:81], v[20:21]
	v_cvt_pk_bf16_f32 v18, v12, v13
	v_pk_mul_f32 v[20:21], v[86:87], v[22:23]
	v_lshlrev_b32_e32 v11, 16, v18
	v_and_b32_e32 v12, 0xffff0000, v18
	v_cvt_pk_bf16_f32 v19, v2, v3
	v_lshlrev_b64 v[2:3], 12, v[36:37]
	v_max3_f32 v11, |v11|, 0, |v12|
	v_lshlrev_b32_e32 v12, 16, v19
	v_and_b32_e32 v13, 0xffff0000, v19
	v_cvt_pk_bf16_f32 v20, v20, v21
	v_lshl_add_u64 v[2:3], s[26:27], 0, v[2:3]
	v_max3_f32 v11, v11, |v12|, |v13|
	v_lshlrev_b32_e32 v12, 16, v20
	v_and_b32_e32 v13, 0xffff0000, v20
	v_pk_mul_f32 v[24:25], v[84:85], v[24:25]
	v_lshl_add_u64 v[2:3], v[70:71], 1, v[2:3]
	v_cvt_pk_bf16_f32 v21, v24, v25
	v_max3_f32 v11, v11, |v12|, |v13|
	v_lshlrev_b32_e32 v12, 16, v21
	v_and_b32_e32 v13, 0xffff0000, v21
	global_store_dwordx4 v[2:3], v[18:21], off
	v_max3_f32 v24, v11, |v12|, |v13|
	v_pk_mul_f32 v[12:13], v[10:11], v[42:43] op_sel_hi:[0,1]
	v_pk_mul_f32 v[18:19], v[10:11], v[46:47] op_sel_hi:[0,1]
	v_pk_mul_f32 v[20:21], v[10:11], v[48:49] op_sel_hi:[0,1]
	v_pk_mul_f32 v[22:23], v[10:11], v[44:45] op_sel_hi:[0,1]
	v_pk_fma_f32 v[12:13], v[66:67], v[12:13], v[16:17]
	v_pk_fma_f32 v[10:11], v[68:69], v[18:19], v[14:15]
	v_pk_fma_f32 v[8:9], v[74:75], v[22:23], v[8:9]
	v_pk_fma_f32 v[6:7], v[72:73], v[20:21], v[6:7]
	global_store_dwordx4 v[4:5], v[10:13], off offset:512
	global_store_dwordx4 v[4:5], v[6:9], off offset:528
	v_mul_f32_e32 v4, v11, v11
	v_mul_f32_e32 v5, v13, v13
	v_fmac_f32_e32 v4, v10, v10
	v_fmac_f32_e32 v5, v12, v12
	v_add_f32_e32 v4, v4, v5
	v_mul_f32_e32 v5, v7, v7
	v_fmac_f32_e32 v5, v6, v6
	v_add_f32_e32 v4, v5, v4
	v_mul_f32_e32 v5, v9, v9
	v_fmac_f32_e32 v5, v8, v8
	v_add_f32_e32 v4, v5, v4
	v_add_f32_e32 v14, v26, v4
	v_pk_mul_f32 v[4:5], v[60:61], v[10:11]
	v_pk_mul_f32 v[6:7], v[64:65], v[6:7]
	v_pk_mul_f32 v[12:13], v[58:59], v[12:13]
	v_pk_mul_f32 v[8:9], v[62:63], v[8:9]
	v_cvt_pk_bf16_f32 v4, v4, v5
	v_cvt_pk_bf16_f32 v5, v12, v13
	v_cvt_pk_bf16_f32 v6, v6, v7
	s_nop 0
	v_cvt_pk_bf16_f32 v7, v8, v9
	global_store_dwordx4 v[2:3], v[4:7], off offset:256
	v_lshlrev_b32_e32 v2, 16, v4
	v_and_b32_e32 v3, 0xffff0000, v4
	v_max3_f32 v2, v24, |v2|, |v3|
	v_lshlrev_b32_e32 v3, 16, v5
	v_and_b32_e32 v4, 0xffff0000, v5
	v_max3_f32 v2, v2, |v3|, |v4|
	v_lshlrev_b32_e32 v3, 16, v6
	v_and_b32_e32 v4, 0xffff0000, v6
	v_max3_f32 v2, v2, |v3|, |v4|
	v_lshlrev_b32_e32 v3, 16, v7
	v_and_b32_e32 v4, 0xffff0000, v7
	v_max3_f32 v4, v2, |v3|, |v4|
	ds_bpermute_b32 v5, v212, v4
	ds_bpermute_b32 v2, v212, v14
	s_waitcnt lgkmcnt(1)
	v_max_f32_e32 v5, v5, v5
	s_waitcnt lgkmcnt(0)
	v_add_f32_e32 v2, v14, v2
	v_max_f32_e32 v4, v4, v5
	ds_bpermute_b32 v3, v213, v2
	ds_bpermute_b32 v5, v213, v4
	s_and_saveexec_b64 s[50:51], s[0:1]
	s_cbranch_execz .LBB0_915
	s_waitcnt lgkmcnt(0)
	v_max_f32_e32 v5, v5, v5
	v_max_f32_e32 v4, v4, v4
	v_add_f32_e32 v7, v2, v3
	v_lshlrev_b64 v[2:3], 7, v[36:37]
	v_max_f32_e32 v6, v4, v5
	v_lshl_add_u64 v[4:5], s[30:31], 0, v[2:3]
	s_lshl_b64 s[16:17], s[46:47], 2
	v_lshl_add_u64 v[2:3], s[34:35], 0, v[2:3]
	v_lshl_add_u64 v[4:5], v[4:5], 0, s[16:17]
	s_lshl_b32 s12, s93, 2
	v_lshl_add_u64 v[2:3], v[2:3], 0, s[16:17]
	v_lshl_add_u64 v[4:5], v[4:5], 0, s[12:13]
	v_lshl_add_u64 v[2:3], v[2:3], 0, s[12:13]
	global_store_dword v[4:5], v7, off
	global_store_dword v[2:3], v6, off

.LBB0_1173:
	s_lshr_b32 s38, s89, 4
	s_add_i32 s38, s38, -1
	s_cmp_gt_i32 s89, 31
	s_cselect_b32 s38, s38, 0
	v_lshl_or_b32 v178, s12, 8, v208
	s_mul_i32 s43, s38, 0xc000
	s_mul_hi_i32 s42, s38, 0xc000
	s_add_u32 s38, s59, s43
	v_ashrrev_i32_e32 v179, 31, v178
	s_addc_u32 s39, s60, s42
	s_waitcnt lgkmcnt(0)
	v_lshlrev_b64 v[114:115], 2, v[178:179]
	v_lshl_add_u64 v[122:123], s[38:39], 0, v[114:115]
	s_add_u32 s38, s61, s43
	v_lshl_add_u32 v196, s89, 8, v206
	v_lshl_add_u64 v[116:117], s[24:25], 0, v[114:115]
	s_addc_u32 s39, s62, s42
	v_ashrrev_i32_e32 v197, 31, v196
	v_lshl_add_u64 v[124:125], s[38:39], 0, v[114:115]
	global_load_dwordx4 v[118:121], v[122:123], off offset:16
	global_load_dwordx4 v[126:129], v[122:123], off
	global_load_dwordx4 v[180:183], v[116:117], off offset:16
	global_load_dwordx4 v[184:187], v[116:117], off
	global_load_dwordx4 v[188:191], v[124:125], off offset:16
	global_load_dwordx4 v[192:195], v[124:125], off
	global_load_dwordx4 v[214:217], v[116:117], off offset:528
	global_load_dwordx4 v[218:221], v[116:117], off offset:512
	global_load_dwordx4 v[222:225], v[124:125], off offset:528
	global_load_dwordx4 v[226:229], v[124:125], off offset:512
	v_lshlrev_b64 v[116:117], 13, v[196:197]
	v_or_b32_e32 v198, 16, v196
	v_lshl_add_u64 v[116:117], s[20:21], 0, v[116:117]
	v_ashrrev_i32_e32 v199, 31, v198
	v_lshl_add_u64 v[200:201], v[116:117], 0, v[114:115]
	v_lshlrev_b64 v[116:117], 13, v[198:199]
	v_lshl_add_u64 v[116:117], s[20:21], 0, v[116:117]
	v_lshl_add_u64 v[202:203], v[116:117], 0, v[114:115]
	global_load_dwordx4 v[230:233], v[200:201], off offset:16
	global_load_dwordx4 v[234:237], v[200:201], off
	global_load_dwordx4 v[238:241], v[200:201], off offset:528
	global_load_dwordx4 v[242:245], v[200:201], off offset:512
	global_load_dwordx4 v[154:157], v[202:203], off offset:16
	global_load_dwordx4 v[158:161], v[202:203], off
	global_load_dwordx4 v[146:149], v[202:203], off offset:528
	global_load_dwordx4 v[150:153], v[202:203], off offset:512
	global_load_dwordx4 v[114:117], v[122:123], off offset:528
	s_nop 0
	global_load_dwordx4 v[122:125], v[122:123], off offset:512
	s_lshl_b32 s38, s12, 2
	s_ashr_i32 s39, s38, 31
	s_waitcnt vmcnt(0)
	v_pk_add_f32 v[190:191], v[190:191], 1.0 op_sel_hi:[1,0]
	v_pk_add_f32 v[194:195], v[194:195], 1.0 op_sel_hi:[1,0]
	v_pk_add_f32 v[204:205], v[192:193], 1.0 op_sel_hi:[1,0]
	v_pk_add_f32 v[246:247], v[188:189], 1.0 op_sel_hi:[1,0]
	v_pk_add_f32 v[224:225], v[224:225], 1.0 op_sel_hi:[1,0]
	v_pk_add_f32 v[228:229], v[228:229], 1.0 op_sel_hi:[1,0]
	v_pk_add_f32 v[226:227], v[226:227], 1.0 op_sel_hi:[1,0]
	v_pk_add_f32 v[222:223], v[222:223], 1.0 op_sel_hi:[1,0]
	v_pk_mul_f32 v[192:193], v[186:187], v[194:195]
	v_pk_mul_f32 v[194:195], v[184:185], v[204:205]
	v_pk_mul_f32 v[188:189], v[182:183], v[190:191]
	v_pk_mul_f32 v[190:191], v[180:181], v[246:247]
	v_pk_mul_f32 v[186:187], v[220:221], v[228:229]
	v_pk_mul_f32 v[184:185], v[218:219], v[226:227]
	v_pk_mul_f32 v[180:181], v[216:217], v[224:225]
	v_pk_mul_f32 v[182:183], v[214:215], v[222:223]
	v_pk_fma_f32 v[144:145], v[144:145], v[128:129], v[236:237]
	v_pk_fma_f32 v[142:143], v[142:143], v[126:127], v[234:235]
	v_mul_f32_e32 v205, v145, v145
	v_mul_f32_e32 v204, v143, v143
	v_pk_fma_f32 v[138:139], v[138:139], v[118:119], v[230:231]
	v_fmac_f32_e32 v204, v142, v142
	v_fmac_f32_e32 v205, v144, v144
	v_add_f32_e32 v204, v204, v205
	v_mul_f32_e32 v205, v139, v139
	v_pk_fma_f32 v[140:141], v[140:141], v[120:121], v[232:233]
	v_fmac_f32_e32 v205, v138, v138
	v_add_f32_e32 v204, v204, v205
	v_mul_f32_e32 v205, v141, v141
	global_store_dwordx4 v[200:201], v[142:145], off
	global_store_dwordx4 v[200:201], v[138:141], off offset:16
	v_fmac_f32_e32 v205, v140, v140
	v_pk_mul_f32 v[142:143], v[194:195], v[142:143]
	v_add_f32_e32 v213, v205, v204
	v_pk_mul_f32 v[204:205], v[188:189], v[140:141]
	v_pk_mul_f32 v[140:141], v[190:191], v[138:139]
	v_cvt_pk_bf16_f32 v138, v142, v143
	v_lshlrev_b64 v[142:143], 12, v[196:197]
	v_lshl_add_u64 v[142:143], s[22:23], 0, v[142:143]
	v_pk_mul_f32 v[144:145], v[192:193], v[144:145]
	v_lshl_add_u64 v[142:143], v[178:179], 1, v[142:143]
	v_cvt_pk_bf16_f32 v139, v144, v145
	v_pk_fma_f32 v[136:137], v[136:137], v[124:125], v[244:245]
	v_pk_fma_f32 v[134:135], v[134:135], v[122:123], v[242:243]
	v_cvt_pk_bf16_f32 v140, v140, v141
	v_cvt_pk_bf16_f32 v141, v204, v205
	global_store_dwordx4 v[142:143], v[138:141], off
	v_pk_fma_f32 v[130:131], v[130:131], v[114:115], v[238:239]
	v_pk_fma_f32 v[132:133], v[132:133], v[116:117], v[240:241]
	v_mul_f32_e32 v138, v135, v135
	v_mul_f32_e32 v139, v137, v137
	v_fmac_f32_e32 v138, v134, v134
	v_fmac_f32_e32 v139, v136, v136
	v_add_f32_e32 v138, v138, v139
	v_mul_f32_e32 v139, v131, v131
	v_fmac_f32_e32 v139, v130, v130
	v_add_f32_e32 v138, v138, v139
	v_mul_f32_e32 v139, v133, v133
	v_fmac_f32_e32 v139, v132, v132
	v_add_f32_e32 v138, v139, v138
	v_and_b32_e32 v139, 64, v212
	v_add_f32_e32 v144, v213, v138
	v_xor_b32_e32 v138, 16, v212
	v_add_u32_e32 v145, 64, v139
	v_cmp_lt_i32_e32 vcc, v138, v145
	global_store_dwordx4 v[200:201], v[134:137], off offset:512
	global_store_dwordx4 v[200:201], v[130:133], off offset:528
	v_cndmask_b32_e32 v138, v212, v138, vcc
	v_lshlrev_b32_e32 v213, 2, v138
	ds_bpermute_b32 v200, v213, v144
	v_pk_mul_f32 v[140:141], v[182:183], v[130:131]
	v_xor_b32_e32 v131, 32, v212
	v_cmp_lt_i32_e32 vcc, v131, v145
	v_pk_mul_f32 v[134:135], v[184:185], v[134:135]
	s_waitcnt lgkmcnt(0)
	v_add_f32_e32 v130, v144, v200
	v_cndmask_b32_e32 v131, v212, v131, vcc
	v_lshlrev_b32_e32 v214, 2, v131
	ds_bpermute_b32 v131, v214, v130
	v_pk_mul_f32 v[136:137], v[186:187], v[136:137]
	v_pk_mul_f32 v[138:139], v[180:181], v[132:133]
	v_cvt_pk_bf16_f32 v132, v134, v135
	v_cvt_pk_bf16_f32 v133, v136, v137
	v_cvt_pk_bf16_f32 v134, v140, v141
	s_nop 0
	v_cvt_pk_bf16_f32 v135, v138, v139
	global_store_dwordx4 v[142:143], v[132:135], off offset:256
	s_and_saveexec_b64 s[42:43], s[0:1]
	s_cbranch_execz .LBB0_1175
	s_waitcnt lgkmcnt(0)
	v_add_f32_e32 v132, v130, v131
	v_lshlrev_b64 v[130:131], 7, v[196:197]
	v_lshl_add_u64 v[130:131], s[26:27], 0, v[130:131]
	v_lshl_add_u64 v[130:131], s[38:39], 2, v[130:131]
	s_lshl_b32 s12, s63, 2
	v_lshl_add_u64 v[130:131], v[130:131], 0, s[12:13]
	global_store_dword v[130:131], v132, off
.LBB0_1175:
	s_or_b64 exec, exec, s[42:43]
	v_or_b32_e32 v200, 32, v196
	v_ashrrev_i32_e32 v201, 31, v200
	s_waitcnt lgkmcnt(0)
	v_lshlrev_b64 v[130:131], 13, v[200:201]
	v_lshl_add_u64 v[130:131], s[20:21], 0, v[130:131]
	v_lshl_add_u64 v[204:205], v[178:179], 2, v[130:131]
	global_load_dwordx4 v[138:141], v[204:205], off offset:16
	global_load_dwordx4 v[142:145], v[204:205], off
	global_load_dwordx4 v[130:133], v[204:205], off offset:528
	global_load_dwordx4 v[134:137], v[204:205], off offset:512
	v_pk_fma_f32 v[112:113], v[112:113], v[128:129], v[160:161]
	v_pk_fma_f32 v[110:111], v[110:111], v[126:127], v[158:159]
	v_pk_fma_f32 v[106:107], v[106:107], v[118:119], v[154:155]
	v_mul_f32_e32 v154, v111, v111
	v_mul_f32_e32 v155, v113, v113
	v_fmac_f32_e32 v154, v110, v110
	v_fmac_f32_e32 v155, v112, v112
	v_add_f32_e32 v154, v154, v155
	v_mul_f32_e32 v155, v107, v107
	v_pk_fma_f32 v[108:109], v[108:109], v[120:121], v[156:157]
	v_fmac_f32_e32 v155, v106, v106
	v_add_f32_e32 v154, v154, v155
	v_mul_f32_e32 v155, v109, v109
	global_store_dwordx4 v[202:203], v[110:113], off
	global_store_dwordx4 v[202:203], v[106:109], off offset:16
	v_fmac_f32_e32 v155, v108, v108
	v_pk_mul_f32 v[110:111], v[194:195], v[110:111]
	v_add_f32_e32 v156, v155, v154
	v_pk_mul_f32 v[154:155], v[188:189], v[108:109]
	v_pk_mul_f32 v[108:109], v[190:191], v[106:107]
	v_cvt_pk_bf16_f32 v106, v110, v111
	v_lshlrev_b64 v[110:111], 12, v[198:199]
	v_lshl_add_u64 v[110:111], s[22:23], 0, v[110:111]
	v_pk_mul_f32 v[112:113], v[192:193], v[112:113]
	v_lshl_add_u64 v[110:111], v[178:179], 1, v[110:111]
	v_cvt_pk_bf16_f32 v107, v112, v113
	v_pk_fma_f32 v[104:105], v[104:105], v[124:125], v[152:153]
	v_pk_fma_f32 v[102:103], v[102:103], v[122:123], v[150:151]
	v_cvt_pk_bf16_f32 v108, v108, v109
	v_cvt_pk_bf16_f32 v109, v154, v155
	global_store_dwordx4 v[110:111], v[106:109], off
	v_pk_fma_f32 v[98:99], v[98:99], v[114:115], v[146:147]
	v_pk_fma_f32 v[100:101], v[100:101], v[116:117], v[148:149]
	v_mul_f32_e32 v106, v103, v103
	v_mul_f32_e32 v107, v105, v105
	v_fmac_f32_e32 v106, v102, v102
	v_fmac_f32_e32 v107, v104, v104
	v_add_f32_e32 v106, v106, v107
	v_mul_f32_e32 v107, v99, v99
	v_fmac_f32_e32 v107, v98, v98
	v_add_f32_e32 v106, v106, v107
	v_mul_f32_e32 v107, v101, v101
	v_fmac_f32_e32 v107, v100, v100
	v_add_f32_e32 v106, v107, v106
	v_add_f32_e32 v112, v156, v106
	ds_bpermute_b32 v113, v213, v112
	global_store_dwordx4 v[202:203], v[102:105], off offset:512
	global_store_dwordx4 v[202:203], v[98:101], off offset:528
	v_pk_mul_f32 v[108:109], v[182:183], v[98:99]
	v_pk_mul_f32 v[102:103], v[184:185], v[102:103]
	v_pk_mul_f32 v[104:105], v[186:187], v[104:105]
	s_waitcnt lgkmcnt(0)
	v_add_f32_e32 v98, v112, v113
	ds_bpermute_b32 v99, v214, v98
	v_pk_mul_f32 v[106:107], v[180:181], v[100:101]
	v_cvt_pk_bf16_f32 v100, v102, v103
	v_cvt_pk_bf16_f32 v101, v104, v105
	v_cvt_pk_bf16_f32 v102, v108, v109
	s_nop 0
	v_cvt_pk_bf16_f32 v103, v106, v107
	global_store_dwordx4 v[110:111], v[100:103], off offset:256
	s_and_saveexec_b64 s[42:43], s[0:1]
	s_cbranch_execz .LBB0_1177
	s_waitcnt lgkmcnt(0)
	v_add_f32_e32 v100, v98, v99
	v_lshlrev_b64 v[98:99], 7, v[198:199]
	v_lshl_add_u64 v[98:99], s[26:27], 0, v[98:99]
	v_lshl_add_u64 v[98:99], s[38:39], 2, v[98:99]
	s_lshl_b32 s12, s63, 2
	v_lshl_add_u64 v[98:99], v[98:99], 0, s[12:13]
	global_store_dword v[98:99], v100, off
.LBB0_1177:
	s_or_b64 exec, exec, s[42:43]
	v_or_b32_e32 v146, 48, v196
	v_ashrrev_i32_e32 v147, 31, v146
	s_waitcnt lgkmcnt(0)
	v_lshlrev_b64 v[98:99], 13, v[146:147]
	v_lshl_add_u64 v[98:99], s[20:21], 0, v[98:99]
	v_lshl_add_u64 v[148:149], v[178:179], 2, v[98:99]
	global_load_dwordx4 v[106:109], v[148:149], off offset:16
	global_load_dwordx4 v[110:113], v[148:149], off
	global_load_dwordx4 v[98:101], v[148:149], off offset:528
	global_load_dwordx4 v[102:105], v[148:149], off offset:512
	s_waitcnt vmcnt(12)
	v_pk_fma_f32 v[96:97], v[96:97], v[128:129], v[144:145]
	v_pk_fma_f32 v[94:95], v[94:95], v[126:127], v[142:143]
	v_pk_fma_f32 v[90:91], v[90:91], v[118:119], v[138:139]
	v_mul_f32_e32 v138, v95, v95
	v_mul_f32_e32 v139, v97, v97
	v_fmac_f32_e32 v138, v94, v94
	v_fmac_f32_e32 v139, v96, v96
	v_add_f32_e32 v138, v138, v139
	v_mul_f32_e32 v139, v91, v91
	v_pk_fma_f32 v[92:93], v[92:93], v[120:121], v[140:141]
	v_fmac_f32_e32 v139, v90, v90
	v_add_f32_e32 v138, v138, v139
	v_mul_f32_e32 v139, v93, v93
	global_store_dwordx4 v[204:205], v[94:97], off
	global_store_dwordx4 v[204:205], v[90:93], off offset:16
	v_fmac_f32_e32 v139, v92, v92
	v_pk_mul_f32 v[94:95], v[194:195], v[94:95]
	v_add_f32_e32 v140, v139, v138
	v_pk_mul_f32 v[138:139], v[188:189], v[92:93]
	v_pk_mul_f32 v[92:93], v[190:191], v[90:91]
	v_cvt_pk_bf16_f32 v90, v94, v95
	v_lshlrev_b64 v[94:95], 12, v[200:201]
	v_lshl_add_u64 v[94:95], s[22:23], 0, v[94:95]
	v_pk_mul_f32 v[96:97], v[192:193], v[96:97]
	v_lshl_add_u64 v[94:95], v[178:179], 1, v[94:95]
	v_cvt_pk_bf16_f32 v91, v96, v97
	s_waitcnt vmcnt(12)
	v_pk_fma_f32 v[88:89], v[88:89], v[124:125], v[136:137]
	v_pk_fma_f32 v[86:87], v[86:87], v[122:123], v[134:135]
	v_cvt_pk_bf16_f32 v92, v92, v93
	v_cvt_pk_bf16_f32 v93, v138, v139
	global_store_dwordx4 v[94:95], v[90:93], off
	v_pk_fma_f32 v[82:83], v[82:83], v[114:115], v[130:131]
	v_pk_fma_f32 v[84:85], v[84:85], v[116:117], v[132:133]
	v_mul_f32_e32 v90, v87, v87
	v_mul_f32_e32 v91, v89, v89
	v_fmac_f32_e32 v90, v86, v86
	v_fmac_f32_e32 v91, v88, v88
	v_add_f32_e32 v90, v90, v91
	v_mul_f32_e32 v91, v83, v83
	v_fmac_f32_e32 v91, v82, v82
	v_add_f32_e32 v90, v90, v91
	v_mul_f32_e32 v91, v85, v85
	v_fmac_f32_e32 v91, v84, v84
	v_add_f32_e32 v90, v91, v90
	v_add_f32_e32 v96, v140, v90
	ds_bpermute_b32 v97, v213, v96
	global_store_dwordx4 v[204:205], v[86:89], off offset:512
	global_store_dwordx4 v[204:205], v[82:85], off offset:528
	v_pk_mul_f32 v[92:93], v[182:183], v[82:83]
	v_pk_mul_f32 v[86:87], v[184:185], v[86:87]
	v_pk_mul_f32 v[88:89], v[186:187], v[88:89]
	s_waitcnt lgkmcnt(0)
	v_add_f32_e32 v82, v96, v97
	ds_bpermute_b32 v83, v214, v82
	v_pk_mul_f32 v[90:91], v[180:181], v[84:85]
	v_cvt_pk_bf16_f32 v84, v86, v87
	v_cvt_pk_bf16_f32 v85, v88, v89
	v_cvt_pk_bf16_f32 v86, v92, v93
	s_nop 0
	v_cvt_pk_bf16_f32 v87, v90, v91
	global_store_dwordx4 v[94:95], v[84:87], off offset:256
	s_and_saveexec_b64 s[42:43], s[0:1]
	s_cbranch_execz .LBB0_1179
	s_waitcnt lgkmcnt(0)
	v_add_f32_e32 v84, v82, v83
	v_lshlrev_b64 v[82:83], 7, v[200:201]
	v_lshl_add_u64 v[82:83], s[26:27], 0, v[82:83]
	v_lshl_add_u64 v[82:83], s[38:39], 2, v[82:83]
	s_lshl_b32 s12, s63, 2
	v_lshl_add_u64 v[82:83], v[82:83], 0, s[12:13]
	global_store_dword v[82:83], v84, off
.LBB0_1179:
	s_or_b64 exec, exec, s[42:43]
	v_add_u32_e32 v130, 0x80, v196
	v_ashrrev_i32_e32 v131, 31, v130
	s_waitcnt lgkmcnt(0)
	v_lshlrev_b64 v[82:83], 13, v[130:131]
	v_lshl_add_u64 v[82:83], s[20:21], 0, v[82:83]
	v_lshl_add_u64 v[132:133], v[178:179], 2, v[82:83]
	global_load_dwordx4 v[90:93], v[132:133], off offset:16
	global_load_dwordx4 v[94:97], v[132:133], off
	global_load_dwordx4 v[82:85], v[132:133], off offset:528
	global_load_dwordx4 v[86:89], v[132:133], off offset:512
	s_waitcnt vmcnt(12)
	v_pk_fma_f32 v[80:81], v[80:81], v[128:129], v[112:113]
	v_pk_fma_f32 v[78:79], v[78:79], v[126:127], v[110:111]
	v_pk_fma_f32 v[74:75], v[74:75], v[118:119], v[106:107]
	v_mul_f32_e32 v106, v79, v79
	v_mul_f32_e32 v107, v81, v81
	v_fmac_f32_e32 v106, v78, v78
	v_fmac_f32_e32 v107, v80, v80
	v_add_f32_e32 v106, v106, v107
	v_mul_f32_e32 v107, v75, v75
	v_pk_fma_f32 v[76:77], v[76:77], v[120:121], v[108:109]
	v_fmac_f32_e32 v107, v74, v74
	v_add_f32_e32 v106, v106, v107
	v_mul_f32_e32 v107, v77, v77
	global_store_dwordx4 v[148:149], v[78:81], off
	global_store_dwordx4 v[148:149], v[74:77], off offset:16
	v_fmac_f32_e32 v107, v76, v76
	v_pk_mul_f32 v[78:79], v[194:195], v[78:79]
	v_add_f32_e32 v108, v107, v106
	v_pk_mul_f32 v[106:107], v[188:189], v[76:77]
	v_pk_mul_f32 v[76:77], v[190:191], v[74:75]
	v_cvt_pk_bf16_f32 v74, v78, v79
	v_lshlrev_b64 v[78:79], 12, v[146:147]
	v_lshl_add_u64 v[78:79], s[22:23], 0, v[78:79]
	v_pk_mul_f32 v[80:81], v[192:193], v[80:81]
	v_lshl_add_u64 v[78:79], v[178:179], 1, v[78:79]
	v_cvt_pk_bf16_f32 v75, v80, v81
	s_waitcnt vmcnt(12)
	v_pk_fma_f32 v[72:73], v[72:73], v[124:125], v[104:105]
	v_pk_fma_f32 v[70:71], v[70:71], v[122:123], v[102:103]
	v_cvt_pk_bf16_f32 v76, v76, v77
	v_cvt_pk_bf16_f32 v77, v106, v107
	global_store_dwordx4 v[78:79], v[74:77], off
	v_pk_fma_f32 v[66:67], v[66:67], v[114:115], v[98:99]
	v_pk_fma_f32 v[68:69], v[68:69], v[116:117], v[100:101]
	v_mul_f32_e32 v74, v71, v71
	v_mul_f32_e32 v75, v73, v73
	v_fmac_f32_e32 v74, v70, v70
	v_fmac_f32_e32 v75, v72, v72
	v_add_f32_e32 v74, v74, v75
	v_mul_f32_e32 v75, v67, v67
	v_fmac_f32_e32 v75, v66, v66
	v_add_f32_e32 v74, v74, v75
	v_mul_f32_e32 v75, v69, v69
	v_fmac_f32_e32 v75, v68, v68
	v_add_f32_e32 v74, v75, v74
	v_add_f32_e32 v80, v108, v74
	ds_bpermute_b32 v81, v213, v80
	global_store_dwordx4 v[148:149], v[70:73], off offset:512
	global_store_dwordx4 v[148:149], v[66:69], off offset:528
	v_pk_mul_f32 v[76:77], v[182:183], v[66:67]
	v_pk_mul_f32 v[70:71], v[184:185], v[70:71]
	v_pk_mul_f32 v[72:73], v[186:187], v[72:73]
	s_waitcnt lgkmcnt(0)
	v_add_f32_e32 v66, v80, v81
	ds_bpermute_b32 v67, v214, v66
	v_pk_mul_f32 v[74:75], v[180:181], v[68:69]
	v_cvt_pk_bf16_f32 v68, v70, v71
	v_cvt_pk_bf16_f32 v69, v72, v73
	v_cvt_pk_bf16_f32 v70, v76, v77
	s_nop 0
	v_cvt_pk_bf16_f32 v71, v74, v75
	global_store_dwordx4 v[78:79], v[68:71], off offset:256
	s_and_saveexec_b64 s[42:43], s[0:1]
	s_cbranch_execz .LBB0_1181
	s_waitcnt lgkmcnt(0)
	v_add_f32_e32 v68, v66, v67
	v_lshlrev_b64 v[66:67], 7, v[146:147]
	v_lshl_add_u64 v[66:67], s[26:27], 0, v[66:67]
	v_lshl_add_u64 v[66:67], s[38:39], 2, v[66:67]
	s_lshl_b32 s12, s63, 2
	v_lshl_add_u64 v[66:67], v[66:67], 0, s[12:13]
	global_store_dword v[66:67], v68, off
.LBB0_1181:
	s_or_b64 exec, exec, s[42:43]
	v_or_b32_e32 v98, 16, v130
	v_ashrrev_i32_e32 v99, 31, v98
	s_waitcnt lgkmcnt(0)
	v_lshlrev_b64 v[66:67], 13, v[98:99]
	v_lshl_add_u64 v[66:67], s[20:21], 0, v[66:67]
	v_lshl_add_u64 v[100:101], v[178:179], 2, v[66:67]
	global_load_dwordx4 v[74:77], v[100:101], off offset:16
	global_load_dwordx4 v[78:81], v[100:101], off
	global_load_dwordx4 v[66:69], v[100:101], off offset:528
	global_load_dwordx4 v[70:73], v[100:101], off offset:512
	s_waitcnt vmcnt(12)
	v_pk_fma_f32 v[64:65], v[64:65], v[128:129], v[96:97]
	v_pk_fma_f32 v[62:63], v[62:63], v[126:127], v[94:95]
	v_pk_fma_f32 v[58:59], v[58:59], v[118:119], v[90:91]
	v_mul_f32_e32 v90, v63, v63
	v_mul_f32_e32 v91, v65, v65
	v_fmac_f32_e32 v90, v62, v62
	v_fmac_f32_e32 v91, v64, v64
	v_add_f32_e32 v90, v90, v91
	v_mul_f32_e32 v91, v59, v59
	v_pk_fma_f32 v[60:61], v[60:61], v[120:121], v[92:93]
	v_fmac_f32_e32 v91, v58, v58
	v_add_f32_e32 v90, v90, v91
	v_mul_f32_e32 v91, v61, v61
	global_store_dwordx4 v[132:133], v[62:65], off
	global_store_dwordx4 v[132:133], v[58:61], off offset:16
	v_fmac_f32_e32 v91, v60, v60
	v_pk_mul_f32 v[62:63], v[194:195], v[62:63]
	v_add_f32_e32 v92, v91, v90
	v_pk_mul_f32 v[90:91], v[188:189], v[60:61]
	v_pk_mul_f32 v[60:61], v[190:191], v[58:59]
	v_cvt_pk_bf16_f32 v58, v62, v63
	v_lshlrev_b64 v[62:63], 12, v[130:131]
	v_lshl_add_u64 v[62:63], s[22:23], 0, v[62:63]
	v_pk_mul_f32 v[64:65], v[192:193], v[64:65]
	v_lshl_add_u64 v[62:63], v[178:179], 1, v[62:63]
	v_cvt_pk_bf16_f32 v59, v64, v65
	s_waitcnt vmcnt(12)
	v_pk_fma_f32 v[56:57], v[56:57], v[124:125], v[88:89]
	v_pk_fma_f32 v[54:55], v[54:55], v[122:123], v[86:87]
	v_cvt_pk_bf16_f32 v60, v60, v61
	v_cvt_pk_bf16_f32 v61, v90, v91
	global_store_dwordx4 v[62:63], v[58:61], off
	v_pk_fma_f32 v[50:51], v[50:51], v[114:115], v[82:83]
	v_pk_fma_f32 v[52:53], v[52:53], v[116:117], v[84:85]
	v_mul_f32_e32 v58, v55, v55
	v_mul_f32_e32 v59, v57, v57
	v_fmac_f32_e32 v58, v54, v54
	v_fmac_f32_e32 v59, v56, v56
	v_add_f32_e32 v58, v58, v59
	v_mul_f32_e32 v59, v51, v51
	v_fmac_f32_e32 v59, v50, v50
	v_add_f32_e32 v58, v58, v59
	v_mul_f32_e32 v59, v53, v53
	v_fmac_f32_e32 v59, v52, v52
	v_add_f32_e32 v58, v59, v58
	v_add_f32_e32 v64, v92, v58
	ds_bpermute_b32 v65, v213, v64
	global_store_dwordx4 v[132:133], v[54:57], off offset:512
	global_store_dwordx4 v[132:133], v[50:53], off offset:528
	v_pk_mul_f32 v[60:61], v[182:183], v[50:51]
	v_pk_mul_f32 v[54:55], v[184:185], v[54:55]
	v_pk_mul_f32 v[56:57], v[186:187], v[56:57]
	s_waitcnt lgkmcnt(0)
	v_add_f32_e32 v50, v64, v65
	ds_bpermute_b32 v51, v214, v50
	v_pk_mul_f32 v[58:59], v[180:181], v[52:53]
	v_cvt_pk_bf16_f32 v52, v54, v55
	v_cvt_pk_bf16_f32 v53, v56, v57
	v_cvt_pk_bf16_f32 v54, v60, v61
	s_nop 0
	v_cvt_pk_bf16_f32 v55, v58, v59
	global_store_dwordx4 v[62:63], v[52:55], off offset:256
	s_and_saveexec_b64 s[42:43], s[0:1]
	s_cbranch_execz .LBB0_1183
	s_waitcnt lgkmcnt(0)
	v_add_f32_e32 v52, v50, v51
	v_lshlrev_b64 v[50:51], 7, v[130:131]
	v_lshl_add_u64 v[50:51], s[26:27], 0, v[50:51]
	v_lshl_add_u64 v[50:51], s[38:39], 2, v[50:51]
	s_lshl_b32 s12, s63, 2
	v_lshl_add_u64 v[50:51], v[50:51], 0, s[12:13]
	global_store_dword v[50:51], v52, off
.LBB0_1183:
	s_or_b64 exec, exec, s[42:43]
	v_or_b32_e32 v82, 32, v130
	v_ashrrev_i32_e32 v83, 31, v82
	s_waitcnt lgkmcnt(0)
	v_lshlrev_b64 v[50:51], 13, v[82:83]
	v_lshl_add_u64 v[50:51], s[20:21], 0, v[50:51]
	v_lshl_add_u64 v[84:85], v[178:179], 2, v[50:51]
	global_load_dwordx4 v[58:61], v[84:85], off offset:16
	global_load_dwordx4 v[62:65], v[84:85], off
	global_load_dwordx4 v[50:53], v[84:85], off offset:528
	global_load_dwordx4 v[54:57], v[84:85], off offset:512
	s_waitcnt vmcnt(12)
	v_pk_fma_f32 v[48:49], v[48:49], v[128:129], v[80:81]
	v_pk_fma_f32 v[46:47], v[46:47], v[126:127], v[78:79]
	v_pk_fma_f32 v[42:43], v[42:43], v[118:119], v[74:75]
	v_mul_f32_e32 v74, v47, v47
	v_mul_f32_e32 v75, v49, v49
	v_fmac_f32_e32 v74, v46, v46
	v_fmac_f32_e32 v75, v48, v48
	v_add_f32_e32 v74, v74, v75
	v_mul_f32_e32 v75, v43, v43
	v_pk_fma_f32 v[44:45], v[44:45], v[120:121], v[76:77]
	v_fmac_f32_e32 v75, v42, v42
	v_add_f32_e32 v74, v74, v75
	v_mul_f32_e32 v75, v45, v45
	global_store_dwordx4 v[100:101], v[46:49], off
	global_store_dwordx4 v[100:101], v[42:45], off offset:16
	v_fmac_f32_e32 v75, v44, v44
	v_pk_mul_f32 v[46:47], v[194:195], v[46:47]
	v_add_f32_e32 v76, v75, v74
	v_pk_mul_f32 v[74:75], v[188:189], v[44:45]
	v_pk_mul_f32 v[44:45], v[190:191], v[42:43]
	v_cvt_pk_bf16_f32 v42, v46, v47
	v_lshlrev_b64 v[46:47], 12, v[98:99]
	v_lshl_add_u64 v[46:47], s[22:23], 0, v[46:47]
	v_pk_mul_f32 v[48:49], v[192:193], v[48:49]
	v_lshl_add_u64 v[46:47], v[178:179], 1, v[46:47]
	v_cvt_pk_bf16_f32 v43, v48, v49
	s_waitcnt vmcnt(12)
	v_pk_fma_f32 v[40:41], v[40:41], v[124:125], v[72:73]
	v_pk_fma_f32 v[38:39], v[38:39], v[122:123], v[70:71]
	v_cvt_pk_bf16_f32 v44, v44, v45
	v_cvt_pk_bf16_f32 v45, v74, v75
	global_store_dwordx4 v[46:47], v[42:45], off
	v_pk_fma_f32 v[34:35], v[34:35], v[114:115], v[66:67]
	v_pk_fma_f32 v[36:37], v[36:37], v[116:117], v[68:69]
	v_mul_f32_e32 v42, v39, v39
	v_mul_f32_e32 v43, v41, v41
	v_fmac_f32_e32 v42, v38, v38
	v_fmac_f32_e32 v43, v40, v40
	v_add_f32_e32 v42, v42, v43
	v_mul_f32_e32 v43, v35, v35
	v_fmac_f32_e32 v43, v34, v34
	v_add_f32_e32 v42, v42, v43
	v_mul_f32_e32 v43, v37, v37
	v_fmac_f32_e32 v43, v36, v36
	v_add_f32_e32 v42, v43, v42
	v_add_f32_e32 v48, v76, v42
	ds_bpermute_b32 v49, v213, v48
	global_store_dwordx4 v[100:101], v[38:41], off offset:512
	global_store_dwordx4 v[100:101], v[34:37], off offset:528
	v_pk_mul_f32 v[44:45], v[182:183], v[34:35]
	v_pk_mul_f32 v[38:39], v[184:185], v[38:39]
	v_pk_mul_f32 v[40:41], v[186:187], v[40:41]
	s_waitcnt lgkmcnt(0)
	v_add_f32_e32 v34, v48, v49
	ds_bpermute_b32 v35, v214, v34
	v_pk_mul_f32 v[42:43], v[180:181], v[36:37]
	v_cvt_pk_bf16_f32 v36, v38, v39
	v_cvt_pk_bf16_f32 v37, v40, v41
	v_cvt_pk_bf16_f32 v38, v44, v45
	s_nop 0
	v_cvt_pk_bf16_f32 v39, v42, v43
	global_store_dwordx4 v[46:47], v[36:39], off offset:256
	s_and_saveexec_b64 s[42:43], s[0:1]
	s_cbranch_execz .LBB0_1185
	s_waitcnt lgkmcnt(0)
	v_add_f32_e32 v36, v34, v35
	v_lshlrev_b64 v[34:35], 7, v[98:99]
	v_lshl_add_u64 v[34:35], s[26:27], 0, v[34:35]
	v_lshl_add_u64 v[34:35], s[38:39], 2, v[34:35]
	s_lshl_b32 s12, s63, 2
	v_lshl_add_u64 v[34:35], v[34:35], 0, s[12:13]
	global_store_dword v[34:35], v36, off
.LBB0_1185:
	s_or_b64 exec, exec, s[42:43]
	v_or_b32_e32 v66, 48, v130
	v_ashrrev_i32_e32 v67, 31, v66
	s_waitcnt lgkmcnt(0)
	v_lshlrev_b64 v[34:35], 13, v[66:67]
	v_lshl_add_u64 v[34:35], s[20:21], 0, v[34:35]
	v_lshl_add_u64 v[68:69], v[178:179], 2, v[34:35]
	global_load_dwordx4 v[42:45], v[68:69], off offset:16
	global_load_dwordx4 v[46:49], v[68:69], off
	global_load_dwordx4 v[34:37], v[68:69], off offset:528
	global_load_dwordx4 v[38:41], v[68:69], off offset:512
	s_waitcnt vmcnt(12)
	v_pk_fma_f32 v[32:33], v[32:33], v[128:129], v[64:65]
	v_pk_fma_f32 v[30:31], v[30:31], v[126:127], v[62:63]
	v_pk_fma_f32 v[26:27], v[26:27], v[118:119], v[58:59]
	v_mul_f32_e32 v58, v31, v31
	v_mul_f32_e32 v59, v33, v33
	v_fmac_f32_e32 v58, v30, v30
	v_fmac_f32_e32 v59, v32, v32
	v_add_f32_e32 v58, v58, v59
	v_mul_f32_e32 v59, v27, v27
	v_pk_fma_f32 v[28:29], v[28:29], v[120:121], v[60:61]
	v_fmac_f32_e32 v59, v26, v26
	v_add_f32_e32 v58, v58, v59
	v_mul_f32_e32 v59, v29, v29
	global_store_dwordx4 v[84:85], v[30:33], off
	global_store_dwordx4 v[84:85], v[26:29], off offset:16
	v_fmac_f32_e32 v59, v28, v28
	v_pk_mul_f32 v[30:31], v[194:195], v[30:31]
	v_add_f32_e32 v60, v59, v58
	v_pk_mul_f32 v[58:59], v[188:189], v[28:29]
	v_pk_mul_f32 v[28:29], v[190:191], v[26:27]
	v_cvt_pk_bf16_f32 v26, v30, v31
	v_lshlrev_b64 v[30:31], 12, v[82:83]
	v_lshl_add_u64 v[30:31], s[22:23], 0, v[30:31]
	v_pk_mul_f32 v[32:33], v[192:193], v[32:33]
	v_lshl_add_u64 v[30:31], v[178:179], 1, v[30:31]
	v_cvt_pk_bf16_f32 v27, v32, v33
	s_waitcnt vmcnt(12)
	v_pk_fma_f32 v[24:25], v[24:25], v[124:125], v[56:57]
	v_pk_fma_f32 v[22:23], v[22:23], v[122:123], v[54:55]
	v_cvt_pk_bf16_f32 v28, v28, v29
	v_cvt_pk_bf16_f32 v29, v58, v59
	global_store_dwordx4 v[30:31], v[26:29], off
	v_pk_fma_f32 v[18:19], v[18:19], v[114:115], v[50:51]
	v_pk_fma_f32 v[20:21], v[20:21], v[116:117], v[52:53]
	v_mul_f32_e32 v26, v23, v23
	v_mul_f32_e32 v27, v25, v25
	v_fmac_f32_e32 v26, v22, v22
	v_fmac_f32_e32 v27, v24, v24
	v_add_f32_e32 v26, v26, v27
	v_mul_f32_e32 v27, v19, v19
	v_fmac_f32_e32 v27, v18, v18
	v_add_f32_e32 v26, v26, v27
	v_mul_f32_e32 v27, v21, v21
	v_fmac_f32_e32 v27, v20, v20
	v_add_f32_e32 v26, v27, v26
	v_add_f32_e32 v32, v60, v26
	ds_bpermute_b32 v33, v213, v32
	global_store_dwordx4 v[84:85], v[22:25], off offset:512
	global_store_dwordx4 v[84:85], v[18:21], off offset:528
	v_pk_mul_f32 v[28:29], v[182:183], v[18:19]
	v_pk_mul_f32 v[22:23], v[184:185], v[22:23]
	v_pk_mul_f32 v[24:25], v[186:187], v[24:25]
	s_waitcnt lgkmcnt(0)
	v_add_f32_e32 v18, v32, v33
	ds_bpermute_b32 v19, v214, v18
	v_pk_mul_f32 v[26:27], v[180:181], v[20:21]
	v_cvt_pk_bf16_f32 v20, v22, v23
	v_cvt_pk_bf16_f32 v21, v24, v25
	v_cvt_pk_bf16_f32 v22, v28, v29
	s_nop 0
	v_cvt_pk_bf16_f32 v23, v26, v27
	global_store_dwordx4 v[30:31], v[20:23], off offset:256
	s_and_saveexec_b64 s[42:43], s[0:1]
	s_cbranch_execz .LBB0_1187
	s_waitcnt lgkmcnt(0)
	v_add_f32_e32 v20, v18, v19
	v_lshlrev_b64 v[18:19], 7, v[82:83]
	v_lshl_add_u64 v[18:19], s[26:27], 0, v[18:19]
	v_lshl_add_u64 v[18:19], s[38:39], 2, v[18:19]
	s_lshl_b32 s12, s63, 2
	v_lshl_add_u64 v[18:19], v[18:19], 0, s[12:13]
	global_store_dword v[18:19], v20, off
.LBB0_1187:
	s_or_b64 exec, exec, s[42:43]
	s_waitcnt vmcnt(8)
	v_pk_fma_f32 v[16:17], v[16:17], v[128:129], v[48:49]
	v_pk_fma_f32 v[14:15], v[14:15], v[126:127], v[46:47]
	s_waitcnt lgkmcnt(0)
	v_mul_f32_e32 v19, v17, v17
	v_mul_f32_e32 v18, v15, v15
	v_pk_fma_f32 v[10:11], v[10:11], v[118:119], v[42:43]
	v_fmac_f32_e32 v18, v14, v14
	v_fmac_f32_e32 v19, v16, v16
	v_add_f32_e32 v18, v18, v19
	v_mul_f32_e32 v19, v11, v11
	v_pk_fma_f32 v[12:13], v[12:13], v[120:121], v[44:45]
	v_fmac_f32_e32 v19, v10, v10
	v_add_f32_e32 v18, v18, v19
	v_mul_f32_e32 v19, v13, v13
	global_store_dwordx4 v[68:69], v[14:17], off
	global_store_dwordx4 v[68:69], v[10:13], off offset:16
	v_fmac_f32_e32 v19, v12, v12
	v_pk_mul_f32 v[14:15], v[194:195], v[14:15]
	v_add_f32_e32 v20, v19, v18
	v_pk_mul_f32 v[18:19], v[188:189], v[12:13]
	v_pk_mul_f32 v[12:13], v[190:191], v[10:11]
	v_cvt_pk_bf16_f32 v10, v14, v15
	v_lshlrev_b64 v[14:15], 12, v[66:67]
	v_lshl_add_u64 v[14:15], s[22:23], 0, v[14:15]
	v_pk_mul_f32 v[16:17], v[192:193], v[16:17]
	v_lshl_add_u64 v[14:15], v[178:179], 1, v[14:15]
	v_cvt_pk_bf16_f32 v11, v16, v17
	s_waitcnt vmcnt(8)
	v_pk_fma_f32 v[8:9], v[8:9], v[124:125], v[40:41]
	v_pk_fma_f32 v[6:7], v[6:7], v[122:123], v[38:39]
	v_cvt_pk_bf16_f32 v12, v12, v13
	v_cvt_pk_bf16_f32 v13, v18, v19
	global_store_dwordx4 v[14:15], v[10:13], off
	v_pk_fma_f32 v[2:3], v[2:3], v[114:115], v[34:35]
	v_pk_fma_f32 v[4:5], v[4:5], v[116:117], v[36:37]
	v_mul_f32_e32 v10, v7, v7
	v_mul_f32_e32 v11, v9, v9
	v_fmac_f32_e32 v10, v6, v6
	v_fmac_f32_e32 v11, v8, v8
	v_add_f32_e32 v10, v10, v11
	v_mul_f32_e32 v11, v3, v3
	v_fmac_f32_e32 v11, v2, v2
	v_add_f32_e32 v10, v10, v11
	v_mul_f32_e32 v11, v5, v5
	v_fmac_f32_e32 v11, v4, v4
	v_add_f32_e32 v10, v11, v10
	v_add_f32_e32 v16, v20, v10
	ds_bpermute_b32 v17, v213, v16
	global_store_dwordx4 v[68:69], v[6:9], off offset:512
	global_store_dwordx4 v[68:69], v[2:5], off offset:528
	v_pk_mul_f32 v[12:13], v[182:183], v[2:3]
	v_pk_mul_f32 v[6:7], v[184:185], v[6:7]
	v_pk_mul_f32 v[8:9], v[186:187], v[8:9]
	s_waitcnt lgkmcnt(0)
	v_add_f32_e32 v2, v16, v17
	ds_bpermute_b32 v3, v214, v2
	v_pk_mul_f32 v[10:11], v[180:181], v[4:5]
	v_cvt_pk_bf16_f32 v4, v6, v7
	v_cvt_pk_bf16_f32 v5, v8, v9
	v_cvt_pk_bf16_f32 v6, v12, v13
	s_nop 0
	v_cvt_pk_bf16_f32 v7, v10, v11
	global_store_dwordx4 v[14:15], v[4:7], off offset:256
	s_and_saveexec_b64 s[42:43], s[0:1]
	s_cbranch_execz .LBB0_1189
	s_waitcnt lgkmcnt(0)
	v_add_f32_e32 v4, v2, v3
	v_lshlrev_b64 v[2:3], 7, v[66:67]
	v_lshl_add_u64 v[2:3], s[26:27], 0, v[2:3]
	v_lshl_add_u64 v[2:3], s[38:39], 2, v[2:3]
	s_lshl_b32 s12, s63, 2
	v_lshl_add_u64 v[2:3], v[2:3], 0, s[12:13]
	global_store_dword v[2:3], v4, off

.LBB0_1758:
	s_lshr_b32 s42, s85, 4
	s_add_i32 s42, s42, -1
	s_cmp_gt_i32 s85, 31
	s_cselect_b32 s42, s42, 0
	v_lshl_or_b32 v90, s12, 8, v230
	s_mul_i32 s45, s42, 0xc000
	s_mul_hi_i32 s44, s42, 0xc000
	s_add_u32 s42, s59, s45
	v_ashrrev_i32_e32 v91, 31, v90
	s_addc_u32 s43, s60, s44
	v_lshlrev_b64 v[36:37], 2, v[90:91]
	v_lshl_add_u64 v[26:27], s[42:43], 0, v[36:37]
	v_lshl_add_u64 v[28:29], s[20:21], 0, v[36:37]
	s_waitcnt lgkmcnt(0)
	global_load_dwordx4 v[2:5], v[26:27], off offset:16
	global_load_dwordx4 v[6:9], v[26:27], off
	global_load_dwordx4 v[10:13], v[28:29], off offset:16
	global_load_dwordx4 v[14:17], v[28:29], off
	s_add_u32 s42, s61, s45
	v_lshl_add_u64 v[30:31], s[24:25], 0, v[36:37]
	s_addc_u32 s43, s62, s44
	v_lshl_add_u64 v[32:33], s[42:43], 0, v[36:37]
	v_lshl_add_u32 v210, s85, 8, v228
	v_ashrrev_i32_e32 v211, 31, v210
	v_or_b32_e32 v34, 16, v210
	v_ashrrev_i32_e32 v35, 31, v34
	s_lshl_b32 s42, s12, 2
	s_ashr_i32 s43, s42, 31
	s_waitcnt vmcnt(0)
	v_pk_mul_f32 v[92:93], v[4:5], v[12:13]
	v_pk_mul_f32 v[86:87], v[8:9], v[16:17]
	v_pk_mul_f32 v[88:89], v[6:7], v[14:15]
	global_load_dwordx4 v[6:9], v[30:31], off offset:16
	global_load_dwordx4 v[14:17], v[30:31], off
	global_load_dwordx4 v[18:21], v[32:33], off offset:16
	global_load_dwordx4 v[22:25], v[32:33], off
	v_pk_mul_f32 v[94:95], v[2:3], v[10:11]
	s_waitcnt vmcnt(0)
	v_pk_add_f32 v[2:3], v[20:21], 1.0 op_sel_hi:[1,0]
	v_pk_add_f32 v[24:25], v[24:25], 1.0 op_sel_hi:[1,0]
	v_pk_add_f32 v[22:23], v[22:23], 1.0 op_sel_hi:[1,0]
	v_pk_add_f32 v[4:5], v[18:19], 1.0 op_sel_hi:[1,0]
	v_pk_mul_f32 v[78:79], v[16:17], v[24:25]
	v_pk_mul_f32 v[80:81], v[14:15], v[22:23]
	v_pk_mul_f32 v[82:83], v[8:9], v[2:3]
	v_pk_mul_f32 v[84:85], v[6:7], v[4:5]
	global_load_dwordx4 v[2:5], v[26:27], off offset:528
	global_load_dwordx4 v[6:9], v[26:27], off offset:512
	global_load_dwordx4 v[10:13], v[28:29], off offset:528
	global_load_dwordx4 v[14:17], v[28:29], off offset:512
	s_waitcnt vmcnt(0)
	v_pk_mul_f32 v[108:109], v[2:3], v[10:11]
	v_pk_mul_f32 v[104:105], v[8:9], v[16:17]
	v_pk_mul_f32 v[106:107], v[6:7], v[14:15]
	global_load_dwordx4 v[6:9], v[30:31], off offset:528
	global_load_dwordx4 v[14:17], v[30:31], off offset:512
	global_load_dwordx4 v[18:21], v[32:33], off offset:528
	global_load_dwordx4 v[22:25], v[32:33], off offset:512
	v_pk_mul_f32 v[110:111], v[4:5], v[12:13]
	s_waitcnt vmcnt(0)
	v_pk_add_f32 v[2:3], v[20:21], 1.0 op_sel_hi:[1,0]
	s_nop 0
	v_pk_mul_f32 v[100:101], v[8:9], v[2:3]
	v_lshlrev_b64 v[2:3], 13, v[210:211]
	v_lshl_add_u64 v[2:3], s[16:17], 0, v[2:3]
	v_lshl_add_u64 v[38:39], v[2:3], 0, v[36:37]
	v_lshlrev_b64 v[2:3], 13, v[34:35]
	v_lshl_add_u64 v[2:3], s[16:17], 0, v[2:3]
	v_pk_add_f32 v[24:25], v[24:25], 1.0 op_sel_hi:[1,0]
	v_pk_add_f32 v[22:23], v[22:23], 1.0 op_sel_hi:[1,0]
	v_pk_add_f32 v[4:5], v[18:19], 1.0 op_sel_hi:[1,0]
	v_lshl_add_u64 v[36:37], v[2:3], 0, v[36:37]
	v_pk_mul_f32 v[96:97], v[16:17], v[24:25]
	v_pk_mul_f32 v[98:99], v[14:15], v[22:23]
	v_pk_mul_f32 v[102:103], v[6:7], v[4:5]
	global_load_dwordx4 v[22:25], v[38:39], off offset:16
	global_load_dwordx4 v[30:33], v[38:39], off
	global_load_dwordx4 v[18:21], v[38:39], off offset:528
	global_load_dwordx4 v[26:29], v[38:39], off offset:512
	global_load_dwordx4 v[10:13], v[36:37], off offset:16
	global_load_dwordx4 v[14:17], v[36:37], off
	global_load_dwordx4 v[2:5], v[36:37], off offset:528
	global_load_dwordx4 v[6:9], v[36:37], off offset:512
	v_lshl_add_u64 v[196:197], v[210:211], 2, s[18:19]
	global_load_dword v40, v[196:197], off
	v_and_b32_e32 v44, 64, v232
	v_xor_b32_e32 v41, 16, v232
	v_add_u32_e32 v234, 64, v44
	v_cmp_lt_i32_e32 vcc, v41, v234
	v_lshlrev_b64 v[42:43], 12, v[210:211]
	v_lshl_add_u64 v[42:43], s[22:23], 0, v[42:43]
	v_cndmask_b32_e32 v41, v232, v41, vcc
	v_lshlrev_b32_e32 v233, 2, v41
	v_lshl_add_u64 v[42:43], v[90:91], 1, v[42:43]
	s_waitcnt vmcnt(0)
	v_pk_mul_f32 v[44:45], v[40:41], v[214:215] op_sel_hi:[0,1]
	v_pk_mul_f32 v[212:213], v[40:41], v[212:213] op_sel_hi:[0,1]
	v_pk_mul_f32 v[214:215], v[40:41], v[218:219] op_sel_hi:[0,1]
	v_pk_mul_f32 v[218:219], v[40:41], v[222:223] op_sel_hi:[0,1]
	v_pk_mul_f32 v[220:221], v[40:41], v[220:221] op_sel_hi:[0,1]
	v_pk_mul_f32 v[216:217], v[40:41], v[216:217] op_sel_hi:[0,1]
	v_pk_mul_f32 v[222:223], v[40:41], v[226:227] op_sel_hi:[0,1]
	v_pk_mul_f32 v[40:41], v[40:41], v[224:225] op_sel_hi:[0,1]
	v_pk_fma_f32 v[32:33], v[86:87], v[212:213], v[32:33]
	v_pk_fma_f32 v[30:31], v[88:89], v[44:45], v[30:31]
	v_pk_fma_f32 v[28:29], v[104:105], v[220:221], v[28:29]
	v_pk_fma_f32 v[26:27], v[106:107], v[218:219], v[26:27]
	v_pk_fma_f32 v[24:25], v[92:93], v[216:217], v[24:25]
	v_pk_fma_f32 v[22:23], v[94:95], v[214:215], v[22:23]
	v_pk_fma_f32 v[20:21], v[110:111], v[40:41], v[20:21]
	v_pk_fma_f32 v[18:19], v[108:109], v[222:223], v[18:19]
	global_store_dwordx4 v[38:39], v[30:33], off
	global_store_dwordx4 v[38:39], v[22:25], off offset:16
	v_mul_f32_e32 v224, v31, v31
	v_mul_f32_e32 v225, v33, v33
	v_pk_mul_f32 v[40:41], v[78:79], v[32:33]
	v_pk_mul_f32 v[44:45], v[80:81], v[30:31]
	v_mul_f32_e32 v31, v27, v27
	v_mul_f32_e32 v33, v29, v29
	v_mul_f32_e32 v226, v23, v23
	v_mul_f32_e32 v227, v25, v25
	v_mul_f32_e32 v235, v19, v19
	v_fmac_f32_e32 v224, v30, v30
	v_fmac_f32_e32 v225, v32, v32
	v_fmac_f32_e32 v31, v26, v26
	v_fmac_f32_e32 v33, v28, v28
	v_pk_mul_f32 v[212:213], v[82:83], v[24:25]
	v_pk_mul_f32 v[214:215], v[84:85], v[22:23]
	v_mul_f32_e32 v236, v21, v21
	v_pk_mul_f32 v[222:223], v[102:103], v[18:19]
	v_fmac_f32_e32 v226, v22, v22
	v_fmac_f32_e32 v227, v24, v24
	v_cvt_pk_bf16_f32 v22, v44, v45
	v_cvt_pk_bf16_f32 v23, v40, v41
	v_cvt_pk_bf16_f32 v24, v214, v215
	v_cvt_pk_bf16_f32 v25, v212, v213
	v_fmac_f32_e32 v235, v18, v18
	v_add_f32_e32 v30, v224, v225
	global_store_dwordx4 v[42:43], v[22:25], off
	v_lshlrev_b32_e32 v32, 16, v22
	v_and_b32_e32 v40, 0xffff0000, v22
	global_store_dwordx4 v[38:39], v[26:29], off offset:512
	global_store_dwordx4 v[38:39], v[18:21], off offset:528
	v_pk_mul_f32 v[220:221], v[100:101], v[20:21]
	v_fmac_f32_e32 v236, v20, v20
	v_add_f32_e32 v18, v31, v33
	v_lshlrev_b32_e32 v41, 16, v23
	v_and_b32_e32 v44, 0xffff0000, v23
	v_add_f32_e32 v19, v226, v30
	v_max3_f32 v20, |v32|, 0, |v40|
	v_add_f32_e32 v18, v235, v18
	v_lshlrev_b32_e32 v45, 16, v24
	v_and_b32_e32 v212, 0xffff0000, v24
	v_add_f32_e32 v19, v227, v19
	v_max3_f32 v20, v20, |v41|, |v44|
	v_add_f32_e32 v18, v236, v18
	v_lshlrev_b32_e32 v213, 16, v25
	v_and_b32_e32 v214, 0xffff0000, v25
	v_max3_f32 v20, v20, |v45|, |v212|
	v_add_f32_e32 v18, v19, v18
	v_pk_mul_f32 v[218:219], v[98:99], v[26:27]
	v_max3_f32 v19, v20, |v213|, |v214|
	v_cvt_pk_bf16_f32 v22, v218, v219
	ds_bpermute_b32 v20, v233, v18
	v_lshlrev_b32_e32 v21, 16, v22
	v_and_b32_e32 v26, 0xffff0000, v22
	v_pk_mul_f32 v[216:217], v[96:97], v[28:29]
	v_max3_f32 v19, v19, |v21|, |v26|
	v_cvt_pk_bf16_f32 v23, v216, v217
	v_cvt_pk_bf16_f32 v24, v222, v223
	v_cvt_pk_bf16_f32 v25, v220, v221
	s_waitcnt lgkmcnt(0)
	v_add_f32_e32 v18, v18, v20
	v_lshlrev_b32_e32 v27, 16, v23
	v_and_b32_e32 v28, 0xffff0000, v23
	v_lshlrev_b32_e32 v29, 16, v24
	v_and_b32_e32 v30, 0xffff0000, v24
	v_max3_f32 v19, v19, |v27|, |v28|
	v_max3_f32 v19, v19, |v29|, |v30|
	v_lshlrev_b32_e32 v21, 16, v25
	v_and_b32_e32 v26, 0xffff0000, v25
	v_max3_f32 v21, v19, |v21|, |v26|
	ds_bpermute_b32 v20, v233, v21
	v_xor_b32_e32 v19, 32, v232
	v_cmp_lt_i32_e32 vcc, v19, v234
	global_store_dwordx4 v[42:43], v[22:25], off offset:256
	s_waitcnt lgkmcnt(0)
	v_max_f32_e32 v20, v20, v20
	v_cndmask_b32_e32 v19, v232, v19, vcc
	v_lshlrev_b32_e32 v216, 2, v19
	v_max_f32_e32 v20, v21, v20
	ds_bpermute_b32 v19, v216, v18
	ds_bpermute_b32 v21, v216, v20
	s_and_saveexec_b64 s[44:45], s[0:1]
	s_cbranch_execz .LBB0_1760
	s_waitcnt lgkmcnt(0)
	v_max_f32_e32 v21, v21, v21
	v_max_f32_e32 v20, v20, v20
	v_add_f32_e32 v23, v18, v19
	v_lshlrev_b64 v[18:19], 7, v[210:211]
	v_max_f32_e32 v22, v20, v21
	v_lshl_add_u64 v[20:21], s[26:27], 0, v[18:19]
	s_lshl_b64 s[86:87], s[42:43], 2
	v_lshl_add_u64 v[18:19], s[28:29], 0, v[18:19]
	v_lshl_add_u64 v[20:21], v[20:21], 0, s[86:87]
	s_lshl_b32 s12, s65, 2
	v_lshl_add_u64 v[18:19], v[18:19], 0, s[86:87]
	v_lshl_add_u64 v[20:21], v[20:21], 0, s[12:13]
	v_lshl_add_u64 v[18:19], v[18:19], 0, s[12:13]
	global_store_dword v[20:21], v23, off
	global_store_dword v[18:19], v22, off
.LBB0_1760:
	s_or_b64 exec, exec, s[44:45]
	v_or_b32_e32 v212, 32, v210
	v_ashrrev_i32_e32 v213, 31, v212
	s_waitcnt lgkmcnt(1)
	v_lshlrev_b64 v[18:19], 13, v[212:213]
	v_lshl_add_u64 v[18:19], s[16:17], 0, v[18:19]
	v_lshl_add_u64 v[214:215], v[90:91], 2, v[18:19]
	global_load_dwordx4 v[26:29], v[214:215], off offset:16
	global_load_dwordx4 v[30:33], v[214:215], off
	s_waitcnt lgkmcnt(0)
	global_load_dwordx4 v[18:21], v[214:215], off offset:528
	global_load_dwordx4 v[22:25], v[214:215], off offset:512
	v_lshl_add_u64 v[38:39], v[34:35], 2, s[18:19]
	global_load_dword v38, v[38:39], off
	v_lshlrev_b64 v[40:41], 12, v[34:35]
	v_lshl_add_u64 v[40:41], s[22:23], 0, v[40:41]
	v_lshl_add_u64 v[40:41], v[90:91], 1, v[40:41]
	s_waitcnt vmcnt(0)
	v_pk_mul_f32 v[44:45], v[38:39], v[192:193] op_sel_hi:[0,1]
	v_pk_mul_f32 v[192:193], v[38:39], v[200:201] op_sel_hi:[0,1]
	v_pk_mul_f32 v[42:43], v[38:39], v[194:195] op_sel_hi:[0,1]
	v_pk_mul_f32 v[194:195], v[38:39], v[198:199] op_sel_hi:[0,1]
	v_pk_mul_f32 v[198:199], v[38:39], v[206:207] op_sel_hi:[0,1]
	v_pk_mul_f32 v[200:201], v[38:39], v[202:203] op_sel_hi:[0,1]
	v_pk_fma_f32 v[10:11], v[94:95], v[192:193], v[10:11]
	v_pk_mul_f32 v[202:203], v[38:39], v[208:209] op_sel_hi:[0,1]
	v_pk_mul_f32 v[38:39], v[38:39], v[204:205] op_sel_hi:[0,1]
	v_pk_fma_f32 v[16:17], v[86:87], v[44:45], v[16:17]
	v_pk_fma_f32 v[14:15], v[88:89], v[42:43], v[14:15]
	v_pk_fma_f32 v[12:13], v[92:93], v[194:195], v[12:13]
	v_pk_fma_f32 v[8:9], v[104:105], v[200:201], v[8:9]
	v_pk_fma_f32 v[6:7], v[106:107], v[198:199], v[6:7]
	v_mul_f32_e32 v206, v11, v11
	v_pk_fma_f32 v[4:5], v[110:111], v[38:39], v[4:5]
	v_pk_fma_f32 v[2:3], v[108:109], v[202:203], v[2:3]
	global_store_dwordx4 v[36:37], v[14:17], off
	global_store_dwordx4 v[36:37], v[10:13], off offset:16
	v_mul_f32_e32 v204, v15, v15
	v_mul_f32_e32 v205, v17, v17
	v_mul_f32_e32 v207, v13, v13
	v_pk_mul_f32 v[38:39], v[78:79], v[16:17]
	v_pk_mul_f32 v[42:43], v[80:81], v[14:15]
	v_pk_mul_f32 v[192:193], v[84:85], v[10:11]
	v_mul_f32_e32 v15, v7, v7
	v_mul_f32_e32 v17, v9, v9
	v_fmac_f32_e32 v206, v10, v10
	v_cvt_pk_bf16_f32 v10, v42, v43
	v_pk_mul_f32 v[44:45], v[82:83], v[12:13]
	v_mul_f32_e32 v208, v3, v3
	v_mul_f32_e32 v209, v5, v5
	v_fmac_f32_e32 v204, v14, v14
	v_fmac_f32_e32 v205, v16, v16
	v_fmac_f32_e32 v207, v12, v12
	v_cvt_pk_bf16_f32 v11, v38, v39
	v_cvt_pk_bf16_f32 v12, v192, v193
	v_cvt_pk_bf16_f32 v13, v44, v45
	v_fmac_f32_e32 v15, v6, v6
	v_fmac_f32_e32 v17, v8, v8
	global_store_dwordx4 v[40:41], v[10:13], off
	v_lshlrev_b32_e32 v16, 16, v10
	v_pk_mul_f32 v[200:201], v[100:101], v[4:5]
	v_and_b32_e32 v10, 0xffff0000, v10
	v_pk_mul_f32 v[202:203], v[102:103], v[2:3]
	v_fmac_f32_e32 v208, v2, v2
	v_fmac_f32_e32 v209, v4, v4
	v_add_f32_e32 v14, v204, v205
	v_lshlrev_b32_e32 v38, 16, v11
	v_and_b32_e32 v11, 0xffff0000, v11
	global_store_dwordx4 v[36:37], v[6:9], off offset:512
	global_store_dwordx4 v[36:37], v[2:5], off offset:528
	v_lshlrev_b32_e32 v39, 16, v12
	v_and_b32_e32 v12, 0xffff0000, v12
	v_add_f32_e32 v2, v15, v17
	v_max3_f32 v4, |v16|, 0, |v10|
	v_add_f32_e32 v3, v206, v14
	v_add_f32_e32 v2, v208, v2
	v_max3_f32 v4, v4, |v38|, |v11|
	v_lshlrev_b32_e32 v42, 16, v13
	v_and_b32_e32 v13, 0xffff0000, v13
	v_add_f32_e32 v3, v207, v3
	v_add_f32_e32 v2, v209, v2
	v_max3_f32 v4, v4, |v39|, |v12|
	v_pk_mul_f32 v[198:199], v[98:99], v[6:7]
	v_add_f32_e32 v2, v3, v2
	v_cvt_pk_bf16_f32 v6, v198, v199
	v_max3_f32 v3, v4, |v42|, |v13|
	v_lshlrev_b32_e32 v5, 16, v6
	v_and_b32_e32 v10, 0xffff0000, v6
	v_pk_mul_f32 v[194:195], v[96:97], v[8:9]
	v_max3_f32 v3, v3, |v5|, |v10|
	v_cvt_pk_bf16_f32 v7, v194, v195
	v_cvt_pk_bf16_f32 v8, v202, v203
	v_cvt_pk_bf16_f32 v9, v200, v201
	ds_bpermute_b32 v4, v233, v2
	v_lshlrev_b32_e32 v14, 16, v7
	v_and_b32_e32 v15, 0xffff0000, v7
	v_lshlrev_b32_e32 v16, 16, v8
	v_and_b32_e32 v17, 0xffff0000, v8
	v_max3_f32 v3, v3, |v14|, |v15|
	v_lshlrev_b32_e32 v36, 16, v9
	v_and_b32_e32 v37, 0xffff0000, v9
	v_max3_f32 v3, v3, |v16|, |v17|
	v_max3_f32 v5, v3, |v36|, |v37|
	ds_bpermute_b32 v10, v233, v5
	s_waitcnt lgkmcnt(1)
	v_add_f32_e32 v2, v2, v4
	ds_bpermute_b32 v3, v216, v2
	global_store_dwordx4 v[40:41], v[6:9], off offset:256
	s_waitcnt lgkmcnt(1)
	v_max_f32_e32 v4, v10, v10
	v_max_f32_e32 v4, v5, v4
	ds_bpermute_b32 v5, v216, v4
	s_and_saveexec_b64 s[44:45], s[0:1]
	s_cbranch_execz .LBB0_1762
	s_waitcnt lgkmcnt(0)
	v_max_f32_e32 v5, v5, v5
	v_max_f32_e32 v4, v4, v4
	v_add_f32_e32 v7, v2, v3
	v_lshlrev_b64 v[2:3], 7, v[34:35]
	v_max_f32_e32 v6, v4, v5
	v_lshl_add_u64 v[4:5], s[26:27], 0, v[2:3]
	s_lshl_b64 s[86:87], s[42:43], 2
	v_lshl_add_u64 v[2:3], s[28:29], 0, v[2:3]
	v_lshl_add_u64 v[4:5], v[4:5], 0, s[86:87]
	s_lshl_b32 s12, s65, 2
	v_lshl_add_u64 v[2:3], v[2:3], 0, s[86:87]
	v_lshl_add_u64 v[4:5], v[4:5], 0, s[12:13]
	v_lshl_add_u64 v[2:3], v[2:3], 0, s[12:13]
	global_store_dword v[4:5], v7, off
	global_store_dword v[2:3], v6, off
.LBB0_1762:
	s_or_b64 exec, exec, s[44:45]
	v_or_b32_e32 v192, 48, v210
	v_ashrrev_i32_e32 v193, 31, v192
	s_waitcnt lgkmcnt(1)
	v_lshlrev_b64 v[2:3], 13, v[192:193]
	v_lshl_add_u64 v[2:3], s[16:17], 0, v[2:3]
	v_lshl_add_u64 v[194:195], v[90:91], 2, v[2:3]
	global_load_dwordx4 v[38:41], v[194:195], off offset:16
	global_load_dwordx4 v[42:45], v[194:195], off
	global_load_dwordx4 v[6:9], v[194:195], off offset:528
	global_load_dwordx4 v[34:37], v[194:195], off offset:512
	v_lshl_add_u64 v[2:3], v[212:213], 2, s[18:19]
	global_load_dword v2, v[2:3], off
	s_waitcnt lgkmcnt(0)
	v_lshlrev_b64 v[4:5], 12, v[212:213]
	v_lshl_add_u64 v[4:5], s[22:23], 0, v[4:5]
	v_lshl_add_u64 v[198:199], v[90:91], 1, v[4:5]
	s_waitcnt vmcnt(0)
	v_pk_mul_f32 v[10:11], v[2:3], v[178:179] op_sel_hi:[0,1]
	v_pk_mul_f32 v[4:5], v[2:3], v[176:177] op_sel_hi:[0,1]
	v_pk_mul_f32 v[14:15], v[2:3], v[182:183] op_sel_hi:[0,1]
	v_pk_mul_f32 v[12:13], v[2:3], v[180:181] op_sel_hi:[0,1]
	v_pk_mul_f32 v[176:177], v[2:3], v[188:189] op_sel_hi:[0,1]
	v_pk_mul_f32 v[16:17], v[2:3], v[184:185] op_sel_hi:[0,1]
	v_pk_mul_f32 v[178:179], v[2:3], v[190:191] op_sel_hi:[0,1]
	v_pk_mul_f32 v[180:181], v[2:3], v[186:187] op_sel_hi:[0,1]
	v_pk_fma_f32 v[2:3], v[88:89], v[10:11], v[30:31]
	v_pk_fma_f32 v[4:5], v[86:87], v[4:5], v[32:33]
	v_pk_fma_f32 v[20:21], v[110:111], v[180:181], v[20:21]
	v_mul_f32_e32 v180, v3, v3
	v_pk_fma_f32 v[12:13], v[92:93], v[12:13], v[28:29]
	v_pk_fma_f32 v[10:11], v[94:95], v[14:15], v[26:27]
	v_pk_fma_f32 v[16:17], v[104:105], v[16:17], v[24:25]
	v_pk_fma_f32 v[14:15], v[106:107], v[176:177], v[22:23]
	global_store_dwordx4 v[214:215], v[2:5], off
	global_store_dwordx4 v[214:215], v[10:13], off offset:16
	v_mul_f32_e32 v181, v5, v5
	v_pk_mul_f32 v[22:23], v[78:79], v[4:5]
	v_pk_mul_f32 v[24:25], v[80:81], v[2:3]
	v_fmac_f32_e32 v180, v2, v2
	v_cvt_pk_bf16_f32 v2, v24, v25
	v_pk_mul_f32 v[26:27], v[82:83], v[12:13]
	v_pk_mul_f32 v[28:29], v[84:85], v[10:11]
	v_fmac_f32_e32 v181, v4, v4
	v_cvt_pk_bf16_f32 v3, v22, v23
	v_cvt_pk_bf16_f32 v4, v28, v29
	v_cvt_pk_bf16_f32 v5, v26, v27
	global_store_dwordx4 v[198:199], v[2:5], off
	v_lshlrev_b32_e32 v23, 16, v2
	v_lshlrev_b32_e32 v24, 16, v3
	v_and_b32_e32 v2, 0xffff0000, v2
	v_and_b32_e32 v3, 0xffff0000, v3
	v_max3_f32 v2, |v23|, 0, |v2|
	v_lshlrev_b32_e32 v25, 16, v4
	v_and_b32_e32 v4, 0xffff0000, v4
	v_max3_f32 v2, v2, |v24|, |v3|
	v_pk_fma_f32 v[18:19], v[108:109], v[178:179], v[18:19]
	v_mul_f32_e32 v182, v11, v11
	v_mul_f32_e32 v183, v13, v13
	v_mul_f32_e32 v11, v15, v15
	v_mul_f32_e32 v13, v17, v17
	v_lshlrev_b32_e32 v26, 16, v5
	v_and_b32_e32 v5, 0xffff0000, v5
	v_max3_f32 v2, v2, |v25|, |v4|
	v_mul_f32_e32 v184, v19, v19
	v_pk_mul_f32 v[30:31], v[96:97], v[16:17]
	v_pk_mul_f32 v[32:33], v[98:99], v[14:15]
	v_fmac_f32_e32 v182, v10, v10
	v_fmac_f32_e32 v11, v14, v14
	v_fmac_f32_e32 v13, v16, v16
	global_store_dwordx4 v[214:215], v[14:17], off offset:512
	global_store_dwordx4 v[214:215], v[18:21], off offset:528
	v_cvt_pk_bf16_f32 v10, v32, v33
	v_max3_f32 v2, v2, |v26|, |v5|
	v_lshlrev_b32_e32 v16, 16, v10
	v_and_b32_e32 v17, 0xffff0000, v10
	v_mul_f32_e32 v185, v21, v21
	v_pk_mul_f32 v[178:179], v[102:103], v[18:19]
	v_fmac_f32_e32 v184, v18, v18
	v_add_f32_e32 v22, v180, v181
	v_add_f32_e32 v14, v11, v13
	v_cvt_pk_bf16_f32 v11, v30, v31
	v_max3_f32 v2, v2, |v16|, |v17|
	v_lshlrev_b32_e32 v18, 16, v11
	v_and_b32_e32 v19, 0xffff0000, v11
	v_pk_mul_f32 v[176:177], v[100:101], v[20:21]
	v_fmac_f32_e32 v183, v12, v12
	v_fmac_f32_e32 v185, v20, v20
	v_cvt_pk_bf16_f32 v12, v178, v179
	v_add_f32_e32 v15, v182, v22
	v_add_f32_e32 v14, v184, v14
	v_lshlrev_b32_e32 v20, 16, v12
	v_and_b32_e32 v21, 0xffff0000, v12
	v_max3_f32 v2, v2, |v18|, |v19|
	v_cvt_pk_bf16_f32 v13, v176, v177
	v_add_f32_e32 v15, v183, v15
	v_lshlrev_b32_e32 v22, 16, v13
	v_and_b32_e32 v23, 0xffff0000, v13
	v_add_f32_e32 v3, v185, v14
	v_max3_f32 v2, v2, |v20|, |v21|
	v_add_f32_e32 v3, v15, v3
	v_max3_f32 v5, v2, |v22|, |v23|
	ds_bpermute_b32 v4, v233, v3
	ds_bpermute_b32 v14, v233, v5
	global_store_dwordx4 v[198:199], v[10:13], off offset:256
	s_waitcnt lgkmcnt(1)
	v_add_f32_e32 v2, v3, v4
	s_waitcnt lgkmcnt(0)
	v_max_f32_e32 v4, v14, v14
	v_max_f32_e32 v4, v5, v4
	ds_bpermute_b32 v3, v216, v2
	ds_bpermute_b32 v5, v216, v4
	s_and_saveexec_b64 s[44:45], s[0:1]
	s_cbranch_execz .LBB0_1764
	s_waitcnt lgkmcnt(0)
	v_max_f32_e32 v5, v5, v5
	v_max_f32_e32 v4, v4, v4
	v_add_f32_e32 v11, v2, v3
	v_lshlrev_b64 v[2:3], 7, v[212:213]
	v_max_f32_e32 v10, v4, v5
	v_lshl_add_u64 v[4:5], s[26:27], 0, v[2:3]
	s_lshl_b64 s[86:87], s[42:43], 2
	v_lshl_add_u64 v[2:3], s[28:29], 0, v[2:3]
	v_lshl_add_u64 v[4:5], v[4:5], 0, s[86:87]
	s_lshl_b32 s12, s65, 2
	v_lshl_add_u64 v[2:3], v[2:3], 0, s[86:87]
	v_lshl_add_u64 v[4:5], v[4:5], 0, s[12:13]
	v_lshl_add_u64 v[2:3], v[2:3], 0, s[12:13]
	global_store_dword v[4:5], v11, off
	global_store_dword v[2:3], v10, off
.LBB0_1764:
	s_or_b64 exec, exec, s[44:45]
	v_add_u32_e32 v176, 0x80, v210
	v_ashrrev_i32_e32 v177, 31, v176
	s_waitcnt lgkmcnt(1)
	v_lshlrev_b64 v[2:3], 13, v[176:177]
	v_lshl_add_u64 v[2:3], s[16:17], 0, v[2:3]
	v_lshl_add_u64 v[178:179], v[90:91], 2, v[2:3]
	global_load_dwordx4 v[14:17], v[178:179], off offset:16
	global_load_dwordx4 v[18:21], v[178:179], off
	s_waitcnt lgkmcnt(0)
	global_load_dwordx4 v[2:5], v[178:179], off offset:528
	global_load_dwordx4 v[10:13], v[178:179], off offset:512
	v_lshl_add_u64 v[22:23], v[192:193], 2, s[18:19]
	global_load_dword v22, v[22:23], off
	v_lshlrev_b64 v[24:25], 12, v[192:193]
	v_lshl_add_u64 v[24:25], s[22:23], 0, v[24:25]
	v_lshl_add_u64 v[180:181], v[90:91], 1, v[24:25]
	s_waitcnt vmcnt(0)
	v_pk_mul_f32 v[26:27], v[22:23], v[162:163] op_sel_hi:[0,1]
	v_pk_mul_f32 v[24:25], v[22:23], v[160:161] op_sel_hi:[0,1]
	v_pk_mul_f32 v[30:31], v[22:23], v[166:167] op_sel_hi:[0,1]
	v_pk_mul_f32 v[28:29], v[22:23], v[164:165] op_sel_hi:[0,1]
	v_pk_mul_f32 v[160:161], v[22:23], v[172:173] op_sel_hi:[0,1]
	v_pk_mul_f32 v[32:33], v[22:23], v[168:169] op_sel_hi:[0,1]
	v_pk_mul_f32 v[162:163], v[22:23], v[174:175] op_sel_hi:[0,1]
	v_pk_mul_f32 v[164:165], v[22:23], v[170:171] op_sel_hi:[0,1]
	v_pk_fma_f32 v[24:25], v[86:87], v[24:25], v[44:45]
	v_pk_fma_f32 v[22:23], v[88:89], v[26:27], v[42:43]
	v_pk_fma_f32 v[28:29], v[92:93], v[28:29], v[40:41]
	v_pk_fma_f32 v[26:27], v[94:95], v[30:31], v[38:39]
	v_pk_fma_f32 v[32:33], v[104:105], v[32:33], v[36:37]
	v_pk_fma_f32 v[30:31], v[106:107], v[160:161], v[34:35]
	v_pk_fma_f32 v[8:9], v[110:111], v[164:165], v[8:9]
	v_pk_fma_f32 v[6:7], v[108:109], v[162:163], v[6:7]
	global_store_dwordx4 v[194:195], v[22:25], off
	global_store_dwordx4 v[194:195], v[26:29], off offset:16
	v_mul_f32_e32 v164, v23, v23
	v_mul_f32_e32 v165, v25, v25
	v_mul_f32_e32 v166, v27, v27
	v_mul_f32_e32 v167, v29, v29
	v_pk_mul_f32 v[34:35], v[78:79], v[24:25]
	v_pk_mul_f32 v[38:39], v[82:83], v[28:29]
	v_pk_mul_f32 v[40:41], v[84:85], v[26:27]
	v_mul_f32_e32 v27, v31, v31
	v_mul_f32_e32 v29, v33, v33
	v_pk_mul_f32 v[36:37], v[80:81], v[22:23]
	v_mul_f32_e32 v168, v7, v7
	v_mul_f32_e32 v169, v9, v9
	v_fmac_f32_e32 v164, v22, v22
	v_fmac_f32_e32 v165, v24, v24
	v_fmac_f32_e32 v167, v28, v28
	v_cvt_pk_bf16_f32 v22, v36, v37
	v_cvt_pk_bf16_f32 v23, v34, v35
	v_fmac_f32_e32 v27, v30, v30
	v_fmac_f32_e32 v29, v32, v32
	v_lshlrev_b32_e32 v28, 16, v22
	v_and_b32_e32 v34, 0xffff0000, v22
	v_pk_mul_f32 v[160:161], v[100:101], v[8:9]
	v_pk_mul_f32 v[162:163], v[102:103], v[6:7]
	v_fmac_f32_e32 v166, v26, v26
	v_cvt_pk_bf16_f32 v24, v40, v41
	v_cvt_pk_bf16_f32 v25, v38, v39
	v_fmac_f32_e32 v168, v6, v6
	v_fmac_f32_e32 v169, v8, v8
	v_add_f32_e32 v26, v164, v165
	global_store_dwordx4 v[180:181], v[22:25], off
	v_lshlrev_b32_e32 v35, 16, v23
	v_and_b32_e32 v36, 0xffff0000, v23
	global_store_dwordx4 v[194:195], v[30:33], off offset:512
	global_store_dwordx4 v[194:195], v[6:9], off offset:528
	v_lshlrev_b32_e32 v37, 16, v24
	v_and_b32_e32 v38, 0xffff0000, v24
	v_add_f32_e32 v6, v27, v29
	v_max3_f32 v8, |v28|, 0, |v34|
	v_add_f32_e32 v7, v166, v26
	v_add_f32_e32 v6, v168, v6
	v_max3_f32 v8, v8, |v35|, |v36|
	v_lshlrev_b32_e32 v39, 16, v25
	v_and_b32_e32 v40, 0xffff0000, v25
	v_add_f32_e32 v7, v167, v7
	v_add_f32_e32 v6, v169, v6
	v_max3_f32 v8, v8, |v37|, |v38|
	v_pk_mul_f32 v[44:45], v[98:99], v[30:31]
	v_add_f32_e32 v6, v7, v6
	v_cvt_pk_bf16_f32 v22, v44, v45
	v_max3_f32 v7, v8, |v39|, |v40|
	v_lshlrev_b32_e32 v9, 16, v22
	v_and_b32_e32 v26, 0xffff0000, v22
	v_pk_mul_f32 v[42:43], v[96:97], v[32:33]
	v_max3_f32 v7, v7, |v9|, |v26|
	v_cvt_pk_bf16_f32 v23, v42, v43
	v_cvt_pk_bf16_f32 v24, v162, v163
	v_cvt_pk_bf16_f32 v25, v160, v161
	ds_bpermute_b32 v8, v233, v6
	v_lshlrev_b32_e32 v27, 16, v23
	v_and_b32_e32 v28, 0xffff0000, v23
	v_lshlrev_b32_e32 v29, 16, v24
	v_and_b32_e32 v30, 0xffff0000, v24
	v_max3_f32 v7, v7, |v27|, |v28|
	v_lshlrev_b32_e32 v31, 16, v25
	v_and_b32_e32 v32, 0xffff0000, v25
	v_max3_f32 v7, v7, |v29|, |v30|
	v_max3_f32 v9, v7, |v31|, |v32|
	ds_bpermute_b32 v26, v233, v9
	s_waitcnt lgkmcnt(1)
	v_add_f32_e32 v6, v6, v8
	ds_bpermute_b32 v7, v216, v6
	global_store_dwordx4 v[180:181], v[22:25], off offset:256
	s_waitcnt lgkmcnt(1)
	v_max_f32_e32 v8, v26, v26
	v_max_f32_e32 v8, v9, v8
	ds_bpermute_b32 v9, v216, v8
	s_and_saveexec_b64 s[44:45], s[0:1]
	s_cbranch_execz .LBB0_1766
	s_waitcnt lgkmcnt(0)
	v_max_f32_e32 v9, v9, v9
	v_max_f32_e32 v8, v8, v8
	v_add_f32_e32 v23, v6, v7
	v_lshlrev_b64 v[6:7], 7, v[192:193]
	v_max_f32_e32 v22, v8, v9
	v_lshl_add_u64 v[8:9], s[26:27], 0, v[6:7]
	s_lshl_b64 s[86:87], s[42:43], 2
	v_lshl_add_u64 v[6:7], s[28:29], 0, v[6:7]
	v_lshl_add_u64 v[8:9], v[8:9], 0, s[86:87]
	s_lshl_b32 s12, s65, 2
	v_lshl_add_u64 v[6:7], v[6:7], 0, s[86:87]
	v_lshl_add_u64 v[8:9], v[8:9], 0, s[12:13]
	v_lshl_add_u64 v[6:7], v[6:7], 0, s[12:13]
	global_store_dword v[8:9], v23, off
	global_store_dword v[6:7], v22, off
.LBB0_1766:
	s_or_b64 exec, exec, s[44:45]
	v_or_b32_e32 v36, 16, v176
	v_ashrrev_i32_e32 v37, 31, v36
	s_waitcnt lgkmcnt(1)
	v_lshlrev_b64 v[6:7], 13, v[36:37]
	v_lshl_add_u64 v[6:7], s[16:17], 0, v[6:7]
	v_lshl_add_u64 v[40:41], v[90:91], 2, v[6:7]
	global_load_dwordx4 v[26:29], v[40:41], off offset:16
	global_load_dwordx4 v[30:33], v[40:41], off
	s_waitcnt lgkmcnt(0)
	global_load_dwordx4 v[6:9], v[40:41], off offset:528
	global_load_dwordx4 v[22:25], v[40:41], off offset:512
	global_load_dword v34, v[196:197], off offset:512
	v_lshlrev_b64 v[38:39], 12, v[176:177]
	v_lshl_add_u64 v[38:39], s[22:23], 0, v[38:39]
	v_lshl_add_u64 v[38:39], v[90:91], 1, v[38:39]
	s_waitcnt vmcnt(0)
	v_pk_mul_f32 v[44:45], v[34:35], v[128:129] op_sel_hi:[0,1]
	v_pk_mul_f32 v[128:129], v[34:35], v[150:151] op_sel_hi:[0,1]
	v_pk_mul_f32 v[42:43], v[34:35], v[146:147] op_sel_hi:[0,1]
	v_pk_mul_f32 v[146:147], v[34:35], v[148:149] op_sel_hi:[0,1]
	v_pk_mul_f32 v[148:149], v[34:35], v[156:157] op_sel_hi:[0,1]
	v_pk_mul_f32 v[150:151], v[34:35], v[152:153] op_sel_hi:[0,1]
	v_pk_fma_f32 v[14:15], v[94:95], v[128:129], v[14:15]
	v_pk_mul_f32 v[152:153], v[34:35], v[158:159] op_sel_hi:[0,1]
	v_pk_mul_f32 v[34:35], v[34:35], v[154:155] op_sel_hi:[0,1]
	v_pk_fma_f32 v[20:21], v[86:87], v[44:45], v[20:21]
	v_pk_fma_f32 v[18:19], v[88:89], v[42:43], v[18:19]
	v_pk_fma_f32 v[16:17], v[92:93], v[146:147], v[16:17]
	v_pk_fma_f32 v[12:13], v[104:105], v[150:151], v[12:13]
	v_pk_fma_f32 v[10:11], v[106:107], v[148:149], v[10:11]
	v_mul_f32_e32 v156, v15, v15
	v_pk_fma_f32 v[4:5], v[110:111], v[34:35], v[4:5]
	v_pk_fma_f32 v[2:3], v[108:109], v[152:153], v[2:3]
	global_store_dwordx4 v[178:179], v[18:21], off
	global_store_dwordx4 v[178:179], v[14:17], off offset:16
	v_mul_f32_e32 v154, v19, v19
	v_mul_f32_e32 v155, v21, v21
	v_mul_f32_e32 v157, v17, v17
	v_pk_mul_f32 v[34:35], v[78:79], v[20:21]
	v_pk_mul_f32 v[42:43], v[80:81], v[18:19]
	v_pk_mul_f32 v[128:129], v[84:85], v[14:15]
	v_mul_f32_e32 v19, v11, v11
	v_mul_f32_e32 v21, v13, v13
	v_fmac_f32_e32 v156, v14, v14
	v_cvt_pk_bf16_f32 v14, v42, v43
	v_pk_mul_f32 v[44:45], v[82:83], v[16:17]
	v_mul_f32_e32 v158, v3, v3
	v_mul_f32_e32 v159, v5, v5
	v_fmac_f32_e32 v154, v18, v18
	v_fmac_f32_e32 v155, v20, v20
	v_fmac_f32_e32 v157, v16, v16
	v_cvt_pk_bf16_f32 v15, v34, v35
	v_cvt_pk_bf16_f32 v16, v128, v129
	v_cvt_pk_bf16_f32 v17, v44, v45
	v_fmac_f32_e32 v19, v10, v10
	v_fmac_f32_e32 v21, v12, v12
	global_store_dwordx4 v[38:39], v[14:17], off
	v_lshlrev_b32_e32 v20, 16, v14
	v_pk_mul_f32 v[150:151], v[100:101], v[4:5]
	v_and_b32_e32 v14, 0xffff0000, v14
	v_pk_mul_f32 v[152:153], v[102:103], v[2:3]
	v_fmac_f32_e32 v158, v2, v2
	v_fmac_f32_e32 v159, v4, v4
	v_add_f32_e32 v18, v154, v155
	v_lshlrev_b32_e32 v34, 16, v15
	v_and_b32_e32 v15, 0xffff0000, v15
	global_store_dwordx4 v[178:179], v[10:13], off offset:512
	global_store_dwordx4 v[178:179], v[2:5], off offset:528
	v_lshlrev_b32_e32 v35, 16, v16
	v_and_b32_e32 v16, 0xffff0000, v16
	v_add_f32_e32 v2, v19, v21
	v_max3_f32 v4, |v20|, 0, |v14|
	v_add_f32_e32 v3, v156, v18
	v_add_f32_e32 v2, v158, v2
	v_max3_f32 v4, v4, |v34|, |v15|
	v_lshlrev_b32_e32 v42, 16, v17
	v_and_b32_e32 v17, 0xffff0000, v17
	v_add_f32_e32 v3, v157, v3
	v_add_f32_e32 v2, v159, v2
	v_max3_f32 v4, v4, |v35|, |v16|
	v_pk_mul_f32 v[148:149], v[98:99], v[10:11]
	v_add_f32_e32 v2, v3, v2
	v_cvt_pk_bf16_f32 v10, v148, v149
	v_max3_f32 v3, v4, |v42|, |v17|
	v_lshlrev_b32_e32 v5, 16, v10
	v_and_b32_e32 v14, 0xffff0000, v10
	v_pk_mul_f32 v[146:147], v[96:97], v[12:13]
	v_max3_f32 v3, v3, |v5|, |v14|
	v_cvt_pk_bf16_f32 v11, v146, v147
	v_cvt_pk_bf16_f32 v12, v152, v153
	v_cvt_pk_bf16_f32 v13, v150, v151
	ds_bpermute_b32 v4, v233, v2
	v_lshlrev_b32_e32 v18, 16, v11
	v_and_b32_e32 v19, 0xffff0000, v11
	v_lshlrev_b32_e32 v20, 16, v12
	v_and_b32_e32 v21, 0xffff0000, v12
	v_max3_f32 v3, v3, |v18|, |v19|
	v_lshlrev_b32_e32 v43, 16, v13
	v_and_b32_e32 v44, 0xffff0000, v13
	v_max3_f32 v3, v3, |v20|, |v21|
	v_max3_f32 v5, v3, |v43|, |v44|
	ds_bpermute_b32 v14, v233, v5
	s_waitcnt lgkmcnt(1)
	v_add_f32_e32 v2, v2, v4
	ds_bpermute_b32 v3, v216, v2
	global_store_dwordx4 v[38:39], v[10:13], off offset:256
	s_waitcnt lgkmcnt(1)
	v_max_f32_e32 v4, v14, v14
	v_max_f32_e32 v4, v5, v4
	ds_bpermute_b32 v5, v216, v4
	s_and_saveexec_b64 s[44:45], s[0:1]
	s_cbranch_execz .LBB0_1768
	s_waitcnt lgkmcnt(0)
	v_max_f32_e32 v5, v5, v5
	v_max_f32_e32 v4, v4, v4
	v_add_f32_e32 v11, v2, v3
	v_lshlrev_b64 v[2:3], 7, v[176:177]
	v_max_f32_e32 v10, v4, v5
	v_lshl_add_u64 v[4:5], s[26:27], 0, v[2:3]
	s_lshl_b64 s[86:87], s[42:43], 2
	v_lshl_add_u64 v[2:3], s[28:29], 0, v[2:3]
	v_lshl_add_u64 v[4:5], v[4:5], 0, s[86:87]
	s_lshl_b32 s12, s65, 2
	v_lshl_add_u64 v[2:3], v[2:3], 0, s[86:87]
	v_lshl_add_u64 v[4:5], v[4:5], 0, s[12:13]
	v_lshl_add_u64 v[2:3], v[2:3], 0, s[12:13]
	global_store_dword v[4:5], v11, off
	global_store_dword v[2:3], v10, off
.LBB0_1768:
	s_or_b64 exec, exec, s[44:45]
	v_or_b32_e32 v34, 32, v176
	v_ashrrev_i32_e32 v35, 31, v34
	s_waitcnt lgkmcnt(1)
	v_lshlrev_b64 v[2:3], 13, v[34:35]
	v_lshl_add_u64 v[2:3], s[16:17], 0, v[2:3]
	v_lshl_add_u64 v[38:39], v[90:91], 2, v[2:3]
	global_load_dwordx4 v[14:17], v[38:39], off offset:16
	global_load_dwordx4 v[18:21], v[38:39], off
	s_waitcnt lgkmcnt(0)
	global_load_dwordx4 v[2:5], v[38:39], off offset:528
	global_load_dwordx4 v[10:13], v[38:39], off offset:512
	v_lshl_add_u64 v[42:43], v[36:37], 2, s[18:19]
	global_load_dword v42, v[42:43], off
	v_lshlrev_b64 v[44:45], 12, v[36:37]
	v_lshl_add_u64 v[44:45], s[22:23], 0, v[44:45]
	v_lshl_add_u64 v[44:45], v[90:91], 1, v[44:45]
	s_waitcnt vmcnt(0)
	v_pk_mul_f32 v[118:119], v[42:43], v[118:119] op_sel_hi:[0,1]
	v_pk_mul_f32 v[114:115], v[42:43], v[114:115] op_sel_hi:[0,1]
	v_pk_mul_f32 v[112:113], v[42:43], v[112:113] op_sel_hi:[0,1]
	v_pk_mul_f32 v[116:117], v[42:43], v[116:117] op_sel_hi:[0,1]
	v_pk_mul_f32 v[124:125], v[42:43], v[124:125] op_sel_hi:[0,1]
	v_pk_mul_f32 v[120:121], v[42:43], v[120:121] op_sel_hi:[0,1]
	v_pk_fma_f32 v[26:27], v[94:95], v[118:119], v[26:27]
	v_pk_mul_f32 v[126:127], v[42:43], v[126:127] op_sel_hi:[0,1]
	v_pk_mul_f32 v[42:43], v[42:43], v[122:123] op_sel_hi:[0,1]
	v_pk_fma_f32 v[32:33], v[86:87], v[112:113], v[32:33]
	v_pk_fma_f32 v[30:31], v[88:89], v[114:115], v[30:31]
	v_pk_fma_f32 v[28:29], v[92:93], v[116:117], v[28:29]
	v_pk_fma_f32 v[24:25], v[104:105], v[120:121], v[24:25]
	v_pk_fma_f32 v[22:23], v[106:107], v[124:125], v[22:23]
	v_mul_f32_e32 v128, v27, v27
	v_pk_fma_f32 v[8:9], v[110:111], v[42:43], v[8:9]
	v_pk_fma_f32 v[6:7], v[108:109], v[126:127], v[6:7]
	global_store_dwordx4 v[40:41], v[30:33], off
	global_store_dwordx4 v[40:41], v[26:29], off offset:16
	v_mul_f32_e32 v126, v31, v31
	v_mul_f32_e32 v127, v33, v33
	v_mul_f32_e32 v129, v29, v29
	v_pk_mul_f32 v[42:43], v[78:79], v[32:33]
	v_pk_mul_f32 v[112:113], v[80:81], v[30:31]
	v_pk_mul_f32 v[116:117], v[84:85], v[26:27]
	v_mul_f32_e32 v31, v23, v23
	v_mul_f32_e32 v33, v25, v25
	v_fmac_f32_e32 v128, v26, v26
	v_cvt_pk_bf16_f32 v26, v112, v113
	v_pk_mul_f32 v[114:115], v[82:83], v[28:29]
	v_mul_f32_e32 v146, v7, v7
	v_mul_f32_e32 v147, v9, v9
	v_fmac_f32_e32 v126, v30, v30
	v_fmac_f32_e32 v127, v32, v32
	v_fmac_f32_e32 v129, v28, v28
	v_cvt_pk_bf16_f32 v27, v42, v43
	v_cvt_pk_bf16_f32 v28, v116, v117
	v_cvt_pk_bf16_f32 v29, v114, v115
	v_fmac_f32_e32 v31, v22, v22
	v_fmac_f32_e32 v33, v24, v24
	global_store_dwordx4 v[44:45], v[26:29], off
	v_lshlrev_b32_e32 v32, 16, v26
	v_pk_mul_f32 v[122:123], v[100:101], v[8:9]
	v_and_b32_e32 v26, 0xffff0000, v26
	v_pk_mul_f32 v[124:125], v[102:103], v[6:7]
	v_fmac_f32_e32 v146, v6, v6
	v_fmac_f32_e32 v147, v8, v8
	v_add_f32_e32 v30, v126, v127
	v_lshlrev_b32_e32 v42, 16, v27
	v_and_b32_e32 v27, 0xffff0000, v27
	global_store_dwordx4 v[40:41], v[22:25], off offset:512
	global_store_dwordx4 v[40:41], v[6:9], off offset:528
	v_lshlrev_b32_e32 v43, 16, v28
	v_and_b32_e32 v28, 0xffff0000, v28
	v_add_f32_e32 v6, v31, v33
	v_max3_f32 v8, |v32|, 0, |v26|
	v_add_f32_e32 v7, v128, v30
	v_add_f32_e32 v6, v146, v6
	v_max3_f32 v8, v8, |v42|, |v27|
	v_lshlrev_b32_e32 v112, 16, v29
	v_and_b32_e32 v29, 0xffff0000, v29
	v_add_f32_e32 v7, v129, v7
	v_add_f32_e32 v6, v147, v6
	v_max3_f32 v8, v8, |v43|, |v28|
	v_pk_mul_f32 v[120:121], v[98:99], v[22:23]
	v_add_f32_e32 v6, v7, v6
	v_cvt_pk_bf16_f32 v22, v120, v121
	v_max3_f32 v7, v8, |v112|, |v29|
	v_lshlrev_b32_e32 v9, 16, v22
	v_and_b32_e32 v26, 0xffff0000, v22
	v_pk_mul_f32 v[118:119], v[96:97], v[24:25]
	v_max3_f32 v7, v7, |v9|, |v26|
	v_cvt_pk_bf16_f32 v23, v118, v119
	v_cvt_pk_bf16_f32 v24, v124, v125
	v_cvt_pk_bf16_f32 v25, v122, v123
	ds_bpermute_b32 v8, v233, v6
	v_lshlrev_b32_e32 v30, 16, v23
	v_and_b32_e32 v31, 0xffff0000, v23
	v_lshlrev_b32_e32 v32, 16, v24
	v_and_b32_e32 v33, 0xffff0000, v24
	v_max3_f32 v7, v7, |v30|, |v31|
	v_lshlrev_b32_e32 v40, 16, v25
	v_and_b32_e32 v41, 0xffff0000, v25
	v_max3_f32 v7, v7, |v32|, |v33|
	v_max3_f32 v9, v7, |v40|, |v41|
	ds_bpermute_b32 v26, v233, v9
	s_waitcnt lgkmcnt(1)
	v_add_f32_e32 v6, v6, v8
	ds_bpermute_b32 v7, v216, v6
	global_store_dwordx4 v[44:45], v[22:25], off offset:256
	s_waitcnt lgkmcnt(1)
	v_max_f32_e32 v8, v26, v26
	v_max_f32_e32 v8, v9, v8
	ds_bpermute_b32 v9, v216, v8
	s_and_saveexec_b64 s[44:45], s[0:1]
	s_cbranch_execz .LBB0_1770
	s_waitcnt lgkmcnt(0)
	v_max_f32_e32 v9, v9, v9
	v_max_f32_e32 v8, v8, v8
	v_add_f32_e32 v23, v6, v7
	v_lshlrev_b64 v[6:7], 7, v[36:37]
	v_max_f32_e32 v22, v8, v9
	v_lshl_add_u64 v[8:9], s[26:27], 0, v[6:7]
	s_lshl_b64 s[86:87], s[42:43], 2
	v_lshl_add_u64 v[6:7], s[28:29], 0, v[6:7]
	v_lshl_add_u64 v[8:9], v[8:9], 0, s[86:87]
	s_lshl_b32 s12, s65, 2
	v_lshl_add_u64 v[6:7], v[6:7], 0, s[86:87]
	v_lshl_add_u64 v[8:9], v[8:9], 0, s[12:13]
	v_lshl_add_u64 v[6:7], v[6:7], 0, s[12:13]
	global_store_dword v[8:9], v23, off
	global_store_dword v[6:7], v22, off
.LBB0_1770:
	s_or_b64 exec, exec, s[44:45]
	v_or_b32_e32 v36, 48, v176
	v_ashrrev_i32_e32 v37, 31, v36
	s_waitcnt lgkmcnt(1)
	v_lshlrev_b64 v[6:7], 13, v[36:37]
	v_lshl_add_u64 v[6:7], s[16:17], 0, v[6:7]
	v_lshl_add_u64 v[40:41], v[90:91], 2, v[6:7]
	global_load_dwordx4 v[26:29], v[40:41], off offset:16
	global_load_dwordx4 v[30:33], v[40:41], off
	s_waitcnt lgkmcnt(0)
	global_load_dwordx4 v[6:9], v[40:41], off offset:528
	global_load_dwordx4 v[22:25], v[40:41], off offset:512
	v_lshl_add_u64 v[42:43], v[34:35], 2, s[18:19]
	global_load_dword v42, v[42:43], off
	v_lshlrev_b64 v[44:45], 12, v[34:35]
	v_lshl_add_u64 v[44:45], s[22:23], 0, v[44:45]
	v_lshl_add_u64 v[44:45], v[90:91], 1, v[44:45]
	s_waitcnt vmcnt(0)
	v_pk_mul_f32 v[68:69], v[42:43], v[68:69] op_sel_hi:[0,1]
	v_pk_mul_f32 v[64:65], v[42:43], v[64:65] op_sel_hi:[0,1]
	v_pk_mul_f32 v[62:63], v[42:43], v[62:63] op_sel_hi:[0,1]
	v_pk_mul_f32 v[66:67], v[42:43], v[66:67] op_sel_hi:[0,1]
	v_pk_mul_f32 v[74:75], v[42:43], v[74:75] op_sel_hi:[0,1]
	v_pk_mul_f32 v[70:71], v[42:43], v[70:71] op_sel_hi:[0,1]
	v_pk_fma_f32 v[14:15], v[94:95], v[68:69], v[14:15]
	v_pk_mul_f32 v[76:77], v[42:43], v[76:77] op_sel_hi:[0,1]
	v_pk_mul_f32 v[42:43], v[42:43], v[72:73] op_sel_hi:[0,1]
	v_pk_fma_f32 v[20:21], v[86:87], v[62:63], v[20:21]
	v_pk_fma_f32 v[18:19], v[88:89], v[64:65], v[18:19]
	v_pk_fma_f32 v[16:17], v[92:93], v[66:67], v[16:17]
	v_pk_fma_f32 v[12:13], v[104:105], v[70:71], v[12:13]
	v_pk_fma_f32 v[10:11], v[106:107], v[74:75], v[10:11]
	v_mul_f32_e32 v112, v15, v15
	v_pk_fma_f32 v[4:5], v[110:111], v[42:43], v[4:5]
	v_pk_fma_f32 v[2:3], v[108:109], v[76:77], v[2:3]
	global_store_dwordx4 v[38:39], v[18:21], off
	global_store_dwordx4 v[38:39], v[14:17], off offset:16
	v_mul_f32_e32 v76, v19, v19
	v_mul_f32_e32 v77, v21, v21
	v_mul_f32_e32 v113, v17, v17
	v_pk_mul_f32 v[42:43], v[78:79], v[20:21]
	v_pk_mul_f32 v[62:63], v[80:81], v[18:19]
	v_pk_mul_f32 v[66:67], v[84:85], v[14:15]
	v_mul_f32_e32 v19, v11, v11
	v_mul_f32_e32 v21, v13, v13
	v_fmac_f32_e32 v112, v14, v14
	v_cvt_pk_bf16_f32 v14, v62, v63
	v_pk_mul_f32 v[64:65], v[82:83], v[16:17]
	v_mul_f32_e32 v114, v3, v3
	v_mul_f32_e32 v115, v5, v5
	v_fmac_f32_e32 v76, v18, v18
	v_fmac_f32_e32 v77, v20, v20
	v_fmac_f32_e32 v113, v16, v16
	v_cvt_pk_bf16_f32 v15, v42, v43
	v_cvt_pk_bf16_f32 v16, v66, v67
	v_cvt_pk_bf16_f32 v17, v64, v65
	v_fmac_f32_e32 v19, v10, v10
	v_fmac_f32_e32 v21, v12, v12
	global_store_dwordx4 v[44:45], v[14:17], off
	v_lshlrev_b32_e32 v20, 16, v14
	v_pk_mul_f32 v[72:73], v[100:101], v[4:5]
	v_and_b32_e32 v14, 0xffff0000, v14
	v_pk_mul_f32 v[74:75], v[102:103], v[2:3]
	v_fmac_f32_e32 v114, v2, v2
	v_fmac_f32_e32 v115, v4, v4
	v_add_f32_e32 v18, v76, v77
	v_lshlrev_b32_e32 v42, 16, v15
	v_and_b32_e32 v15, 0xffff0000, v15
	global_store_dwordx4 v[38:39], v[10:13], off offset:512
	global_store_dwordx4 v[38:39], v[2:5], off offset:528
	v_lshlrev_b32_e32 v43, 16, v16
	v_and_b32_e32 v16, 0xffff0000, v16
	v_add_f32_e32 v2, v19, v21
	v_max3_f32 v4, |v20|, 0, |v14|
	v_add_f32_e32 v3, v112, v18
	v_add_f32_e32 v2, v114, v2
	v_max3_f32 v4, v4, |v42|, |v15|
	v_lshlrev_b32_e32 v62, 16, v17
	v_and_b32_e32 v17, 0xffff0000, v17
	v_add_f32_e32 v3, v113, v3
	v_add_f32_e32 v2, v115, v2
	v_max3_f32 v4, v4, |v43|, |v16|
	v_pk_mul_f32 v[70:71], v[98:99], v[10:11]
	v_add_f32_e32 v2, v3, v2
	v_cvt_pk_bf16_f32 v10, v70, v71
	v_max3_f32 v3, v4, |v62|, |v17|
	v_lshlrev_b32_e32 v5, 16, v10
	v_and_b32_e32 v14, 0xffff0000, v10
	v_pk_mul_f32 v[68:69], v[96:97], v[12:13]
	v_max3_f32 v3, v3, |v5|, |v14|
	v_cvt_pk_bf16_f32 v11, v68, v69
	v_cvt_pk_bf16_f32 v12, v74, v75
	v_cvt_pk_bf16_f32 v13, v72, v73
	ds_bpermute_b32 v4, v233, v2
	v_lshlrev_b32_e32 v18, 16, v11
	v_and_b32_e32 v19, 0xffff0000, v11
	v_lshlrev_b32_e32 v20, 16, v12
	v_and_b32_e32 v21, 0xffff0000, v12
	v_max3_f32 v3, v3, |v18|, |v19|
	v_lshlrev_b32_e32 v38, 16, v13
	v_and_b32_e32 v39, 0xffff0000, v13
	v_max3_f32 v3, v3, |v20|, |v21|
	v_max3_f32 v5, v3, |v38|, |v39|
	ds_bpermute_b32 v14, v233, v5
	s_waitcnt lgkmcnt(1)
	v_add_f32_e32 v2, v2, v4
	ds_bpermute_b32 v3, v216, v2
	global_store_dwordx4 v[44:45], v[10:13], off offset:256
	s_waitcnt lgkmcnt(1)
	v_max_f32_e32 v4, v14, v14
	v_max_f32_e32 v4, v5, v4
	ds_bpermute_b32 v5, v216, v4
	s_and_saveexec_b64 s[44:45], s[0:1]
	s_cbranch_execz .LBB0_1772
	s_waitcnt lgkmcnt(0)
	v_max_f32_e32 v5, v5, v5
	v_max_f32_e32 v4, v4, v4
	v_add_f32_e32 v11, v2, v3
	v_lshlrev_b64 v[2:3], 7, v[34:35]
	v_max_f32_e32 v10, v4, v5
	v_lshl_add_u64 v[4:5], s[26:27], 0, v[2:3]
	s_lshl_b64 s[86:87], s[42:43], 2
	v_lshl_add_u64 v[2:3], s[28:29], 0, v[2:3]
	v_lshl_add_u64 v[4:5], v[4:5], 0, s[86:87]
	s_lshl_b32 s12, s65, 2
	v_lshl_add_u64 v[2:3], v[2:3], 0, s[86:87]
	v_lshl_add_u64 v[4:5], v[4:5], 0, s[12:13]
	v_lshl_add_u64 v[2:3], v[2:3], 0, s[12:13]
	global_store_dword v[4:5], v11, off
	global_store_dword v[2:3], v10, off
.LBB0_1772:
	s_or_b64 exec, exec, s[44:45]
	s_waitcnt lgkmcnt(1)
	v_lshl_add_u64 v[2:3], v[36:37], 2, s[18:19]
	global_load_dword v2, v[2:3], off
	s_waitcnt lgkmcnt(0)
	v_lshlrev_b64 v[4:5], 12, v[36:37]
	v_lshl_add_u64 v[4:5], s[22:23], 0, v[4:5]
	v_lshl_add_u64 v[18:19], v[90:91], 1, v[4:5]
	s_waitcnt vmcnt(0)
	v_pk_mul_f32 v[10:11], v[2:3], v[48:49] op_sel_hi:[0,1]
	v_pk_mul_f32 v[4:5], v[2:3], v[46:47] op_sel_hi:[0,1]
	v_pk_mul_f32 v[14:15], v[2:3], v[52:53] op_sel_hi:[0,1]
	v_pk_mul_f32 v[12:13], v[2:3], v[50:51] op_sel_hi:[0,1]
	v_pk_mul_f32 v[20:21], v[2:3], v[58:59] op_sel_hi:[0,1]
	v_pk_mul_f32 v[16:17], v[2:3], v[54:55] op_sel_hi:[0,1]
	v_pk_mul_f32 v[34:35], v[2:3], v[60:61] op_sel_hi:[0,1]
	v_pk_mul_f32 v[38:39], v[2:3], v[56:57] op_sel_hi:[0,1]
	v_pk_fma_f32 v[2:3], v[88:89], v[10:11], v[30:31]
	v_pk_fma_f32 v[4:5], v[86:87], v[4:5], v[32:33]
	v_pk_fma_f32 v[12:13], v[92:93], v[12:13], v[28:29]
	v_pk_fma_f32 v[8:9], v[110:111], v[38:39], v[8:9]
	v_mul_f32_e32 v38, v3, v3
	v_pk_fma_f32 v[10:11], v[94:95], v[14:15], v[26:27]
	v_pk_fma_f32 v[14:15], v[106:107], v[20:21], v[22:23]
	global_store_dwordx4 v[40:41], v[2:5], off
	global_store_dwordx4 v[40:41], v[10:13], off offset:16
	v_mul_f32_e32 v39, v5, v5
	v_mul_f32_e32 v43, v13, v13
	v_pk_mul_f32 v[22:23], v[80:81], v[2:3]
	v_fmac_f32_e32 v38, v2, v2
	v_cvt_pk_bf16_f32 v2, v22, v23
	v_pk_fma_f32 v[16:17], v[104:105], v[16:17], v[24:25]
	v_pk_mul_f32 v[20:21], v[78:79], v[4:5]
	v_pk_mul_f32 v[24:25], v[82:83], v[12:13]
	v_pk_mul_f32 v[26:27], v[84:85], v[10:11]
	v_fmac_f32_e32 v39, v4, v4
	v_fmac_f32_e32 v43, v12, v12
	v_cvt_pk_bf16_f32 v3, v20, v21
	v_cvt_pk_bf16_f32 v4, v26, v27
	v_cvt_pk_bf16_f32 v5, v24, v25
	global_store_dwordx4 v[18:19], v[2:5], off
	v_lshlrev_b32_e32 v12, 16, v2
	v_lshlrev_b32_e32 v20, 16, v3
	v_and_b32_e32 v2, 0xffff0000, v2
	v_and_b32_e32 v3, 0xffff0000, v3
	v_max3_f32 v2, |v12|, 0, |v2|
	v_pk_fma_f32 v[6:7], v[108:109], v[34:35], v[6:7]
	v_mul_f32_e32 v42, v11, v11
	v_mul_f32_e32 v11, v15, v15
	v_mul_f32_e32 v13, v17, v17
	v_lshlrev_b32_e32 v21, 16, v4
	v_and_b32_e32 v4, 0xffff0000, v4
	v_max3_f32 v2, v2, |v20|, |v3|
	v_mul_f32_e32 v44, v7, v7
	v_fmac_f32_e32 v11, v14, v14
	v_fmac_f32_e32 v13, v16, v16
	v_lshlrev_b32_e32 v22, 16, v5
	v_and_b32_e32 v5, 0xffff0000, v5
	v_max3_f32 v2, v2, |v21|, |v4|
	v_pk_mul_f32 v[30:31], v[98:99], v[14:15]
	v_pk_mul_f32 v[34:35], v[102:103], v[6:7]
	v_fmac_f32_e32 v44, v6, v6
	global_store_dwordx4 v[40:41], v[14:17], off offset:512
	global_store_dwordx4 v[40:41], v[6:9], off offset:528
	v_add_f32_e32 v11, v11, v13
	v_max3_f32 v2, v2, |v22|, |v5|
	v_cvt_pk_bf16_f32 v6, v30, v31
	v_mul_f32_e32 v45, v9, v9
	v_lshlrev_b32_e32 v12, 16, v6
	v_and_b32_e32 v13, 0xffff0000, v6
	v_pk_mul_f32 v[28:29], v[96:97], v[16:17]
	v_fmac_f32_e32 v42, v10, v10
	v_add_f32_e32 v10, v38, v39
	v_cvt_pk_bf16_f32 v7, v28, v29
	v_max3_f32 v2, v2, |v12|, |v13|
	v_lshlrev_b32_e32 v14, 16, v7
	v_and_b32_e32 v15, 0xffff0000, v7
	v_pk_mul_f32 v[32:33], v[100:101], v[8:9]
	v_fmac_f32_e32 v45, v8, v8
	v_cvt_pk_bf16_f32 v8, v34, v35
	v_add_f32_e32 v10, v42, v10
	v_add_f32_e32 v11, v44, v11
	v_lshlrev_b32_e32 v16, 16, v8
	v_and_b32_e32 v17, 0xffff0000, v8
	v_max3_f32 v2, v2, |v14|, |v15|
	v_cvt_pk_bf16_f32 v9, v32, v33
	v_add_f32_e32 v10, v43, v10
	v_lshlrev_b32_e32 v23, 16, v9
	v_and_b32_e32 v24, 0xffff0000, v9
	v_add_f32_e32 v3, v45, v11
	v_max3_f32 v2, v2, |v16|, |v17|
	v_add_f32_e32 v3, v10, v3
	v_max3_f32 v5, v2, |v23|, |v24|
	ds_bpermute_b32 v4, v233, v3
	ds_bpermute_b32 v10, v233, v5
	global_store_dwordx4 v[18:19], v[6:9], off offset:256
	s_waitcnt lgkmcnt(1)
	v_add_f32_e32 v2, v3, v4
	s_waitcnt lgkmcnt(0)
	v_max_f32_e32 v4, v10, v10
	v_max_f32_e32 v4, v5, v4
	ds_bpermute_b32 v3, v216, v2
	ds_bpermute_b32 v5, v216, v4
	s_and_saveexec_b64 s[44:45], s[0:1]
	s_cbranch_execz .LBB0_1774
	s_waitcnt lgkmcnt(0)
	v_max_f32_e32 v5, v5, v5
	v_max_f32_e32 v4, v4, v4
	v_add_f32_e32 v7, v2, v3
	v_lshlrev_b64 v[2:3], 7, v[36:37]
	v_max_f32_e32 v6, v4, v5
	v_lshl_add_u64 v[4:5], s[26:27], 0, v[2:3]
	s_lshl_b64 s[42:43], s[42:43], 2
	v_lshl_add_u64 v[2:3], s[28:29], 0, v[2:3]
	v_lshl_add_u64 v[4:5], v[4:5], 0, s[42:43]
	s_lshl_b32 s12, s65, 2
	v_lshl_add_u64 v[2:3], v[2:3], 0, s[42:43]
	v_lshl_add_u64 v[4:5], v[4:5], 0, s[12:13]
	v_lshl_add_u64 v[2:3], v[2:3], 0, s[12:13]
	global_store_dword v[4:5], v7, off
	global_store_dword v[2:3], v6, off

.LBB0_2025:
	s_lshr_b32 s34, s81, 4
	s_add_i32 s34, s34, -1
	s_cmp_gt_i32 s81, 31
	s_cselect_b32 s34, s34, 0
	v_lshl_or_b32 v178, s12, 8, v208
	s_mul_i32 s37, s34, 0xc000
	s_mul_hi_i32 s36, s34, 0xc000
	s_add_u32 s34, s55, s37
	v_ashrrev_i32_e32 v179, 31, v178
	s_addc_u32 s35, s56, s36
	v_lshlrev_b64 v[114:115], 2, v[178:179]
	v_lshl_add_u64 v[122:123], s[34:35], 0, v[114:115]
	s_add_u32 s34, s57, s37
	v_lshl_add_u32 v196, s81, 8, v206
	v_lshl_add_u64 v[116:117], s[20:21], 0, v[114:115]
	s_addc_u32 s35, s58, s36
	v_ashrrev_i32_e32 v197, 31, v196
	v_lshl_add_u64 v[124:125], s[34:35], 0, v[114:115]
	global_load_dwordx4 v[118:121], v[122:123], off offset:16
	global_load_dwordx4 v[126:129], v[122:123], off
	global_load_dwordx4 v[180:183], v[116:117], off offset:16
	global_load_dwordx4 v[184:187], v[116:117], off
	global_load_dwordx4 v[188:191], v[124:125], off offset:16
	global_load_dwordx4 v[192:195], v[124:125], off
	global_load_dwordx4 v[214:217], v[116:117], off offset:528
	global_load_dwordx4 v[218:221], v[116:117], off offset:512
	global_load_dwordx4 v[222:225], v[124:125], off offset:528
	global_load_dwordx4 v[226:229], v[124:125], off offset:512
	v_lshlrev_b64 v[116:117], 13, v[196:197]
	v_or_b32_e32 v198, 16, v196
	v_lshl_add_u64 v[116:117], s[16:17], 0, v[116:117]
	v_ashrrev_i32_e32 v199, 31, v198
	v_lshl_add_u64 v[200:201], v[116:117], 0, v[114:115]
	v_lshlrev_b64 v[116:117], 13, v[198:199]
	v_lshl_add_u64 v[116:117], s[16:17], 0, v[116:117]
	v_lshl_add_u64 v[202:203], v[116:117], 0, v[114:115]
	global_load_dwordx4 v[230:233], v[200:201], off offset:16
	global_load_dwordx4 v[234:237], v[200:201], off
	global_load_dwordx4 v[238:241], v[200:201], off offset:528
	global_load_dwordx4 v[242:245], v[200:201], off offset:512
	global_load_dwordx4 v[154:157], v[202:203], off offset:16
	global_load_dwordx4 v[158:161], v[202:203], off
	global_load_dwordx4 v[146:149], v[202:203], off offset:528
	global_load_dwordx4 v[150:153], v[202:203], off offset:512
	global_load_dwordx4 v[114:117], v[122:123], off offset:528
	s_nop 0
	global_load_dwordx4 v[122:125], v[122:123], off offset:512
	s_lshl_b32 s34, s12, 2
	s_ashr_i32 s35, s34, 31
	s_waitcnt vmcnt(0)
	v_pk_add_f32 v[190:191], v[190:191], 1.0 op_sel_hi:[1,0]
	v_pk_add_f32 v[194:195], v[194:195], 1.0 op_sel_hi:[1,0]
	v_pk_add_f32 v[204:205], v[192:193], 1.0 op_sel_hi:[1,0]
	v_pk_add_f32 v[246:247], v[188:189], 1.0 op_sel_hi:[1,0]
	v_pk_add_f32 v[224:225], v[224:225], 1.0 op_sel_hi:[1,0]
	v_pk_add_f32 v[228:229], v[228:229], 1.0 op_sel_hi:[1,0]
	v_pk_add_f32 v[226:227], v[226:227], 1.0 op_sel_hi:[1,0]
	v_pk_add_f32 v[222:223], v[222:223], 1.0 op_sel_hi:[1,0]
	v_pk_mul_f32 v[192:193], v[186:187], v[194:195]
	v_pk_mul_f32 v[194:195], v[184:185], v[204:205]
	v_pk_mul_f32 v[188:189], v[182:183], v[190:191]
	v_pk_mul_f32 v[190:191], v[180:181], v[246:247]
	v_pk_mul_f32 v[186:187], v[220:221], v[228:229]
	v_pk_mul_f32 v[184:185], v[218:219], v[226:227]
	v_pk_mul_f32 v[180:181], v[216:217], v[224:225]
	v_pk_mul_f32 v[182:183], v[214:215], v[222:223]
	v_pk_fma_f32 v[144:145], v[144:145], v[128:129], v[236:237]
	v_pk_fma_f32 v[142:143], v[142:143], v[126:127], v[234:235]
	v_mul_f32_e32 v205, v145, v145
	v_mul_f32_e32 v204, v143, v143
	v_pk_fma_f32 v[138:139], v[138:139], v[118:119], v[230:231]
	v_fmac_f32_e32 v204, v142, v142
	v_fmac_f32_e32 v205, v144, v144
	v_add_f32_e32 v204, v204, v205
	v_mul_f32_e32 v205, v139, v139
	v_pk_fma_f32 v[140:141], v[140:141], v[120:121], v[232:233]
	v_fmac_f32_e32 v205, v138, v138
	v_add_f32_e32 v204, v204, v205
	v_mul_f32_e32 v205, v141, v141
	global_store_dwordx4 v[200:201], v[142:145], off
	global_store_dwordx4 v[200:201], v[138:141], off offset:16
	v_fmac_f32_e32 v205, v140, v140
	v_pk_mul_f32 v[142:143], v[194:195], v[142:143]
	v_add_f32_e32 v213, v205, v204
	v_pk_mul_f32 v[204:205], v[188:189], v[140:141]
	v_pk_mul_f32 v[140:141], v[190:191], v[138:139]
	v_cvt_pk_bf16_f32 v138, v142, v143
	v_lshlrev_b64 v[142:143], 12, v[196:197]
	v_lshl_add_u64 v[142:143], s[18:19], 0, v[142:143]
	v_pk_mul_f32 v[144:145], v[192:193], v[144:145]
	v_lshl_add_u64 v[142:143], v[178:179], 1, v[142:143]
	v_cvt_pk_bf16_f32 v139, v144, v145
	v_pk_fma_f32 v[136:137], v[136:137], v[124:125], v[244:245]
	v_pk_fma_f32 v[134:135], v[134:135], v[122:123], v[242:243]
	v_cvt_pk_bf16_f32 v140, v140, v141
	v_cvt_pk_bf16_f32 v141, v204, v205
	global_store_dwordx4 v[142:143], v[138:141], off
	v_pk_fma_f32 v[130:131], v[130:131], v[114:115], v[238:239]
	v_pk_fma_f32 v[132:133], v[132:133], v[116:117], v[240:241]
	v_mul_f32_e32 v138, v135, v135
	v_mul_f32_e32 v139, v137, v137
	v_fmac_f32_e32 v138, v134, v134
	v_fmac_f32_e32 v139, v136, v136
	v_add_f32_e32 v138, v138, v139
	v_mul_f32_e32 v139, v131, v131
	v_fmac_f32_e32 v139, v130, v130
	v_add_f32_e32 v138, v138, v139
	v_mul_f32_e32 v139, v133, v133
	v_fmac_f32_e32 v139, v132, v132
	v_add_f32_e32 v138, v139, v138
	v_and_b32_e32 v139, 64, v212
	v_add_f32_e32 v144, v213, v138
	v_xor_b32_e32 v138, 16, v212
	v_add_u32_e32 v145, 64, v139
	v_cmp_lt_i32_e32 vcc, v138, v145
	global_store_dwordx4 v[200:201], v[134:137], off offset:512
	global_store_dwordx4 v[200:201], v[130:133], off offset:528
	v_cndmask_b32_e32 v138, v212, v138, vcc
	v_lshlrev_b32_e32 v213, 2, v138
	ds_bpermute_b32 v200, v213, v144
	v_pk_mul_f32 v[140:141], v[182:183], v[130:131]
	v_xor_b32_e32 v131, 32, v212
	v_cmp_lt_i32_e32 vcc, v131, v145
	v_pk_mul_f32 v[134:135], v[184:185], v[134:135]
	s_waitcnt lgkmcnt(0)
	v_add_f32_e32 v130, v144, v200
	v_cndmask_b32_e32 v131, v212, v131, vcc
	v_lshlrev_b32_e32 v214, 2, v131
	ds_bpermute_b32 v131, v214, v130
	v_pk_mul_f32 v[136:137], v[186:187], v[136:137]
	v_pk_mul_f32 v[138:139], v[180:181], v[132:133]
	v_cvt_pk_bf16_f32 v132, v134, v135
	v_cvt_pk_bf16_f32 v133, v136, v137
	v_cvt_pk_bf16_f32 v134, v140, v141
	s_nop 0
	v_cvt_pk_bf16_f32 v135, v138, v139
	global_store_dwordx4 v[142:143], v[132:135], off offset:256
	s_and_saveexec_b64 s[36:37], s[0:1]
	s_cbranch_execz .LBB0_2027
	s_waitcnt lgkmcnt(0)
	v_add_f32_e32 v132, v130, v131
	v_lshlrev_b64 v[130:131], 7, v[196:197]
	v_lshl_add_u64 v[130:131], s[22:23], 0, v[130:131]
	v_lshl_add_u64 v[130:131], s[34:35], 2, v[130:131]
	s_lshl_b32 s12, s59, 2
	v_lshl_add_u64 v[130:131], v[130:131], 0, s[12:13]
	global_store_dword v[130:131], v132, off
.LBB0_2027:
	s_or_b64 exec, exec, s[36:37]
	v_or_b32_e32 v200, 32, v196
	v_ashrrev_i32_e32 v201, 31, v200
	s_waitcnt lgkmcnt(0)
	v_lshlrev_b64 v[130:131], 13, v[200:201]
	v_lshl_add_u64 v[130:131], s[16:17], 0, v[130:131]
	v_lshl_add_u64 v[204:205], v[178:179], 2, v[130:131]
	global_load_dwordx4 v[138:141], v[204:205], off offset:16
	global_load_dwordx4 v[142:145], v[204:205], off
	global_load_dwordx4 v[130:133], v[204:205], off offset:528
	global_load_dwordx4 v[134:137], v[204:205], off offset:512
	v_pk_fma_f32 v[112:113], v[112:113], v[128:129], v[160:161]
	v_pk_fma_f32 v[110:111], v[110:111], v[126:127], v[158:159]
	v_pk_fma_f32 v[106:107], v[106:107], v[118:119], v[154:155]
	v_mul_f32_e32 v154, v111, v111
	v_mul_f32_e32 v155, v113, v113
	v_fmac_f32_e32 v154, v110, v110
	v_fmac_f32_e32 v155, v112, v112
	v_add_f32_e32 v154, v154, v155
	v_mul_f32_e32 v155, v107, v107
	v_pk_fma_f32 v[108:109], v[108:109], v[120:121], v[156:157]
	v_fmac_f32_e32 v155, v106, v106
	v_add_f32_e32 v154, v154, v155
	v_mul_f32_e32 v155, v109, v109
	global_store_dwordx4 v[202:203], v[110:113], off
	global_store_dwordx4 v[202:203], v[106:109], off offset:16
	v_fmac_f32_e32 v155, v108, v108
	v_pk_mul_f32 v[110:111], v[194:195], v[110:111]
	v_add_f32_e32 v156, v155, v154
	v_pk_mul_f32 v[154:155], v[188:189], v[108:109]
	v_pk_mul_f32 v[108:109], v[190:191], v[106:107]
	v_cvt_pk_bf16_f32 v106, v110, v111
	v_lshlrev_b64 v[110:111], 12, v[198:199]
	v_lshl_add_u64 v[110:111], s[18:19], 0, v[110:111]
	v_pk_mul_f32 v[112:113], v[192:193], v[112:113]
	v_lshl_add_u64 v[110:111], v[178:179], 1, v[110:111]
	v_cvt_pk_bf16_f32 v107, v112, v113
	v_pk_fma_f32 v[104:105], v[104:105], v[124:125], v[152:153]
	v_pk_fma_f32 v[102:103], v[102:103], v[122:123], v[150:151]
	v_cvt_pk_bf16_f32 v108, v108, v109
	v_cvt_pk_bf16_f32 v109, v154, v155
	global_store_dwordx4 v[110:111], v[106:109], off
	v_pk_fma_f32 v[98:99], v[98:99], v[114:115], v[146:147]
	v_pk_fma_f32 v[100:101], v[100:101], v[116:117], v[148:149]
	v_mul_f32_e32 v106, v103, v103
	v_mul_f32_e32 v107, v105, v105
	v_fmac_f32_e32 v106, v102, v102
	v_fmac_f32_e32 v107, v104, v104
	v_add_f32_e32 v106, v106, v107
	v_mul_f32_e32 v107, v99, v99
	v_fmac_f32_e32 v107, v98, v98
	v_add_f32_e32 v106, v106, v107
	v_mul_f32_e32 v107, v101, v101
	v_fmac_f32_e32 v107, v100, v100
	v_add_f32_e32 v106, v107, v106
	v_add_f32_e32 v112, v156, v106
	ds_bpermute_b32 v113, v213, v112
	global_store_dwordx4 v[202:203], v[102:105], off offset:512
	global_store_dwordx4 v[202:203], v[98:101], off offset:528
	v_pk_mul_f32 v[108:109], v[182:183], v[98:99]
	v_pk_mul_f32 v[102:103], v[184:185], v[102:103]
	v_pk_mul_f32 v[104:105], v[186:187], v[104:105]
	s_waitcnt lgkmcnt(0)
	v_add_f32_e32 v98, v112, v113
	ds_bpermute_b32 v99, v214, v98
	v_pk_mul_f32 v[106:107], v[180:181], v[100:101]
	v_cvt_pk_bf16_f32 v100, v102, v103
	v_cvt_pk_bf16_f32 v101, v104, v105
	v_cvt_pk_bf16_f32 v102, v108, v109
	s_nop 0
	v_cvt_pk_bf16_f32 v103, v106, v107
	global_store_dwordx4 v[110:111], v[100:103], off offset:256
	s_and_saveexec_b64 s[36:37], s[0:1]
	s_cbranch_execz .LBB0_2029
	s_waitcnt lgkmcnt(0)
	v_add_f32_e32 v100, v98, v99
	v_lshlrev_b64 v[98:99], 7, v[198:199]
	v_lshl_add_u64 v[98:99], s[22:23], 0, v[98:99]
	v_lshl_add_u64 v[98:99], s[34:35], 2, v[98:99]
	s_lshl_b32 s12, s59, 2
	v_lshl_add_u64 v[98:99], v[98:99], 0, s[12:13]
	global_store_dword v[98:99], v100, off
.LBB0_2029:
	s_or_b64 exec, exec, s[36:37]
	v_or_b32_e32 v146, 48, v196
	v_ashrrev_i32_e32 v147, 31, v146
	s_waitcnt lgkmcnt(0)
	v_lshlrev_b64 v[98:99], 13, v[146:147]
	v_lshl_add_u64 v[98:99], s[16:17], 0, v[98:99]
	v_lshl_add_u64 v[148:149], v[178:179], 2, v[98:99]
	global_load_dwordx4 v[106:109], v[148:149], off offset:16
	global_load_dwordx4 v[110:113], v[148:149], off
	global_load_dwordx4 v[98:101], v[148:149], off offset:528
	global_load_dwordx4 v[102:105], v[148:149], off offset:512
	s_waitcnt vmcnt(12)
	v_pk_fma_f32 v[96:97], v[96:97], v[128:129], v[144:145]
	v_pk_fma_f32 v[94:95], v[94:95], v[126:127], v[142:143]
	v_pk_fma_f32 v[90:91], v[90:91], v[118:119], v[138:139]
	v_mul_f32_e32 v138, v95, v95
	v_mul_f32_e32 v139, v97, v97
	v_fmac_f32_e32 v138, v94, v94
	v_fmac_f32_e32 v139, v96, v96
	v_add_f32_e32 v138, v138, v139
	v_mul_f32_e32 v139, v91, v91
	v_pk_fma_f32 v[92:93], v[92:93], v[120:121], v[140:141]
	v_fmac_f32_e32 v139, v90, v90
	v_add_f32_e32 v138, v138, v139
	v_mul_f32_e32 v139, v93, v93
	global_store_dwordx4 v[204:205], v[94:97], off
	global_store_dwordx4 v[204:205], v[90:93], off offset:16
	v_fmac_f32_e32 v139, v92, v92
	v_pk_mul_f32 v[94:95], v[194:195], v[94:95]
	v_add_f32_e32 v140, v139, v138
	v_pk_mul_f32 v[138:139], v[188:189], v[92:93]
	v_pk_mul_f32 v[92:93], v[190:191], v[90:91]
	v_cvt_pk_bf16_f32 v90, v94, v95
	v_lshlrev_b64 v[94:95], 12, v[200:201]
	v_lshl_add_u64 v[94:95], s[18:19], 0, v[94:95]
	v_pk_mul_f32 v[96:97], v[192:193], v[96:97]
	v_lshl_add_u64 v[94:95], v[178:179], 1, v[94:95]
	v_cvt_pk_bf16_f32 v91, v96, v97
	s_waitcnt vmcnt(12)
	v_pk_fma_f32 v[88:89], v[88:89], v[124:125], v[136:137]
	v_pk_fma_f32 v[86:87], v[86:87], v[122:123], v[134:135]
	v_cvt_pk_bf16_f32 v92, v92, v93
	v_cvt_pk_bf16_f32 v93, v138, v139
	global_store_dwordx4 v[94:95], v[90:93], off
	v_pk_fma_f32 v[82:83], v[82:83], v[114:115], v[130:131]
	v_pk_fma_f32 v[84:85], v[84:85], v[116:117], v[132:133]
	v_mul_f32_e32 v90, v87, v87
	v_mul_f32_e32 v91, v89, v89
	v_fmac_f32_e32 v90, v86, v86
	v_fmac_f32_e32 v91, v88, v88
	v_add_f32_e32 v90, v90, v91
	v_mul_f32_e32 v91, v83, v83
	v_fmac_f32_e32 v91, v82, v82
	v_add_f32_e32 v90, v90, v91
	v_mul_f32_e32 v91, v85, v85
	v_fmac_f32_e32 v91, v84, v84
	v_add_f32_e32 v90, v91, v90
	v_add_f32_e32 v96, v140, v90
	ds_bpermute_b32 v97, v213, v96
	global_store_dwordx4 v[204:205], v[86:89], off offset:512
	global_store_dwordx4 v[204:205], v[82:85], off offset:528
	v_pk_mul_f32 v[92:93], v[182:183], v[82:83]
	v_pk_mul_f32 v[86:87], v[184:185], v[86:87]
	v_pk_mul_f32 v[88:89], v[186:187], v[88:89]
	s_waitcnt lgkmcnt(0)
	v_add_f32_e32 v82, v96, v97
	ds_bpermute_b32 v83, v214, v82
	v_pk_mul_f32 v[90:91], v[180:181], v[84:85]
	v_cvt_pk_bf16_f32 v84, v86, v87
	v_cvt_pk_bf16_f32 v85, v88, v89
	v_cvt_pk_bf16_f32 v86, v92, v93
	s_nop 0
	v_cvt_pk_bf16_f32 v87, v90, v91
	global_store_dwordx4 v[94:95], v[84:87], off offset:256
	s_and_saveexec_b64 s[36:37], s[0:1]
	s_cbranch_execz .LBB0_2031
	s_waitcnt lgkmcnt(0)
	v_add_f32_e32 v84, v82, v83
	v_lshlrev_b64 v[82:83], 7, v[200:201]
	v_lshl_add_u64 v[82:83], s[22:23], 0, v[82:83]
	v_lshl_add_u64 v[82:83], s[34:35], 2, v[82:83]
	s_lshl_b32 s12, s59, 2
	v_lshl_add_u64 v[82:83], v[82:83], 0, s[12:13]
	global_store_dword v[82:83], v84, off
.LBB0_2031:
	s_or_b64 exec, exec, s[36:37]
	v_add_u32_e32 v130, 0x80, v196
	v_ashrrev_i32_e32 v131, 31, v130
	s_waitcnt lgkmcnt(0)
	v_lshlrev_b64 v[82:83], 13, v[130:131]
	v_lshl_add_u64 v[82:83], s[16:17], 0, v[82:83]
	v_lshl_add_u64 v[132:133], v[178:179], 2, v[82:83]
	global_load_dwordx4 v[90:93], v[132:133], off offset:16
	global_load_dwordx4 v[94:97], v[132:133], off
	global_load_dwordx4 v[82:85], v[132:133], off offset:528
	global_load_dwordx4 v[86:89], v[132:133], off offset:512
	s_waitcnt vmcnt(12)
	v_pk_fma_f32 v[80:81], v[80:81], v[128:129], v[112:113]
	v_pk_fma_f32 v[78:79], v[78:79], v[126:127], v[110:111]
	v_pk_fma_f32 v[74:75], v[74:75], v[118:119], v[106:107]
	v_mul_f32_e32 v106, v79, v79
	v_mul_f32_e32 v107, v81, v81
	v_fmac_f32_e32 v106, v78, v78
	v_fmac_f32_e32 v107, v80, v80
	v_add_f32_e32 v106, v106, v107
	v_mul_f32_e32 v107, v75, v75
	v_pk_fma_f32 v[76:77], v[76:77], v[120:121], v[108:109]
	v_fmac_f32_e32 v107, v74, v74
	v_add_f32_e32 v106, v106, v107
	v_mul_f32_e32 v107, v77, v77
	global_store_dwordx4 v[148:149], v[78:81], off
	global_store_dwordx4 v[148:149], v[74:77], off offset:16
	v_fmac_f32_e32 v107, v76, v76
	v_pk_mul_f32 v[78:79], v[194:195], v[78:79]
	v_add_f32_e32 v108, v107, v106
	v_pk_mul_f32 v[106:107], v[188:189], v[76:77]
	v_pk_mul_f32 v[76:77], v[190:191], v[74:75]
	v_cvt_pk_bf16_f32 v74, v78, v79
	v_lshlrev_b64 v[78:79], 12, v[146:147]
	v_lshl_add_u64 v[78:79], s[18:19], 0, v[78:79]
	v_pk_mul_f32 v[80:81], v[192:193], v[80:81]
	v_lshl_add_u64 v[78:79], v[178:179], 1, v[78:79]
	v_cvt_pk_bf16_f32 v75, v80, v81
	s_waitcnt vmcnt(12)
	v_pk_fma_f32 v[72:73], v[72:73], v[124:125], v[104:105]
	v_pk_fma_f32 v[70:71], v[70:71], v[122:123], v[102:103]
	v_cvt_pk_bf16_f32 v76, v76, v77
	v_cvt_pk_bf16_f32 v77, v106, v107
	global_store_dwordx4 v[78:79], v[74:77], off
	v_pk_fma_f32 v[66:67], v[66:67], v[114:115], v[98:99]
	v_pk_fma_f32 v[68:69], v[68:69], v[116:117], v[100:101]
	v_mul_f32_e32 v74, v71, v71
	v_mul_f32_e32 v75, v73, v73
	v_fmac_f32_e32 v74, v70, v70
	v_fmac_f32_e32 v75, v72, v72
	v_add_f32_e32 v74, v74, v75
	v_mul_f32_e32 v75, v67, v67
	v_fmac_f32_e32 v75, v66, v66
	v_add_f32_e32 v74, v74, v75
	v_mul_f32_e32 v75, v69, v69
	v_fmac_f32_e32 v75, v68, v68
	v_add_f32_e32 v74, v75, v74
	v_add_f32_e32 v80, v108, v74
	ds_bpermute_b32 v81, v213, v80
	global_store_dwordx4 v[148:149], v[70:73], off offset:512
	global_store_dwordx4 v[148:149], v[66:69], off offset:528
	v_pk_mul_f32 v[76:77], v[182:183], v[66:67]
	v_pk_mul_f32 v[70:71], v[184:185], v[70:71]
	v_pk_mul_f32 v[72:73], v[186:187], v[72:73]
	s_waitcnt lgkmcnt(0)
	v_add_f32_e32 v66, v80, v81
	ds_bpermute_b32 v67, v214, v66
	v_pk_mul_f32 v[74:75], v[180:181], v[68:69]
	v_cvt_pk_bf16_f32 v68, v70, v71
	v_cvt_pk_bf16_f32 v69, v72, v73
	v_cvt_pk_bf16_f32 v70, v76, v77
	s_nop 0
	v_cvt_pk_bf16_f32 v71, v74, v75
	global_store_dwordx4 v[78:79], v[68:71], off offset:256
	s_and_saveexec_b64 s[36:37], s[0:1]
	s_cbranch_execz .LBB0_2033
	s_waitcnt lgkmcnt(0)
	v_add_f32_e32 v68, v66, v67
	v_lshlrev_b64 v[66:67], 7, v[146:147]
	v_lshl_add_u64 v[66:67], s[22:23], 0, v[66:67]
	v_lshl_add_u64 v[66:67], s[34:35], 2, v[66:67]
	s_lshl_b32 s12, s59, 2
	v_lshl_add_u64 v[66:67], v[66:67], 0, s[12:13]
	global_store_dword v[66:67], v68, off
.LBB0_2033:
	s_or_b64 exec, exec, s[36:37]
	v_or_b32_e32 v98, 16, v130
	v_ashrrev_i32_e32 v99, 31, v98
	s_waitcnt lgkmcnt(0)
	v_lshlrev_b64 v[66:67], 13, v[98:99]
	v_lshl_add_u64 v[66:67], s[16:17], 0, v[66:67]
	v_lshl_add_u64 v[100:101], v[178:179], 2, v[66:67]
	global_load_dwordx4 v[74:77], v[100:101], off offset:16
	global_load_dwordx4 v[78:81], v[100:101], off
	global_load_dwordx4 v[66:69], v[100:101], off offset:528
	global_load_dwordx4 v[70:73], v[100:101], off offset:512
	s_waitcnt vmcnt(12)
	v_pk_fma_f32 v[64:65], v[64:65], v[128:129], v[96:97]
	v_pk_fma_f32 v[62:63], v[62:63], v[126:127], v[94:95]
	v_pk_fma_f32 v[58:59], v[58:59], v[118:119], v[90:91]
	v_mul_f32_e32 v90, v63, v63
	v_mul_f32_e32 v91, v65, v65
	v_fmac_f32_e32 v90, v62, v62
	v_fmac_f32_e32 v91, v64, v64
	v_add_f32_e32 v90, v90, v91
	v_mul_f32_e32 v91, v59, v59
	v_pk_fma_f32 v[60:61], v[60:61], v[120:121], v[92:93]
	v_fmac_f32_e32 v91, v58, v58
	v_add_f32_e32 v90, v90, v91
	v_mul_f32_e32 v91, v61, v61
	global_store_dwordx4 v[132:133], v[62:65], off
	global_store_dwordx4 v[132:133], v[58:61], off offset:16
	v_fmac_f32_e32 v91, v60, v60
	v_pk_mul_f32 v[62:63], v[194:195], v[62:63]
	v_add_f32_e32 v92, v91, v90
	v_pk_mul_f32 v[90:91], v[188:189], v[60:61]
	v_pk_mul_f32 v[60:61], v[190:191], v[58:59]
	v_cvt_pk_bf16_f32 v58, v62, v63
	v_lshlrev_b64 v[62:63], 12, v[130:131]
	v_lshl_add_u64 v[62:63], s[18:19], 0, v[62:63]
	v_pk_mul_f32 v[64:65], v[192:193], v[64:65]
	v_lshl_add_u64 v[62:63], v[178:179], 1, v[62:63]
	v_cvt_pk_bf16_f32 v59, v64, v65
	s_waitcnt vmcnt(12)
	v_pk_fma_f32 v[56:57], v[56:57], v[124:125], v[88:89]
	v_pk_fma_f32 v[54:55], v[54:55], v[122:123], v[86:87]
	v_cvt_pk_bf16_f32 v60, v60, v61
	v_cvt_pk_bf16_f32 v61, v90, v91
	global_store_dwordx4 v[62:63], v[58:61], off
	v_pk_fma_f32 v[50:51], v[50:51], v[114:115], v[82:83]
	v_pk_fma_f32 v[52:53], v[52:53], v[116:117], v[84:85]
	v_mul_f32_e32 v58, v55, v55
	v_mul_f32_e32 v59, v57, v57
	v_fmac_f32_e32 v58, v54, v54
	v_fmac_f32_e32 v59, v56, v56
	v_add_f32_e32 v58, v58, v59
	v_mul_f32_e32 v59, v51, v51
	v_fmac_f32_e32 v59, v50, v50
	v_add_f32_e32 v58, v58, v59
	v_mul_f32_e32 v59, v53, v53
	v_fmac_f32_e32 v59, v52, v52
	v_add_f32_e32 v58, v59, v58
	v_add_f32_e32 v64, v92, v58
	ds_bpermute_b32 v65, v213, v64
	global_store_dwordx4 v[132:133], v[54:57], off offset:512
	global_store_dwordx4 v[132:133], v[50:53], off offset:528
	v_pk_mul_f32 v[60:61], v[182:183], v[50:51]
	v_pk_mul_f32 v[54:55], v[184:185], v[54:55]
	v_pk_mul_f32 v[56:57], v[186:187], v[56:57]
	s_waitcnt lgkmcnt(0)
	v_add_f32_e32 v50, v64, v65
	ds_bpermute_b32 v51, v214, v50
	v_pk_mul_f32 v[58:59], v[180:181], v[52:53]
	v_cvt_pk_bf16_f32 v52, v54, v55
	v_cvt_pk_bf16_f32 v53, v56, v57
	v_cvt_pk_bf16_f32 v54, v60, v61
	s_nop 0
	v_cvt_pk_bf16_f32 v55, v58, v59
	global_store_dwordx4 v[62:63], v[52:55], off offset:256
	s_and_saveexec_b64 s[36:37], s[0:1]
	s_cbranch_execz .LBB0_2035
	s_waitcnt lgkmcnt(0)
	v_add_f32_e32 v52, v50, v51
	v_lshlrev_b64 v[50:51], 7, v[130:131]
	v_lshl_add_u64 v[50:51], s[22:23], 0, v[50:51]
	v_lshl_add_u64 v[50:51], s[34:35], 2, v[50:51]
	s_lshl_b32 s12, s59, 2
	v_lshl_add_u64 v[50:51], v[50:51], 0, s[12:13]
	global_store_dword v[50:51], v52, off
.LBB0_2035:
	s_or_b64 exec, exec, s[36:37]
	v_or_b32_e32 v82, 32, v130
	v_ashrrev_i32_e32 v83, 31, v82
	s_waitcnt lgkmcnt(0)
	v_lshlrev_b64 v[50:51], 13, v[82:83]
	v_lshl_add_u64 v[50:51], s[16:17], 0, v[50:51]
	v_lshl_add_u64 v[84:85], v[178:179], 2, v[50:51]
	global_load_dwordx4 v[58:61], v[84:85], off offset:16
	global_load_dwordx4 v[62:65], v[84:85], off
	global_load_dwordx4 v[50:53], v[84:85], off offset:528
	global_load_dwordx4 v[54:57], v[84:85], off offset:512
	s_waitcnt vmcnt(12)
	v_pk_fma_f32 v[48:49], v[48:49], v[128:129], v[80:81]
	v_pk_fma_f32 v[46:47], v[46:47], v[126:127], v[78:79]
	v_pk_fma_f32 v[42:43], v[42:43], v[118:119], v[74:75]
	v_mul_f32_e32 v74, v47, v47
	v_mul_f32_e32 v75, v49, v49
	v_fmac_f32_e32 v74, v46, v46
	v_fmac_f32_e32 v75, v48, v48
	v_add_f32_e32 v74, v74, v75
	v_mul_f32_e32 v75, v43, v43
	v_pk_fma_f32 v[44:45], v[44:45], v[120:121], v[76:77]
	v_fmac_f32_e32 v75, v42, v42
	v_add_f32_e32 v74, v74, v75
	v_mul_f32_e32 v75, v45, v45
	global_store_dwordx4 v[100:101], v[46:49], off
	global_store_dwordx4 v[100:101], v[42:45], off offset:16
	v_fmac_f32_e32 v75, v44, v44
	v_pk_mul_f32 v[46:47], v[194:195], v[46:47]
	v_add_f32_e32 v76, v75, v74
	v_pk_mul_f32 v[74:75], v[188:189], v[44:45]
	v_pk_mul_f32 v[44:45], v[190:191], v[42:43]
	v_cvt_pk_bf16_f32 v42, v46, v47
	v_lshlrev_b64 v[46:47], 12, v[98:99]
	v_lshl_add_u64 v[46:47], s[18:19], 0, v[46:47]
	v_pk_mul_f32 v[48:49], v[192:193], v[48:49]
	v_lshl_add_u64 v[46:47], v[178:179], 1, v[46:47]
	v_cvt_pk_bf16_f32 v43, v48, v49
	s_waitcnt vmcnt(12)
	v_pk_fma_f32 v[40:41], v[40:41], v[124:125], v[72:73]
	v_pk_fma_f32 v[38:39], v[38:39], v[122:123], v[70:71]
	v_cvt_pk_bf16_f32 v44, v44, v45
	v_cvt_pk_bf16_f32 v45, v74, v75
	global_store_dwordx4 v[46:47], v[42:45], off
	v_pk_fma_f32 v[34:35], v[34:35], v[114:115], v[66:67]
	v_pk_fma_f32 v[36:37], v[36:37], v[116:117], v[68:69]
	v_mul_f32_e32 v42, v39, v39
	v_mul_f32_e32 v43, v41, v41
	v_fmac_f32_e32 v42, v38, v38
	v_fmac_f32_e32 v43, v40, v40
	v_add_f32_e32 v42, v42, v43
	v_mul_f32_e32 v43, v35, v35
	v_fmac_f32_e32 v43, v34, v34
	v_add_f32_e32 v42, v42, v43
	v_mul_f32_e32 v43, v37, v37
	v_fmac_f32_e32 v43, v36, v36
	v_add_f32_e32 v42, v43, v42
	v_add_f32_e32 v48, v76, v42
	ds_bpermute_b32 v49, v213, v48
	global_store_dwordx4 v[100:101], v[38:41], off offset:512
	global_store_dwordx4 v[100:101], v[34:37], off offset:528
	v_pk_mul_f32 v[44:45], v[182:183], v[34:35]
	v_pk_mul_f32 v[38:39], v[184:185], v[38:39]
	v_pk_mul_f32 v[40:41], v[186:187], v[40:41]
	s_waitcnt lgkmcnt(0)
	v_add_f32_e32 v34, v48, v49
	ds_bpermute_b32 v35, v214, v34
	v_pk_mul_f32 v[42:43], v[180:181], v[36:37]
	v_cvt_pk_bf16_f32 v36, v38, v39
	v_cvt_pk_bf16_f32 v37, v40, v41
	v_cvt_pk_bf16_f32 v38, v44, v45
	s_nop 0
	v_cvt_pk_bf16_f32 v39, v42, v43
	global_store_dwordx4 v[46:47], v[36:39], off offset:256
	s_and_saveexec_b64 s[36:37], s[0:1]
	s_cbranch_execz .LBB0_2037
	s_waitcnt lgkmcnt(0)
	v_add_f32_e32 v36, v34, v35
	v_lshlrev_b64 v[34:35], 7, v[98:99]
	v_lshl_add_u64 v[34:35], s[22:23], 0, v[34:35]
	v_lshl_add_u64 v[34:35], s[34:35], 2, v[34:35]
	s_lshl_b32 s12, s59, 2
	v_lshl_add_u64 v[34:35], v[34:35], 0, s[12:13]
	global_store_dword v[34:35], v36, off
.LBB0_2037:
	s_or_b64 exec, exec, s[36:37]
	v_or_b32_e32 v66, 48, v130
	v_ashrrev_i32_e32 v67, 31, v66
	s_waitcnt lgkmcnt(0)
	v_lshlrev_b64 v[34:35], 13, v[66:67]
	v_lshl_add_u64 v[34:35], s[16:17], 0, v[34:35]
	v_lshl_add_u64 v[68:69], v[178:179], 2, v[34:35]
	global_load_dwordx4 v[42:45], v[68:69], off offset:16
	global_load_dwordx4 v[46:49], v[68:69], off
	global_load_dwordx4 v[34:37], v[68:69], off offset:528
	global_load_dwordx4 v[38:41], v[68:69], off offset:512
	s_waitcnt vmcnt(12)
	v_pk_fma_f32 v[32:33], v[32:33], v[128:129], v[64:65]
	v_pk_fma_f32 v[30:31], v[30:31], v[126:127], v[62:63]
	v_pk_fma_f32 v[26:27], v[26:27], v[118:119], v[58:59]
	v_mul_f32_e32 v58, v31, v31
	v_mul_f32_e32 v59, v33, v33
	v_fmac_f32_e32 v58, v30, v30
	v_fmac_f32_e32 v59, v32, v32
	v_add_f32_e32 v58, v58, v59
	v_mul_f32_e32 v59, v27, v27
	v_pk_fma_f32 v[28:29], v[28:29], v[120:121], v[60:61]
	v_fmac_f32_e32 v59, v26, v26
	v_add_f32_e32 v58, v58, v59
	v_mul_f32_e32 v59, v29, v29
	global_store_dwordx4 v[84:85], v[30:33], off
	global_store_dwordx4 v[84:85], v[26:29], off offset:16
	v_fmac_f32_e32 v59, v28, v28
	v_pk_mul_f32 v[30:31], v[194:195], v[30:31]
	v_add_f32_e32 v60, v59, v58
	v_pk_mul_f32 v[58:59], v[188:189], v[28:29]
	v_pk_mul_f32 v[28:29], v[190:191], v[26:27]
	v_cvt_pk_bf16_f32 v26, v30, v31
	v_lshlrev_b64 v[30:31], 12, v[82:83]
	v_lshl_add_u64 v[30:31], s[18:19], 0, v[30:31]
	v_pk_mul_f32 v[32:33], v[192:193], v[32:33]
	v_lshl_add_u64 v[30:31], v[178:179], 1, v[30:31]
	v_cvt_pk_bf16_f32 v27, v32, v33
	s_waitcnt vmcnt(12)
	v_pk_fma_f32 v[24:25], v[24:25], v[124:125], v[56:57]
	v_pk_fma_f32 v[22:23], v[22:23], v[122:123], v[54:55]
	v_cvt_pk_bf16_f32 v28, v28, v29
	v_cvt_pk_bf16_f32 v29, v58, v59
	global_store_dwordx4 v[30:31], v[26:29], off
	v_pk_fma_f32 v[18:19], v[18:19], v[114:115], v[50:51]
	v_pk_fma_f32 v[20:21], v[20:21], v[116:117], v[52:53]
	v_mul_f32_e32 v26, v23, v23
	v_mul_f32_e32 v27, v25, v25
	v_fmac_f32_e32 v26, v22, v22
	v_fmac_f32_e32 v27, v24, v24
	v_add_f32_e32 v26, v26, v27
	v_mul_f32_e32 v27, v19, v19
	v_fmac_f32_e32 v27, v18, v18
	v_add_f32_e32 v26, v26, v27
	v_mul_f32_e32 v27, v21, v21
	v_fmac_f32_e32 v27, v20, v20
	v_add_f32_e32 v26, v27, v26
	v_add_f32_e32 v32, v60, v26
	ds_bpermute_b32 v33, v213, v32
	global_store_dwordx4 v[84:85], v[22:25], off offset:512
	global_store_dwordx4 v[84:85], v[18:21], off offset:528
	v_pk_mul_f32 v[28:29], v[182:183], v[18:19]
	v_pk_mul_f32 v[22:23], v[184:185], v[22:23]
	v_pk_mul_f32 v[24:25], v[186:187], v[24:25]
	s_waitcnt lgkmcnt(0)
	v_add_f32_e32 v18, v32, v33
	ds_bpermute_b32 v19, v214, v18
	v_pk_mul_f32 v[26:27], v[180:181], v[20:21]
	v_cvt_pk_bf16_f32 v20, v22, v23
	v_cvt_pk_bf16_f32 v21, v24, v25
	v_cvt_pk_bf16_f32 v22, v28, v29
	s_nop 0
	v_cvt_pk_bf16_f32 v23, v26, v27
	global_store_dwordx4 v[30:31], v[20:23], off offset:256
	s_and_saveexec_b64 s[36:37], s[0:1]
	s_cbranch_execz .LBB0_2039
	s_waitcnt lgkmcnt(0)
	v_add_f32_e32 v20, v18, v19
	v_lshlrev_b64 v[18:19], 7, v[82:83]
	v_lshl_add_u64 v[18:19], s[22:23], 0, v[18:19]
	v_lshl_add_u64 v[18:19], s[34:35], 2, v[18:19]
	s_lshl_b32 s12, s59, 2
	v_lshl_add_u64 v[18:19], v[18:19], 0, s[12:13]
	global_store_dword v[18:19], v20, off
.LBB0_2039:
	s_or_b64 exec, exec, s[36:37]
	s_waitcnt vmcnt(8)
	v_pk_fma_f32 v[16:17], v[16:17], v[128:129], v[48:49]
	v_pk_fma_f32 v[14:15], v[14:15], v[126:127], v[46:47]
	s_waitcnt lgkmcnt(0)
	v_mul_f32_e32 v19, v17, v17
	v_mul_f32_e32 v18, v15, v15
	v_pk_fma_f32 v[10:11], v[10:11], v[118:119], v[42:43]
	v_fmac_f32_e32 v18, v14, v14
	v_fmac_f32_e32 v19, v16, v16
	v_add_f32_e32 v18, v18, v19
	v_mul_f32_e32 v19, v11, v11
	v_pk_fma_f32 v[12:13], v[12:13], v[120:121], v[44:45]
	v_fmac_f32_e32 v19, v10, v10
	v_add_f32_e32 v18, v18, v19
	v_mul_f32_e32 v19, v13, v13
	global_store_dwordx4 v[68:69], v[14:17], off
	global_store_dwordx4 v[68:69], v[10:13], off offset:16
	v_fmac_f32_e32 v19, v12, v12
	v_pk_mul_f32 v[14:15], v[194:195], v[14:15]
	v_add_f32_e32 v20, v19, v18
	v_pk_mul_f32 v[18:19], v[188:189], v[12:13]
	v_pk_mul_f32 v[12:13], v[190:191], v[10:11]
	v_cvt_pk_bf16_f32 v10, v14, v15
	v_lshlrev_b64 v[14:15], 12, v[66:67]
	v_lshl_add_u64 v[14:15], s[18:19], 0, v[14:15]
	v_pk_mul_f32 v[16:17], v[192:193], v[16:17]
	v_lshl_add_u64 v[14:15], v[178:179], 1, v[14:15]
	v_cvt_pk_bf16_f32 v11, v16, v17
	s_waitcnt vmcnt(8)
	v_pk_fma_f32 v[8:9], v[8:9], v[124:125], v[40:41]
	v_pk_fma_f32 v[6:7], v[6:7], v[122:123], v[38:39]
	v_cvt_pk_bf16_f32 v12, v12, v13
	v_cvt_pk_bf16_f32 v13, v18, v19
	global_store_dwordx4 v[14:15], v[10:13], off
	v_pk_fma_f32 v[2:3], v[2:3], v[114:115], v[34:35]
	v_pk_fma_f32 v[4:5], v[4:5], v[116:117], v[36:37]
	v_mul_f32_e32 v10, v7, v7
	v_mul_f32_e32 v11, v9, v9
	v_fmac_f32_e32 v10, v6, v6
	v_fmac_f32_e32 v11, v8, v8
	v_add_f32_e32 v10, v10, v11
	v_mul_f32_e32 v11, v3, v3
	v_fmac_f32_e32 v11, v2, v2
	v_add_f32_e32 v10, v10, v11
	v_mul_f32_e32 v11, v5, v5
	v_fmac_f32_e32 v11, v4, v4
	v_add_f32_e32 v10, v11, v10
	v_add_f32_e32 v16, v20, v10
	ds_bpermute_b32 v17, v213, v16
	global_store_dwordx4 v[68:69], v[6:9], off offset:512
	global_store_dwordx4 v[68:69], v[2:5], off offset:528
	v_pk_mul_f32 v[12:13], v[182:183], v[2:3]
	v_pk_mul_f32 v[6:7], v[184:185], v[6:7]
	v_pk_mul_f32 v[8:9], v[186:187], v[8:9]
	s_waitcnt lgkmcnt(0)
	v_add_f32_e32 v2, v16, v17
	ds_bpermute_b32 v3, v214, v2
	v_pk_mul_f32 v[10:11], v[180:181], v[4:5]
	v_cvt_pk_bf16_f32 v4, v6, v7
	v_cvt_pk_bf16_f32 v5, v8, v9
	v_cvt_pk_bf16_f32 v6, v12, v13
	s_nop 0
	v_cvt_pk_bf16_f32 v7, v10, v11
	global_store_dwordx4 v[14:15], v[4:7], off offset:256
	s_and_saveexec_b64 s[36:37], s[0:1]
	s_cbranch_execz .LBB0_2041
	s_waitcnt lgkmcnt(0)
	v_add_f32_e32 v4, v2, v3
	v_lshlrev_b64 v[2:3], 7, v[66:67]
	v_lshl_add_u64 v[2:3], s[22:23], 0, v[2:3]
	v_lshl_add_u64 v[2:3], s[34:35], 2, v[2:3]
	s_lshl_b32 s12, s59, 2
	v_lshl_add_u64 v[2:3], v[2:3], 0, s[12:13]
	global_store_dword v[2:3], v4, off

.LBB0_2768:
	s_lshr_b32 s40, s81, 4
	s_add_i32 s40, s40, -1
	s_cmp_gt_i32 s81, 31
	s_cselect_b32 s40, s40, 0
	v_lshl_or_b32 v90, s12, 8, v230
	s_mul_i32 s43, s40, 0xc000
	s_mul_hi_i32 s42, s40, 0xc000
	s_add_u32 s40, s57, s43
	v_ashrrev_i32_e32 v91, 31, v90
	s_addc_u32 s41, s58, s42
	v_lshlrev_b64 v[36:37], 2, v[90:91]
	v_lshl_add_u64 v[26:27], s[40:41], 0, v[36:37]
	v_lshl_add_u64 v[28:29], s[20:21], 0, v[36:37]
	s_waitcnt lgkmcnt(0)
	global_load_dwordx4 v[2:5], v[26:27], off offset:16
	global_load_dwordx4 v[6:9], v[26:27], off
	global_load_dwordx4 v[10:13], v[28:29], off offset:16
	global_load_dwordx4 v[14:17], v[28:29], off
	s_add_u32 s40, s59, s43
	v_lshl_add_u64 v[30:31], s[24:25], 0, v[36:37]
	s_addc_u32 s41, s60, s42
	v_lshl_add_u64 v[32:33], s[40:41], 0, v[36:37]
	v_lshl_add_u32 v210, s81, 8, v228
	v_ashrrev_i32_e32 v211, 31, v210
	v_or_b32_e32 v34, 16, v210
	v_ashrrev_i32_e32 v35, 31, v34
	s_lshl_b32 s40, s12, 2
	s_ashr_i32 s41, s40, 31
	s_waitcnt vmcnt(0)
	v_pk_mul_f32 v[92:93], v[4:5], v[12:13]
	v_pk_mul_f32 v[86:87], v[8:9], v[16:17]
	v_pk_mul_f32 v[88:89], v[6:7], v[14:15]
	global_load_dwordx4 v[6:9], v[30:31], off offset:16
	global_load_dwordx4 v[14:17], v[30:31], off
	global_load_dwordx4 v[18:21], v[32:33], off offset:16
	global_load_dwordx4 v[22:25], v[32:33], off
	v_pk_mul_f32 v[94:95], v[2:3], v[10:11]
	s_waitcnt vmcnt(0)
	v_pk_add_f32 v[2:3], v[20:21], 1.0 op_sel_hi:[1,0]
	v_pk_add_f32 v[24:25], v[24:25], 1.0 op_sel_hi:[1,0]
	v_pk_add_f32 v[22:23], v[22:23], 1.0 op_sel_hi:[1,0]
	v_pk_add_f32 v[4:5], v[18:19], 1.0 op_sel_hi:[1,0]
	v_pk_mul_f32 v[78:79], v[16:17], v[24:25]
	v_pk_mul_f32 v[80:81], v[14:15], v[22:23]
	v_pk_mul_f32 v[82:83], v[8:9], v[2:3]
	v_pk_mul_f32 v[84:85], v[6:7], v[4:5]
	global_load_dwordx4 v[2:5], v[26:27], off offset:528
	global_load_dwordx4 v[6:9], v[26:27], off offset:512
	global_load_dwordx4 v[10:13], v[28:29], off offset:528
	global_load_dwordx4 v[14:17], v[28:29], off offset:512
	s_waitcnt vmcnt(0)
	v_pk_mul_f32 v[108:109], v[2:3], v[10:11]
	v_pk_mul_f32 v[104:105], v[8:9], v[16:17]
	v_pk_mul_f32 v[106:107], v[6:7], v[14:15]
	global_load_dwordx4 v[6:9], v[30:31], off offset:528
	global_load_dwordx4 v[14:17], v[30:31], off offset:512
	global_load_dwordx4 v[18:21], v[32:33], off offset:528
	global_load_dwordx4 v[22:25], v[32:33], off offset:512
	v_pk_mul_f32 v[110:111], v[4:5], v[12:13]
	s_waitcnt vmcnt(0)
	v_pk_add_f32 v[2:3], v[20:21], 1.0 op_sel_hi:[1,0]
	s_nop 0
	v_pk_mul_f32 v[100:101], v[8:9], v[2:3]
	v_lshlrev_b64 v[2:3], 13, v[210:211]
	v_lshl_add_u64 v[2:3], s[16:17], 0, v[2:3]
	v_lshl_add_u64 v[38:39], v[2:3], 0, v[36:37]
	v_lshlrev_b64 v[2:3], 13, v[34:35]
	v_lshl_add_u64 v[2:3], s[16:17], 0, v[2:3]
	v_pk_add_f32 v[24:25], v[24:25], 1.0 op_sel_hi:[1,0]
	v_pk_add_f32 v[22:23], v[22:23], 1.0 op_sel_hi:[1,0]
	v_pk_add_f32 v[4:5], v[18:19], 1.0 op_sel_hi:[1,0]
	v_lshl_add_u64 v[36:37], v[2:3], 0, v[36:37]
	v_pk_mul_f32 v[96:97], v[16:17], v[24:25]
	v_pk_mul_f32 v[98:99], v[14:15], v[22:23]
	v_pk_mul_f32 v[102:103], v[6:7], v[4:5]
	global_load_dwordx4 v[22:25], v[38:39], off offset:16
	global_load_dwordx4 v[30:33], v[38:39], off
	global_load_dwordx4 v[18:21], v[38:39], off offset:528
	global_load_dwordx4 v[26:29], v[38:39], off offset:512
	global_load_dwordx4 v[10:13], v[36:37], off offset:16
	global_load_dwordx4 v[14:17], v[36:37], off
	global_load_dwordx4 v[2:5], v[36:37], off offset:528
	global_load_dwordx4 v[6:9], v[36:37], off offset:512
	v_lshl_add_u64 v[196:197], v[210:211], 2, s[18:19]
	global_load_dword v40, v[196:197], off
	v_and_b32_e32 v44, 64, v232
	v_xor_b32_e32 v41, 16, v232
	v_add_u32_e32 v234, 64, v44
	v_cmp_lt_i32_e32 vcc, v41, v234
	v_lshlrev_b64 v[42:43], 12, v[210:211]
	v_lshl_add_u64 v[42:43], s[22:23], 0, v[42:43]
	v_cndmask_b32_e32 v41, v232, v41, vcc
	v_lshlrev_b32_e32 v233, 2, v41
	v_lshl_add_u64 v[42:43], v[90:91], 1, v[42:43]
	s_waitcnt vmcnt(0)
	v_pk_mul_f32 v[44:45], v[40:41], v[214:215] op_sel_hi:[0,1]
	v_pk_mul_f32 v[212:213], v[40:41], v[212:213] op_sel_hi:[0,1]
	v_pk_mul_f32 v[214:215], v[40:41], v[218:219] op_sel_hi:[0,1]
	v_pk_mul_f32 v[218:219], v[40:41], v[222:223] op_sel_hi:[0,1]
	v_pk_mul_f32 v[220:221], v[40:41], v[220:221] op_sel_hi:[0,1]
	v_pk_mul_f32 v[216:217], v[40:41], v[216:217] op_sel_hi:[0,1]
	v_pk_mul_f32 v[222:223], v[40:41], v[226:227] op_sel_hi:[0,1]
	v_pk_mul_f32 v[40:41], v[40:41], v[224:225] op_sel_hi:[0,1]
	v_pk_fma_f32 v[32:33], v[86:87], v[212:213], v[32:33]
	v_pk_fma_f32 v[30:31], v[88:89], v[44:45], v[30:31]
	v_pk_fma_f32 v[28:29], v[104:105], v[220:221], v[28:29]
	v_pk_fma_f32 v[26:27], v[106:107], v[218:219], v[26:27]
	v_pk_fma_f32 v[24:25], v[92:93], v[216:217], v[24:25]
	v_pk_fma_f32 v[22:23], v[94:95], v[214:215], v[22:23]
	v_pk_fma_f32 v[20:21], v[110:111], v[40:41], v[20:21]
	v_pk_fma_f32 v[18:19], v[108:109], v[222:223], v[18:19]
	global_store_dwordx4 v[38:39], v[30:33], off
	global_store_dwordx4 v[38:39], v[22:25], off offset:16
	v_mul_f32_e32 v224, v31, v31
	v_mul_f32_e32 v225, v33, v33
	v_pk_mul_f32 v[40:41], v[78:79], v[32:33]
	v_pk_mul_f32 v[44:45], v[80:81], v[30:31]
	v_mul_f32_e32 v31, v27, v27
	v_mul_f32_e32 v33, v29, v29
	v_mul_f32_e32 v226, v23, v23
	v_mul_f32_e32 v227, v25, v25
	v_mul_f32_e32 v235, v19, v19
	v_fmac_f32_e32 v224, v30, v30
	v_fmac_f32_e32 v225, v32, v32
	v_fmac_f32_e32 v31, v26, v26
	v_fmac_f32_e32 v33, v28, v28
	v_pk_mul_f32 v[212:213], v[82:83], v[24:25]
	v_pk_mul_f32 v[214:215], v[84:85], v[22:23]
	v_mul_f32_e32 v236, v21, v21
	v_pk_mul_f32 v[222:223], v[102:103], v[18:19]
	v_fmac_f32_e32 v226, v22, v22
	v_fmac_f32_e32 v227, v24, v24
	v_cvt_pk_bf16_f32 v22, v44, v45
	v_cvt_pk_bf16_f32 v23, v40, v41
	v_cvt_pk_bf16_f32 v24, v214, v215
	v_cvt_pk_bf16_f32 v25, v212, v213
	v_fmac_f32_e32 v235, v18, v18
	v_add_f32_e32 v30, v224, v225
	global_store_dwordx4 v[42:43], v[22:25], off
	v_lshlrev_b32_e32 v32, 16, v22
	v_and_b32_e32 v40, 0xffff0000, v22
	global_store_dwordx4 v[38:39], v[26:29], off offset:512
	global_store_dwordx4 v[38:39], v[18:21], off offset:528
	v_pk_mul_f32 v[220:221], v[100:101], v[20:21]
	v_fmac_f32_e32 v236, v20, v20
	v_add_f32_e32 v18, v31, v33
	v_lshlrev_b32_e32 v41, 16, v23
	v_and_b32_e32 v44, 0xffff0000, v23
	v_add_f32_e32 v19, v226, v30
	v_max3_f32 v20, |v32|, 0, |v40|
	v_add_f32_e32 v18, v235, v18
	v_lshlrev_b32_e32 v45, 16, v24
	v_and_b32_e32 v212, 0xffff0000, v24
	v_add_f32_e32 v19, v227, v19
	v_max3_f32 v20, v20, |v41|, |v44|
	v_add_f32_e32 v18, v236, v18
	v_lshlrev_b32_e32 v213, 16, v25
	v_and_b32_e32 v214, 0xffff0000, v25
	v_max3_f32 v20, v20, |v45|, |v212|
	v_add_f32_e32 v18, v19, v18
	v_pk_mul_f32 v[218:219], v[98:99], v[26:27]
	v_max3_f32 v19, v20, |v213|, |v214|
	v_cvt_pk_bf16_f32 v22, v218, v219
	ds_bpermute_b32 v20, v233, v18
	v_lshlrev_b32_e32 v21, 16, v22
	v_and_b32_e32 v26, 0xffff0000, v22
	v_pk_mul_f32 v[216:217], v[96:97], v[28:29]
	v_max3_f32 v19, v19, |v21|, |v26|
	v_cvt_pk_bf16_f32 v23, v216, v217
	v_cvt_pk_bf16_f32 v24, v222, v223
	v_cvt_pk_bf16_f32 v25, v220, v221
	s_waitcnt lgkmcnt(0)
	v_add_f32_e32 v18, v18, v20
	v_lshlrev_b32_e32 v27, 16, v23
	v_and_b32_e32 v28, 0xffff0000, v23
	v_lshlrev_b32_e32 v29, 16, v24
	v_and_b32_e32 v30, 0xffff0000, v24
	v_max3_f32 v19, v19, |v27|, |v28|
	v_max3_f32 v19, v19, |v29|, |v30|
	v_lshlrev_b32_e32 v21, 16, v25
	v_and_b32_e32 v26, 0xffff0000, v25
	v_max3_f32 v21, v19, |v21|, |v26|
	ds_bpermute_b32 v20, v233, v21
	v_xor_b32_e32 v19, 32, v232
	v_cmp_lt_i32_e32 vcc, v19, v234
	global_store_dwordx4 v[42:43], v[22:25], off offset:256
	s_waitcnt lgkmcnt(0)
	v_max_f32_e32 v20, v20, v20
	v_cndmask_b32_e32 v19, v232, v19, vcc
	v_lshlrev_b32_e32 v216, 2, v19
	v_max_f32_e32 v20, v21, v20
	ds_bpermute_b32 v19, v216, v18
	ds_bpermute_b32 v21, v216, v20
	s_and_saveexec_b64 s[42:43], s[0:1]
	s_cbranch_execz .LBB0_2770
	s_waitcnt lgkmcnt(0)
	v_max_f32_e32 v21, v21, v21
	v_max_f32_e32 v20, v20, v20
	v_add_f32_e32 v23, v18, v19
	v_lshlrev_b64 v[18:19], 7, v[210:211]
	v_max_f32_e32 v22, v20, v21
	v_lshl_add_u64 v[20:21], s[26:27], 0, v[18:19]
	s_lshl_b64 s[82:83], s[40:41], 2
	v_lshl_add_u64 v[18:19], s[28:29], 0, v[18:19]
	v_lshl_add_u64 v[20:21], v[20:21], 0, s[82:83]
	s_lshl_b32 s12, s63, 2
	v_lshl_add_u64 v[18:19], v[18:19], 0, s[82:83]
	v_lshl_add_u64 v[20:21], v[20:21], 0, s[12:13]
	v_lshl_add_u64 v[18:19], v[18:19], 0, s[12:13]
	global_store_dword v[20:21], v23, off
	global_store_dword v[18:19], v22, off
.LBB0_2770:
	s_or_b64 exec, exec, s[42:43]
	v_or_b32_e32 v212, 32, v210
	v_ashrrev_i32_e32 v213, 31, v212
	s_waitcnt lgkmcnt(1)
	v_lshlrev_b64 v[18:19], 13, v[212:213]
	v_lshl_add_u64 v[18:19], s[16:17], 0, v[18:19]
	v_lshl_add_u64 v[214:215], v[90:91], 2, v[18:19]
	global_load_dwordx4 v[26:29], v[214:215], off offset:16
	global_load_dwordx4 v[30:33], v[214:215], off
	s_waitcnt lgkmcnt(0)
	global_load_dwordx4 v[18:21], v[214:215], off offset:528
	global_load_dwordx4 v[22:25], v[214:215], off offset:512
	v_lshl_add_u64 v[38:39], v[34:35], 2, s[18:19]
	global_load_dword v38, v[38:39], off
	v_lshlrev_b64 v[40:41], 12, v[34:35]
	v_lshl_add_u64 v[40:41], s[22:23], 0, v[40:41]
	v_lshl_add_u64 v[40:41], v[90:91], 1, v[40:41]
	s_waitcnt vmcnt(0)
	v_pk_mul_f32 v[44:45], v[38:39], v[192:193] op_sel_hi:[0,1]
	v_pk_mul_f32 v[192:193], v[38:39], v[200:201] op_sel_hi:[0,1]
	v_pk_mul_f32 v[42:43], v[38:39], v[194:195] op_sel_hi:[0,1]
	v_pk_mul_f32 v[194:195], v[38:39], v[198:199] op_sel_hi:[0,1]
	v_pk_mul_f32 v[198:199], v[38:39], v[206:207] op_sel_hi:[0,1]
	v_pk_mul_f32 v[200:201], v[38:39], v[202:203] op_sel_hi:[0,1]
	v_pk_fma_f32 v[10:11], v[94:95], v[192:193], v[10:11]
	v_pk_mul_f32 v[202:203], v[38:39], v[208:209] op_sel_hi:[0,1]
	v_pk_mul_f32 v[38:39], v[38:39], v[204:205] op_sel_hi:[0,1]
	v_pk_fma_f32 v[16:17], v[86:87], v[44:45], v[16:17]
	v_pk_fma_f32 v[14:15], v[88:89], v[42:43], v[14:15]
	v_pk_fma_f32 v[12:13], v[92:93], v[194:195], v[12:13]
	v_pk_fma_f32 v[8:9], v[104:105], v[200:201], v[8:9]
	v_pk_fma_f32 v[6:7], v[106:107], v[198:199], v[6:7]
	v_mul_f32_e32 v206, v11, v11
	v_pk_fma_f32 v[4:5], v[110:111], v[38:39], v[4:5]
	v_pk_fma_f32 v[2:3], v[108:109], v[202:203], v[2:3]
	global_store_dwordx4 v[36:37], v[14:17], off
	global_store_dwordx4 v[36:37], v[10:13], off offset:16
	v_mul_f32_e32 v204, v15, v15
	v_mul_f32_e32 v205, v17, v17
	v_mul_f32_e32 v207, v13, v13
	v_pk_mul_f32 v[38:39], v[78:79], v[16:17]
	v_pk_mul_f32 v[42:43], v[80:81], v[14:15]
	v_pk_mul_f32 v[192:193], v[84:85], v[10:11]
	v_mul_f32_e32 v15, v7, v7
	v_mul_f32_e32 v17, v9, v9
	v_fmac_f32_e32 v206, v10, v10
	v_cvt_pk_bf16_f32 v10, v42, v43
	v_pk_mul_f32 v[44:45], v[82:83], v[12:13]
	v_mul_f32_e32 v208, v3, v3
	v_mul_f32_e32 v209, v5, v5
	v_fmac_f32_e32 v204, v14, v14
	v_fmac_f32_e32 v205, v16, v16
	v_fmac_f32_e32 v207, v12, v12
	v_cvt_pk_bf16_f32 v11, v38, v39
	v_cvt_pk_bf16_f32 v12, v192, v193
	v_cvt_pk_bf16_f32 v13, v44, v45
	v_fmac_f32_e32 v15, v6, v6
	v_fmac_f32_e32 v17, v8, v8
	global_store_dwordx4 v[40:41], v[10:13], off
	v_lshlrev_b32_e32 v16, 16, v10
	v_pk_mul_f32 v[200:201], v[100:101], v[4:5]
	v_and_b32_e32 v10, 0xffff0000, v10
	v_pk_mul_f32 v[202:203], v[102:103], v[2:3]
	v_fmac_f32_e32 v208, v2, v2
	v_fmac_f32_e32 v209, v4, v4
	v_add_f32_e32 v14, v204, v205
	v_lshlrev_b32_e32 v38, 16, v11
	v_and_b32_e32 v11, 0xffff0000, v11
	global_store_dwordx4 v[36:37], v[6:9], off offset:512
	global_store_dwordx4 v[36:37], v[2:5], off offset:528
	v_lshlrev_b32_e32 v39, 16, v12
	v_and_b32_e32 v12, 0xffff0000, v12
	v_add_f32_e32 v2, v15, v17
	v_max3_f32 v4, |v16|, 0, |v10|
	v_add_f32_e32 v3, v206, v14
	v_add_f32_e32 v2, v208, v2
	v_max3_f32 v4, v4, |v38|, |v11|
	v_lshlrev_b32_e32 v42, 16, v13
	v_and_b32_e32 v13, 0xffff0000, v13
	v_add_f32_e32 v3, v207, v3
	v_add_f32_e32 v2, v209, v2
	v_max3_f32 v4, v4, |v39|, |v12|
	v_pk_mul_f32 v[198:199], v[98:99], v[6:7]
	v_add_f32_e32 v2, v3, v2
	v_cvt_pk_bf16_f32 v6, v198, v199
	v_max3_f32 v3, v4, |v42|, |v13|
	v_lshlrev_b32_e32 v5, 16, v6
	v_and_b32_e32 v10, 0xffff0000, v6
	v_pk_mul_f32 v[194:195], v[96:97], v[8:9]
	v_max3_f32 v3, v3, |v5|, |v10|
	v_cvt_pk_bf16_f32 v7, v194, v195
	v_cvt_pk_bf16_f32 v8, v202, v203
	v_cvt_pk_bf16_f32 v9, v200, v201
	ds_bpermute_b32 v4, v233, v2
	v_lshlrev_b32_e32 v14, 16, v7
	v_and_b32_e32 v15, 0xffff0000, v7
	v_lshlrev_b32_e32 v16, 16, v8
	v_and_b32_e32 v17, 0xffff0000, v8
	v_max3_f32 v3, v3, |v14|, |v15|
	v_lshlrev_b32_e32 v36, 16, v9
	v_and_b32_e32 v37, 0xffff0000, v9
	v_max3_f32 v3, v3, |v16|, |v17|
	v_max3_f32 v5, v3, |v36|, |v37|
	ds_bpermute_b32 v10, v233, v5
	s_waitcnt lgkmcnt(1)
	v_add_f32_e32 v2, v2, v4
	ds_bpermute_b32 v3, v216, v2
	global_store_dwordx4 v[40:41], v[6:9], off offset:256
	s_waitcnt lgkmcnt(1)
	v_max_f32_e32 v4, v10, v10
	v_max_f32_e32 v4, v5, v4
	ds_bpermute_b32 v5, v216, v4
	s_and_saveexec_b64 s[42:43], s[0:1]
	s_cbranch_execz .LBB0_2772
	s_waitcnt lgkmcnt(0)
	v_max_f32_e32 v5, v5, v5
	v_max_f32_e32 v4, v4, v4
	v_add_f32_e32 v7, v2, v3
	v_lshlrev_b64 v[2:3], 7, v[34:35]
	v_max_f32_e32 v6, v4, v5
	v_lshl_add_u64 v[4:5], s[26:27], 0, v[2:3]
	s_lshl_b64 s[82:83], s[40:41], 2
	v_lshl_add_u64 v[2:3], s[28:29], 0, v[2:3]
	v_lshl_add_u64 v[4:5], v[4:5], 0, s[82:83]
	s_lshl_b32 s12, s63, 2
	v_lshl_add_u64 v[2:3], v[2:3], 0, s[82:83]
	v_lshl_add_u64 v[4:5], v[4:5], 0, s[12:13]
	v_lshl_add_u64 v[2:3], v[2:3], 0, s[12:13]
	global_store_dword v[4:5], v7, off
	global_store_dword v[2:3], v6, off
.LBB0_2772:
	s_or_b64 exec, exec, s[42:43]
	v_or_b32_e32 v192, 48, v210
	v_ashrrev_i32_e32 v193, 31, v192
	s_waitcnt lgkmcnt(1)
	v_lshlrev_b64 v[2:3], 13, v[192:193]
	v_lshl_add_u64 v[2:3], s[16:17], 0, v[2:3]
	v_lshl_add_u64 v[194:195], v[90:91], 2, v[2:3]
	global_load_dwordx4 v[38:41], v[194:195], off offset:16
	global_load_dwordx4 v[42:45], v[194:195], off
	global_load_dwordx4 v[6:9], v[194:195], off offset:528
	global_load_dwordx4 v[34:37], v[194:195], off offset:512
	v_lshl_add_u64 v[2:3], v[212:213], 2, s[18:19]
	global_load_dword v2, v[2:3], off
	s_waitcnt lgkmcnt(0)
	v_lshlrev_b64 v[4:5], 12, v[212:213]
	v_lshl_add_u64 v[4:5], s[22:23], 0, v[4:5]
	v_lshl_add_u64 v[198:199], v[90:91], 1, v[4:5]
	s_waitcnt vmcnt(0)
	v_pk_mul_f32 v[10:11], v[2:3], v[178:179] op_sel_hi:[0,1]
	v_pk_mul_f32 v[4:5], v[2:3], v[176:177] op_sel_hi:[0,1]
	v_pk_mul_f32 v[14:15], v[2:3], v[182:183] op_sel_hi:[0,1]
	v_pk_mul_f32 v[12:13], v[2:3], v[180:181] op_sel_hi:[0,1]
	v_pk_mul_f32 v[176:177], v[2:3], v[188:189] op_sel_hi:[0,1]
	v_pk_mul_f32 v[16:17], v[2:3], v[184:185] op_sel_hi:[0,1]
	v_pk_mul_f32 v[178:179], v[2:3], v[190:191] op_sel_hi:[0,1]
	v_pk_mul_f32 v[180:181], v[2:3], v[186:187] op_sel_hi:[0,1]
	v_pk_fma_f32 v[2:3], v[88:89], v[10:11], v[30:31]
	v_pk_fma_f32 v[4:5], v[86:87], v[4:5], v[32:33]
	v_pk_fma_f32 v[20:21], v[110:111], v[180:181], v[20:21]
	v_mul_f32_e32 v180, v3, v3
	v_pk_fma_f32 v[12:13], v[92:93], v[12:13], v[28:29]
	v_pk_fma_f32 v[10:11], v[94:95], v[14:15], v[26:27]
	v_pk_fma_f32 v[16:17], v[104:105], v[16:17], v[24:25]
	v_pk_fma_f32 v[14:15], v[106:107], v[176:177], v[22:23]
	global_store_dwordx4 v[214:215], v[2:5], off
	global_store_dwordx4 v[214:215], v[10:13], off offset:16
	v_mul_f32_e32 v181, v5, v5
	v_pk_mul_f32 v[22:23], v[78:79], v[4:5]
	v_pk_mul_f32 v[24:25], v[80:81], v[2:3]
	v_fmac_f32_e32 v180, v2, v2
	v_cvt_pk_bf16_f32 v2, v24, v25
	v_pk_mul_f32 v[26:27], v[82:83], v[12:13]
	v_pk_mul_f32 v[28:29], v[84:85], v[10:11]
	v_fmac_f32_e32 v181, v4, v4
	v_cvt_pk_bf16_f32 v3, v22, v23
	v_cvt_pk_bf16_f32 v4, v28, v29
	v_cvt_pk_bf16_f32 v5, v26, v27
	global_store_dwordx4 v[198:199], v[2:5], off
	v_lshlrev_b32_e32 v23, 16, v2
	v_lshlrev_b32_e32 v24, 16, v3
	v_and_b32_e32 v2, 0xffff0000, v2
	v_and_b32_e32 v3, 0xffff0000, v3
	v_max3_f32 v2, |v23|, 0, |v2|
	v_lshlrev_b32_e32 v25, 16, v4
	v_and_b32_e32 v4, 0xffff0000, v4
	v_max3_f32 v2, v2, |v24|, |v3|
	v_pk_fma_f32 v[18:19], v[108:109], v[178:179], v[18:19]
	v_mul_f32_e32 v182, v11, v11
	v_mul_f32_e32 v183, v13, v13
	v_mul_f32_e32 v11, v15, v15
	v_mul_f32_e32 v13, v17, v17
	v_lshlrev_b32_e32 v26, 16, v5
	v_and_b32_e32 v5, 0xffff0000, v5
	v_max3_f32 v2, v2, |v25|, |v4|
	v_mul_f32_e32 v184, v19, v19
	v_pk_mul_f32 v[30:31], v[96:97], v[16:17]
	v_pk_mul_f32 v[32:33], v[98:99], v[14:15]
	v_fmac_f32_e32 v182, v10, v10
	v_fmac_f32_e32 v11, v14, v14
	v_fmac_f32_e32 v13, v16, v16
	global_store_dwordx4 v[214:215], v[14:17], off offset:512
	global_store_dwordx4 v[214:215], v[18:21], off offset:528
	v_cvt_pk_bf16_f32 v10, v32, v33
	v_max3_f32 v2, v2, |v26|, |v5|
	v_lshlrev_b32_e32 v16, 16, v10
	v_and_b32_e32 v17, 0xffff0000, v10
	v_mul_f32_e32 v185, v21, v21
	v_pk_mul_f32 v[178:179], v[102:103], v[18:19]
	v_fmac_f32_e32 v184, v18, v18
	v_add_f32_e32 v22, v180, v181
	v_add_f32_e32 v14, v11, v13
	v_cvt_pk_bf16_f32 v11, v30, v31
	v_max3_f32 v2, v2, |v16|, |v17|
	v_lshlrev_b32_e32 v18, 16, v11
	v_and_b32_e32 v19, 0xffff0000, v11
	v_pk_mul_f32 v[176:177], v[100:101], v[20:21]
	v_fmac_f32_e32 v183, v12, v12
	v_fmac_f32_e32 v185, v20, v20
	v_cvt_pk_bf16_f32 v12, v178, v179
	v_add_f32_e32 v15, v182, v22
	v_add_f32_e32 v14, v184, v14
	v_lshlrev_b32_e32 v20, 16, v12
	v_and_b32_e32 v21, 0xffff0000, v12
	v_max3_f32 v2, v2, |v18|, |v19|
	v_cvt_pk_bf16_f32 v13, v176, v177
	v_add_f32_e32 v15, v183, v15
	v_lshlrev_b32_e32 v22, 16, v13
	v_and_b32_e32 v23, 0xffff0000, v13
	v_add_f32_e32 v3, v185, v14
	v_max3_f32 v2, v2, |v20|, |v21|
	v_add_f32_e32 v3, v15, v3
	v_max3_f32 v5, v2, |v22|, |v23|
	ds_bpermute_b32 v4, v233, v3
	ds_bpermute_b32 v14, v233, v5
	global_store_dwordx4 v[198:199], v[10:13], off offset:256
	s_waitcnt lgkmcnt(1)
	v_add_f32_e32 v2, v3, v4
	s_waitcnt lgkmcnt(0)
	v_max_f32_e32 v4, v14, v14
	v_max_f32_e32 v4, v5, v4
	ds_bpermute_b32 v3, v216, v2
	ds_bpermute_b32 v5, v216, v4
	s_and_saveexec_b64 s[42:43], s[0:1]
	s_cbranch_execz .LBB0_2774
	s_waitcnt lgkmcnt(0)
	v_max_f32_e32 v5, v5, v5
	v_max_f32_e32 v4, v4, v4
	v_add_f32_e32 v11, v2, v3
	v_lshlrev_b64 v[2:3], 7, v[212:213]
	v_max_f32_e32 v10, v4, v5
	v_lshl_add_u64 v[4:5], s[26:27], 0, v[2:3]
	s_lshl_b64 s[82:83], s[40:41], 2
	v_lshl_add_u64 v[2:3], s[28:29], 0, v[2:3]
	v_lshl_add_u64 v[4:5], v[4:5], 0, s[82:83]
	s_lshl_b32 s12, s63, 2
	v_lshl_add_u64 v[2:3], v[2:3], 0, s[82:83]
	v_lshl_add_u64 v[4:5], v[4:5], 0, s[12:13]
	v_lshl_add_u64 v[2:3], v[2:3], 0, s[12:13]
	global_store_dword v[4:5], v11, off
	global_store_dword v[2:3], v10, off
.LBB0_2774:
	s_or_b64 exec, exec, s[42:43]
	v_add_u32_e32 v176, 0x80, v210
	v_ashrrev_i32_e32 v177, 31, v176
	s_waitcnt lgkmcnt(1)
	v_lshlrev_b64 v[2:3], 13, v[176:177]
	v_lshl_add_u64 v[2:3], s[16:17], 0, v[2:3]
	v_lshl_add_u64 v[178:179], v[90:91], 2, v[2:3]
	global_load_dwordx4 v[14:17], v[178:179], off offset:16
	global_load_dwordx4 v[18:21], v[178:179], off
	s_waitcnt lgkmcnt(0)
	global_load_dwordx4 v[2:5], v[178:179], off offset:528
	global_load_dwordx4 v[10:13], v[178:179], off offset:512
	v_lshl_add_u64 v[22:23], v[192:193], 2, s[18:19]
	global_load_dword v22, v[22:23], off
	v_lshlrev_b64 v[24:25], 12, v[192:193]
	v_lshl_add_u64 v[24:25], s[22:23], 0, v[24:25]
	v_lshl_add_u64 v[180:181], v[90:91], 1, v[24:25]
	s_waitcnt vmcnt(0)
	v_pk_mul_f32 v[26:27], v[22:23], v[162:163] op_sel_hi:[0,1]
	v_pk_mul_f32 v[24:25], v[22:23], v[160:161] op_sel_hi:[0,1]
	v_pk_mul_f32 v[30:31], v[22:23], v[166:167] op_sel_hi:[0,1]
	v_pk_mul_f32 v[28:29], v[22:23], v[164:165] op_sel_hi:[0,1]
	v_pk_mul_f32 v[160:161], v[22:23], v[172:173] op_sel_hi:[0,1]
	v_pk_mul_f32 v[32:33], v[22:23], v[168:169] op_sel_hi:[0,1]
	v_pk_mul_f32 v[162:163], v[22:23], v[174:175] op_sel_hi:[0,1]
	v_pk_mul_f32 v[164:165], v[22:23], v[170:171] op_sel_hi:[0,1]
	v_pk_fma_f32 v[24:25], v[86:87], v[24:25], v[44:45]
	v_pk_fma_f32 v[22:23], v[88:89], v[26:27], v[42:43]
	v_pk_fma_f32 v[28:29], v[92:93], v[28:29], v[40:41]
	v_pk_fma_f32 v[26:27], v[94:95], v[30:31], v[38:39]
	v_pk_fma_f32 v[32:33], v[104:105], v[32:33], v[36:37]
	v_pk_fma_f32 v[30:31], v[106:107], v[160:161], v[34:35]
	v_pk_fma_f32 v[8:9], v[110:111], v[164:165], v[8:9]
	v_pk_fma_f32 v[6:7], v[108:109], v[162:163], v[6:7]
	global_store_dwordx4 v[194:195], v[22:25], off
	global_store_dwordx4 v[194:195], v[26:29], off offset:16
	v_mul_f32_e32 v164, v23, v23
	v_mul_f32_e32 v165, v25, v25
	v_mul_f32_e32 v166, v27, v27
	v_mul_f32_e32 v167, v29, v29
	v_pk_mul_f32 v[34:35], v[78:79], v[24:25]
	v_pk_mul_f32 v[38:39], v[82:83], v[28:29]
	v_pk_mul_f32 v[40:41], v[84:85], v[26:27]
	v_mul_f32_e32 v27, v31, v31
	v_mul_f32_e32 v29, v33, v33
	v_pk_mul_f32 v[36:37], v[80:81], v[22:23]
	v_mul_f32_e32 v168, v7, v7
	v_mul_f32_e32 v169, v9, v9
	v_fmac_f32_e32 v164, v22, v22
	v_fmac_f32_e32 v165, v24, v24
	v_fmac_f32_e32 v167, v28, v28
	v_cvt_pk_bf16_f32 v22, v36, v37
	v_cvt_pk_bf16_f32 v23, v34, v35
	v_fmac_f32_e32 v27, v30, v30
	v_fmac_f32_e32 v29, v32, v32
	v_lshlrev_b32_e32 v28, 16, v22
	v_and_b32_e32 v34, 0xffff0000, v22
	v_pk_mul_f32 v[160:161], v[100:101], v[8:9]
	v_pk_mul_f32 v[162:163], v[102:103], v[6:7]
	v_fmac_f32_e32 v166, v26, v26
	v_cvt_pk_bf16_f32 v24, v40, v41
	v_cvt_pk_bf16_f32 v25, v38, v39
	v_fmac_f32_e32 v168, v6, v6
	v_fmac_f32_e32 v169, v8, v8
	v_add_f32_e32 v26, v164, v165
	global_store_dwordx4 v[180:181], v[22:25], off
	v_lshlrev_b32_e32 v35, 16, v23
	v_and_b32_e32 v36, 0xffff0000, v23
	global_store_dwordx4 v[194:195], v[30:33], off offset:512
	global_store_dwordx4 v[194:195], v[6:9], off offset:528
	v_lshlrev_b32_e32 v37, 16, v24
	v_and_b32_e32 v38, 0xffff0000, v24
	v_add_f32_e32 v6, v27, v29
	v_max3_f32 v8, |v28|, 0, |v34|
	v_add_f32_e32 v7, v166, v26
	v_add_f32_e32 v6, v168, v6
	v_max3_f32 v8, v8, |v35|, |v36|
	v_lshlrev_b32_e32 v39, 16, v25
	v_and_b32_e32 v40, 0xffff0000, v25
	v_add_f32_e32 v7, v167, v7
	v_add_f32_e32 v6, v169, v6
	v_max3_f32 v8, v8, |v37|, |v38|
	v_pk_mul_f32 v[44:45], v[98:99], v[30:31]
	v_add_f32_e32 v6, v7, v6
	v_cvt_pk_bf16_f32 v22, v44, v45
	v_max3_f32 v7, v8, |v39|, |v40|
	v_lshlrev_b32_e32 v9, 16, v22
	v_and_b32_e32 v26, 0xffff0000, v22
	v_pk_mul_f32 v[42:43], v[96:97], v[32:33]
	v_max3_f32 v7, v7, |v9|, |v26|
	v_cvt_pk_bf16_f32 v23, v42, v43
	v_cvt_pk_bf16_f32 v24, v162, v163
	v_cvt_pk_bf16_f32 v25, v160, v161
	ds_bpermute_b32 v8, v233, v6
	v_lshlrev_b32_e32 v27, 16, v23
	v_and_b32_e32 v28, 0xffff0000, v23
	v_lshlrev_b32_e32 v29, 16, v24
	v_and_b32_e32 v30, 0xffff0000, v24
	v_max3_f32 v7, v7, |v27|, |v28|
	v_lshlrev_b32_e32 v31, 16, v25
	v_and_b32_e32 v32, 0xffff0000, v25
	v_max3_f32 v7, v7, |v29|, |v30|
	v_max3_f32 v9, v7, |v31|, |v32|
	ds_bpermute_b32 v26, v233, v9
	s_waitcnt lgkmcnt(1)
	v_add_f32_e32 v6, v6, v8
	ds_bpermute_b32 v7, v216, v6
	global_store_dwordx4 v[180:181], v[22:25], off offset:256
	s_waitcnt lgkmcnt(1)
	v_max_f32_e32 v8, v26, v26
	v_max_f32_e32 v8, v9, v8
	ds_bpermute_b32 v9, v216, v8
	s_and_saveexec_b64 s[42:43], s[0:1]
	s_cbranch_execz .LBB0_2776
	s_waitcnt lgkmcnt(0)
	v_max_f32_e32 v9, v9, v9
	v_max_f32_e32 v8, v8, v8
	v_add_f32_e32 v23, v6, v7
	v_lshlrev_b64 v[6:7], 7, v[192:193]
	v_max_f32_e32 v22, v8, v9
	v_lshl_add_u64 v[8:9], s[26:27], 0, v[6:7]
	s_lshl_b64 s[82:83], s[40:41], 2
	v_lshl_add_u64 v[6:7], s[28:29], 0, v[6:7]
	v_lshl_add_u64 v[8:9], v[8:9], 0, s[82:83]
	s_lshl_b32 s12, s63, 2
	v_lshl_add_u64 v[6:7], v[6:7], 0, s[82:83]
	v_lshl_add_u64 v[8:9], v[8:9], 0, s[12:13]
	v_lshl_add_u64 v[6:7], v[6:7], 0, s[12:13]
	global_store_dword v[8:9], v23, off
	global_store_dword v[6:7], v22, off
.LBB0_2776:
	s_or_b64 exec, exec, s[42:43]
	v_or_b32_e32 v36, 16, v176
	v_ashrrev_i32_e32 v37, 31, v36
	s_waitcnt lgkmcnt(1)
	v_lshlrev_b64 v[6:7], 13, v[36:37]
	v_lshl_add_u64 v[6:7], s[16:17], 0, v[6:7]
	v_lshl_add_u64 v[40:41], v[90:91], 2, v[6:7]
	global_load_dwordx4 v[26:29], v[40:41], off offset:16
	global_load_dwordx4 v[30:33], v[40:41], off
	s_waitcnt lgkmcnt(0)
	global_load_dwordx4 v[6:9], v[40:41], off offset:528
	global_load_dwordx4 v[22:25], v[40:41], off offset:512
	global_load_dword v34, v[196:197], off offset:512
	v_lshlrev_b64 v[38:39], 12, v[176:177]
	v_lshl_add_u64 v[38:39], s[22:23], 0, v[38:39]
	v_lshl_add_u64 v[38:39], v[90:91], 1, v[38:39]
	s_waitcnt vmcnt(0)
	v_pk_mul_f32 v[44:45], v[34:35], v[128:129] op_sel_hi:[0,1]
	v_pk_mul_f32 v[128:129], v[34:35], v[150:151] op_sel_hi:[0,1]
	v_pk_mul_f32 v[42:43], v[34:35], v[146:147] op_sel_hi:[0,1]
	v_pk_mul_f32 v[146:147], v[34:35], v[148:149] op_sel_hi:[0,1]
	v_pk_mul_f32 v[148:149], v[34:35], v[156:157] op_sel_hi:[0,1]
	v_pk_mul_f32 v[150:151], v[34:35], v[152:153] op_sel_hi:[0,1]
	v_pk_fma_f32 v[14:15], v[94:95], v[128:129], v[14:15]
	v_pk_mul_f32 v[152:153], v[34:35], v[158:159] op_sel_hi:[0,1]
	v_pk_mul_f32 v[34:35], v[34:35], v[154:155] op_sel_hi:[0,1]
	v_pk_fma_f32 v[20:21], v[86:87], v[44:45], v[20:21]
	v_pk_fma_f32 v[18:19], v[88:89], v[42:43], v[18:19]
	v_pk_fma_f32 v[16:17], v[92:93], v[146:147], v[16:17]
	v_pk_fma_f32 v[12:13], v[104:105], v[150:151], v[12:13]
	v_pk_fma_f32 v[10:11], v[106:107], v[148:149], v[10:11]
	v_mul_f32_e32 v156, v15, v15
	v_pk_fma_f32 v[4:5], v[110:111], v[34:35], v[4:5]
	v_pk_fma_f32 v[2:3], v[108:109], v[152:153], v[2:3]
	global_store_dwordx4 v[178:179], v[18:21], off
	global_store_dwordx4 v[178:179], v[14:17], off offset:16
	v_mul_f32_e32 v154, v19, v19
	v_mul_f32_e32 v155, v21, v21
	v_mul_f32_e32 v157, v17, v17
	v_pk_mul_f32 v[34:35], v[78:79], v[20:21]
	v_pk_mul_f32 v[42:43], v[80:81], v[18:19]
	v_pk_mul_f32 v[128:129], v[84:85], v[14:15]
	v_mul_f32_e32 v19, v11, v11
	v_mul_f32_e32 v21, v13, v13
	v_fmac_f32_e32 v156, v14, v14
	v_cvt_pk_bf16_f32 v14, v42, v43
	v_pk_mul_f32 v[44:45], v[82:83], v[16:17]
	v_mul_f32_e32 v158, v3, v3
	v_mul_f32_e32 v159, v5, v5
	v_fmac_f32_e32 v154, v18, v18
	v_fmac_f32_e32 v155, v20, v20
	v_fmac_f32_e32 v157, v16, v16
	v_cvt_pk_bf16_f32 v15, v34, v35
	v_cvt_pk_bf16_f32 v16, v128, v129
	v_cvt_pk_bf16_f32 v17, v44, v45
	v_fmac_f32_e32 v19, v10, v10
	v_fmac_f32_e32 v21, v12, v12
	global_store_dwordx4 v[38:39], v[14:17], off
	v_lshlrev_b32_e32 v20, 16, v14
	v_pk_mul_f32 v[150:151], v[100:101], v[4:5]
	v_and_b32_e32 v14, 0xffff0000, v14
	v_pk_mul_f32 v[152:153], v[102:103], v[2:3]
	v_fmac_f32_e32 v158, v2, v2
	v_fmac_f32_e32 v159, v4, v4
	v_add_f32_e32 v18, v154, v155
	v_lshlrev_b32_e32 v34, 16, v15
	v_and_b32_e32 v15, 0xffff0000, v15
	global_store_dwordx4 v[178:179], v[10:13], off offset:512
	global_store_dwordx4 v[178:179], v[2:5], off offset:528
	v_lshlrev_b32_e32 v35, 16, v16
	v_and_b32_e32 v16, 0xffff0000, v16
	v_add_f32_e32 v2, v19, v21
	v_max3_f32 v4, |v20|, 0, |v14|
	v_add_f32_e32 v3, v156, v18
	v_add_f32_e32 v2, v158, v2
	v_max3_f32 v4, v4, |v34|, |v15|
	v_lshlrev_b32_e32 v42, 16, v17
	v_and_b32_e32 v17, 0xffff0000, v17
	v_add_f32_e32 v3, v157, v3
	v_add_f32_e32 v2, v159, v2
	v_max3_f32 v4, v4, |v35|, |v16|
	v_pk_mul_f32 v[148:149], v[98:99], v[10:11]
	v_add_f32_e32 v2, v3, v2
	v_cvt_pk_bf16_f32 v10, v148, v149
	v_max3_f32 v3, v4, |v42|, |v17|
	v_lshlrev_b32_e32 v5, 16, v10
	v_and_b32_e32 v14, 0xffff0000, v10
	v_pk_mul_f32 v[146:147], v[96:97], v[12:13]
	v_max3_f32 v3, v3, |v5|, |v14|
	v_cvt_pk_bf16_f32 v11, v146, v147
	v_cvt_pk_bf16_f32 v12, v152, v153
	v_cvt_pk_bf16_f32 v13, v150, v151
	ds_bpermute_b32 v4, v233, v2
	v_lshlrev_b32_e32 v18, 16, v11
	v_and_b32_e32 v19, 0xffff0000, v11
	v_lshlrev_b32_e32 v20, 16, v12
	v_and_b32_e32 v21, 0xffff0000, v12
	v_max3_f32 v3, v3, |v18|, |v19|
	v_lshlrev_b32_e32 v43, 16, v13
	v_and_b32_e32 v44, 0xffff0000, v13
	v_max3_f32 v3, v3, |v20|, |v21|
	v_max3_f32 v5, v3, |v43|, |v44|
	ds_bpermute_b32 v14, v233, v5
	s_waitcnt lgkmcnt(1)
	v_add_f32_e32 v2, v2, v4
	ds_bpermute_b32 v3, v216, v2
	global_store_dwordx4 v[38:39], v[10:13], off offset:256
	s_waitcnt lgkmcnt(1)
	v_max_f32_e32 v4, v14, v14
	v_max_f32_e32 v4, v5, v4
	ds_bpermute_b32 v5, v216, v4
	s_and_saveexec_b64 s[42:43], s[0:1]
	s_cbranch_execz .LBB0_2778
	s_waitcnt lgkmcnt(0)
	v_max_f32_e32 v5, v5, v5
	v_max_f32_e32 v4, v4, v4
	v_add_f32_e32 v11, v2, v3
	v_lshlrev_b64 v[2:3], 7, v[176:177]
	v_max_f32_e32 v10, v4, v5
	v_lshl_add_u64 v[4:5], s[26:27], 0, v[2:3]
	s_lshl_b64 s[82:83], s[40:41], 2
	v_lshl_add_u64 v[2:3], s[28:29], 0, v[2:3]
	v_lshl_add_u64 v[4:5], v[4:5], 0, s[82:83]
	s_lshl_b32 s12, s63, 2
	v_lshl_add_u64 v[2:3], v[2:3], 0, s[82:83]
	v_lshl_add_u64 v[4:5], v[4:5], 0, s[12:13]
	v_lshl_add_u64 v[2:3], v[2:3], 0, s[12:13]
	global_store_dword v[4:5], v11, off
	global_store_dword v[2:3], v10, off
.LBB0_2778:
	s_or_b64 exec, exec, s[42:43]
	v_or_b32_e32 v34, 32, v176
	v_ashrrev_i32_e32 v35, 31, v34
	s_waitcnt lgkmcnt(1)
	v_lshlrev_b64 v[2:3], 13, v[34:35]
	v_lshl_add_u64 v[2:3], s[16:17], 0, v[2:3]
	v_lshl_add_u64 v[38:39], v[90:91], 2, v[2:3]
	global_load_dwordx4 v[14:17], v[38:39], off offset:16
	global_load_dwordx4 v[18:21], v[38:39], off
	s_waitcnt lgkmcnt(0)
	global_load_dwordx4 v[2:5], v[38:39], off offset:528
	global_load_dwordx4 v[10:13], v[38:39], off offset:512
	v_lshl_add_u64 v[42:43], v[36:37], 2, s[18:19]
	global_load_dword v42, v[42:43], off
	v_lshlrev_b64 v[44:45], 12, v[36:37]
	v_lshl_add_u64 v[44:45], s[22:23], 0, v[44:45]
	v_lshl_add_u64 v[44:45], v[90:91], 1, v[44:45]
	s_waitcnt vmcnt(0)
	v_pk_mul_f32 v[118:119], v[42:43], v[118:119] op_sel_hi:[0,1]
	v_pk_mul_f32 v[114:115], v[42:43], v[114:115] op_sel_hi:[0,1]
	v_pk_mul_f32 v[112:113], v[42:43], v[112:113] op_sel_hi:[0,1]
	v_pk_mul_f32 v[116:117], v[42:43], v[116:117] op_sel_hi:[0,1]
	v_pk_mul_f32 v[124:125], v[42:43], v[124:125] op_sel_hi:[0,1]
	v_pk_mul_f32 v[120:121], v[42:43], v[120:121] op_sel_hi:[0,1]
	v_pk_fma_f32 v[26:27], v[94:95], v[118:119], v[26:27]
	v_pk_mul_f32 v[126:127], v[42:43], v[126:127] op_sel_hi:[0,1]
	v_pk_mul_f32 v[42:43], v[42:43], v[122:123] op_sel_hi:[0,1]
	v_pk_fma_f32 v[32:33], v[86:87], v[112:113], v[32:33]
	v_pk_fma_f32 v[30:31], v[88:89], v[114:115], v[30:31]
	v_pk_fma_f32 v[28:29], v[92:93], v[116:117], v[28:29]
	v_pk_fma_f32 v[24:25], v[104:105], v[120:121], v[24:25]
	v_pk_fma_f32 v[22:23], v[106:107], v[124:125], v[22:23]
	v_mul_f32_e32 v128, v27, v27
	v_pk_fma_f32 v[8:9], v[110:111], v[42:43], v[8:9]
	v_pk_fma_f32 v[6:7], v[108:109], v[126:127], v[6:7]
	global_store_dwordx4 v[40:41], v[30:33], off
	global_store_dwordx4 v[40:41], v[26:29], off offset:16
	v_mul_f32_e32 v126, v31, v31
	v_mul_f32_e32 v127, v33, v33
	v_mul_f32_e32 v129, v29, v29
	v_pk_mul_f32 v[42:43], v[78:79], v[32:33]
	v_pk_mul_f32 v[112:113], v[80:81], v[30:31]
	v_pk_mul_f32 v[116:117], v[84:85], v[26:27]
	v_mul_f32_e32 v31, v23, v23
	v_mul_f32_e32 v33, v25, v25
	v_fmac_f32_e32 v128, v26, v26
	v_cvt_pk_bf16_f32 v26, v112, v113
	v_pk_mul_f32 v[114:115], v[82:83], v[28:29]
	v_mul_f32_e32 v146, v7, v7
	v_mul_f32_e32 v147, v9, v9
	v_fmac_f32_e32 v126, v30, v30
	v_fmac_f32_e32 v127, v32, v32
	v_fmac_f32_e32 v129, v28, v28
	v_cvt_pk_bf16_f32 v27, v42, v43
	v_cvt_pk_bf16_f32 v28, v116, v117
	v_cvt_pk_bf16_f32 v29, v114, v115
	v_fmac_f32_e32 v31, v22, v22
	v_fmac_f32_e32 v33, v24, v24
	global_store_dwordx4 v[44:45], v[26:29], off
	v_lshlrev_b32_e32 v32, 16, v26
	v_pk_mul_f32 v[122:123], v[100:101], v[8:9]
	v_and_b32_e32 v26, 0xffff0000, v26
	v_pk_mul_f32 v[124:125], v[102:103], v[6:7]
	v_fmac_f32_e32 v146, v6, v6
	v_fmac_f32_e32 v147, v8, v8
	v_add_f32_e32 v30, v126, v127
	v_lshlrev_b32_e32 v42, 16, v27
	v_and_b32_e32 v27, 0xffff0000, v27
	global_store_dwordx4 v[40:41], v[22:25], off offset:512
	global_store_dwordx4 v[40:41], v[6:9], off offset:528
	v_lshlrev_b32_e32 v43, 16, v28
	v_and_b32_e32 v28, 0xffff0000, v28
	v_add_f32_e32 v6, v31, v33
	v_max3_f32 v8, |v32|, 0, |v26|
	v_add_f32_e32 v7, v128, v30
	v_add_f32_e32 v6, v146, v6
	v_max3_f32 v8, v8, |v42|, |v27|
	v_lshlrev_b32_e32 v112, 16, v29
	v_and_b32_e32 v29, 0xffff0000, v29
	v_add_f32_e32 v7, v129, v7
	v_add_f32_e32 v6, v147, v6
	v_max3_f32 v8, v8, |v43|, |v28|
	v_pk_mul_f32 v[120:121], v[98:99], v[22:23]
	v_add_f32_e32 v6, v7, v6
	v_cvt_pk_bf16_f32 v22, v120, v121
	v_max3_f32 v7, v8, |v112|, |v29|
	v_lshlrev_b32_e32 v9, 16, v22
	v_and_b32_e32 v26, 0xffff0000, v22
	v_pk_mul_f32 v[118:119], v[96:97], v[24:25]
	v_max3_f32 v7, v7, |v9|, |v26|
	v_cvt_pk_bf16_f32 v23, v118, v119
	v_cvt_pk_bf16_f32 v24, v124, v125
	v_cvt_pk_bf16_f32 v25, v122, v123
	ds_bpermute_b32 v8, v233, v6
	v_lshlrev_b32_e32 v30, 16, v23
	v_and_b32_e32 v31, 0xffff0000, v23
	v_lshlrev_b32_e32 v32, 16, v24
	v_and_b32_e32 v33, 0xffff0000, v24
	v_max3_f32 v7, v7, |v30|, |v31|
	v_lshlrev_b32_e32 v40, 16, v25
	v_and_b32_e32 v41, 0xffff0000, v25
	v_max3_f32 v7, v7, |v32|, |v33|
	v_max3_f32 v9, v7, |v40|, |v41|
	ds_bpermute_b32 v26, v233, v9
	s_waitcnt lgkmcnt(1)
	v_add_f32_e32 v6, v6, v8
	ds_bpermute_b32 v7, v216, v6
	global_store_dwordx4 v[44:45], v[22:25], off offset:256
	s_waitcnt lgkmcnt(1)
	v_max_f32_e32 v8, v26, v26
	v_max_f32_e32 v8, v9, v8
	ds_bpermute_b32 v9, v216, v8
	s_and_saveexec_b64 s[42:43], s[0:1]
	s_cbranch_execz .LBB0_2780
	s_waitcnt lgkmcnt(0)
	v_max_f32_e32 v9, v9, v9
	v_max_f32_e32 v8, v8, v8
	v_add_f32_e32 v23, v6, v7
	v_lshlrev_b64 v[6:7], 7, v[36:37]
	v_max_f32_e32 v22, v8, v9
	v_lshl_add_u64 v[8:9], s[26:27], 0, v[6:7]
	s_lshl_b64 s[82:83], s[40:41], 2
	v_lshl_add_u64 v[6:7], s[28:29], 0, v[6:7]
	v_lshl_add_u64 v[8:9], v[8:9], 0, s[82:83]
	s_lshl_b32 s12, s63, 2
	v_lshl_add_u64 v[6:7], v[6:7], 0, s[82:83]
	v_lshl_add_u64 v[8:9], v[8:9], 0, s[12:13]
	v_lshl_add_u64 v[6:7], v[6:7], 0, s[12:13]
	global_store_dword v[8:9], v23, off
	global_store_dword v[6:7], v22, off
.LBB0_2780:
	s_or_b64 exec, exec, s[42:43]
	v_or_b32_e32 v36, 48, v176
	v_ashrrev_i32_e32 v37, 31, v36
	s_waitcnt lgkmcnt(1)
	v_lshlrev_b64 v[6:7], 13, v[36:37]
	v_lshl_add_u64 v[6:7], s[16:17], 0, v[6:7]
	v_lshl_add_u64 v[40:41], v[90:91], 2, v[6:7]
	global_load_dwordx4 v[26:29], v[40:41], off offset:16
	global_load_dwordx4 v[30:33], v[40:41], off
	s_waitcnt lgkmcnt(0)
	global_load_dwordx4 v[6:9], v[40:41], off offset:528
	global_load_dwordx4 v[22:25], v[40:41], off offset:512
	v_lshl_add_u64 v[42:43], v[34:35], 2, s[18:19]
	global_load_dword v42, v[42:43], off
	v_lshlrev_b64 v[44:45], 12, v[34:35]
	v_lshl_add_u64 v[44:45], s[22:23], 0, v[44:45]
	v_lshl_add_u64 v[44:45], v[90:91], 1, v[44:45]
	s_waitcnt vmcnt(0)
	v_pk_mul_f32 v[68:69], v[42:43], v[68:69] op_sel_hi:[0,1]
	v_pk_mul_f32 v[64:65], v[42:43], v[64:65] op_sel_hi:[0,1]
	v_pk_mul_f32 v[62:63], v[42:43], v[62:63] op_sel_hi:[0,1]
	v_pk_mul_f32 v[66:67], v[42:43], v[66:67] op_sel_hi:[0,1]
	v_pk_mul_f32 v[74:75], v[42:43], v[74:75] op_sel_hi:[0,1]
	v_pk_mul_f32 v[70:71], v[42:43], v[70:71] op_sel_hi:[0,1]
	v_pk_fma_f32 v[14:15], v[94:95], v[68:69], v[14:15]
	v_pk_mul_f32 v[76:77], v[42:43], v[76:77] op_sel_hi:[0,1]
	v_pk_mul_f32 v[42:43], v[42:43], v[72:73] op_sel_hi:[0,1]
	v_pk_fma_f32 v[20:21], v[86:87], v[62:63], v[20:21]
	v_pk_fma_f32 v[18:19], v[88:89], v[64:65], v[18:19]
	v_pk_fma_f32 v[16:17], v[92:93], v[66:67], v[16:17]
	v_pk_fma_f32 v[12:13], v[104:105], v[70:71], v[12:13]
	v_pk_fma_f32 v[10:11], v[106:107], v[74:75], v[10:11]
	v_mul_f32_e32 v112, v15, v15
	v_pk_fma_f32 v[4:5], v[110:111], v[42:43], v[4:5]
	v_pk_fma_f32 v[2:3], v[108:109], v[76:77], v[2:3]
	global_store_dwordx4 v[38:39], v[18:21], off
	global_store_dwordx4 v[38:39], v[14:17], off offset:16
	v_mul_f32_e32 v76, v19, v19
	v_mul_f32_e32 v77, v21, v21
	v_mul_f32_e32 v113, v17, v17
	v_pk_mul_f32 v[42:43], v[78:79], v[20:21]
	v_pk_mul_f32 v[62:63], v[80:81], v[18:19]
	v_pk_mul_f32 v[66:67], v[84:85], v[14:15]
	v_mul_f32_e32 v19, v11, v11
	v_mul_f32_e32 v21, v13, v13
	v_fmac_f32_e32 v112, v14, v14
	v_cvt_pk_bf16_f32 v14, v62, v63
	v_pk_mul_f32 v[64:65], v[82:83], v[16:17]
	v_mul_f32_e32 v114, v3, v3
	v_mul_f32_e32 v115, v5, v5
	v_fmac_f32_e32 v76, v18, v18
	v_fmac_f32_e32 v77, v20, v20
	v_fmac_f32_e32 v113, v16, v16
	v_cvt_pk_bf16_f32 v15, v42, v43
	v_cvt_pk_bf16_f32 v16, v66, v67
	v_cvt_pk_bf16_f32 v17, v64, v65
	v_fmac_f32_e32 v19, v10, v10
	v_fmac_f32_e32 v21, v12, v12
	global_store_dwordx4 v[44:45], v[14:17], off
	v_lshlrev_b32_e32 v20, 16, v14
	v_pk_mul_f32 v[72:73], v[100:101], v[4:5]
	v_and_b32_e32 v14, 0xffff0000, v14
	v_pk_mul_f32 v[74:75], v[102:103], v[2:3]
	v_fmac_f32_e32 v114, v2, v2
	v_fmac_f32_e32 v115, v4, v4
	v_add_f32_e32 v18, v76, v77
	v_lshlrev_b32_e32 v42, 16, v15
	v_and_b32_e32 v15, 0xffff0000, v15
	global_store_dwordx4 v[38:39], v[10:13], off offset:512
	global_store_dwordx4 v[38:39], v[2:5], off offset:528
	v_lshlrev_b32_e32 v43, 16, v16
	v_and_b32_e32 v16, 0xffff0000, v16
	v_add_f32_e32 v2, v19, v21
	v_max3_f32 v4, |v20|, 0, |v14|
	v_add_f32_e32 v3, v112, v18
	v_add_f32_e32 v2, v114, v2
	v_max3_f32 v4, v4, |v42|, |v15|
	v_lshlrev_b32_e32 v62, 16, v17
	v_and_b32_e32 v17, 0xffff0000, v17
	v_add_f32_e32 v3, v113, v3
	v_add_f32_e32 v2, v115, v2
	v_max3_f32 v4, v4, |v43|, |v16|
	v_pk_mul_f32 v[70:71], v[98:99], v[10:11]
	v_add_f32_e32 v2, v3, v2
	v_cvt_pk_bf16_f32 v10, v70, v71
	v_max3_f32 v3, v4, |v62|, |v17|
	v_lshlrev_b32_e32 v5, 16, v10
	v_and_b32_e32 v14, 0xffff0000, v10
	v_pk_mul_f32 v[68:69], v[96:97], v[12:13]
	v_max3_f32 v3, v3, |v5|, |v14|
	v_cvt_pk_bf16_f32 v11, v68, v69
	v_cvt_pk_bf16_f32 v12, v74, v75
	v_cvt_pk_bf16_f32 v13, v72, v73
	ds_bpermute_b32 v4, v233, v2
	v_lshlrev_b32_e32 v18, 16, v11
	v_and_b32_e32 v19, 0xffff0000, v11
	v_lshlrev_b32_e32 v20, 16, v12
	v_and_b32_e32 v21, 0xffff0000, v12
	v_max3_f32 v3, v3, |v18|, |v19|
	v_lshlrev_b32_e32 v38, 16, v13
	v_and_b32_e32 v39, 0xffff0000, v13
	v_max3_f32 v3, v3, |v20|, |v21|
	v_max3_f32 v5, v3, |v38|, |v39|
	ds_bpermute_b32 v14, v233, v5
	s_waitcnt lgkmcnt(1)
	v_add_f32_e32 v2, v2, v4
	ds_bpermute_b32 v3, v216, v2
	global_store_dwordx4 v[44:45], v[10:13], off offset:256
	s_waitcnt lgkmcnt(1)
	v_max_f32_e32 v4, v14, v14
	v_max_f32_e32 v4, v5, v4
	ds_bpermute_b32 v5, v216, v4
	s_and_saveexec_b64 s[42:43], s[0:1]
	s_cbranch_execz .LBB0_2782
	s_waitcnt lgkmcnt(0)
	v_max_f32_e32 v5, v5, v5
	v_max_f32_e32 v4, v4, v4
	v_add_f32_e32 v11, v2, v3
	v_lshlrev_b64 v[2:3], 7, v[34:35]
	v_max_f32_e32 v10, v4, v5
	v_lshl_add_u64 v[4:5], s[26:27], 0, v[2:3]
	s_lshl_b64 s[82:83], s[40:41], 2
	v_lshl_add_u64 v[2:3], s[28:29], 0, v[2:3]
	v_lshl_add_u64 v[4:5], v[4:5], 0, s[82:83]
	s_lshl_b32 s12, s63, 2
	v_lshl_add_u64 v[2:3], v[2:3], 0, s[82:83]
	v_lshl_add_u64 v[4:5], v[4:5], 0, s[12:13]
	v_lshl_add_u64 v[2:3], v[2:3], 0, s[12:13]
	global_store_dword v[4:5], v11, off
	global_store_dword v[2:3], v10, off
.LBB0_2782:
	s_or_b64 exec, exec, s[42:43]
	s_waitcnt lgkmcnt(1)
	v_lshl_add_u64 v[2:3], v[36:37], 2, s[18:19]
	global_load_dword v2, v[2:3], off
	s_waitcnt lgkmcnt(0)
	v_lshlrev_b64 v[4:5], 12, v[36:37]
	v_lshl_add_u64 v[4:5], s[22:23], 0, v[4:5]
	v_lshl_add_u64 v[18:19], v[90:91], 1, v[4:5]
	s_waitcnt vmcnt(0)
	v_pk_mul_f32 v[10:11], v[2:3], v[48:49] op_sel_hi:[0,1]
	v_pk_mul_f32 v[4:5], v[2:3], v[46:47] op_sel_hi:[0,1]
	v_pk_mul_f32 v[14:15], v[2:3], v[52:53] op_sel_hi:[0,1]
	v_pk_mul_f32 v[12:13], v[2:3], v[50:51] op_sel_hi:[0,1]
	v_pk_mul_f32 v[20:21], v[2:3], v[58:59] op_sel_hi:[0,1]
	v_pk_mul_f32 v[16:17], v[2:3], v[54:55] op_sel_hi:[0,1]
	v_pk_mul_f32 v[34:35], v[2:3], v[60:61] op_sel_hi:[0,1]
	v_pk_mul_f32 v[38:39], v[2:3], v[56:57] op_sel_hi:[0,1]
	v_pk_fma_f32 v[2:3], v[88:89], v[10:11], v[30:31]
	v_pk_fma_f32 v[4:5], v[86:87], v[4:5], v[32:33]
	v_pk_fma_f32 v[12:13], v[92:93], v[12:13], v[28:29]
	v_pk_fma_f32 v[8:9], v[110:111], v[38:39], v[8:9]
	v_mul_f32_e32 v38, v3, v3
	v_pk_fma_f32 v[10:11], v[94:95], v[14:15], v[26:27]
	v_pk_fma_f32 v[14:15], v[106:107], v[20:21], v[22:23]
	global_store_dwordx4 v[40:41], v[2:5], off
	global_store_dwordx4 v[40:41], v[10:13], off offset:16
	v_mul_f32_e32 v39, v5, v5
	v_mul_f32_e32 v43, v13, v13
	v_pk_mul_f32 v[22:23], v[80:81], v[2:3]
	v_fmac_f32_e32 v38, v2, v2
	v_cvt_pk_bf16_f32 v2, v22, v23
	v_pk_fma_f32 v[16:17], v[104:105], v[16:17], v[24:25]
	v_pk_mul_f32 v[20:21], v[78:79], v[4:5]
	v_pk_mul_f32 v[24:25], v[82:83], v[12:13]
	v_pk_mul_f32 v[26:27], v[84:85], v[10:11]
	v_fmac_f32_e32 v39, v4, v4
	v_fmac_f32_e32 v43, v12, v12
	v_cvt_pk_bf16_f32 v3, v20, v21
	v_cvt_pk_bf16_f32 v4, v26, v27
	v_cvt_pk_bf16_f32 v5, v24, v25
	global_store_dwordx4 v[18:19], v[2:5], off
	v_lshlrev_b32_e32 v12, 16, v2
	v_lshlrev_b32_e32 v20, 16, v3
	v_and_b32_e32 v2, 0xffff0000, v2
	v_and_b32_e32 v3, 0xffff0000, v3
	v_max3_f32 v2, |v12|, 0, |v2|
	v_pk_fma_f32 v[6:7], v[108:109], v[34:35], v[6:7]
	v_mul_f32_e32 v42, v11, v11
	v_mul_f32_e32 v11, v15, v15
	v_mul_f32_e32 v13, v17, v17
	v_lshlrev_b32_e32 v21, 16, v4
	v_and_b32_e32 v4, 0xffff0000, v4
	v_max3_f32 v2, v2, |v20|, |v3|
	v_mul_f32_e32 v44, v7, v7
	v_fmac_f32_e32 v11, v14, v14
	v_fmac_f32_e32 v13, v16, v16
	v_lshlrev_b32_e32 v22, 16, v5
	v_and_b32_e32 v5, 0xffff0000, v5
	v_max3_f32 v2, v2, |v21|, |v4|
	v_pk_mul_f32 v[30:31], v[98:99], v[14:15]
	v_pk_mul_f32 v[34:35], v[102:103], v[6:7]
	v_fmac_f32_e32 v44, v6, v6
	global_store_dwordx4 v[40:41], v[14:17], off offset:512
	global_store_dwordx4 v[40:41], v[6:9], off offset:528
	v_add_f32_e32 v11, v11, v13
	v_max3_f32 v2, v2, |v22|, |v5|
	v_cvt_pk_bf16_f32 v6, v30, v31
	v_mul_f32_e32 v45, v9, v9
	v_lshlrev_b32_e32 v12, 16, v6
	v_and_b32_e32 v13, 0xffff0000, v6
	v_pk_mul_f32 v[28:29], v[96:97], v[16:17]
	v_fmac_f32_e32 v42, v10, v10
	v_add_f32_e32 v10, v38, v39
	v_cvt_pk_bf16_f32 v7, v28, v29
	v_max3_f32 v2, v2, |v12|, |v13|
	v_lshlrev_b32_e32 v14, 16, v7
	v_and_b32_e32 v15, 0xffff0000, v7
	v_pk_mul_f32 v[32:33], v[100:101], v[8:9]
	v_fmac_f32_e32 v45, v8, v8
	v_cvt_pk_bf16_f32 v8, v34, v35
	v_add_f32_e32 v10, v42, v10
	v_add_f32_e32 v11, v44, v11
	v_lshlrev_b32_e32 v16, 16, v8
	v_and_b32_e32 v17, 0xffff0000, v8
	v_max3_f32 v2, v2, |v14|, |v15|
	v_cvt_pk_bf16_f32 v9, v32, v33
	v_add_f32_e32 v10, v43, v10
	v_lshlrev_b32_e32 v23, 16, v9
	v_and_b32_e32 v24, 0xffff0000, v9
	v_add_f32_e32 v3, v45, v11
	v_max3_f32 v2, v2, |v16|, |v17|
	v_add_f32_e32 v3, v10, v3
	v_max3_f32 v5, v2, |v23|, |v24|
	ds_bpermute_b32 v4, v233, v3
	ds_bpermute_b32 v10, v233, v5
	global_store_dwordx4 v[18:19], v[6:9], off offset:256
	s_waitcnt lgkmcnt(1)
	v_add_f32_e32 v2, v3, v4
	s_waitcnt lgkmcnt(0)
	v_max_f32_e32 v4, v10, v10
	v_max_f32_e32 v4, v5, v4
	ds_bpermute_b32 v3, v216, v2
	ds_bpermute_b32 v5, v216, v4
	s_and_saveexec_b64 s[42:43], s[0:1]
	s_cbranch_execz .LBB0_2784
	s_waitcnt lgkmcnt(0)
	v_max_f32_e32 v5, v5, v5
	v_max_f32_e32 v4, v4, v4
	v_add_f32_e32 v7, v2, v3
	v_lshlrev_b64 v[2:3], 7, v[36:37]
	v_max_f32_e32 v6, v4, v5
	v_lshl_add_u64 v[4:5], s[26:27], 0, v[2:3]
	s_lshl_b64 s[40:41], s[40:41], 2
	v_lshl_add_u64 v[2:3], s[28:29], 0, v[2:3]
	v_lshl_add_u64 v[4:5], v[4:5], 0, s[40:41]
	s_lshl_b32 s12, s63, 2
	v_lshl_add_u64 v[2:3], v[2:3], 0, s[40:41]
	v_lshl_add_u64 v[4:5], v[4:5], 0, s[12:13]
	v_lshl_add_u64 v[2:3], v[2:3], 0, s[12:13]
	global_store_dword v[4:5], v7, off
	global_store_dword v[2:3], v6, off

.LBB0_3035:
	s_lshr_b32 s34, s69, 4
	s_add_i32 s34, s34, -1
	s_cmp_gt_i32 s69, 31
	s_cselect_b32 s34, s34, 0
	v_lshl_or_b32 v178, s12, 8, v208
	s_mul_i32 s37, s34, 0xc000
	s_mul_hi_i32 s36, s34, 0xc000
	s_add_u32 s34, s51, s37
	v_ashrrev_i32_e32 v179, 31, v178
	s_addc_u32 s35, s54, s36
	v_lshlrev_b64 v[114:115], 2, v[178:179]
	v_lshl_add_u64 v[122:123], s[34:35], 0, v[114:115]
	s_add_u32 s34, s55, s37
	v_lshl_add_u32 v196, s69, 8, v206
	v_lshl_add_u64 v[116:117], s[20:21], 0, v[114:115]
	s_addc_u32 s35, s56, s36
	v_ashrrev_i32_e32 v197, 31, v196
	v_lshl_add_u64 v[124:125], s[34:35], 0, v[114:115]
	global_load_dwordx4 v[118:121], v[122:123], off offset:16
	global_load_dwordx4 v[126:129], v[122:123], off
	global_load_dwordx4 v[180:183], v[116:117], off offset:16
	global_load_dwordx4 v[184:187], v[116:117], off
	global_load_dwordx4 v[188:191], v[124:125], off offset:16
	global_load_dwordx4 v[192:195], v[124:125], off
	global_load_dwordx4 v[214:217], v[116:117], off offset:528
	global_load_dwordx4 v[218:221], v[116:117], off offset:512
	global_load_dwordx4 v[222:225], v[124:125], off offset:528
	global_load_dwordx4 v[226:229], v[124:125], off offset:512
	v_lshlrev_b64 v[116:117], 13, v[196:197]
	v_or_b32_e32 v198, 16, v196
	v_lshl_add_u64 v[116:117], s[16:17], 0, v[116:117]
	v_ashrrev_i32_e32 v199, 31, v198
	v_lshl_add_u64 v[200:201], v[116:117], 0, v[114:115]
	v_lshlrev_b64 v[116:117], 13, v[198:199]
	v_lshl_add_u64 v[116:117], s[16:17], 0, v[116:117]
	v_lshl_add_u64 v[202:203], v[116:117], 0, v[114:115]
	global_load_dwordx4 v[230:233], v[200:201], off offset:16
	global_load_dwordx4 v[234:237], v[200:201], off
	global_load_dwordx4 v[238:241], v[200:201], off offset:528
	global_load_dwordx4 v[242:245], v[200:201], off offset:512
	global_load_dwordx4 v[154:157], v[202:203], off offset:16
	global_load_dwordx4 v[158:161], v[202:203], off
	global_load_dwordx4 v[146:149], v[202:203], off offset:528
	global_load_dwordx4 v[150:153], v[202:203], off offset:512
	global_load_dwordx4 v[114:117], v[122:123], off offset:528
	s_nop 0
	global_load_dwordx4 v[122:125], v[122:123], off offset:512
	s_lshl_b32 s34, s12, 2
	s_ashr_i32 s35, s34, 31
	s_waitcnt vmcnt(0)
	v_pk_add_f32 v[190:191], v[190:191], 1.0 op_sel_hi:[1,0]
	v_pk_add_f32 v[194:195], v[194:195], 1.0 op_sel_hi:[1,0]
	v_pk_add_f32 v[204:205], v[192:193], 1.0 op_sel_hi:[1,0]
	v_pk_add_f32 v[246:247], v[188:189], 1.0 op_sel_hi:[1,0]
	v_pk_add_f32 v[224:225], v[224:225], 1.0 op_sel_hi:[1,0]
	v_pk_add_f32 v[228:229], v[228:229], 1.0 op_sel_hi:[1,0]
	v_pk_add_f32 v[226:227], v[226:227], 1.0 op_sel_hi:[1,0]
	v_pk_add_f32 v[222:223], v[222:223], 1.0 op_sel_hi:[1,0]
	v_pk_mul_f32 v[192:193], v[186:187], v[194:195]
	v_pk_mul_f32 v[194:195], v[184:185], v[204:205]
	v_pk_mul_f32 v[188:189], v[182:183], v[190:191]
	v_pk_mul_f32 v[190:191], v[180:181], v[246:247]
	v_pk_mul_f32 v[186:187], v[220:221], v[228:229]
	v_pk_mul_f32 v[184:185], v[218:219], v[226:227]
	v_pk_mul_f32 v[180:181], v[216:217], v[224:225]
	v_pk_mul_f32 v[182:183], v[214:215], v[222:223]
	v_pk_fma_f32 v[144:145], v[144:145], v[128:129], v[236:237]
	v_pk_fma_f32 v[142:143], v[142:143], v[126:127], v[234:235]
	v_mul_f32_e32 v205, v145, v145
	v_mul_f32_e32 v204, v143, v143
	v_pk_fma_f32 v[138:139], v[138:139], v[118:119], v[230:231]
	v_fmac_f32_e32 v204, v142, v142
	v_fmac_f32_e32 v205, v144, v144
	v_add_f32_e32 v204, v204, v205
	v_mul_f32_e32 v205, v139, v139
	v_pk_fma_f32 v[140:141], v[140:141], v[120:121], v[232:233]
	v_fmac_f32_e32 v205, v138, v138
	v_add_f32_e32 v204, v204, v205
	v_mul_f32_e32 v205, v141, v141
	global_store_dwordx4 v[200:201], v[142:145], off
	global_store_dwordx4 v[200:201], v[138:141], off offset:16
	v_fmac_f32_e32 v205, v140, v140
	v_pk_mul_f32 v[142:143], v[194:195], v[142:143]
	v_add_f32_e32 v213, v205, v204
	v_pk_mul_f32 v[204:205], v[188:189], v[140:141]
	v_pk_mul_f32 v[140:141], v[190:191], v[138:139]
	v_cvt_pk_bf16_f32 v138, v142, v143
	v_lshlrev_b64 v[142:143], 12, v[196:197]
	v_lshl_add_u64 v[142:143], s[18:19], 0, v[142:143]
	v_pk_mul_f32 v[144:145], v[192:193], v[144:145]
	v_lshl_add_u64 v[142:143], v[178:179], 1, v[142:143]
	v_cvt_pk_bf16_f32 v139, v144, v145
	v_pk_fma_f32 v[136:137], v[136:137], v[124:125], v[244:245]
	v_pk_fma_f32 v[134:135], v[134:135], v[122:123], v[242:243]
	v_cvt_pk_bf16_f32 v140, v140, v141
	v_cvt_pk_bf16_f32 v141, v204, v205
	global_store_dwordx4 v[142:143], v[138:141], off
	v_pk_fma_f32 v[130:131], v[130:131], v[114:115], v[238:239]
	v_pk_fma_f32 v[132:133], v[132:133], v[116:117], v[240:241]
	v_mul_f32_e32 v138, v135, v135
	v_mul_f32_e32 v139, v137, v137
	v_fmac_f32_e32 v138, v134, v134
	v_fmac_f32_e32 v139, v136, v136
	v_add_f32_e32 v138, v138, v139
	v_mul_f32_e32 v139, v131, v131
	v_fmac_f32_e32 v139, v130, v130
	v_add_f32_e32 v138, v138, v139
	v_mul_f32_e32 v139, v133, v133
	v_fmac_f32_e32 v139, v132, v132
	v_add_f32_e32 v138, v139, v138
	v_and_b32_e32 v139, 64, v212
	v_add_f32_e32 v144, v213, v138
	v_xor_b32_e32 v138, 16, v212
	v_add_u32_e32 v145, 64, v139
	v_cmp_lt_i32_e32 vcc, v138, v145
	global_store_dwordx4 v[200:201], v[134:137], off offset:512
	global_store_dwordx4 v[200:201], v[130:133], off offset:528
	v_cndmask_b32_e32 v138, v212, v138, vcc
	v_lshlrev_b32_e32 v213, 2, v138
	ds_bpermute_b32 v200, v213, v144
	v_pk_mul_f32 v[140:141], v[182:183], v[130:131]
	v_xor_b32_e32 v131, 32, v212
	v_cmp_lt_i32_e32 vcc, v131, v145
	v_pk_mul_f32 v[134:135], v[184:185], v[134:135]
	s_waitcnt lgkmcnt(0)
	v_add_f32_e32 v130, v144, v200
	v_cndmask_b32_e32 v131, v212, v131, vcc
	v_lshlrev_b32_e32 v214, 2, v131
	ds_bpermute_b32 v131, v214, v130
	v_pk_mul_f32 v[136:137], v[186:187], v[136:137]
	v_pk_mul_f32 v[138:139], v[180:181], v[132:133]
	v_cvt_pk_bf16_f32 v132, v134, v135
	v_cvt_pk_bf16_f32 v133, v136, v137
	v_cvt_pk_bf16_f32 v134, v140, v141
	s_nop 0
	v_cvt_pk_bf16_f32 v135, v138, v139
	global_store_dwordx4 v[142:143], v[132:135], off offset:256
	s_and_saveexec_b64 s[36:37], s[0:1]
	s_cbranch_execz .LBB0_3037
	s_waitcnt lgkmcnt(0)
	v_add_f32_e32 v132, v130, v131
	v_lshlrev_b64 v[130:131], 7, v[196:197]
	v_lshl_add_u64 v[130:131], s[22:23], 0, v[130:131]
	v_lshl_add_u64 v[130:131], s[34:35], 2, v[130:131]
	s_lshl_b32 s12, s57, 2
	v_lshl_add_u64 v[130:131], v[130:131], 0, s[12:13]
	global_store_dword v[130:131], v132, off
.LBB0_3037:
	s_or_b64 exec, exec, s[36:37]
	v_or_b32_e32 v200, 32, v196
	v_ashrrev_i32_e32 v201, 31, v200
	s_waitcnt lgkmcnt(0)
	v_lshlrev_b64 v[130:131], 13, v[200:201]
	v_lshl_add_u64 v[130:131], s[16:17], 0, v[130:131]
	v_lshl_add_u64 v[204:205], v[178:179], 2, v[130:131]
	global_load_dwordx4 v[138:141], v[204:205], off offset:16
	global_load_dwordx4 v[142:145], v[204:205], off
	global_load_dwordx4 v[130:133], v[204:205], off offset:528
	global_load_dwordx4 v[134:137], v[204:205], off offset:512
	v_pk_fma_f32 v[112:113], v[112:113], v[128:129], v[160:161]
	v_pk_fma_f32 v[110:111], v[110:111], v[126:127], v[158:159]
	v_pk_fma_f32 v[106:107], v[106:107], v[118:119], v[154:155]
	v_mul_f32_e32 v154, v111, v111
	v_mul_f32_e32 v155, v113, v113
	v_fmac_f32_e32 v154, v110, v110
	v_fmac_f32_e32 v155, v112, v112
	v_add_f32_e32 v154, v154, v155
	v_mul_f32_e32 v155, v107, v107
	v_pk_fma_f32 v[108:109], v[108:109], v[120:121], v[156:157]
	v_fmac_f32_e32 v155, v106, v106
	v_add_f32_e32 v154, v154, v155
	v_mul_f32_e32 v155, v109, v109
	global_store_dwordx4 v[202:203], v[110:113], off
	global_store_dwordx4 v[202:203], v[106:109], off offset:16
	v_fmac_f32_e32 v155, v108, v108
	v_pk_mul_f32 v[110:111], v[194:195], v[110:111]
	v_add_f32_e32 v156, v155, v154
	v_pk_mul_f32 v[154:155], v[188:189], v[108:109]
	v_pk_mul_f32 v[108:109], v[190:191], v[106:107]
	v_cvt_pk_bf16_f32 v106, v110, v111
	v_lshlrev_b64 v[110:111], 12, v[198:199]
	v_lshl_add_u64 v[110:111], s[18:19], 0, v[110:111]
	v_pk_mul_f32 v[112:113], v[192:193], v[112:113]
	v_lshl_add_u64 v[110:111], v[178:179], 1, v[110:111]
	v_cvt_pk_bf16_f32 v107, v112, v113
	v_pk_fma_f32 v[104:105], v[104:105], v[124:125], v[152:153]
	v_pk_fma_f32 v[102:103], v[102:103], v[122:123], v[150:151]
	v_cvt_pk_bf16_f32 v108, v108, v109
	v_cvt_pk_bf16_f32 v109, v154, v155
	global_store_dwordx4 v[110:111], v[106:109], off
	v_pk_fma_f32 v[98:99], v[98:99], v[114:115], v[146:147]
	v_pk_fma_f32 v[100:101], v[100:101], v[116:117], v[148:149]
	v_mul_f32_e32 v106, v103, v103
	v_mul_f32_e32 v107, v105, v105
	v_fmac_f32_e32 v106, v102, v102
	v_fmac_f32_e32 v107, v104, v104
	v_add_f32_e32 v106, v106, v107
	v_mul_f32_e32 v107, v99, v99
	v_fmac_f32_e32 v107, v98, v98
	v_add_f32_e32 v106, v106, v107
	v_mul_f32_e32 v107, v101, v101
	v_fmac_f32_e32 v107, v100, v100
	v_add_f32_e32 v106, v107, v106
	v_add_f32_e32 v112, v156, v106
	ds_bpermute_b32 v113, v213, v112
	global_store_dwordx4 v[202:203], v[102:105], off offset:512
	global_store_dwordx4 v[202:203], v[98:101], off offset:528
	v_pk_mul_f32 v[108:109], v[182:183], v[98:99]
	v_pk_mul_f32 v[102:103], v[184:185], v[102:103]
	v_pk_mul_f32 v[104:105], v[186:187], v[104:105]
	s_waitcnt lgkmcnt(0)
	v_add_f32_e32 v98, v112, v113
	ds_bpermute_b32 v99, v214, v98
	v_pk_mul_f32 v[106:107], v[180:181], v[100:101]
	v_cvt_pk_bf16_f32 v100, v102, v103
	v_cvt_pk_bf16_f32 v101, v104, v105
	v_cvt_pk_bf16_f32 v102, v108, v109
	s_nop 0
	v_cvt_pk_bf16_f32 v103, v106, v107
	global_store_dwordx4 v[110:111], v[100:103], off offset:256
	s_and_saveexec_b64 s[36:37], s[0:1]
	s_cbranch_execz .LBB0_3039
	s_waitcnt lgkmcnt(0)
	v_add_f32_e32 v100, v98, v99
	v_lshlrev_b64 v[98:99], 7, v[198:199]
	v_lshl_add_u64 v[98:99], s[22:23], 0, v[98:99]
	v_lshl_add_u64 v[98:99], s[34:35], 2, v[98:99]
	s_lshl_b32 s12, s57, 2
	v_lshl_add_u64 v[98:99], v[98:99], 0, s[12:13]
	global_store_dword v[98:99], v100, off
.LBB0_3039:
	s_or_b64 exec, exec, s[36:37]
	v_or_b32_e32 v146, 48, v196
	v_ashrrev_i32_e32 v147, 31, v146
	s_waitcnt lgkmcnt(0)
	v_lshlrev_b64 v[98:99], 13, v[146:147]
	v_lshl_add_u64 v[98:99], s[16:17], 0, v[98:99]
	v_lshl_add_u64 v[148:149], v[178:179], 2, v[98:99]
	global_load_dwordx4 v[106:109], v[148:149], off offset:16
	global_load_dwordx4 v[110:113], v[148:149], off
	global_load_dwordx4 v[98:101], v[148:149], off offset:528
	global_load_dwordx4 v[102:105], v[148:149], off offset:512
	s_waitcnt vmcnt(12)
	v_pk_fma_f32 v[96:97], v[96:97], v[128:129], v[144:145]
	v_pk_fma_f32 v[94:95], v[94:95], v[126:127], v[142:143]
	v_pk_fma_f32 v[90:91], v[90:91], v[118:119], v[138:139]
	v_mul_f32_e32 v138, v95, v95
	v_mul_f32_e32 v139, v97, v97
	v_fmac_f32_e32 v138, v94, v94
	v_fmac_f32_e32 v139, v96, v96
	v_add_f32_e32 v138, v138, v139
	v_mul_f32_e32 v139, v91, v91
	v_pk_fma_f32 v[92:93], v[92:93], v[120:121], v[140:141]
	v_fmac_f32_e32 v139, v90, v90
	v_add_f32_e32 v138, v138, v139
	v_mul_f32_e32 v139, v93, v93
	global_store_dwordx4 v[204:205], v[94:97], off
	global_store_dwordx4 v[204:205], v[90:93], off offset:16
	v_fmac_f32_e32 v139, v92, v92
	v_pk_mul_f32 v[94:95], v[194:195], v[94:95]
	v_add_f32_e32 v140, v139, v138
	v_pk_mul_f32 v[138:139], v[188:189], v[92:93]
	v_pk_mul_f32 v[92:93], v[190:191], v[90:91]
	v_cvt_pk_bf16_f32 v90, v94, v95
	v_lshlrev_b64 v[94:95], 12, v[200:201]
	v_lshl_add_u64 v[94:95], s[18:19], 0, v[94:95]
	v_pk_mul_f32 v[96:97], v[192:193], v[96:97]
	v_lshl_add_u64 v[94:95], v[178:179], 1, v[94:95]
	v_cvt_pk_bf16_f32 v91, v96, v97
	s_waitcnt vmcnt(12)
	v_pk_fma_f32 v[88:89], v[88:89], v[124:125], v[136:137]
	v_pk_fma_f32 v[86:87], v[86:87], v[122:123], v[134:135]
	v_cvt_pk_bf16_f32 v92, v92, v93
	v_cvt_pk_bf16_f32 v93, v138, v139
	global_store_dwordx4 v[94:95], v[90:93], off
	v_pk_fma_f32 v[82:83], v[82:83], v[114:115], v[130:131]
	v_pk_fma_f32 v[84:85], v[84:85], v[116:117], v[132:133]
	v_mul_f32_e32 v90, v87, v87
	v_mul_f32_e32 v91, v89, v89
	v_fmac_f32_e32 v90, v86, v86
	v_fmac_f32_e32 v91, v88, v88
	v_add_f32_e32 v90, v90, v91
	v_mul_f32_e32 v91, v83, v83
	v_fmac_f32_e32 v91, v82, v82
	v_add_f32_e32 v90, v90, v91
	v_mul_f32_e32 v91, v85, v85
	v_fmac_f32_e32 v91, v84, v84
	v_add_f32_e32 v90, v91, v90
	v_add_f32_e32 v96, v140, v90
	ds_bpermute_b32 v97, v213, v96
	global_store_dwordx4 v[204:205], v[86:89], off offset:512
	global_store_dwordx4 v[204:205], v[82:85], off offset:528
	v_pk_mul_f32 v[92:93], v[182:183], v[82:83]
	v_pk_mul_f32 v[86:87], v[184:185], v[86:87]
	v_pk_mul_f32 v[88:89], v[186:187], v[88:89]
	s_waitcnt lgkmcnt(0)
	v_add_f32_e32 v82, v96, v97
	ds_bpermute_b32 v83, v214, v82
	v_pk_mul_f32 v[90:91], v[180:181], v[84:85]
	v_cvt_pk_bf16_f32 v84, v86, v87
	v_cvt_pk_bf16_f32 v85, v88, v89
	v_cvt_pk_bf16_f32 v86, v92, v93
	s_nop 0
	v_cvt_pk_bf16_f32 v87, v90, v91
	global_store_dwordx4 v[94:95], v[84:87], off offset:256
	s_and_saveexec_b64 s[36:37], s[0:1]
	s_cbranch_execz .LBB0_3041
	s_waitcnt lgkmcnt(0)
	v_add_f32_e32 v84, v82, v83
	v_lshlrev_b64 v[82:83], 7, v[200:201]
	v_lshl_add_u64 v[82:83], s[22:23], 0, v[82:83]
	v_lshl_add_u64 v[82:83], s[34:35], 2, v[82:83]
	s_lshl_b32 s12, s57, 2
	v_lshl_add_u64 v[82:83], v[82:83], 0, s[12:13]
	global_store_dword v[82:83], v84, off
.LBB0_3041:
	s_or_b64 exec, exec, s[36:37]
	v_add_u32_e32 v130, 0x80, v196
	v_ashrrev_i32_e32 v131, 31, v130
	s_waitcnt lgkmcnt(0)
	v_lshlrev_b64 v[82:83], 13, v[130:131]
	v_lshl_add_u64 v[82:83], s[16:17], 0, v[82:83]
	v_lshl_add_u64 v[132:133], v[178:179], 2, v[82:83]
	global_load_dwordx4 v[90:93], v[132:133], off offset:16
	global_load_dwordx4 v[94:97], v[132:133], off
	global_load_dwordx4 v[82:85], v[132:133], off offset:528
	global_load_dwordx4 v[86:89], v[132:133], off offset:512
	s_waitcnt vmcnt(12)
	v_pk_fma_f32 v[80:81], v[80:81], v[128:129], v[112:113]
	v_pk_fma_f32 v[78:79], v[78:79], v[126:127], v[110:111]
	v_pk_fma_f32 v[74:75], v[74:75], v[118:119], v[106:107]
	v_mul_f32_e32 v106, v79, v79
	v_mul_f32_e32 v107, v81, v81
	v_fmac_f32_e32 v106, v78, v78
	v_fmac_f32_e32 v107, v80, v80
	v_add_f32_e32 v106, v106, v107
	v_mul_f32_e32 v107, v75, v75
	v_pk_fma_f32 v[76:77], v[76:77], v[120:121], v[108:109]
	v_fmac_f32_e32 v107, v74, v74
	v_add_f32_e32 v106, v106, v107
	v_mul_f32_e32 v107, v77, v77
	global_store_dwordx4 v[148:149], v[78:81], off
	global_store_dwordx4 v[148:149], v[74:77], off offset:16
	v_fmac_f32_e32 v107, v76, v76
	v_pk_mul_f32 v[78:79], v[194:195], v[78:79]
	v_add_f32_e32 v108, v107, v106
	v_pk_mul_f32 v[106:107], v[188:189], v[76:77]
	v_pk_mul_f32 v[76:77], v[190:191], v[74:75]
	v_cvt_pk_bf16_f32 v74, v78, v79
	v_lshlrev_b64 v[78:79], 12, v[146:147]
	v_lshl_add_u64 v[78:79], s[18:19], 0, v[78:79]
	v_pk_mul_f32 v[80:81], v[192:193], v[80:81]
	v_lshl_add_u64 v[78:79], v[178:179], 1, v[78:79]
	v_cvt_pk_bf16_f32 v75, v80, v81
	s_waitcnt vmcnt(12)
	v_pk_fma_f32 v[72:73], v[72:73], v[124:125], v[104:105]
	v_pk_fma_f32 v[70:71], v[70:71], v[122:123], v[102:103]
	v_cvt_pk_bf16_f32 v76, v76, v77
	v_cvt_pk_bf16_f32 v77, v106, v107
	global_store_dwordx4 v[78:79], v[74:77], off
	v_pk_fma_f32 v[66:67], v[66:67], v[114:115], v[98:99]
	v_pk_fma_f32 v[68:69], v[68:69], v[116:117], v[100:101]
	v_mul_f32_e32 v74, v71, v71
	v_mul_f32_e32 v75, v73, v73
	v_fmac_f32_e32 v74, v70, v70
	v_fmac_f32_e32 v75, v72, v72
	v_add_f32_e32 v74, v74, v75
	v_mul_f32_e32 v75, v67, v67
	v_fmac_f32_e32 v75, v66, v66
	v_add_f32_e32 v74, v74, v75
	v_mul_f32_e32 v75, v69, v69
	v_fmac_f32_e32 v75, v68, v68
	v_add_f32_e32 v74, v75, v74
	v_add_f32_e32 v80, v108, v74
	ds_bpermute_b32 v81, v213, v80
	global_store_dwordx4 v[148:149], v[70:73], off offset:512
	global_store_dwordx4 v[148:149], v[66:69], off offset:528
	v_pk_mul_f32 v[76:77], v[182:183], v[66:67]
	v_pk_mul_f32 v[70:71], v[184:185], v[70:71]
	v_pk_mul_f32 v[72:73], v[186:187], v[72:73]
	s_waitcnt lgkmcnt(0)
	v_add_f32_e32 v66, v80, v81
	ds_bpermute_b32 v67, v214, v66
	v_pk_mul_f32 v[74:75], v[180:181], v[68:69]
	v_cvt_pk_bf16_f32 v68, v70, v71
	v_cvt_pk_bf16_f32 v69, v72, v73
	v_cvt_pk_bf16_f32 v70, v76, v77
	s_nop 0
	v_cvt_pk_bf16_f32 v71, v74, v75
	global_store_dwordx4 v[78:79], v[68:71], off offset:256
	s_and_saveexec_b64 s[36:37], s[0:1]
	s_cbranch_execz .LBB0_3043
	s_waitcnt lgkmcnt(0)
	v_add_f32_e32 v68, v66, v67
	v_lshlrev_b64 v[66:67], 7, v[146:147]
	v_lshl_add_u64 v[66:67], s[22:23], 0, v[66:67]
	v_lshl_add_u64 v[66:67], s[34:35], 2, v[66:67]
	s_lshl_b32 s12, s57, 2
	v_lshl_add_u64 v[66:67], v[66:67], 0, s[12:13]
	global_store_dword v[66:67], v68, off
.LBB0_3043:
	s_or_b64 exec, exec, s[36:37]
	v_or_b32_e32 v98, 16, v130
	v_ashrrev_i32_e32 v99, 31, v98
	s_waitcnt lgkmcnt(0)
	v_lshlrev_b64 v[66:67], 13, v[98:99]
	v_lshl_add_u64 v[66:67], s[16:17], 0, v[66:67]
	v_lshl_add_u64 v[100:101], v[178:179], 2, v[66:67]
	global_load_dwordx4 v[74:77], v[100:101], off offset:16
	global_load_dwordx4 v[78:81], v[100:101], off
	global_load_dwordx4 v[66:69], v[100:101], off offset:528
	global_load_dwordx4 v[70:73], v[100:101], off offset:512
	s_waitcnt vmcnt(12)
	v_pk_fma_f32 v[64:65], v[64:65], v[128:129], v[96:97]
	v_pk_fma_f32 v[62:63], v[62:63], v[126:127], v[94:95]
	v_pk_fma_f32 v[58:59], v[58:59], v[118:119], v[90:91]
	v_mul_f32_e32 v90, v63, v63
	v_mul_f32_e32 v91, v65, v65
	v_fmac_f32_e32 v90, v62, v62
	v_fmac_f32_e32 v91, v64, v64
	v_add_f32_e32 v90, v90, v91
	v_mul_f32_e32 v91, v59, v59
	v_pk_fma_f32 v[60:61], v[60:61], v[120:121], v[92:93]
	v_fmac_f32_e32 v91, v58, v58
	v_add_f32_e32 v90, v90, v91
	v_mul_f32_e32 v91, v61, v61
	global_store_dwordx4 v[132:133], v[62:65], off
	global_store_dwordx4 v[132:133], v[58:61], off offset:16
	v_fmac_f32_e32 v91, v60, v60
	v_pk_mul_f32 v[62:63], v[194:195], v[62:63]
	v_add_f32_e32 v92, v91, v90
	v_pk_mul_f32 v[90:91], v[188:189], v[60:61]
	v_pk_mul_f32 v[60:61], v[190:191], v[58:59]
	v_cvt_pk_bf16_f32 v58, v62, v63
	v_lshlrev_b64 v[62:63], 12, v[130:131]
	v_lshl_add_u64 v[62:63], s[18:19], 0, v[62:63]
	v_pk_mul_f32 v[64:65], v[192:193], v[64:65]
	v_lshl_add_u64 v[62:63], v[178:179], 1, v[62:63]
	v_cvt_pk_bf16_f32 v59, v64, v65
	s_waitcnt vmcnt(12)
	v_pk_fma_f32 v[56:57], v[56:57], v[124:125], v[88:89]
	v_pk_fma_f32 v[54:55], v[54:55], v[122:123], v[86:87]
	v_cvt_pk_bf16_f32 v60, v60, v61
	v_cvt_pk_bf16_f32 v61, v90, v91
	global_store_dwordx4 v[62:63], v[58:61], off
	v_pk_fma_f32 v[50:51], v[50:51], v[114:115], v[82:83]
	v_pk_fma_f32 v[52:53], v[52:53], v[116:117], v[84:85]
	v_mul_f32_e32 v58, v55, v55
	v_mul_f32_e32 v59, v57, v57
	v_fmac_f32_e32 v58, v54, v54
	v_fmac_f32_e32 v59, v56, v56
	v_add_f32_e32 v58, v58, v59
	v_mul_f32_e32 v59, v51, v51
	v_fmac_f32_e32 v59, v50, v50
	v_add_f32_e32 v58, v58, v59
	v_mul_f32_e32 v59, v53, v53
	v_fmac_f32_e32 v59, v52, v52
	v_add_f32_e32 v58, v59, v58
	v_add_f32_e32 v64, v92, v58
	ds_bpermute_b32 v65, v213, v64
	global_store_dwordx4 v[132:133], v[54:57], off offset:512
	global_store_dwordx4 v[132:133], v[50:53], off offset:528
	v_pk_mul_f32 v[60:61], v[182:183], v[50:51]
	v_pk_mul_f32 v[54:55], v[184:185], v[54:55]
	v_pk_mul_f32 v[56:57], v[186:187], v[56:57]
	s_waitcnt lgkmcnt(0)
	v_add_f32_e32 v50, v64, v65
	ds_bpermute_b32 v51, v214, v50
	v_pk_mul_f32 v[58:59], v[180:181], v[52:53]
	v_cvt_pk_bf16_f32 v52, v54, v55
	v_cvt_pk_bf16_f32 v53, v56, v57
	v_cvt_pk_bf16_f32 v54, v60, v61
	s_nop 0
	v_cvt_pk_bf16_f32 v55, v58, v59
	global_store_dwordx4 v[62:63], v[52:55], off offset:256
	s_and_saveexec_b64 s[36:37], s[0:1]
	s_cbranch_execz .LBB0_3045
	s_waitcnt lgkmcnt(0)
	v_add_f32_e32 v52, v50, v51
	v_lshlrev_b64 v[50:51], 7, v[130:131]
	v_lshl_add_u64 v[50:51], s[22:23], 0, v[50:51]
	v_lshl_add_u64 v[50:51], s[34:35], 2, v[50:51]
	s_lshl_b32 s12, s57, 2
	v_lshl_add_u64 v[50:51], v[50:51], 0, s[12:13]
	global_store_dword v[50:51], v52, off
.LBB0_3045:
	s_or_b64 exec, exec, s[36:37]
	v_or_b32_e32 v82, 32, v130
	v_ashrrev_i32_e32 v83, 31, v82
	s_waitcnt lgkmcnt(0)
	v_lshlrev_b64 v[50:51], 13, v[82:83]
	v_lshl_add_u64 v[50:51], s[16:17], 0, v[50:51]
	v_lshl_add_u64 v[84:85], v[178:179], 2, v[50:51]
	global_load_dwordx4 v[58:61], v[84:85], off offset:16
	global_load_dwordx4 v[62:65], v[84:85], off
	global_load_dwordx4 v[50:53], v[84:85], off offset:528
	global_load_dwordx4 v[54:57], v[84:85], off offset:512
	s_waitcnt vmcnt(12)
	v_pk_fma_f32 v[48:49], v[48:49], v[128:129], v[80:81]
	v_pk_fma_f32 v[46:47], v[46:47], v[126:127], v[78:79]
	v_pk_fma_f32 v[42:43], v[42:43], v[118:119], v[74:75]
	v_mul_f32_e32 v74, v47, v47
	v_mul_f32_e32 v75, v49, v49
	v_fmac_f32_e32 v74, v46, v46
	v_fmac_f32_e32 v75, v48, v48
	v_add_f32_e32 v74, v74, v75
	v_mul_f32_e32 v75, v43, v43
	v_pk_fma_f32 v[44:45], v[44:45], v[120:121], v[76:77]
	v_fmac_f32_e32 v75, v42, v42
	v_add_f32_e32 v74, v74, v75
	v_mul_f32_e32 v75, v45, v45
	global_store_dwordx4 v[100:101], v[46:49], off
	global_store_dwordx4 v[100:101], v[42:45], off offset:16
	v_fmac_f32_e32 v75, v44, v44
	v_pk_mul_f32 v[46:47], v[194:195], v[46:47]
	v_add_f32_e32 v76, v75, v74
	v_pk_mul_f32 v[74:75], v[188:189], v[44:45]
	v_pk_mul_f32 v[44:45], v[190:191], v[42:43]
	v_cvt_pk_bf16_f32 v42, v46, v47
	v_lshlrev_b64 v[46:47], 12, v[98:99]
	v_lshl_add_u64 v[46:47], s[18:19], 0, v[46:47]
	v_pk_mul_f32 v[48:49], v[192:193], v[48:49]
	v_lshl_add_u64 v[46:47], v[178:179], 1, v[46:47]
	v_cvt_pk_bf16_f32 v43, v48, v49
	s_waitcnt vmcnt(12)
	v_pk_fma_f32 v[40:41], v[40:41], v[124:125], v[72:73]
	v_pk_fma_f32 v[38:39], v[38:39], v[122:123], v[70:71]
	v_cvt_pk_bf16_f32 v44, v44, v45
	v_cvt_pk_bf16_f32 v45, v74, v75
	global_store_dwordx4 v[46:47], v[42:45], off
	v_pk_fma_f32 v[34:35], v[34:35], v[114:115], v[66:67]
	v_pk_fma_f32 v[36:37], v[36:37], v[116:117], v[68:69]
	v_mul_f32_e32 v42, v39, v39
	v_mul_f32_e32 v43, v41, v41
	v_fmac_f32_e32 v42, v38, v38
	v_fmac_f32_e32 v43, v40, v40
	v_add_f32_e32 v42, v42, v43
	v_mul_f32_e32 v43, v35, v35
	v_fmac_f32_e32 v43, v34, v34
	v_add_f32_e32 v42, v42, v43
	v_mul_f32_e32 v43, v37, v37
	v_fmac_f32_e32 v43, v36, v36
	v_add_f32_e32 v42, v43, v42
	v_add_f32_e32 v48, v76, v42
	ds_bpermute_b32 v49, v213, v48
	global_store_dwordx4 v[100:101], v[38:41], off offset:512
	global_store_dwordx4 v[100:101], v[34:37], off offset:528
	v_pk_mul_f32 v[44:45], v[182:183], v[34:35]
	v_pk_mul_f32 v[38:39], v[184:185], v[38:39]
	v_pk_mul_f32 v[40:41], v[186:187], v[40:41]
	s_waitcnt lgkmcnt(0)
	v_add_f32_e32 v34, v48, v49
	ds_bpermute_b32 v35, v214, v34
	v_pk_mul_f32 v[42:43], v[180:181], v[36:37]
	v_cvt_pk_bf16_f32 v36, v38, v39
	v_cvt_pk_bf16_f32 v37, v40, v41
	v_cvt_pk_bf16_f32 v38, v44, v45
	s_nop 0
	v_cvt_pk_bf16_f32 v39, v42, v43
	global_store_dwordx4 v[46:47], v[36:39], off offset:256
	s_and_saveexec_b64 s[36:37], s[0:1]
	s_cbranch_execz .LBB0_3047
	s_waitcnt lgkmcnt(0)
	v_add_f32_e32 v36, v34, v35
	v_lshlrev_b64 v[34:35], 7, v[98:99]
	v_lshl_add_u64 v[34:35], s[22:23], 0, v[34:35]
	v_lshl_add_u64 v[34:35], s[34:35], 2, v[34:35]
	s_lshl_b32 s12, s57, 2
	v_lshl_add_u64 v[34:35], v[34:35], 0, s[12:13]
	global_store_dword v[34:35], v36, off
.LBB0_3047:
	s_or_b64 exec, exec, s[36:37]
	v_or_b32_e32 v66, 48, v130
	v_ashrrev_i32_e32 v67, 31, v66
	s_waitcnt lgkmcnt(0)
	v_lshlrev_b64 v[34:35], 13, v[66:67]
	v_lshl_add_u64 v[34:35], s[16:17], 0, v[34:35]
	v_lshl_add_u64 v[68:69], v[178:179], 2, v[34:35]
	global_load_dwordx4 v[42:45], v[68:69], off offset:16
	global_load_dwordx4 v[46:49], v[68:69], off
	global_load_dwordx4 v[34:37], v[68:69], off offset:528
	global_load_dwordx4 v[38:41], v[68:69], off offset:512
	s_waitcnt vmcnt(12)
	v_pk_fma_f32 v[32:33], v[32:33], v[128:129], v[64:65]
	v_pk_fma_f32 v[30:31], v[30:31], v[126:127], v[62:63]
	v_pk_fma_f32 v[26:27], v[26:27], v[118:119], v[58:59]
	v_mul_f32_e32 v58, v31, v31
	v_mul_f32_e32 v59, v33, v33
	v_fmac_f32_e32 v58, v30, v30
	v_fmac_f32_e32 v59, v32, v32
	v_add_f32_e32 v58, v58, v59
	v_mul_f32_e32 v59, v27, v27
	v_pk_fma_f32 v[28:29], v[28:29], v[120:121], v[60:61]
	v_fmac_f32_e32 v59, v26, v26
	v_add_f32_e32 v58, v58, v59
	v_mul_f32_e32 v59, v29, v29
	global_store_dwordx4 v[84:85], v[30:33], off
	global_store_dwordx4 v[84:85], v[26:29], off offset:16
	v_fmac_f32_e32 v59, v28, v28
	v_pk_mul_f32 v[30:31], v[194:195], v[30:31]
	v_add_f32_e32 v60, v59, v58
	v_pk_mul_f32 v[58:59], v[188:189], v[28:29]
	v_pk_mul_f32 v[28:29], v[190:191], v[26:27]
	v_cvt_pk_bf16_f32 v26, v30, v31
	v_lshlrev_b64 v[30:31], 12, v[82:83]
	v_lshl_add_u64 v[30:31], s[18:19], 0, v[30:31]
	v_pk_mul_f32 v[32:33], v[192:193], v[32:33]
	v_lshl_add_u64 v[30:31], v[178:179], 1, v[30:31]
	v_cvt_pk_bf16_f32 v27, v32, v33
	s_waitcnt vmcnt(12)
	v_pk_fma_f32 v[24:25], v[24:25], v[124:125], v[56:57]
	v_pk_fma_f32 v[22:23], v[22:23], v[122:123], v[54:55]
	v_cvt_pk_bf16_f32 v28, v28, v29
	v_cvt_pk_bf16_f32 v29, v58, v59
	global_store_dwordx4 v[30:31], v[26:29], off
	v_pk_fma_f32 v[18:19], v[18:19], v[114:115], v[50:51]
	v_pk_fma_f32 v[20:21], v[20:21], v[116:117], v[52:53]
	v_mul_f32_e32 v26, v23, v23
	v_mul_f32_e32 v27, v25, v25
	v_fmac_f32_e32 v26, v22, v22
	v_fmac_f32_e32 v27, v24, v24
	v_add_f32_e32 v26, v26, v27
	v_mul_f32_e32 v27, v19, v19
	v_fmac_f32_e32 v27, v18, v18
	v_add_f32_e32 v26, v26, v27
	v_mul_f32_e32 v27, v21, v21
	v_fmac_f32_e32 v27, v20, v20
	v_add_f32_e32 v26, v27, v26
	v_add_f32_e32 v32, v60, v26
	ds_bpermute_b32 v33, v213, v32
	global_store_dwordx4 v[84:85], v[22:25], off offset:512
	global_store_dwordx4 v[84:85], v[18:21], off offset:528
	v_pk_mul_f32 v[28:29], v[182:183], v[18:19]
	v_pk_mul_f32 v[22:23], v[184:185], v[22:23]
	v_pk_mul_f32 v[24:25], v[186:187], v[24:25]
	s_waitcnt lgkmcnt(0)
	v_add_f32_e32 v18, v32, v33
	ds_bpermute_b32 v19, v214, v18
	v_pk_mul_f32 v[26:27], v[180:181], v[20:21]
	v_cvt_pk_bf16_f32 v20, v22, v23
	v_cvt_pk_bf16_f32 v21, v24, v25
	v_cvt_pk_bf16_f32 v22, v28, v29
	s_nop 0
	v_cvt_pk_bf16_f32 v23, v26, v27
	global_store_dwordx4 v[30:31], v[20:23], off offset:256
	s_and_saveexec_b64 s[36:37], s[0:1]
	s_cbranch_execz .LBB0_3049
	s_waitcnt lgkmcnt(0)
	v_add_f32_e32 v20, v18, v19
	v_lshlrev_b64 v[18:19], 7, v[82:83]
	v_lshl_add_u64 v[18:19], s[22:23], 0, v[18:19]
	v_lshl_add_u64 v[18:19], s[34:35], 2, v[18:19]
	s_lshl_b32 s12, s57, 2
	v_lshl_add_u64 v[18:19], v[18:19], 0, s[12:13]
	global_store_dword v[18:19], v20, off
.LBB0_3049:
	s_or_b64 exec, exec, s[36:37]
	s_waitcnt vmcnt(8)
	v_pk_fma_f32 v[16:17], v[16:17], v[128:129], v[48:49]
	v_pk_fma_f32 v[14:15], v[14:15], v[126:127], v[46:47]
	s_waitcnt lgkmcnt(0)
	v_mul_f32_e32 v19, v17, v17
	v_mul_f32_e32 v18, v15, v15
	v_pk_fma_f32 v[10:11], v[10:11], v[118:119], v[42:43]
	v_fmac_f32_e32 v18, v14, v14
	v_fmac_f32_e32 v19, v16, v16
	v_add_f32_e32 v18, v18, v19
	v_mul_f32_e32 v19, v11, v11
	v_pk_fma_f32 v[12:13], v[12:13], v[120:121], v[44:45]
	v_fmac_f32_e32 v19, v10, v10
	v_add_f32_e32 v18, v18, v19
	v_mul_f32_e32 v19, v13, v13
	global_store_dwordx4 v[68:69], v[14:17], off
	global_store_dwordx4 v[68:69], v[10:13], off offset:16
	v_fmac_f32_e32 v19, v12, v12
	v_pk_mul_f32 v[14:15], v[194:195], v[14:15]
	v_add_f32_e32 v20, v19, v18
	v_pk_mul_f32 v[18:19], v[188:189], v[12:13]
	v_pk_mul_f32 v[12:13], v[190:191], v[10:11]
	v_cvt_pk_bf16_f32 v10, v14, v15
	v_lshlrev_b64 v[14:15], 12, v[66:67]
	v_lshl_add_u64 v[14:15], s[18:19], 0, v[14:15]
	v_pk_mul_f32 v[16:17], v[192:193], v[16:17]
	v_lshl_add_u64 v[14:15], v[178:179], 1, v[14:15]
	v_cvt_pk_bf16_f32 v11, v16, v17
	s_waitcnt vmcnt(8)
	v_pk_fma_f32 v[8:9], v[8:9], v[124:125], v[40:41]
	v_pk_fma_f32 v[6:7], v[6:7], v[122:123], v[38:39]
	v_cvt_pk_bf16_f32 v12, v12, v13
	v_cvt_pk_bf16_f32 v13, v18, v19
	global_store_dwordx4 v[14:15], v[10:13], off
	v_pk_fma_f32 v[2:3], v[2:3], v[114:115], v[34:35]
	v_pk_fma_f32 v[4:5], v[4:5], v[116:117], v[36:37]
	v_mul_f32_e32 v10, v7, v7
	v_mul_f32_e32 v11, v9, v9
	v_fmac_f32_e32 v10, v6, v6
	v_fmac_f32_e32 v11, v8, v8
	v_add_f32_e32 v10, v10, v11
	v_mul_f32_e32 v11, v3, v3
	v_fmac_f32_e32 v11, v2, v2
	v_add_f32_e32 v10, v10, v11
	v_mul_f32_e32 v11, v5, v5
	v_fmac_f32_e32 v11, v4, v4
	v_add_f32_e32 v10, v11, v10
	v_add_f32_e32 v16, v20, v10
	ds_bpermute_b32 v17, v213, v16
	global_store_dwordx4 v[68:69], v[6:9], off offset:512
	global_store_dwordx4 v[68:69], v[2:5], off offset:528
	v_pk_mul_f32 v[12:13], v[182:183], v[2:3]
	v_pk_mul_f32 v[6:7], v[184:185], v[6:7]
	v_pk_mul_f32 v[8:9], v[186:187], v[8:9]
	s_waitcnt lgkmcnt(0)
	v_add_f32_e32 v2, v16, v17
	ds_bpermute_b32 v3, v214, v2
	v_pk_mul_f32 v[10:11], v[180:181], v[4:5]
	v_cvt_pk_bf16_f32 v4, v6, v7
	v_cvt_pk_bf16_f32 v5, v8, v9
	v_cvt_pk_bf16_f32 v6, v12, v13
	s_nop 0
	v_cvt_pk_bf16_f32 v7, v10, v11
	global_store_dwordx4 v[14:15], v[4:7], off offset:256
	s_and_saveexec_b64 s[36:37], s[0:1]
	s_cbranch_execz .LBB0_3051
	s_waitcnt lgkmcnt(0)
	v_add_f32_e32 v4, v2, v3
	v_lshlrev_b64 v[2:3], 7, v[66:67]
	v_lshl_add_u64 v[2:3], s[22:23], 0, v[2:3]
	v_lshl_add_u64 v[2:3], s[34:35], 2, v[2:3]
	s_lshl_b32 s12, s57, 2
	v_lshl_add_u64 v[2:3], v[2:3], 0, s[12:13]
	global_store_dword v[2:3], v4, off

.LBB0_3617:
	s_lshr_b32 s40, s69, 4
	s_add_i32 s40, s40, -1
	s_cmp_gt_i32 s69, 31
	s_cselect_b32 s40, s40, 0
	v_lshl_or_b32 v90, s12, 8, v230
	s_mul_i32 s43, s40, 0xc000
	s_mul_hi_i32 s42, s40, 0xc000
	s_add_u32 s40, s55, s43
	v_ashrrev_i32_e32 v91, 31, v90
	s_addc_u32 s41, s56, s42
	v_lshlrev_b64 v[36:37], 2, v[90:91]
	v_lshl_add_u64 v[26:27], s[40:41], 0, v[36:37]
	v_lshl_add_u64 v[28:29], s[20:21], 0, v[36:37]
	s_waitcnt lgkmcnt(0)
	global_load_dwordx4 v[2:5], v[26:27], off offset:16
	global_load_dwordx4 v[6:9], v[26:27], off
	global_load_dwordx4 v[10:13], v[28:29], off offset:16
	global_load_dwordx4 v[14:17], v[28:29], off
	s_add_u32 s40, s48, s43
	v_lshl_add_u64 v[30:31], s[24:25], 0, v[36:37]
	s_addc_u32 s41, s49, s42
	v_lshl_add_u64 v[32:33], s[40:41], 0, v[36:37]
	v_lshl_add_u32 v210, s69, 8, v228
	v_ashrrev_i32_e32 v211, 31, v210
	v_or_b32_e32 v34, 16, v210
	v_ashrrev_i32_e32 v35, 31, v34
	s_lshl_b32 s40, s12, 2
	s_ashr_i32 s41, s40, 31
	s_waitcnt vmcnt(0)
	v_pk_mul_f32 v[92:93], v[4:5], v[12:13]
	v_pk_mul_f32 v[86:87], v[8:9], v[16:17]
	v_pk_mul_f32 v[88:89], v[6:7], v[14:15]
	global_load_dwordx4 v[6:9], v[30:31], off offset:16
	global_load_dwordx4 v[14:17], v[30:31], off
	global_load_dwordx4 v[18:21], v[32:33], off offset:16
	global_load_dwordx4 v[22:25], v[32:33], off
	v_pk_mul_f32 v[94:95], v[2:3], v[10:11]
	s_waitcnt vmcnt(0)
	v_pk_add_f32 v[2:3], v[20:21], 1.0 op_sel_hi:[1,0]
	v_pk_add_f32 v[24:25], v[24:25], 1.0 op_sel_hi:[1,0]
	v_pk_add_f32 v[22:23], v[22:23], 1.0 op_sel_hi:[1,0]
	v_pk_add_f32 v[4:5], v[18:19], 1.0 op_sel_hi:[1,0]
	v_pk_mul_f32 v[78:79], v[16:17], v[24:25]
	v_pk_mul_f32 v[80:81], v[14:15], v[22:23]
	v_pk_mul_f32 v[82:83], v[8:9], v[2:3]
	v_pk_mul_f32 v[84:85], v[6:7], v[4:5]
	global_load_dwordx4 v[2:5], v[26:27], off offset:528
	global_load_dwordx4 v[6:9], v[26:27], off offset:512
	global_load_dwordx4 v[10:13], v[28:29], off offset:528
	global_load_dwordx4 v[14:17], v[28:29], off offset:512
	s_waitcnt vmcnt(0)
	v_pk_mul_f32 v[108:109], v[2:3], v[10:11]
	v_pk_mul_f32 v[104:105], v[8:9], v[16:17]
	v_pk_mul_f32 v[106:107], v[6:7], v[14:15]
	global_load_dwordx4 v[6:9], v[30:31], off offset:528
	global_load_dwordx4 v[14:17], v[30:31], off offset:512
	global_load_dwordx4 v[18:21], v[32:33], off offset:528
	global_load_dwordx4 v[22:25], v[32:33], off offset:512
	v_pk_mul_f32 v[110:111], v[4:5], v[12:13]
	s_waitcnt vmcnt(0)
	v_pk_add_f32 v[2:3], v[20:21], 1.0 op_sel_hi:[1,0]
	s_nop 0
	v_pk_mul_f32 v[100:101], v[8:9], v[2:3]
	v_lshlrev_b64 v[2:3], 13, v[210:211]
	v_lshl_add_u64 v[2:3], s[16:17], 0, v[2:3]
	v_lshl_add_u64 v[38:39], v[2:3], 0, v[36:37]
	v_lshlrev_b64 v[2:3], 13, v[34:35]
	v_lshl_add_u64 v[2:3], s[16:17], 0, v[2:3]
	v_pk_add_f32 v[24:25], v[24:25], 1.0 op_sel_hi:[1,0]
	v_pk_add_f32 v[22:23], v[22:23], 1.0 op_sel_hi:[1,0]
	v_pk_add_f32 v[4:5], v[18:19], 1.0 op_sel_hi:[1,0]
	v_lshl_add_u64 v[36:37], v[2:3], 0, v[36:37]
	v_pk_mul_f32 v[96:97], v[16:17], v[24:25]
	v_pk_mul_f32 v[98:99], v[14:15], v[22:23]
	v_pk_mul_f32 v[102:103], v[6:7], v[4:5]
	global_load_dwordx4 v[22:25], v[38:39], off offset:16
	global_load_dwordx4 v[30:33], v[38:39], off
	global_load_dwordx4 v[18:21], v[38:39], off offset:528
	global_load_dwordx4 v[26:29], v[38:39], off offset:512
	global_load_dwordx4 v[10:13], v[36:37], off offset:16
	global_load_dwordx4 v[14:17], v[36:37], off
	global_load_dwordx4 v[2:5], v[36:37], off offset:528
	global_load_dwordx4 v[6:9], v[36:37], off offset:512
	v_lshl_add_u64 v[196:197], v[210:211], 2, s[18:19]
	global_load_dword v40, v[196:197], off
	v_and_b32_e32 v44, 64, v232
	v_xor_b32_e32 v41, 16, v232
	v_add_u32_e32 v234, 64, v44
	v_cmp_lt_i32_e32 vcc, v41, v234
	v_lshlrev_b64 v[42:43], 12, v[210:211]
	v_lshl_add_u64 v[42:43], s[22:23], 0, v[42:43]
	v_cndmask_b32_e32 v41, v232, v41, vcc
	v_lshlrev_b32_e32 v233, 2, v41
	v_lshl_add_u64 v[42:43], v[90:91], 1, v[42:43]
	s_waitcnt vmcnt(0)
	v_pk_mul_f32 v[44:45], v[40:41], v[214:215] op_sel_hi:[0,1]
	v_pk_mul_f32 v[212:213], v[40:41], v[212:213] op_sel_hi:[0,1]
	v_pk_mul_f32 v[214:215], v[40:41], v[218:219] op_sel_hi:[0,1]
	v_pk_mul_f32 v[218:219], v[40:41], v[222:223] op_sel_hi:[0,1]
	v_pk_mul_f32 v[220:221], v[40:41], v[220:221] op_sel_hi:[0,1]
	v_pk_mul_f32 v[216:217], v[40:41], v[216:217] op_sel_hi:[0,1]
	v_pk_mul_f32 v[222:223], v[40:41], v[226:227] op_sel_hi:[0,1]
	v_pk_mul_f32 v[40:41], v[40:41], v[224:225] op_sel_hi:[0,1]
	v_pk_fma_f32 v[32:33], v[86:87], v[212:213], v[32:33]
	v_pk_fma_f32 v[30:31], v[88:89], v[44:45], v[30:31]
	v_pk_fma_f32 v[28:29], v[104:105], v[220:221], v[28:29]
	v_pk_fma_f32 v[26:27], v[106:107], v[218:219], v[26:27]
	v_pk_fma_f32 v[24:25], v[92:93], v[216:217], v[24:25]
	v_pk_fma_f32 v[22:23], v[94:95], v[214:215], v[22:23]
	v_pk_fma_f32 v[20:21], v[110:111], v[40:41], v[20:21]
	v_pk_fma_f32 v[18:19], v[108:109], v[222:223], v[18:19]
	global_store_dwordx4 v[38:39], v[30:33], off
	global_store_dwordx4 v[38:39], v[22:25], off offset:16
	v_mul_f32_e32 v224, v31, v31
	v_mul_f32_e32 v225, v33, v33
	v_pk_mul_f32 v[40:41], v[78:79], v[32:33]
	v_pk_mul_f32 v[44:45], v[80:81], v[30:31]
	v_mul_f32_e32 v31, v27, v27
	v_mul_f32_e32 v33, v29, v29
	v_mul_f32_e32 v226, v23, v23
	v_mul_f32_e32 v227, v25, v25
	v_mul_f32_e32 v235, v19, v19
	v_fmac_f32_e32 v224, v30, v30
	v_fmac_f32_e32 v225, v32, v32
	v_fmac_f32_e32 v31, v26, v26
	v_fmac_f32_e32 v33, v28, v28
	v_pk_mul_f32 v[212:213], v[82:83], v[24:25]
	v_pk_mul_f32 v[214:215], v[84:85], v[22:23]
	v_mul_f32_e32 v236, v21, v21
	v_pk_mul_f32 v[222:223], v[102:103], v[18:19]
	v_fmac_f32_e32 v226, v22, v22
	v_fmac_f32_e32 v227, v24, v24
	v_cvt_pk_bf16_f32 v22, v44, v45
	v_cvt_pk_bf16_f32 v23, v40, v41
	v_cvt_pk_bf16_f32 v24, v214, v215
	v_cvt_pk_bf16_f32 v25, v212, v213
	v_fmac_f32_e32 v235, v18, v18
	v_add_f32_e32 v30, v224, v225
	global_store_dwordx4 v[42:43], v[22:25], off
	v_lshlrev_b32_e32 v32, 16, v22
	v_and_b32_e32 v40, 0xffff0000, v22
	global_store_dwordx4 v[38:39], v[26:29], off offset:512
	global_store_dwordx4 v[38:39], v[18:21], off offset:528
	v_pk_mul_f32 v[220:221], v[100:101], v[20:21]
	v_fmac_f32_e32 v236, v20, v20
	v_add_f32_e32 v18, v31, v33
	v_lshlrev_b32_e32 v41, 16, v23
	v_and_b32_e32 v44, 0xffff0000, v23
	v_add_f32_e32 v19, v226, v30
	v_max3_f32 v20, |v32|, 0, |v40|
	v_add_f32_e32 v18, v235, v18
	v_lshlrev_b32_e32 v45, 16, v24
	v_and_b32_e32 v212, 0xffff0000, v24
	v_add_f32_e32 v19, v227, v19
	v_max3_f32 v20, v20, |v41|, |v44|
	v_add_f32_e32 v18, v236, v18
	v_lshlrev_b32_e32 v213, 16, v25
	v_and_b32_e32 v214, 0xffff0000, v25
	v_max3_f32 v20, v20, |v45|, |v212|
	v_add_f32_e32 v18, v19, v18
	v_pk_mul_f32 v[218:219], v[98:99], v[26:27]
	v_max3_f32 v19, v20, |v213|, |v214|
	v_cvt_pk_bf16_f32 v22, v218, v219
	ds_bpermute_b32 v20, v233, v18
	v_lshlrev_b32_e32 v21, 16, v22
	v_and_b32_e32 v26, 0xffff0000, v22
	v_pk_mul_f32 v[216:217], v[96:97], v[28:29]
	v_max3_f32 v19, v19, |v21|, |v26|
	v_cvt_pk_bf16_f32 v23, v216, v217
	v_cvt_pk_bf16_f32 v24, v222, v223
	v_cvt_pk_bf16_f32 v25, v220, v221
	s_waitcnt lgkmcnt(0)
	v_add_f32_e32 v18, v18, v20
	v_lshlrev_b32_e32 v27, 16, v23
	v_and_b32_e32 v28, 0xffff0000, v23
	v_lshlrev_b32_e32 v29, 16, v24
	v_and_b32_e32 v30, 0xffff0000, v24
	v_max3_f32 v19, v19, |v27|, |v28|
	v_max3_f32 v19, v19, |v29|, |v30|
	v_lshlrev_b32_e32 v21, 16, v25
	v_and_b32_e32 v26, 0xffff0000, v25
	v_max3_f32 v21, v19, |v21|, |v26|
	ds_bpermute_b32 v20, v233, v21
	v_xor_b32_e32 v19, 32, v232
	v_cmp_lt_i32_e32 vcc, v19, v234
	global_store_dwordx4 v[42:43], v[22:25], off offset:256
	s_waitcnt lgkmcnt(0)
	v_max_f32_e32 v20, v20, v20
	v_cndmask_b32_e32 v19, v232, v19, vcc
	v_lshlrev_b32_e32 v216, 2, v19
	v_max_f32_e32 v20, v21, v20
	ds_bpermute_b32 v19, v216, v18
	ds_bpermute_b32 v21, v216, v20
	s_and_saveexec_b64 s[42:43], s[0:1]
	s_cbranch_execz .LBB0_3619
	s_waitcnt lgkmcnt(0)
	v_max_f32_e32 v21, v21, v21
	v_max_f32_e32 v20, v20, v20
	v_add_f32_e32 v23, v18, v19
	v_lshlrev_b64 v[18:19], 7, v[210:211]
	v_max_f32_e32 v22, v20, v21
	v_lshl_add_u64 v[20:21], s[26:27], 0, v[18:19]
	s_lshl_b64 s[70:71], s[40:41], 2
	v_lshl_add_u64 v[18:19], s[28:29], 0, v[18:19]
	v_lshl_add_u64 v[20:21], v[20:21], 0, s[70:71]
	s_lshl_b32 s12, s59, 2
	v_lshl_add_u64 v[18:19], v[18:19], 0, s[70:71]
	v_lshl_add_u64 v[20:21], v[20:21], 0, s[12:13]
	v_lshl_add_u64 v[18:19], v[18:19], 0, s[12:13]
	global_store_dword v[20:21], v23, off
	global_store_dword v[18:19], v22, off
.LBB0_3619:
	s_or_b64 exec, exec, s[42:43]
	v_or_b32_e32 v212, 32, v210
	v_ashrrev_i32_e32 v213, 31, v212
	s_waitcnt lgkmcnt(1)
	v_lshlrev_b64 v[18:19], 13, v[212:213]
	v_lshl_add_u64 v[18:19], s[16:17], 0, v[18:19]
	v_lshl_add_u64 v[214:215], v[90:91], 2, v[18:19]
	global_load_dwordx4 v[26:29], v[214:215], off offset:16
	global_load_dwordx4 v[30:33], v[214:215], off
	s_waitcnt lgkmcnt(0)
	global_load_dwordx4 v[18:21], v[214:215], off offset:528
	global_load_dwordx4 v[22:25], v[214:215], off offset:512
	v_lshl_add_u64 v[38:39], v[34:35], 2, s[18:19]
	global_load_dword v38, v[38:39], off
	v_lshlrev_b64 v[40:41], 12, v[34:35]
	v_lshl_add_u64 v[40:41], s[22:23], 0, v[40:41]
	v_lshl_add_u64 v[40:41], v[90:91], 1, v[40:41]
	s_waitcnt vmcnt(0)
	v_pk_mul_f32 v[44:45], v[38:39], v[192:193] op_sel_hi:[0,1]
	v_pk_mul_f32 v[192:193], v[38:39], v[200:201] op_sel_hi:[0,1]
	v_pk_mul_f32 v[42:43], v[38:39], v[194:195] op_sel_hi:[0,1]
	v_pk_mul_f32 v[194:195], v[38:39], v[198:199] op_sel_hi:[0,1]
	v_pk_mul_f32 v[198:199], v[38:39], v[206:207] op_sel_hi:[0,1]
	v_pk_mul_f32 v[200:201], v[38:39], v[202:203] op_sel_hi:[0,1]
	v_pk_fma_f32 v[10:11], v[94:95], v[192:193], v[10:11]
	v_pk_mul_f32 v[202:203], v[38:39], v[208:209] op_sel_hi:[0,1]
	v_pk_mul_f32 v[38:39], v[38:39], v[204:205] op_sel_hi:[0,1]
	v_pk_fma_f32 v[16:17], v[86:87], v[44:45], v[16:17]
	v_pk_fma_f32 v[14:15], v[88:89], v[42:43], v[14:15]
	v_pk_fma_f32 v[12:13], v[92:93], v[194:195], v[12:13]
	v_pk_fma_f32 v[8:9], v[104:105], v[200:201], v[8:9]
	v_pk_fma_f32 v[6:7], v[106:107], v[198:199], v[6:7]
	v_mul_f32_e32 v206, v11, v11
	v_pk_fma_f32 v[4:5], v[110:111], v[38:39], v[4:5]
	v_pk_fma_f32 v[2:3], v[108:109], v[202:203], v[2:3]
	global_store_dwordx4 v[36:37], v[14:17], off
	global_store_dwordx4 v[36:37], v[10:13], off offset:16
	v_mul_f32_e32 v204, v15, v15
	v_mul_f32_e32 v205, v17, v17
	v_mul_f32_e32 v207, v13, v13
	v_pk_mul_f32 v[38:39], v[78:79], v[16:17]
	v_pk_mul_f32 v[42:43], v[80:81], v[14:15]
	v_pk_mul_f32 v[192:193], v[84:85], v[10:11]
	v_mul_f32_e32 v15, v7, v7
	v_mul_f32_e32 v17, v9, v9
	v_fmac_f32_e32 v206, v10, v10
	v_cvt_pk_bf16_f32 v10, v42, v43
	v_pk_mul_f32 v[44:45], v[82:83], v[12:13]
	v_mul_f32_e32 v208, v3, v3
	v_mul_f32_e32 v209, v5, v5
	v_fmac_f32_e32 v204, v14, v14
	v_fmac_f32_e32 v205, v16, v16
	v_fmac_f32_e32 v207, v12, v12
	v_cvt_pk_bf16_f32 v11, v38, v39
	v_cvt_pk_bf16_f32 v12, v192, v193
	v_cvt_pk_bf16_f32 v13, v44, v45
	v_fmac_f32_e32 v15, v6, v6
	v_fmac_f32_e32 v17, v8, v8
	global_store_dwordx4 v[40:41], v[10:13], off
	v_lshlrev_b32_e32 v16, 16, v10
	v_pk_mul_f32 v[200:201], v[100:101], v[4:5]
	v_and_b32_e32 v10, 0xffff0000, v10
	v_pk_mul_f32 v[202:203], v[102:103], v[2:3]
	v_fmac_f32_e32 v208, v2, v2
	v_fmac_f32_e32 v209, v4, v4
	v_add_f32_e32 v14, v204, v205
	v_lshlrev_b32_e32 v38, 16, v11
	v_and_b32_e32 v11, 0xffff0000, v11
	global_store_dwordx4 v[36:37], v[6:9], off offset:512
	global_store_dwordx4 v[36:37], v[2:5], off offset:528
	v_lshlrev_b32_e32 v39, 16, v12
	v_and_b32_e32 v12, 0xffff0000, v12
	v_add_f32_e32 v2, v15, v17
	v_max3_f32 v4, |v16|, 0, |v10|
	v_add_f32_e32 v3, v206, v14
	v_add_f32_e32 v2, v208, v2
	v_max3_f32 v4, v4, |v38|, |v11|
	v_lshlrev_b32_e32 v42, 16, v13
	v_and_b32_e32 v13, 0xffff0000, v13
	v_add_f32_e32 v3, v207, v3
	v_add_f32_e32 v2, v209, v2
	v_max3_f32 v4, v4, |v39|, |v12|
	v_pk_mul_f32 v[198:199], v[98:99], v[6:7]
	v_add_f32_e32 v2, v3, v2
	v_cvt_pk_bf16_f32 v6, v198, v199
	v_max3_f32 v3, v4, |v42|, |v13|
	v_lshlrev_b32_e32 v5, 16, v6
	v_and_b32_e32 v10, 0xffff0000, v6
	v_pk_mul_f32 v[194:195], v[96:97], v[8:9]
	v_max3_f32 v3, v3, |v5|, |v10|
	v_cvt_pk_bf16_f32 v7, v194, v195
	v_cvt_pk_bf16_f32 v8, v202, v203
	v_cvt_pk_bf16_f32 v9, v200, v201
	ds_bpermute_b32 v4, v233, v2
	v_lshlrev_b32_e32 v14, 16, v7
	v_and_b32_e32 v15, 0xffff0000, v7
	v_lshlrev_b32_e32 v16, 16, v8
	v_and_b32_e32 v17, 0xffff0000, v8
	v_max3_f32 v3, v3, |v14|, |v15|
	v_lshlrev_b32_e32 v36, 16, v9
	v_and_b32_e32 v37, 0xffff0000, v9
	v_max3_f32 v3, v3, |v16|, |v17|
	v_max3_f32 v5, v3, |v36|, |v37|
	ds_bpermute_b32 v10, v233, v5
	s_waitcnt lgkmcnt(1)
	v_add_f32_e32 v2, v2, v4
	ds_bpermute_b32 v3, v216, v2
	global_store_dwordx4 v[40:41], v[6:9], off offset:256
	s_waitcnt lgkmcnt(1)
	v_max_f32_e32 v4, v10, v10
	v_max_f32_e32 v4, v5, v4
	ds_bpermute_b32 v5, v216, v4
	s_and_saveexec_b64 s[42:43], s[0:1]
	s_cbranch_execz .LBB0_3621
	s_waitcnt lgkmcnt(0)
	v_max_f32_e32 v5, v5, v5
	v_max_f32_e32 v4, v4, v4
	v_add_f32_e32 v7, v2, v3
	v_lshlrev_b64 v[2:3], 7, v[34:35]
	v_max_f32_e32 v6, v4, v5
	v_lshl_add_u64 v[4:5], s[26:27], 0, v[2:3]
	s_lshl_b64 s[70:71], s[40:41], 2
	v_lshl_add_u64 v[2:3], s[28:29], 0, v[2:3]
	v_lshl_add_u64 v[4:5], v[4:5], 0, s[70:71]
	s_lshl_b32 s12, s59, 2
	v_lshl_add_u64 v[2:3], v[2:3], 0, s[70:71]
	v_lshl_add_u64 v[4:5], v[4:5], 0, s[12:13]
	v_lshl_add_u64 v[2:3], v[2:3], 0, s[12:13]
	global_store_dword v[4:5], v7, off
	global_store_dword v[2:3], v6, off
.LBB0_3621:
	s_or_b64 exec, exec, s[42:43]
	v_or_b32_e32 v192, 48, v210
	v_ashrrev_i32_e32 v193, 31, v192
	s_waitcnt lgkmcnt(1)
	v_lshlrev_b64 v[2:3], 13, v[192:193]
	v_lshl_add_u64 v[2:3], s[16:17], 0, v[2:3]
	v_lshl_add_u64 v[194:195], v[90:91], 2, v[2:3]
	global_load_dwordx4 v[38:41], v[194:195], off offset:16
	global_load_dwordx4 v[42:45], v[194:195], off
	global_load_dwordx4 v[6:9], v[194:195], off offset:528
	global_load_dwordx4 v[34:37], v[194:195], off offset:512
	v_lshl_add_u64 v[2:3], v[212:213], 2, s[18:19]
	global_load_dword v2, v[2:3], off
	s_waitcnt lgkmcnt(0)
	v_lshlrev_b64 v[4:5], 12, v[212:213]
	v_lshl_add_u64 v[4:5], s[22:23], 0, v[4:5]
	v_lshl_add_u64 v[198:199], v[90:91], 1, v[4:5]
	s_waitcnt vmcnt(0)
	v_pk_mul_f32 v[10:11], v[2:3], v[178:179] op_sel_hi:[0,1]
	v_pk_mul_f32 v[4:5], v[2:3], v[176:177] op_sel_hi:[0,1]
	v_pk_mul_f32 v[14:15], v[2:3], v[182:183] op_sel_hi:[0,1]
	v_pk_mul_f32 v[12:13], v[2:3], v[180:181] op_sel_hi:[0,1]
	v_pk_mul_f32 v[176:177], v[2:3], v[188:189] op_sel_hi:[0,1]
	v_pk_mul_f32 v[16:17], v[2:3], v[184:185] op_sel_hi:[0,1]
	v_pk_mul_f32 v[178:179], v[2:3], v[190:191] op_sel_hi:[0,1]
	v_pk_mul_f32 v[180:181], v[2:3], v[186:187] op_sel_hi:[0,1]
	v_pk_fma_f32 v[2:3], v[88:89], v[10:11], v[30:31]
	v_pk_fma_f32 v[4:5], v[86:87], v[4:5], v[32:33]
	v_pk_fma_f32 v[20:21], v[110:111], v[180:181], v[20:21]
	v_mul_f32_e32 v180, v3, v3
	v_pk_fma_f32 v[12:13], v[92:93], v[12:13], v[28:29]
	v_pk_fma_f32 v[10:11], v[94:95], v[14:15], v[26:27]
	v_pk_fma_f32 v[16:17], v[104:105], v[16:17], v[24:25]
	v_pk_fma_f32 v[14:15], v[106:107], v[176:177], v[22:23]
	global_store_dwordx4 v[214:215], v[2:5], off
	global_store_dwordx4 v[214:215], v[10:13], off offset:16
	v_mul_f32_e32 v181, v5, v5
	v_pk_mul_f32 v[22:23], v[78:79], v[4:5]
	v_pk_mul_f32 v[24:25], v[80:81], v[2:3]
	v_fmac_f32_e32 v180, v2, v2
	v_cvt_pk_bf16_f32 v2, v24, v25
	v_pk_mul_f32 v[26:27], v[82:83], v[12:13]
	v_pk_mul_f32 v[28:29], v[84:85], v[10:11]
	v_fmac_f32_e32 v181, v4, v4
	v_cvt_pk_bf16_f32 v3, v22, v23
	v_cvt_pk_bf16_f32 v4, v28, v29
	v_cvt_pk_bf16_f32 v5, v26, v27
	global_store_dwordx4 v[198:199], v[2:5], off
	v_lshlrev_b32_e32 v23, 16, v2
	v_lshlrev_b32_e32 v24, 16, v3
	v_and_b32_e32 v2, 0xffff0000, v2
	v_and_b32_e32 v3, 0xffff0000, v3
	v_max3_f32 v2, |v23|, 0, |v2|
	v_lshlrev_b32_e32 v25, 16, v4
	v_and_b32_e32 v4, 0xffff0000, v4
	v_max3_f32 v2, v2, |v24|, |v3|
	v_pk_fma_f32 v[18:19], v[108:109], v[178:179], v[18:19]
	v_mul_f32_e32 v182, v11, v11
	v_mul_f32_e32 v183, v13, v13
	v_mul_f32_e32 v11, v15, v15
	v_mul_f32_e32 v13, v17, v17
	v_lshlrev_b32_e32 v26, 16, v5
	v_and_b32_e32 v5, 0xffff0000, v5
	v_max3_f32 v2, v2, |v25|, |v4|
	v_mul_f32_e32 v184, v19, v19
	v_pk_mul_f32 v[30:31], v[96:97], v[16:17]
	v_pk_mul_f32 v[32:33], v[98:99], v[14:15]
	v_fmac_f32_e32 v182, v10, v10
	v_fmac_f32_e32 v11, v14, v14
	v_fmac_f32_e32 v13, v16, v16
	global_store_dwordx4 v[214:215], v[14:17], off offset:512
	global_store_dwordx4 v[214:215], v[18:21], off offset:528
	v_cvt_pk_bf16_f32 v10, v32, v33
	v_max3_f32 v2, v2, |v26|, |v5|
	v_lshlrev_b32_e32 v16, 16, v10
	v_and_b32_e32 v17, 0xffff0000, v10
	v_mul_f32_e32 v185, v21, v21
	v_pk_mul_f32 v[178:179], v[102:103], v[18:19]
	v_fmac_f32_e32 v184, v18, v18
	v_add_f32_e32 v22, v180, v181
	v_add_f32_e32 v14, v11, v13
	v_cvt_pk_bf16_f32 v11, v30, v31
	v_max3_f32 v2, v2, |v16|, |v17|
	v_lshlrev_b32_e32 v18, 16, v11
	v_and_b32_e32 v19, 0xffff0000, v11
	v_pk_mul_f32 v[176:177], v[100:101], v[20:21]
	v_fmac_f32_e32 v183, v12, v12
	v_fmac_f32_e32 v185, v20, v20
	v_cvt_pk_bf16_f32 v12, v178, v179
	v_add_f32_e32 v15, v182, v22
	v_add_f32_e32 v14, v184, v14
	v_lshlrev_b32_e32 v20, 16, v12
	v_and_b32_e32 v21, 0xffff0000, v12
	v_max3_f32 v2, v2, |v18|, |v19|
	v_cvt_pk_bf16_f32 v13, v176, v177
	v_add_f32_e32 v15, v183, v15
	v_lshlrev_b32_e32 v22, 16, v13
	v_and_b32_e32 v23, 0xffff0000, v13
	v_add_f32_e32 v3, v185, v14
	v_max3_f32 v2, v2, |v20|, |v21|
	v_add_f32_e32 v3, v15, v3
	v_max3_f32 v5, v2, |v22|, |v23|
	ds_bpermute_b32 v4, v233, v3
	ds_bpermute_b32 v14, v233, v5
	global_store_dwordx4 v[198:199], v[10:13], off offset:256
	s_waitcnt lgkmcnt(1)
	v_add_f32_e32 v2, v3, v4
	s_waitcnt lgkmcnt(0)
	v_max_f32_e32 v4, v14, v14
	v_max_f32_e32 v4, v5, v4
	ds_bpermute_b32 v3, v216, v2
	ds_bpermute_b32 v5, v216, v4
	s_and_saveexec_b64 s[42:43], s[0:1]
	s_cbranch_execz .LBB0_3623
	s_waitcnt lgkmcnt(0)
	v_max_f32_e32 v5, v5, v5
	v_max_f32_e32 v4, v4, v4
	v_add_f32_e32 v11, v2, v3
	v_lshlrev_b64 v[2:3], 7, v[212:213]
	v_max_f32_e32 v10, v4, v5
	v_lshl_add_u64 v[4:5], s[26:27], 0, v[2:3]
	s_lshl_b64 s[70:71], s[40:41], 2
	v_lshl_add_u64 v[2:3], s[28:29], 0, v[2:3]
	v_lshl_add_u64 v[4:5], v[4:5], 0, s[70:71]
	s_lshl_b32 s12, s59, 2
	v_lshl_add_u64 v[2:3], v[2:3], 0, s[70:71]
	v_lshl_add_u64 v[4:5], v[4:5], 0, s[12:13]
	v_lshl_add_u64 v[2:3], v[2:3], 0, s[12:13]
	global_store_dword v[4:5], v11, off
	global_store_dword v[2:3], v10, off
.LBB0_3623:
	s_or_b64 exec, exec, s[42:43]
	v_add_u32_e32 v176, 0x80, v210
	v_ashrrev_i32_e32 v177, 31, v176
	s_waitcnt lgkmcnt(1)
	v_lshlrev_b64 v[2:3], 13, v[176:177]
	v_lshl_add_u64 v[2:3], s[16:17], 0, v[2:3]
	v_lshl_add_u64 v[178:179], v[90:91], 2, v[2:3]
	global_load_dwordx4 v[14:17], v[178:179], off offset:16
	global_load_dwordx4 v[18:21], v[178:179], off
	s_waitcnt lgkmcnt(0)
	global_load_dwordx4 v[2:5], v[178:179], off offset:528
	global_load_dwordx4 v[10:13], v[178:179], off offset:512
	v_lshl_add_u64 v[22:23], v[192:193], 2, s[18:19]
	global_load_dword v22, v[22:23], off
	v_lshlrev_b64 v[24:25], 12, v[192:193]
	v_lshl_add_u64 v[24:25], s[22:23], 0, v[24:25]
	v_lshl_add_u64 v[180:181], v[90:91], 1, v[24:25]
	s_waitcnt vmcnt(0)
	v_pk_mul_f32 v[26:27], v[22:23], v[162:163] op_sel_hi:[0,1]
	v_pk_mul_f32 v[24:25], v[22:23], v[160:161] op_sel_hi:[0,1]
	v_pk_mul_f32 v[30:31], v[22:23], v[166:167] op_sel_hi:[0,1]
	v_pk_mul_f32 v[28:29], v[22:23], v[164:165] op_sel_hi:[0,1]
	v_pk_mul_f32 v[160:161], v[22:23], v[172:173] op_sel_hi:[0,1]
	v_pk_mul_f32 v[32:33], v[22:23], v[168:169] op_sel_hi:[0,1]
	v_pk_mul_f32 v[162:163], v[22:23], v[174:175] op_sel_hi:[0,1]
	v_pk_mul_f32 v[164:165], v[22:23], v[170:171] op_sel_hi:[0,1]
	v_pk_fma_f32 v[24:25], v[86:87], v[24:25], v[44:45]
	v_pk_fma_f32 v[22:23], v[88:89], v[26:27], v[42:43]
	v_pk_fma_f32 v[28:29], v[92:93], v[28:29], v[40:41]
	v_pk_fma_f32 v[26:27], v[94:95], v[30:31], v[38:39]
	v_pk_fma_f32 v[32:33], v[104:105], v[32:33], v[36:37]
	v_pk_fma_f32 v[30:31], v[106:107], v[160:161], v[34:35]
	v_pk_fma_f32 v[8:9], v[110:111], v[164:165], v[8:9]
	v_pk_fma_f32 v[6:7], v[108:109], v[162:163], v[6:7]
	global_store_dwordx4 v[194:195], v[22:25], off
	global_store_dwordx4 v[194:195], v[26:29], off offset:16
	v_mul_f32_e32 v164, v23, v23
	v_mul_f32_e32 v165, v25, v25
	v_mul_f32_e32 v166, v27, v27
	v_mul_f32_e32 v167, v29, v29
	v_pk_mul_f32 v[34:35], v[78:79], v[24:25]
	v_pk_mul_f32 v[38:39], v[82:83], v[28:29]
	v_pk_mul_f32 v[40:41], v[84:85], v[26:27]
	v_mul_f32_e32 v27, v31, v31
	v_mul_f32_e32 v29, v33, v33
	v_pk_mul_f32 v[36:37], v[80:81], v[22:23]
	v_mul_f32_e32 v168, v7, v7
	v_mul_f32_e32 v169, v9, v9
	v_fmac_f32_e32 v164, v22, v22
	v_fmac_f32_e32 v165, v24, v24
	v_fmac_f32_e32 v167, v28, v28
	v_cvt_pk_bf16_f32 v22, v36, v37
	v_cvt_pk_bf16_f32 v23, v34, v35
	v_fmac_f32_e32 v27, v30, v30
	v_fmac_f32_e32 v29, v32, v32
	v_lshlrev_b32_e32 v28, 16, v22
	v_and_b32_e32 v34, 0xffff0000, v22
	v_pk_mul_f32 v[160:161], v[100:101], v[8:9]
	v_pk_mul_f32 v[162:163], v[102:103], v[6:7]
	v_fmac_f32_e32 v166, v26, v26
	v_cvt_pk_bf16_f32 v24, v40, v41
	v_cvt_pk_bf16_f32 v25, v38, v39
	v_fmac_f32_e32 v168, v6, v6
	v_fmac_f32_e32 v169, v8, v8
	v_add_f32_e32 v26, v164, v165
	global_store_dwordx4 v[180:181], v[22:25], off
	v_lshlrev_b32_e32 v35, 16, v23
	v_and_b32_e32 v36, 0xffff0000, v23
	global_store_dwordx4 v[194:195], v[30:33], off offset:512
	global_store_dwordx4 v[194:195], v[6:9], off offset:528
	v_lshlrev_b32_e32 v37, 16, v24
	v_and_b32_e32 v38, 0xffff0000, v24
	v_add_f32_e32 v6, v27, v29
	v_max3_f32 v8, |v28|, 0, |v34|
	v_add_f32_e32 v7, v166, v26
	v_add_f32_e32 v6, v168, v6
	v_max3_f32 v8, v8, |v35|, |v36|
	v_lshlrev_b32_e32 v39, 16, v25
	v_and_b32_e32 v40, 0xffff0000, v25
	v_add_f32_e32 v7, v167, v7
	v_add_f32_e32 v6, v169, v6
	v_max3_f32 v8, v8, |v37|, |v38|
	v_pk_mul_f32 v[44:45], v[98:99], v[30:31]
	v_add_f32_e32 v6, v7, v6
	v_cvt_pk_bf16_f32 v22, v44, v45
	v_max3_f32 v7, v8, |v39|, |v40|
	v_lshlrev_b32_e32 v9, 16, v22
	v_and_b32_e32 v26, 0xffff0000, v22
	v_pk_mul_f32 v[42:43], v[96:97], v[32:33]
	v_max3_f32 v7, v7, |v9|, |v26|
	v_cvt_pk_bf16_f32 v23, v42, v43
	v_cvt_pk_bf16_f32 v24, v162, v163
	v_cvt_pk_bf16_f32 v25, v160, v161
	ds_bpermute_b32 v8, v233, v6
	v_lshlrev_b32_e32 v27, 16, v23
	v_and_b32_e32 v28, 0xffff0000, v23
	v_lshlrev_b32_e32 v29, 16, v24
	v_and_b32_e32 v30, 0xffff0000, v24
	v_max3_f32 v7, v7, |v27|, |v28|
	v_lshlrev_b32_e32 v31, 16, v25
	v_and_b32_e32 v32, 0xffff0000, v25
	v_max3_f32 v7, v7, |v29|, |v30|
	v_max3_f32 v9, v7, |v31|, |v32|
	ds_bpermute_b32 v26, v233, v9
	s_waitcnt lgkmcnt(1)
	v_add_f32_e32 v6, v6, v8
	ds_bpermute_b32 v7, v216, v6
	global_store_dwordx4 v[180:181], v[22:25], off offset:256
	s_waitcnt lgkmcnt(1)
	v_max_f32_e32 v8, v26, v26
	v_max_f32_e32 v8, v9, v8
	ds_bpermute_b32 v9, v216, v8
	s_and_saveexec_b64 s[42:43], s[0:1]
	s_cbranch_execz .LBB0_3625
	s_waitcnt lgkmcnt(0)
	v_max_f32_e32 v9, v9, v9
	v_max_f32_e32 v8, v8, v8
	v_add_f32_e32 v23, v6, v7
	v_lshlrev_b64 v[6:7], 7, v[192:193]
	v_max_f32_e32 v22, v8, v9
	v_lshl_add_u64 v[8:9], s[26:27], 0, v[6:7]
	s_lshl_b64 s[70:71], s[40:41], 2
	v_lshl_add_u64 v[6:7], s[28:29], 0, v[6:7]
	v_lshl_add_u64 v[8:9], v[8:9], 0, s[70:71]
	s_lshl_b32 s12, s59, 2
	v_lshl_add_u64 v[6:7], v[6:7], 0, s[70:71]
	v_lshl_add_u64 v[8:9], v[8:9], 0, s[12:13]
	v_lshl_add_u64 v[6:7], v[6:7], 0, s[12:13]
	global_store_dword v[8:9], v23, off
	global_store_dword v[6:7], v22, off
.LBB0_3625:
	s_or_b64 exec, exec, s[42:43]
	v_or_b32_e32 v36, 16, v176
	v_ashrrev_i32_e32 v37, 31, v36
	s_waitcnt lgkmcnt(1)
	v_lshlrev_b64 v[6:7], 13, v[36:37]
	v_lshl_add_u64 v[6:7], s[16:17], 0, v[6:7]
	v_lshl_add_u64 v[40:41], v[90:91], 2, v[6:7]
	global_load_dwordx4 v[26:29], v[40:41], off offset:16
	global_load_dwordx4 v[30:33], v[40:41], off
	s_waitcnt lgkmcnt(0)
	global_load_dwordx4 v[6:9], v[40:41], off offset:528
	global_load_dwordx4 v[22:25], v[40:41], off offset:512
	global_load_dword v34, v[196:197], off offset:512
	v_lshlrev_b64 v[38:39], 12, v[176:177]
	v_lshl_add_u64 v[38:39], s[22:23], 0, v[38:39]
	v_lshl_add_u64 v[38:39], v[90:91], 1, v[38:39]
	s_waitcnt vmcnt(0)
	v_pk_mul_f32 v[44:45], v[34:35], v[128:129] op_sel_hi:[0,1]
	v_pk_mul_f32 v[128:129], v[34:35], v[150:151] op_sel_hi:[0,1]
	v_pk_mul_f32 v[42:43], v[34:35], v[146:147] op_sel_hi:[0,1]
	v_pk_mul_f32 v[146:147], v[34:35], v[148:149] op_sel_hi:[0,1]
	v_pk_mul_f32 v[148:149], v[34:35], v[156:157] op_sel_hi:[0,1]
	v_pk_mul_f32 v[150:151], v[34:35], v[152:153] op_sel_hi:[0,1]
	v_pk_fma_f32 v[14:15], v[94:95], v[128:129], v[14:15]
	v_pk_mul_f32 v[152:153], v[34:35], v[158:159] op_sel_hi:[0,1]
	v_pk_mul_f32 v[34:35], v[34:35], v[154:155] op_sel_hi:[0,1]
	v_pk_fma_f32 v[20:21], v[86:87], v[44:45], v[20:21]
	v_pk_fma_f32 v[18:19], v[88:89], v[42:43], v[18:19]
	v_pk_fma_f32 v[16:17], v[92:93], v[146:147], v[16:17]
	v_pk_fma_f32 v[12:13], v[104:105], v[150:151], v[12:13]
	v_pk_fma_f32 v[10:11], v[106:107], v[148:149], v[10:11]
	v_mul_f32_e32 v156, v15, v15
	v_pk_fma_f32 v[4:5], v[110:111], v[34:35], v[4:5]
	v_pk_fma_f32 v[2:3], v[108:109], v[152:153], v[2:3]
	global_store_dwordx4 v[178:179], v[18:21], off
	global_store_dwordx4 v[178:179], v[14:17], off offset:16
	v_mul_f32_e32 v154, v19, v19
	v_mul_f32_e32 v155, v21, v21
	v_mul_f32_e32 v157, v17, v17
	v_pk_mul_f32 v[34:35], v[78:79], v[20:21]
	v_pk_mul_f32 v[42:43], v[80:81], v[18:19]
	v_pk_mul_f32 v[128:129], v[84:85], v[14:15]
	v_mul_f32_e32 v19, v11, v11
	v_mul_f32_e32 v21, v13, v13
	v_fmac_f32_e32 v156, v14, v14
	v_cvt_pk_bf16_f32 v14, v42, v43
	v_pk_mul_f32 v[44:45], v[82:83], v[16:17]
	v_mul_f32_e32 v158, v3, v3
	v_mul_f32_e32 v159, v5, v5
	v_fmac_f32_e32 v154, v18, v18
	v_fmac_f32_e32 v155, v20, v20
	v_fmac_f32_e32 v157, v16, v16
	v_cvt_pk_bf16_f32 v15, v34, v35
	v_cvt_pk_bf16_f32 v16, v128, v129
	v_cvt_pk_bf16_f32 v17, v44, v45
	v_fmac_f32_e32 v19, v10, v10
	v_fmac_f32_e32 v21, v12, v12
	global_store_dwordx4 v[38:39], v[14:17], off
	v_lshlrev_b32_e32 v20, 16, v14
	v_pk_mul_f32 v[150:151], v[100:101], v[4:5]
	v_and_b32_e32 v14, 0xffff0000, v14
	v_pk_mul_f32 v[152:153], v[102:103], v[2:3]
	v_fmac_f32_e32 v158, v2, v2
	v_fmac_f32_e32 v159, v4, v4
	v_add_f32_e32 v18, v154, v155
	v_lshlrev_b32_e32 v34, 16, v15
	v_and_b32_e32 v15, 0xffff0000, v15
	global_store_dwordx4 v[178:179], v[10:13], off offset:512
	global_store_dwordx4 v[178:179], v[2:5], off offset:528
	v_lshlrev_b32_e32 v35, 16, v16
	v_and_b32_e32 v16, 0xffff0000, v16
	v_add_f32_e32 v2, v19, v21
	v_max3_f32 v4, |v20|, 0, |v14|
	v_add_f32_e32 v3, v156, v18
	v_add_f32_e32 v2, v158, v2
	v_max3_f32 v4, v4, |v34|, |v15|
	v_lshlrev_b32_e32 v42, 16, v17
	v_and_b32_e32 v17, 0xffff0000, v17
	v_add_f32_e32 v3, v157, v3
	v_add_f32_e32 v2, v159, v2
	v_max3_f32 v4, v4, |v35|, |v16|
	v_pk_mul_f32 v[148:149], v[98:99], v[10:11]
	v_add_f32_e32 v2, v3, v2
	v_cvt_pk_bf16_f32 v10, v148, v149
	v_max3_f32 v3, v4, |v42|, |v17|
	v_lshlrev_b32_e32 v5, 16, v10
	v_and_b32_e32 v14, 0xffff0000, v10
	v_pk_mul_f32 v[146:147], v[96:97], v[12:13]
	v_max3_f32 v3, v3, |v5|, |v14|
	v_cvt_pk_bf16_f32 v11, v146, v147
	v_cvt_pk_bf16_f32 v12, v152, v153
	v_cvt_pk_bf16_f32 v13, v150, v151
	ds_bpermute_b32 v4, v233, v2
	v_lshlrev_b32_e32 v18, 16, v11
	v_and_b32_e32 v19, 0xffff0000, v11
	v_lshlrev_b32_e32 v20, 16, v12
	v_and_b32_e32 v21, 0xffff0000, v12
	v_max3_f32 v3, v3, |v18|, |v19|
	v_lshlrev_b32_e32 v43, 16, v13
	v_and_b32_e32 v44, 0xffff0000, v13
	v_max3_f32 v3, v3, |v20|, |v21|
	v_max3_f32 v5, v3, |v43|, |v44|
	ds_bpermute_b32 v14, v233, v5
	s_waitcnt lgkmcnt(1)
	v_add_f32_e32 v2, v2, v4
	ds_bpermute_b32 v3, v216, v2
	global_store_dwordx4 v[38:39], v[10:13], off offset:256
	s_waitcnt lgkmcnt(1)
	v_max_f32_e32 v4, v14, v14
	v_max_f32_e32 v4, v5, v4
	ds_bpermute_b32 v5, v216, v4
	s_and_saveexec_b64 s[42:43], s[0:1]
	s_cbranch_execz .LBB0_3627
	s_waitcnt lgkmcnt(0)
	v_max_f32_e32 v5, v5, v5
	v_max_f32_e32 v4, v4, v4
	v_add_f32_e32 v11, v2, v3
	v_lshlrev_b64 v[2:3], 7, v[176:177]
	v_max_f32_e32 v10, v4, v5
	v_lshl_add_u64 v[4:5], s[26:27], 0, v[2:3]
	s_lshl_b64 s[70:71], s[40:41], 2
	v_lshl_add_u64 v[2:3], s[28:29], 0, v[2:3]
	v_lshl_add_u64 v[4:5], v[4:5], 0, s[70:71]
	s_lshl_b32 s12, s59, 2
	v_lshl_add_u64 v[2:3], v[2:3], 0, s[70:71]
	v_lshl_add_u64 v[4:5], v[4:5], 0, s[12:13]
	v_lshl_add_u64 v[2:3], v[2:3], 0, s[12:13]
	global_store_dword v[4:5], v11, off
	global_store_dword v[2:3], v10, off
.LBB0_3627:
	s_or_b64 exec, exec, s[42:43]
	v_or_b32_e32 v34, 32, v176
	v_ashrrev_i32_e32 v35, 31, v34
	s_waitcnt lgkmcnt(1)
	v_lshlrev_b64 v[2:3], 13, v[34:35]
	v_lshl_add_u64 v[2:3], s[16:17], 0, v[2:3]
	v_lshl_add_u64 v[38:39], v[90:91], 2, v[2:3]
	global_load_dwordx4 v[14:17], v[38:39], off offset:16
	global_load_dwordx4 v[18:21], v[38:39], off
	s_waitcnt lgkmcnt(0)
	global_load_dwordx4 v[2:5], v[38:39], off offset:528
	global_load_dwordx4 v[10:13], v[38:39], off offset:512
	v_lshl_add_u64 v[42:43], v[36:37], 2, s[18:19]
	global_load_dword v42, v[42:43], off
	v_lshlrev_b64 v[44:45], 12, v[36:37]
	v_lshl_add_u64 v[44:45], s[22:23], 0, v[44:45]
	v_lshl_add_u64 v[44:45], v[90:91], 1, v[44:45]
	s_waitcnt vmcnt(0)
	v_pk_mul_f32 v[118:119], v[42:43], v[118:119] op_sel_hi:[0,1]
	v_pk_mul_f32 v[114:115], v[42:43], v[114:115] op_sel_hi:[0,1]
	v_pk_mul_f32 v[112:113], v[42:43], v[112:113] op_sel_hi:[0,1]
	v_pk_mul_f32 v[116:117], v[42:43], v[116:117] op_sel_hi:[0,1]
	v_pk_mul_f32 v[124:125], v[42:43], v[124:125] op_sel_hi:[0,1]
	v_pk_mul_f32 v[120:121], v[42:43], v[120:121] op_sel_hi:[0,1]
	v_pk_fma_f32 v[26:27], v[94:95], v[118:119], v[26:27]
	v_pk_mul_f32 v[126:127], v[42:43], v[126:127] op_sel_hi:[0,1]
	v_pk_mul_f32 v[42:43], v[42:43], v[122:123] op_sel_hi:[0,1]
	v_pk_fma_f32 v[32:33], v[86:87], v[112:113], v[32:33]
	v_pk_fma_f32 v[30:31], v[88:89], v[114:115], v[30:31]
	v_pk_fma_f32 v[28:29], v[92:93], v[116:117], v[28:29]
	v_pk_fma_f32 v[24:25], v[104:105], v[120:121], v[24:25]
	v_pk_fma_f32 v[22:23], v[106:107], v[124:125], v[22:23]
	v_mul_f32_e32 v128, v27, v27
	v_pk_fma_f32 v[8:9], v[110:111], v[42:43], v[8:9]
	v_pk_fma_f32 v[6:7], v[108:109], v[126:127], v[6:7]
	global_store_dwordx4 v[40:41], v[30:33], off
	global_store_dwordx4 v[40:41], v[26:29], off offset:16
	v_mul_f32_e32 v126, v31, v31
	v_mul_f32_e32 v127, v33, v33
	v_mul_f32_e32 v129, v29, v29
	v_pk_mul_f32 v[42:43], v[78:79], v[32:33]
	v_pk_mul_f32 v[112:113], v[80:81], v[30:31]
	v_pk_mul_f32 v[116:117], v[84:85], v[26:27]
	v_mul_f32_e32 v31, v23, v23
	v_mul_f32_e32 v33, v25, v25
	v_fmac_f32_e32 v128, v26, v26
	v_cvt_pk_bf16_f32 v26, v112, v113
	v_pk_mul_f32 v[114:115], v[82:83], v[28:29]
	v_mul_f32_e32 v146, v7, v7
	v_mul_f32_e32 v147, v9, v9
	v_fmac_f32_e32 v126, v30, v30
	v_fmac_f32_e32 v127, v32, v32
	v_fmac_f32_e32 v129, v28, v28
	v_cvt_pk_bf16_f32 v27, v42, v43
	v_cvt_pk_bf16_f32 v28, v116, v117
	v_cvt_pk_bf16_f32 v29, v114, v115
	v_fmac_f32_e32 v31, v22, v22
	v_fmac_f32_e32 v33, v24, v24
	global_store_dwordx4 v[44:45], v[26:29], off
	v_lshlrev_b32_e32 v32, 16, v26
	v_pk_mul_f32 v[122:123], v[100:101], v[8:9]
	v_and_b32_e32 v26, 0xffff0000, v26
	v_pk_mul_f32 v[124:125], v[102:103], v[6:7]
	v_fmac_f32_e32 v146, v6, v6
	v_fmac_f32_e32 v147, v8, v8
	v_add_f32_e32 v30, v126, v127
	v_lshlrev_b32_e32 v42, 16, v27
	v_and_b32_e32 v27, 0xffff0000, v27
	global_store_dwordx4 v[40:41], v[22:25], off offset:512
	global_store_dwordx4 v[40:41], v[6:9], off offset:528
	v_lshlrev_b32_e32 v43, 16, v28
	v_and_b32_e32 v28, 0xffff0000, v28
	v_add_f32_e32 v6, v31, v33
	v_max3_f32 v8, |v32|, 0, |v26|
	v_add_f32_e32 v7, v128, v30
	v_add_f32_e32 v6, v146, v6
	v_max3_f32 v8, v8, |v42|, |v27|
	v_lshlrev_b32_e32 v112, 16, v29
	v_and_b32_e32 v29, 0xffff0000, v29
	v_add_f32_e32 v7, v129, v7
	v_add_f32_e32 v6, v147, v6
	v_max3_f32 v8, v8, |v43|, |v28|
	v_pk_mul_f32 v[120:121], v[98:99], v[22:23]
	v_add_f32_e32 v6, v7, v6
	v_cvt_pk_bf16_f32 v22, v120, v121
	v_max3_f32 v7, v8, |v112|, |v29|
	v_lshlrev_b32_e32 v9, 16, v22
	v_and_b32_e32 v26, 0xffff0000, v22
	v_pk_mul_f32 v[118:119], v[96:97], v[24:25]
	v_max3_f32 v7, v7, |v9|, |v26|
	v_cvt_pk_bf16_f32 v23, v118, v119
	v_cvt_pk_bf16_f32 v24, v124, v125
	v_cvt_pk_bf16_f32 v25, v122, v123
	ds_bpermute_b32 v8, v233, v6
	v_lshlrev_b32_e32 v30, 16, v23
	v_and_b32_e32 v31, 0xffff0000, v23
	v_lshlrev_b32_e32 v32, 16, v24
	v_and_b32_e32 v33, 0xffff0000, v24
	v_max3_f32 v7, v7, |v30|, |v31|
	v_lshlrev_b32_e32 v40, 16, v25
	v_and_b32_e32 v41, 0xffff0000, v25
	v_max3_f32 v7, v7, |v32|, |v33|
	v_max3_f32 v9, v7, |v40|, |v41|
	ds_bpermute_b32 v26, v233, v9
	s_waitcnt lgkmcnt(1)
	v_add_f32_e32 v6, v6, v8
	ds_bpermute_b32 v7, v216, v6
	global_store_dwordx4 v[44:45], v[22:25], off offset:256
	s_waitcnt lgkmcnt(1)
	v_max_f32_e32 v8, v26, v26
	v_max_f32_e32 v8, v9, v8
	ds_bpermute_b32 v9, v216, v8
	s_and_saveexec_b64 s[42:43], s[0:1]
	s_cbranch_execz .LBB0_3629
	s_waitcnt lgkmcnt(0)
	v_max_f32_e32 v9, v9, v9
	v_max_f32_e32 v8, v8, v8
	v_add_f32_e32 v23, v6, v7
	v_lshlrev_b64 v[6:7], 7, v[36:37]
	v_max_f32_e32 v22, v8, v9
	v_lshl_add_u64 v[8:9], s[26:27], 0, v[6:7]
	s_lshl_b64 s[70:71], s[40:41], 2
	v_lshl_add_u64 v[6:7], s[28:29], 0, v[6:7]
	v_lshl_add_u64 v[8:9], v[8:9], 0, s[70:71]
	s_lshl_b32 s12, s59, 2
	v_lshl_add_u64 v[6:7], v[6:7], 0, s[70:71]
	v_lshl_add_u64 v[8:9], v[8:9], 0, s[12:13]
	v_lshl_add_u64 v[6:7], v[6:7], 0, s[12:13]
	global_store_dword v[8:9], v23, off
	global_store_dword v[6:7], v22, off
.LBB0_3629:
	s_or_b64 exec, exec, s[42:43]
	v_or_b32_e32 v36, 48, v176
	v_ashrrev_i32_e32 v37, 31, v36
	s_waitcnt lgkmcnt(1)
	v_lshlrev_b64 v[6:7], 13, v[36:37]
	v_lshl_add_u64 v[6:7], s[16:17], 0, v[6:7]
	v_lshl_add_u64 v[40:41], v[90:91], 2, v[6:7]
	global_load_dwordx4 v[26:29], v[40:41], off offset:16
	global_load_dwordx4 v[30:33], v[40:41], off
	s_waitcnt lgkmcnt(0)
	global_load_dwordx4 v[6:9], v[40:41], off offset:528
	global_load_dwordx4 v[22:25], v[40:41], off offset:512
	v_lshl_add_u64 v[42:43], v[34:35], 2, s[18:19]
	global_load_dword v42, v[42:43], off
	v_lshlrev_b64 v[44:45], 12, v[34:35]
	v_lshl_add_u64 v[44:45], s[22:23], 0, v[44:45]
	v_lshl_add_u64 v[44:45], v[90:91], 1, v[44:45]
	s_waitcnt vmcnt(0)
	v_pk_mul_f32 v[68:69], v[42:43], v[68:69] op_sel_hi:[0,1]
	v_pk_mul_f32 v[64:65], v[42:43], v[64:65] op_sel_hi:[0,1]
	v_pk_mul_f32 v[62:63], v[42:43], v[62:63] op_sel_hi:[0,1]
	v_pk_mul_f32 v[66:67], v[42:43], v[66:67] op_sel_hi:[0,1]
	v_pk_mul_f32 v[74:75], v[42:43], v[74:75] op_sel_hi:[0,1]
	v_pk_mul_f32 v[70:71], v[42:43], v[70:71] op_sel_hi:[0,1]
	v_pk_fma_f32 v[14:15], v[94:95], v[68:69], v[14:15]
	v_pk_mul_f32 v[76:77], v[42:43], v[76:77] op_sel_hi:[0,1]
	v_pk_mul_f32 v[42:43], v[42:43], v[72:73] op_sel_hi:[0,1]
	v_pk_fma_f32 v[20:21], v[86:87], v[62:63], v[20:21]
	v_pk_fma_f32 v[18:19], v[88:89], v[64:65], v[18:19]
	v_pk_fma_f32 v[16:17], v[92:93], v[66:67], v[16:17]
	v_pk_fma_f32 v[12:13], v[104:105], v[70:71], v[12:13]
	v_pk_fma_f32 v[10:11], v[106:107], v[74:75], v[10:11]
	v_mul_f32_e32 v112, v15, v15
	v_pk_fma_f32 v[4:5], v[110:111], v[42:43], v[4:5]
	v_pk_fma_f32 v[2:3], v[108:109], v[76:77], v[2:3]
	global_store_dwordx4 v[38:39], v[18:21], off
	global_store_dwordx4 v[38:39], v[14:17], off offset:16
	v_mul_f32_e32 v76, v19, v19
	v_mul_f32_e32 v77, v21, v21
	v_mul_f32_e32 v113, v17, v17
	v_pk_mul_f32 v[42:43], v[78:79], v[20:21]
	v_pk_mul_f32 v[62:63], v[80:81], v[18:19]
	v_pk_mul_f32 v[66:67], v[84:85], v[14:15]
	v_mul_f32_e32 v19, v11, v11
	v_mul_f32_e32 v21, v13, v13
	v_fmac_f32_e32 v112, v14, v14
	v_cvt_pk_bf16_f32 v14, v62, v63
	v_pk_mul_f32 v[64:65], v[82:83], v[16:17]
	v_mul_f32_e32 v114, v3, v3
	v_mul_f32_e32 v115, v5, v5
	v_fmac_f32_e32 v76, v18, v18
	v_fmac_f32_e32 v77, v20, v20
	v_fmac_f32_e32 v113, v16, v16
	v_cvt_pk_bf16_f32 v15, v42, v43
	v_cvt_pk_bf16_f32 v16, v66, v67
	v_cvt_pk_bf16_f32 v17, v64, v65
	v_fmac_f32_e32 v19, v10, v10
	v_fmac_f32_e32 v21, v12, v12
	global_store_dwordx4 v[44:45], v[14:17], off
	v_lshlrev_b32_e32 v20, 16, v14
	v_pk_mul_f32 v[72:73], v[100:101], v[4:5]
	v_and_b32_e32 v14, 0xffff0000, v14
	v_pk_mul_f32 v[74:75], v[102:103], v[2:3]
	v_fmac_f32_e32 v114, v2, v2
	v_fmac_f32_e32 v115, v4, v4
	v_add_f32_e32 v18, v76, v77
	v_lshlrev_b32_e32 v42, 16, v15
	v_and_b32_e32 v15, 0xffff0000, v15
	global_store_dwordx4 v[38:39], v[10:13], off offset:512
	global_store_dwordx4 v[38:39], v[2:5], off offset:528
	v_lshlrev_b32_e32 v43, 16, v16
	v_and_b32_e32 v16, 0xffff0000, v16
	v_add_f32_e32 v2, v19, v21
	v_max3_f32 v4, |v20|, 0, |v14|
	v_add_f32_e32 v3, v112, v18
	v_add_f32_e32 v2, v114, v2
	v_max3_f32 v4, v4, |v42|, |v15|
	v_lshlrev_b32_e32 v62, 16, v17
	v_and_b32_e32 v17, 0xffff0000, v17
	v_add_f32_e32 v3, v113, v3
	v_add_f32_e32 v2, v115, v2
	v_max3_f32 v4, v4, |v43|, |v16|
	v_pk_mul_f32 v[70:71], v[98:99], v[10:11]
	v_add_f32_e32 v2, v3, v2
	v_cvt_pk_bf16_f32 v10, v70, v71
	v_max3_f32 v3, v4, |v62|, |v17|
	v_lshlrev_b32_e32 v5, 16, v10
	v_and_b32_e32 v14, 0xffff0000, v10
	v_pk_mul_f32 v[68:69], v[96:97], v[12:13]
	v_max3_f32 v3, v3, |v5|, |v14|
	v_cvt_pk_bf16_f32 v11, v68, v69
	v_cvt_pk_bf16_f32 v12, v74, v75
	v_cvt_pk_bf16_f32 v13, v72, v73
	ds_bpermute_b32 v4, v233, v2
	v_lshlrev_b32_e32 v18, 16, v11
	v_and_b32_e32 v19, 0xffff0000, v11
	v_lshlrev_b32_e32 v20, 16, v12
	v_and_b32_e32 v21, 0xffff0000, v12
	v_max3_f32 v3, v3, |v18|, |v19|
	v_lshlrev_b32_e32 v38, 16, v13
	v_and_b32_e32 v39, 0xffff0000, v13
	v_max3_f32 v3, v3, |v20|, |v21|
	v_max3_f32 v5, v3, |v38|, |v39|
	ds_bpermute_b32 v14, v233, v5
	s_waitcnt lgkmcnt(1)
	v_add_f32_e32 v2, v2, v4
	ds_bpermute_b32 v3, v216, v2
	global_store_dwordx4 v[44:45], v[10:13], off offset:256
	s_waitcnt lgkmcnt(1)
	v_max_f32_e32 v4, v14, v14
	v_max_f32_e32 v4, v5, v4
	ds_bpermute_b32 v5, v216, v4
	s_and_saveexec_b64 s[42:43], s[0:1]
	s_cbranch_execz .LBB0_3631
	s_waitcnt lgkmcnt(0)
	v_max_f32_e32 v5, v5, v5
	v_max_f32_e32 v4, v4, v4
	v_add_f32_e32 v11, v2, v3
	v_lshlrev_b64 v[2:3], 7, v[34:35]
	v_max_f32_e32 v10, v4, v5
	v_lshl_add_u64 v[4:5], s[26:27], 0, v[2:3]
	s_lshl_b64 s[70:71], s[40:41], 2
	v_lshl_add_u64 v[2:3], s[28:29], 0, v[2:3]
	v_lshl_add_u64 v[4:5], v[4:5], 0, s[70:71]
	s_lshl_b32 s12, s59, 2
	v_lshl_add_u64 v[2:3], v[2:3], 0, s[70:71]
	v_lshl_add_u64 v[4:5], v[4:5], 0, s[12:13]
	v_lshl_add_u64 v[2:3], v[2:3], 0, s[12:13]
	global_store_dword v[4:5], v11, off
	global_store_dword v[2:3], v10, off
.LBB0_3631:
	s_or_b64 exec, exec, s[42:43]
	s_waitcnt lgkmcnt(1)
	v_lshl_add_u64 v[2:3], v[36:37], 2, s[18:19]
	global_load_dword v2, v[2:3], off
	s_waitcnt lgkmcnt(0)
	v_lshlrev_b64 v[4:5], 12, v[36:37]
	v_lshl_add_u64 v[4:5], s[22:23], 0, v[4:5]
	v_lshl_add_u64 v[18:19], v[90:91], 1, v[4:5]
	s_waitcnt vmcnt(0)
	v_pk_mul_f32 v[10:11], v[2:3], v[48:49] op_sel_hi:[0,1]
	v_pk_mul_f32 v[4:5], v[2:3], v[46:47] op_sel_hi:[0,1]
	v_pk_mul_f32 v[14:15], v[2:3], v[52:53] op_sel_hi:[0,1]
	v_pk_mul_f32 v[12:13], v[2:3], v[50:51] op_sel_hi:[0,1]
	v_pk_mul_f32 v[20:21], v[2:3], v[58:59] op_sel_hi:[0,1]
	v_pk_mul_f32 v[16:17], v[2:3], v[54:55] op_sel_hi:[0,1]
	v_pk_mul_f32 v[34:35], v[2:3], v[60:61] op_sel_hi:[0,1]
	v_pk_mul_f32 v[38:39], v[2:3], v[56:57] op_sel_hi:[0,1]
	v_pk_fma_f32 v[2:3], v[88:89], v[10:11], v[30:31]
	v_pk_fma_f32 v[4:5], v[86:87], v[4:5], v[32:33]
	v_pk_fma_f32 v[12:13], v[92:93], v[12:13], v[28:29]
	v_pk_fma_f32 v[8:9], v[110:111], v[38:39], v[8:9]
	v_mul_f32_e32 v38, v3, v3
	v_pk_fma_f32 v[10:11], v[94:95], v[14:15], v[26:27]
	v_pk_fma_f32 v[14:15], v[106:107], v[20:21], v[22:23]
	global_store_dwordx4 v[40:41], v[2:5], off
	global_store_dwordx4 v[40:41], v[10:13], off offset:16
	v_mul_f32_e32 v39, v5, v5
	v_mul_f32_e32 v43, v13, v13
	v_pk_mul_f32 v[22:23], v[80:81], v[2:3]
	v_fmac_f32_e32 v38, v2, v2
	v_cvt_pk_bf16_f32 v2, v22, v23
	v_pk_fma_f32 v[16:17], v[104:105], v[16:17], v[24:25]
	v_pk_mul_f32 v[20:21], v[78:79], v[4:5]
	v_pk_mul_f32 v[24:25], v[82:83], v[12:13]
	v_pk_mul_f32 v[26:27], v[84:85], v[10:11]
	v_fmac_f32_e32 v39, v4, v4
	v_fmac_f32_e32 v43, v12, v12
	v_cvt_pk_bf16_f32 v3, v20, v21
	v_cvt_pk_bf16_f32 v4, v26, v27
	v_cvt_pk_bf16_f32 v5, v24, v25
	global_store_dwordx4 v[18:19], v[2:5], off
	v_lshlrev_b32_e32 v12, 16, v2
	v_lshlrev_b32_e32 v20, 16, v3
	v_and_b32_e32 v2, 0xffff0000, v2
	v_and_b32_e32 v3, 0xffff0000, v3
	v_max3_f32 v2, |v12|, 0, |v2|
	v_pk_fma_f32 v[6:7], v[108:109], v[34:35], v[6:7]
	v_mul_f32_e32 v42, v11, v11
	v_mul_f32_e32 v11, v15, v15
	v_mul_f32_e32 v13, v17, v17
	v_lshlrev_b32_e32 v21, 16, v4
	v_and_b32_e32 v4, 0xffff0000, v4
	v_max3_f32 v2, v2, |v20|, |v3|
	v_mul_f32_e32 v44, v7, v7
	v_fmac_f32_e32 v11, v14, v14
	v_fmac_f32_e32 v13, v16, v16
	v_lshlrev_b32_e32 v22, 16, v5
	v_and_b32_e32 v5, 0xffff0000, v5
	v_max3_f32 v2, v2, |v21|, |v4|
	v_pk_mul_f32 v[30:31], v[98:99], v[14:15]
	v_pk_mul_f32 v[34:35], v[102:103], v[6:7]
	v_fmac_f32_e32 v44, v6, v6
	global_store_dwordx4 v[40:41], v[14:17], off offset:512
	global_store_dwordx4 v[40:41], v[6:9], off offset:528
	v_add_f32_e32 v11, v11, v13
	v_max3_f32 v2, v2, |v22|, |v5|
	v_cvt_pk_bf16_f32 v6, v30, v31
	v_mul_f32_e32 v45, v9, v9
	v_lshlrev_b32_e32 v12, 16, v6
	v_and_b32_e32 v13, 0xffff0000, v6
	v_pk_mul_f32 v[28:29], v[96:97], v[16:17]
	v_fmac_f32_e32 v42, v10, v10
	v_add_f32_e32 v10, v38, v39
	v_cvt_pk_bf16_f32 v7, v28, v29
	v_max3_f32 v2, v2, |v12|, |v13|
	v_lshlrev_b32_e32 v14, 16, v7
	v_and_b32_e32 v15, 0xffff0000, v7
	v_pk_mul_f32 v[32:33], v[100:101], v[8:9]
	v_fmac_f32_e32 v45, v8, v8
	v_cvt_pk_bf16_f32 v8, v34, v35
	v_add_f32_e32 v10, v42, v10
	v_add_f32_e32 v11, v44, v11
	v_lshlrev_b32_e32 v16, 16, v8
	v_and_b32_e32 v17, 0xffff0000, v8
	v_max3_f32 v2, v2, |v14|, |v15|
	v_cvt_pk_bf16_f32 v9, v32, v33
	v_add_f32_e32 v10, v43, v10
	v_lshlrev_b32_e32 v23, 16, v9
	v_and_b32_e32 v24, 0xffff0000, v9
	v_add_f32_e32 v3, v45, v11
	v_max3_f32 v2, v2, |v16|, |v17|
	v_add_f32_e32 v3, v10, v3
	v_max3_f32 v5, v2, |v23|, |v24|
	ds_bpermute_b32 v4, v233, v3
	ds_bpermute_b32 v10, v233, v5
	global_store_dwordx4 v[18:19], v[6:9], off offset:256
	s_waitcnt lgkmcnt(1)
	v_add_f32_e32 v2, v3, v4
	s_waitcnt lgkmcnt(0)
	v_max_f32_e32 v4, v10, v10
	v_max_f32_e32 v4, v5, v4
	ds_bpermute_b32 v3, v216, v2
	ds_bpermute_b32 v5, v216, v4
	s_and_saveexec_b64 s[42:43], s[0:1]
	s_cbranch_execz .LBB0_3633
	s_waitcnt lgkmcnt(0)
	v_max_f32_e32 v5, v5, v5
	v_max_f32_e32 v4, v4, v4
	v_add_f32_e32 v7, v2, v3
	v_lshlrev_b64 v[2:3], 7, v[36:37]
	v_max_f32_e32 v6, v4, v5
	v_lshl_add_u64 v[4:5], s[26:27], 0, v[2:3]
	s_lshl_b64 s[40:41], s[40:41], 2
	v_lshl_add_u64 v[2:3], s[28:29], 0, v[2:3]
	v_lshl_add_u64 v[4:5], v[4:5], 0, s[40:41]
	s_lshl_b32 s12, s59, 2
	v_lshl_add_u64 v[2:3], v[2:3], 0, s[40:41]
	v_lshl_add_u64 v[4:5], v[4:5], 0, s[12:13]
	v_lshl_add_u64 v[2:3], v[2:3], 0, s[12:13]
	global_store_dword v[4:5], v7, off
	global_store_dword v[2:3], v6, off

.LBB0_3882:
	s_lshr_b32 s24, s55, 4
	s_add_i32 s24, s24, -1
	s_cmp_gt_i32 s55, 31
	v_lshl_add_u32 v164, s55, 8, v166
	s_cselect_b32 s24, s24, 0
	v_or_b32_e32 v188, 16, v164
	v_lshl_or_b32 v130, s56, 8, v168
	s_mul_hi_i32 s25, s24, 0xc000
	s_mul_i32 s24, s24, 0xc000
	v_ashrrev_i32_e32 v165, 31, v164
	v_ashrrev_i32_e32 v189, 31, v188
	s_add_u32 s24, s43, s24
	v_ashrrev_i32_e32 v131, 31, v130
	v_lshlrev_b64 v[172:173], 13, v[164:165]
	v_lshlrev_b64 v[188:189], 13, v[188:189]
	s_addc_u32 s25, s44, s25
	v_lshlrev_b64 v[162:163], 2, v[130:131]
	v_lshl_add_u64 v[172:173], s[12:13], 0, v[172:173]
	v_lshl_add_u64 v[188:189], s[12:13], 0, v[188:189]
	v_lshl_add_u64 v[134:135], s[24:25], 0, v[162:163]
	v_lshl_add_u64 v[204:205], v[172:173], 0, v[162:163]
	v_lshl_add_u64 v[206:207], v[188:189], 0, v[162:163]
	global_load_dwordx4 v[138:141], v[134:135], off offset:16
	global_load_dwordx4 v[142:145], v[134:135], off
	global_load_dwordx4 v[130:133], v[134:135], off offset:528
	s_nop 0
	global_load_dwordx4 v[134:137], v[134:135], off offset:512
	s_nop 0
	global_load_dwordx4 v[172:175], v[204:205], off offset:16
	global_load_dwordx4 v[176:179], v[204:205], off
	global_load_dwordx4 v[180:183], v[204:205], off offset:528
	global_load_dwordx4 v[184:187], v[204:205], off offset:512
	global_load_dwordx4 v[188:191], v[206:207], off offset:16
	global_load_dwordx4 v[192:195], v[206:207], off
	global_load_dwordx4 v[196:199], v[206:207], off offset:528
	global_load_dwordx4 v[200:203], v[206:207], off offset:512
	s_waitcnt vmcnt(0)
	v_pk_fma_f32 v[128:129], v[128:129], v[144:145], v[178:179]
	v_pk_fma_f32 v[126:127], v[126:127], v[142:143], v[176:177]
	v_pk_fma_f32 v[120:121], v[120:121], v[136:137], v[186:187]
	v_pk_fma_f32 v[118:119], v[118:119], v[134:135], v[184:185]
	v_pk_fma_f32 v[124:125], v[124:125], v[140:141], v[174:175]
	v_pk_fma_f32 v[122:123], v[122:123], v[138:139], v[172:173]
	global_store_dwordx4 v[204:205], v[126:129], off
	global_store_dwordx4 v[204:205], v[122:125], off offset:16
	v_pk_fma_f32 v[116:117], v[116:117], v[132:133], v[182:183]
	v_pk_fma_f32 v[114:115], v[114:115], v[130:131], v[180:181]
	global_store_dwordx4 v[204:205], v[118:121], off offset:512
	global_store_dwordx4 v[204:205], v[114:117], off offset:528
	s_nop 1
	v_or_b32_e32 v114, 32, v164
	v_ashrrev_i32_e32 v115, 31, v114
	v_lshlrev_b64 v[114:115], 13, v[114:115]
	v_lshl_add_u64 v[114:115], s[12:13], 0, v[114:115]
	v_lshl_add_u64 v[172:173], v[114:115], 0, v[162:163]
	global_load_dwordx4 v[114:117], v[172:173], off offset:16
	global_load_dwordx4 v[118:121], v[172:173], off
	global_load_dwordx4 v[122:125], v[172:173], off offset:528
	global_load_dwordx4 v[126:129], v[172:173], off offset:512
	v_pk_fma_f32 v[112:113], v[112:113], v[144:145], v[194:195]
	v_pk_fma_f32 v[110:111], v[110:111], v[142:143], v[192:193]
	v_pk_fma_f32 v[104:105], v[104:105], v[136:137], v[202:203]
	v_pk_fma_f32 v[102:103], v[102:103], v[134:135], v[200:201]
	v_pk_fma_f32 v[108:109], v[108:109], v[140:141], v[190:191]
	v_pk_fma_f32 v[106:107], v[106:107], v[138:139], v[188:189]
	global_store_dwordx4 v[206:207], v[110:113], off
	global_store_dwordx4 v[206:207], v[106:109], off offset:16
	v_pk_fma_f32 v[100:101], v[100:101], v[132:133], v[198:199]
	v_pk_fma_f32 v[98:99], v[98:99], v[130:131], v[196:197]
	global_store_dwordx4 v[206:207], v[102:105], off offset:512
	global_store_dwordx4 v[206:207], v[98:101], off offset:528
	s_nop 1
	v_or_b32_e32 v98, 48, v164
	v_ashrrev_i32_e32 v99, 31, v98
	v_lshlrev_b64 v[98:99], 13, v[98:99]
	v_lshl_add_u64 v[98:99], s[12:13], 0, v[98:99]
	v_lshl_add_u64 v[174:175], v[98:99], 0, v[162:163]
	global_load_dwordx4 v[98:101], v[174:175], off offset:16
	global_load_dwordx4 v[102:105], v[174:175], off
	global_load_dwordx4 v[106:109], v[174:175], off offset:528
	global_load_dwordx4 v[110:113], v[174:175], off offset:512
	s_waitcnt vmcnt(0)
	v_pk_fma_f32 v[96:97], v[96:97], v[144:145], v[120:121]
	v_pk_fma_f32 v[94:95], v[94:95], v[142:143], v[118:119]
	v_pk_fma_f32 v[88:89], v[88:89], v[136:137], v[128:129]
	v_pk_fma_f32 v[86:87], v[86:87], v[134:135], v[126:127]
	v_pk_fma_f32 v[92:93], v[92:93], v[140:141], v[116:117]
	v_pk_fma_f32 v[90:91], v[90:91], v[138:139], v[114:115]
	global_store_dwordx4 v[172:173], v[94:97], off
	global_store_dwordx4 v[172:173], v[90:93], off offset:16
	v_pk_fma_f32 v[84:85], v[84:85], v[132:133], v[124:125]
	v_pk_fma_f32 v[82:83], v[82:83], v[130:131], v[122:123]
	global_store_dwordx4 v[172:173], v[86:89], off offset:512
	global_store_dwordx4 v[172:173], v[82:85], off offset:528
	v_add_co_u32_e32 v116, vcc, s52, v204
	v_lshl_add_u64 v[114:115], v[204:205], 0, s[20:21]
	s_nop 0
	v_addc_co_u32_e32 v117, vcc, 0, v205, vcc
	global_load_dwordx4 v[82:85], v[116:117], off
	global_load_dwordx4 v[86:89], v[114:115], off offset:528
	global_load_dwordx4 v[90:93], v[114:115], off offset:16
	global_load_dwordx4 v[94:97], v[114:115], off offset:512
	v_pk_fma_f32 v[80:81], v[80:81], v[144:145], v[104:105]
	v_pk_fma_f32 v[78:79], v[78:79], v[142:143], v[102:103]
	v_pk_fma_f32 v[72:73], v[72:73], v[136:137], v[112:113]
	v_pk_fma_f32 v[70:71], v[70:71], v[134:135], v[110:111]
	v_pk_fma_f32 v[76:77], v[76:77], v[140:141], v[100:101]
	v_pk_fma_f32 v[74:75], v[74:75], v[138:139], v[98:99]
	global_store_dwordx4 v[174:175], v[78:81], off
	global_store_dwordx4 v[174:175], v[74:77], off offset:16
	v_pk_fma_f32 v[68:69], v[68:69], v[132:133], v[108:109]
	v_pk_fma_f32 v[66:67], v[66:67], v[130:131], v[106:107]
	global_store_dwordx4 v[174:175], v[70:73], off offset:512
	global_store_dwordx4 v[174:175], v[66:69], off offset:528
	s_nop 1
	v_add_u32_e32 v66, 0x90, v164
	v_ashrrev_i32_e32 v67, 31, v66
	v_lshlrev_b64 v[66:67], 13, v[66:67]
	v_lshl_add_u64 v[66:67], s[12:13], 0, v[66:67]
	v_lshl_add_u64 v[98:99], v[66:67], 0, v[162:163]
	global_load_dwordx4 v[66:69], v[98:99], off offset:16
	global_load_dwordx4 v[70:73], v[98:99], off
	global_load_dwordx4 v[74:77], v[98:99], off offset:528
	global_load_dwordx4 v[78:81], v[98:99], off offset:512
	s_waitcnt vmcnt(0)
	v_pk_fma_f32 v[64:65], v[64:65], v[144:145], v[84:85]
	v_pk_fma_f32 v[62:63], v[62:63], v[142:143], v[82:83]
	v_pk_fma_f32 v[56:57], v[56:57], v[136:137], v[96:97]
	v_pk_fma_f32 v[54:55], v[54:55], v[134:135], v[94:95]
	v_pk_fma_f32 v[60:61], v[60:61], v[140:141], v[92:93]
	v_pk_fma_f32 v[58:59], v[58:59], v[138:139], v[90:91]
	global_store_dwordx4 v[116:117], v[62:65], off
	global_store_dwordx4 v[114:115], v[58:61], off offset:16
	v_pk_fma_f32 v[52:53], v[52:53], v[132:133], v[88:89]
	v_pk_fma_f32 v[50:51], v[50:51], v[130:131], v[86:87]
	global_store_dwordx4 v[114:115], v[54:57], off offset:512
	global_store_dwordx4 v[114:115], v[50:53], off offset:528
	s_nop 1
	v_add_u32_e32 v50, 0xa0, v164
	v_ashrrev_i32_e32 v51, 31, v50
	v_lshlrev_b64 v[50:51], 13, v[50:51]
	v_lshl_add_u64 v[50:51], s[12:13], 0, v[50:51]
	v_lshl_add_u64 v[82:83], v[50:51], 0, v[162:163]
	global_load_dwordx4 v[50:53], v[82:83], off offset:16
	global_load_dwordx4 v[54:57], v[82:83], off
	global_load_dwordx4 v[58:61], v[82:83], off offset:528
	global_load_dwordx4 v[62:65], v[82:83], off offset:512
	v_pk_fma_f32 v[48:49], v[48:49], v[144:145], v[72:73]
	v_pk_fma_f32 v[46:47], v[46:47], v[142:143], v[70:71]
	v_pk_fma_f32 v[40:41], v[40:41], v[136:137], v[80:81]
	v_pk_fma_f32 v[38:39], v[38:39], v[134:135], v[78:79]
	v_pk_fma_f32 v[44:45], v[44:45], v[140:141], v[68:69]
	v_pk_fma_f32 v[42:43], v[42:43], v[138:139], v[66:67]
	global_store_dwordx4 v[98:99], v[46:49], off
	global_store_dwordx4 v[98:99], v[42:45], off offset:16
	v_pk_fma_f32 v[36:37], v[36:37], v[132:133], v[76:77]
	v_pk_fma_f32 v[34:35], v[34:35], v[130:131], v[74:75]
	global_store_dwordx4 v[98:99], v[38:41], off offset:512
	global_store_dwordx4 v[98:99], v[34:37], off offset:528
	s_nop 1
	v_add_u32_e32 v34, 0xb0, v164
	v_ashrrev_i32_e32 v35, 31, v34
	v_lshlrev_b64 v[34:35], 13, v[34:35]
	v_lshl_add_u64 v[34:35], s[12:13], 0, v[34:35]
	v_lshl_add_u64 v[66:67], v[34:35], 0, v[162:163]
	global_load_dwordx4 v[34:37], v[66:67], off offset:16
	global_load_dwordx4 v[38:41], v[66:67], off
	global_load_dwordx4 v[42:45], v[66:67], off offset:528
	global_load_dwordx4 v[46:49], v[66:67], off offset:512
	s_waitcnt vmcnt(0)
	v_pk_fma_f32 v[32:33], v[32:33], v[144:145], v[56:57]
	v_pk_fma_f32 v[30:31], v[30:31], v[142:143], v[54:55]
	v_pk_fma_f32 v[24:25], v[24:25], v[136:137], v[64:65]
	v_pk_fma_f32 v[22:23], v[22:23], v[134:135], v[62:63]
	v_pk_fma_f32 v[28:29], v[28:29], v[140:141], v[52:53]
	v_pk_fma_f32 v[26:27], v[26:27], v[138:139], v[50:51]
	global_store_dwordx4 v[82:83], v[30:33], off
	global_store_dwordx4 v[82:83], v[26:29], off offset:16
	v_pk_fma_f32 v[20:21], v[20:21], v[132:133], v[60:61]
	v_pk_fma_f32 v[18:19], v[18:19], v[130:131], v[58:59]
	global_store_dwordx4 v[82:83], v[22:25], off offset:512
	global_store_dwordx4 v[82:83], v[18:21], off offset:528
	v_pk_fma_f32 v[16:17], v[16:17], v[144:145], v[40:41]
	v_pk_fma_f32 v[14:15], v[14:15], v[142:143], v[38:39]
	v_pk_fma_f32 v[8:9], v[8:9], v[136:137], v[48:49]
	v_pk_fma_f32 v[6:7], v[6:7], v[134:135], v[46:47]
	v_pk_fma_f32 v[12:13], v[12:13], v[140:141], v[36:37]
	v_pk_fma_f32 v[10:11], v[10:11], v[138:139], v[34:35]
	global_store_dwordx4 v[66:67], v[14:17], off
	global_store_dwordx4 v[66:67], v[10:13], off offset:16
	v_pk_fma_f32 v[4:5], v[4:5], v[132:133], v[44:45]
	v_pk_fma_f32 v[2:3], v[2:3], v[130:131], v[42:43]
	global_store_dwordx4 v[66:67], v[6:9], off offset:512
	global_store_dwordx4 v[66:67], v[2:5], off offset:528
	s_and_b64 vcc, exec, s[0:1]
	s_mov_b64 s[0:1], -1
	s_cbranch_vccnz .LBB0_3866
	s_andn2_b64 vcc, exec, s[10:11]
	s_cbranch_vccnz .LBB0_3865
	s_barrier
	s_branch .LBB0_3865

.LBB0_3940:
	s_ashr_i32 s3, s2, 31
	s_lshl_b64 s[6:7], s[2:3], 13
	v_lshl_add_u64 v[34:35], v[78:79], 0, s[6:7]
	v_add_co_u32_e32 v90, vcc, 0x1000, v34
	global_load_dwordx4 v[62:65], v[34:35], off
	global_load_dwordx4 v[58:61], v[34:35], off offset:1024
	global_load_dwordx4 v[54:57], v[34:35], off offset:2048
	global_load_dwordx4 v[50:53], v[34:35], off offset:3072
	v_addc_co_u32_e32 v91, vcc, 0, v35, vcc
	global_load_dwordx4 v[46:49], v[90:91], off
	global_load_dwordx4 v[42:45], v[90:91], off offset:1024
	global_load_dwordx4 v[38:41], v[90:91], off offset:2048
	global_load_dwordx4 v[34:37], v[90:91], off offset:3072
	s_add_i32 s2, s2, s8
	s_cmpk_lt_i32 s2, 0x4000
	s_cselect_b64 s[4:5], -1, 0
	s_cmpk_gt_i32 s2, 0x3fff
	s_cbranch_scc1 .LBB0_3942
	s_ashr_i32 s3, s2, 31
	s_lshl_b64 s[10:11], s[2:3], 13
	v_lshl_add_u64 v[18:19], v[78:79], 0, s[10:11]
	v_add_co_u32_e32 v90, vcc, 0x1000, v18
	global_load_dwordx4 v[14:17], v[18:19], off
	global_load_dwordx4 v[10:13], v[18:19], off offset:1024
	global_load_dwordx4 v[6:9], v[18:19], off offset:2048
	global_load_dwordx4 v[2:5], v[18:19], off offset:3072
	v_addc_co_u32_e32 v91, vcc, 0, v19, vcc
	global_load_dwordx4 v[30:33], v[90:91], off
	global_load_dwordx4 v[26:29], v[90:91], off offset:1024
	global_load_dwordx4 v[22:25], v[90:91], off offset:2048
	global_load_dwordx4 v[18:21], v[90:91], off offset:3072
